# mid8 stack plus nt cache policy on the once-read f32 weight loads of all conversion items
# baseline (speedup 1.0000x reference)
;     ...
;     const int kb = item / nblk, nb = item % nblk, k0 = 64 * kb, n0 = 32 * nb;
;     { float wv[32];
;       const float* wp = W + (size_t)(k0 + (lane >> 5)) * ldw + n0 + (lane & 31);
; #pragma unroll
;       for (int i = 0; i < 32; ++i) wv[i] = wp[(size_t)(2 * i) * ldw];
; #pragma unroll
;       for (int i = 0; i < 32; ++i) scr[(2 * i + (lane >> 5)) * 33 + (lane & 31)] = wv[i]; }
; __device__ __forceinline__ void transpose_early(const Args& a, Frame& F, LAS float* scr, int r) {
;     ...
;     if (r < IT_FD) { p0_transpose_item(a.in[I_W1D], D, FF, W1D, 0, D / 32, scr, r, F.lane); return; } r -= IT_FD;
.LBB0_100:
	s_cmp_lt_u32 s15, 0xffffd400
	s_cbranch_scc0 .LBB0_102
	v_mov_b32_e32 v7, v6
	s_and_b32 s9, s15, 0xffc0
	v_ashrrev_i32_e32 v10, 5, v7
	v_add_u32_e32 v4, s9, v10
	v_ashrrev_i32_e32 v5, 31, v4
	s_and_b32 s8, s16, 0x7e0
	v_lshlrev_b64 v[4:5], 13, v[4:5]
	v_lshl_add_u64 v[4:5], s[62:63], 0, v[4:5]
	s_lshl_b32 s6, s8, 2
	v_lshlrev_b32_e32 v2, 2, v7
	v_lshl_add_u64 v[4:5], v[4:5], 0, s[6:7]
	v_and_b32_e32 v2, 0x7c, v2
	v_lshl_add_u64 v[4:5], v[4:5], 0, v[2:3]
	s_movk_i32 s6, 0x4000
	v_add_co_u32_e32 v8, vcc, s6, v4
	s_mov_b32 s6, 0x8000
	s_nop 0
	v_addc_co_u32_e32 v9, vcc, 0, v5, vcc
	global_load_dword v11, v[4:5], off nt
	global_load_dword v12, v[8:9], off nt
	v_add_co_u32_e32 v8, vcc, s6, v4
	s_mov_b32 s6, 0xc000
	s_nop 0
	v_addc_co_u32_e32 v9, vcc, 0, v5, vcc
	global_load_dword v13, v[8:9], off nt
	v_add_co_u32_e32 v8, vcc, s6, v4
	s_mov_b32 s6, 0x10000
	s_nop 0
	v_addc_co_u32_e32 v9, vcc, 0, v5, vcc
	global_load_dword v14, v[8:9], off nt
	v_add_co_u32_e32 v8, vcc, s6, v4
	s_mov_b32 s6, 0x14000
	s_nop 0
	v_addc_co_u32_e32 v9, vcc, 0, v5, vcc
	global_load_dword v15, v[8:9], off nt
	v_add_co_u32_e32 v8, vcc, s6, v4
	s_mov_b32 s6, 0x18000
	s_nop 0
	v_addc_co_u32_e32 v9, vcc, 0, v5, vcc
	global_load_dword v16, v[8:9], off nt
	v_add_co_u32_e32 v8, vcc, s6, v4
	s_mov_b32 s6, 0x1c000
	s_nop 0
	v_addc_co_u32_e32 v9, vcc, 0, v5, vcc
	global_load_dword v17, v[8:9], off nt
	v_add_co_u32_e32 v8, vcc, s6, v4
	s_mov_b32 s6, 0x20000
	s_nop 0
	v_addc_co_u32_e32 v9, vcc, 0, v5, vcc
	global_load_dword v18, v[8:9], off nt
	v_add_co_u32_e32 v8, vcc, s6, v4
	s_mov_b32 s6, 0x24000
	s_nop 0
	v_addc_co_u32_e32 v9, vcc, 0, v5, vcc
	global_load_dword v19, v[8:9], off nt
	v_add_co_u32_e32 v8, vcc, s6, v4
	s_mov_b32 s6, 0x28000
	s_nop 0
	v_addc_co_u32_e32 v9, vcc, 0, v5, vcc
	global_load_dword v20, v[8:9], off nt
	v_add_co_u32_e32 v8, vcc, s6, v4
	s_mov_b32 s6, 0x30000
	s_nop 0
	v_addc_co_u32_e32 v9, vcc, 0, v5, vcc
	global_load_dword v21, v[8:9], off nt
	v_add_co_u32_e32 v8, vcc, s17, v4
	s_nop 1
	v_addc_co_u32_e32 v9, vcc, 0, v5, vcc
	global_load_dword v22, v[8:9], off nt
	v_add_co_u32_e32 v8, vcc, s6, v4
	s_mov_b32 s6, 0x34000
	s_nop 0
	v_addc_co_u32_e32 v9, vcc, 0, v5, vcc
	global_load_dword v23, v[8:9], off nt
	v_add_co_u32_e32 v8, vcc, s6, v4
	s_mov_b32 s6, 0x38000
	s_nop 0
	v_addc_co_u32_e32 v9, vcc, 0, v5, vcc
	global_load_dword v24, v[8:9], off nt
	v_add_co_u32_e32 v8, vcc, s6, v4
	s_mov_b32 s6, 0x3c000
	s_nop 0
	v_addc_co_u32_e32 v9, vcc, 0, v5, vcc
	global_load_dword v25, v[8:9], off nt
	v_add_co_u32_e32 v8, vcc, s6, v4
	s_mov_b32 s6, 0x40000
	s_nop 0
	v_addc_co_u32_e32 v9, vcc, 0, v5, vcc
	global_load_dword v26, v[8:9], off nt
	v_add_co_u32_e32 v8, vcc, s6, v4
	s_mov_b32 s6, 0x44000
	s_nop 0
	v_addc_co_u32_e32 v9, vcc, 0, v5, vcc
	global_load_dword v27, v[8:9], off nt
	v_add_co_u32_e32 v8, vcc, s6, v4
	s_mov_b32 s6, 0x48000
	s_nop 0
	v_addc_co_u32_e32 v9, vcc, 0, v5, vcc
	global_load_dword v28, v[8:9], off nt
	v_add_co_u32_e32 v8, vcc, s6, v4
	s_mov_b32 s6, 0x4c000
	s_nop 0
	v_addc_co_u32_e32 v9, vcc, 0, v5, vcc
	global_load_dword v29, v[8:9], off nt
	v_add_co_u32_e32 v8, vcc, s6, v4
	s_mov_b32 s6, 0x50000
	s_nop 0
	v_addc_co_u32_e32 v9, vcc, 0, v5, vcc
	global_load_dword v30, v[8:9], off nt
	v_add_co_u32_e32 v8, vcc, s6, v4
	s_mov_b32 s6, 0x54000
	s_nop 0
	v_addc_co_u32_e32 v9, vcc, 0, v5, vcc
	global_load_dword v31, v[8:9], off nt
	v_add_co_u32_e32 v8, vcc, s6, v4
	s_mov_b32 s6, 0x5c000
	s_nop 0
	v_addc_co_u32_e32 v9, vcc, 0, v5, vcc
	global_load_dword v32, v[8:9], off nt
	v_add_co_u32_e32 v8, vcc, s18, v4
	s_nop 1
	v_addc_co_u32_e32 v9, vcc, 0, v5, vcc
	global_load_dword v33, v[8:9], off nt
	v_add_co_u32_e32 v8, vcc, s6, v4
	s_mov_b32 s6, 0x60000
	s_nop 0
	v_addc_co_u32_e32 v9, vcc, 0, v5, vcc
	global_load_dword v34, v[8:9], off nt
	v_add_co_u32_e32 v8, vcc, s6, v4
	s_mov_b32 s6, 0x64000
	s_nop 0
	v_addc_co_u32_e32 v9, vcc, 0, v5, vcc
	global_load_dword v35, v[8:9], off nt
	v_add_co_u32_e32 v8, vcc, s6, v4
	s_mov_b32 s6, 0x68000
	s_nop 0
	v_addc_co_u32_e32 v9, vcc, 0, v5, vcc
	global_load_dword v36, v[8:9], off nt
	v_add_co_u32_e32 v8, vcc, s6, v4
	s_mov_b32 s6, 0x6c000
	s_nop 0
	v_addc_co_u32_e32 v9, vcc, 0, v5, vcc
	global_load_dword v37, v[8:9], off nt
	v_add_co_u32_e32 v8, vcc, s6, v4
	s_mov_b32 s6, 0x70000
	s_nop 0
	v_addc_co_u32_e32 v9, vcc, 0, v5, vcc
	global_load_dword v38, v[8:9], off nt
	v_add_co_u32_e32 v8, vcc, s6, v4
	s_mov_b32 s6, 0x74000
	s_nop 0
	v_addc_co_u32_e32 v9, vcc, 0, v5, vcc
	global_load_dword v39, v[8:9], off nt
	v_add_co_u32_e32 v8, vcc, s6, v4
	s_mov_b32 s6, 0x78000
	s_nop 0
	v_addc_co_u32_e32 v9, vcc, 0, v5, vcc
	global_load_dword v40, v[8:9], off nt
	v_add_co_u32_e32 v8, vcc, s6, v4
	s_mov_b32 s6, 0x7c000
	s_nop 0
	v_addc_co_u32_e32 v9, vcc, 0, v5, vcc
	v_add_co_u32_e32 v4, vcc, s6, v4
	global_load_dword v8, v[8:9], off nt
	s_nop 0
	v_addc_co_u32_e32 v5, vcc, 0, v5, vcc
	global_load_dword v4, v[4:5], off nt
	v_mul_lo_u32 v5, v10, s19
	v_add3_u32 v2, s12, v2, v5
	v_add_u32_e32 v5, 0x400, v2
	s_waitcnt vmcnt(0)
; #define GAS __attribute__((address_space(1)))
; #define LAS __attribute__((address_space(3)))
; #define LDS_WAIT() asm volatile("s_waitcnt lgkmcnt(0)" ::: "memory")
; __device__ __forceinline__ unsigned pk2(float lo, float hi) { return f2bf(lo) | (f2bf(hi) << 16); }
;     ...
; #pragma unroll
;       for (int i = 0; i < 32; ++i) scr[(2 * i + (lane >> 5)) * 33 + (lane & 31)] = wv[i]; }
;     LDS_WAIT(); asm volatile("" ::: "memory");
;     const int c = lane & 7;
;     const int r0 = (mode == 0) ? n0 : (256 * (n0 >> 7) + (n0 & 127) + (mode == 2 ? 128 : 0));
; #pragma unroll
;     for (int j = 0; j < 4; ++j) { const int n = (lane >> 3) + 8 * j; const LAS float* s = scr + (8 * c) * 33 + n;
;         v4u o; o.x = pk2(s[0 * 33], s[1 * 33]); o.y = pk2(s[2 * 33], s[3 * 33]); o.z = pk2(s[4 * 33], s[5 * 33]); o.w = pk2(s[6 * 33], s[7 * 33]);
;         *(GAS v4u*)(WT + (size_t)(r0 + n) * ldt + k0 + 8 * c) = o; }
;     LDS_WAIT(); asm volatile("" ::: "memory");
	ds_write2_b32 v2, v11, v12 offset1:66
	ds_write2_b32 v2, v13, v14 offset0:132 offset1:198
	ds_write2_b32 v5, v15, v16 offset0:8 offset1:74
	ds_write2_b32 v5, v17, v18 offset0:140 offset1:206
	v_add_u32_e32 v5, 0x800, v2
	ds_write2_b32 v5, v19, v20 offset0:16 offset1:82
	ds_write2_b32 v5, v21, v22 offset0:148 offset1:214
	v_add_u32_e32 v5, 0xc00, v2
	ds_write2_b32 v5, v23, v24 offset0:24 offset1:90
	ds_write2_b32 v5, v25, v26 offset0:156 offset1:222
	v_add_u32_e32 v5, 0x1000, v2
	ds_write2_b32 v5, v27, v28 offset0:32 offset1:98
	ds_write2_b32 v5, v29, v30 offset0:164 offset1:230
	v_add_u32_e32 v5, 0x1400, v2
	ds_write2_b32 v5, v31, v32 offset0:40 offset1:106
	ds_write2_b32 v5, v33, v34 offset0:172 offset1:238
	v_add_u32_e32 v5, 0x1800, v2
	v_add_u32_e32 v2, 0x1c00, v2
	ds_write2_b32 v5, v35, v36 offset0:48 offset1:114
	ds_write2_b32 v5, v37, v38 offset0:180 offset1:246
	ds_write2_b32 v2, v39, v40 offset0:56 offset1:122
	ds_write2_b32 v2, v8, v4 offset0:188 offset1:254
	v_lshlrev_b32_e32 v2, 3, v7
	s_lshl_b32 s6, s9, 1
	v_and_b32_e32 v2, 56, v2
	s_add_u32 s72, s13, s6
	v_ashrrev_i32_e32 v28, 3, v7
	v_mul_u32_u24_e32 v7, 0x84, v2
	s_addc_u32 s73, s14, 0
	v_lshlrev_b32_e32 v2, 1, v2
	s_waitcnt lgkmcnt(0)
	v_lshl_add_u64 v[4:5], s[72:73], 0, v[2:3]
	v_lshlrev_b32_e32 v2, 2, v28
	v_add3_u32 v2, s12, v7, v2
	ds_read2_b32 v[12:13], v2 offset0:33 offset1:41
	ds_read2_b32 v[14:15], v2 offset1:8
	ds_read2_b32 v[16:17], v2 offset0:66 offset1:74
	ds_read2_b32 v[18:19], v2 offset0:99 offset1:107
	ds_read2_b32 v[20:21], v2 offset0:132 offset1:140
	ds_read2_b32 v[22:23], v2 offset0:165 offset1:173
	ds_read2_b32 v[24:25], v2 offset0:198 offset1:206
	ds_read2_b32 v[26:27], v2 offset0:231 offset1:239
	s_waitcnt lgkmcnt(7)
	v_bfe_u32 v8, v12, 16, 1
	s_waitcnt lgkmcnt(6)
	v_bfe_u32 v7, v14, 16, 1
	v_add3_u32 v7, v14, v7, s20
	v_lshrrev_b32_e32 v7, 16, v7
	v_add3_u32 v8, v12, v8, s20
	v_and_or_b32 v8, v8, s21, v7
	s_waitcnt lgkmcnt(5)
	v_bfe_u32 v7, v16, 16, 1
	v_add3_u32 v7, v16, v7, s20
	s_waitcnt lgkmcnt(4)
	v_bfe_u32 v9, v18, 16, 1
	v_lshrrev_b32_e32 v7, 16, v7
	v_add3_u32 v9, v18, v9, s20
	v_and_or_b32 v9, v9, s21, v7
	s_waitcnt lgkmcnt(3)
	v_bfe_u32 v7, v20, 16, 1
	v_add3_u32 v7, v20, v7, s20
	s_waitcnt lgkmcnt(2)
	v_bfe_u32 v10, v22, 16, 1
	v_lshrrev_b32_e32 v7, 16, v7
	v_add3_u32 v10, v22, v10, s20
	v_and_or_b32 v10, v10, s21, v7
	s_waitcnt lgkmcnt(1)
	v_bfe_u32 v7, v24, 16, 1
	v_add3_u32 v7, v24, v7, s20
	s_waitcnt lgkmcnt(0)
	v_bfe_u32 v11, v26, 16, 1
	v_lshrrev_b32_e32 v7, 16, v7
	v_add3_u32 v11, v26, v11, s20
	v_and_or_b32 v11, v11, s21, v7
	v_add_u32_e32 v7, s8, v28
	v_mad_i64_i32 v[28:29], s[8:9], v7, s22, v[4:5]
	global_store_dwordx4 v[28:29], v[8:11], off
	v_bfe_u32 v12, v27, 16, 1
	v_add3_u32 v12, v27, v12, s20
	v_bfe_u32 v8, v15, 16, 1
	v_add3_u32 v8, v15, v8, s20
	v_bfe_u32 v9, v13, 16, 1
	v_lshrrev_b32_e32 v8, 16, v8
	v_add3_u32 v9, v13, v9, s20
	v_and_or_b32 v8, v9, s21, v8
	v_bfe_u32 v9, v17, 16, 1
	v_add3_u32 v9, v17, v9, s20
	v_bfe_u32 v10, v19, 16, 1
	v_lshrrev_b32_e32 v9, 16, v9
	v_add3_u32 v10, v19, v10, s20
	v_and_or_b32 v9, v10, s21, v9
	v_bfe_u32 v10, v21, 16, 1
	v_add3_u32 v10, v21, v10, s20
	v_bfe_u32 v11, v23, 16, 1
	v_lshrrev_b32_e32 v10, 16, v10
	v_add3_u32 v11, v23, v11, s20
	v_and_or_b32 v10, v11, s21, v10
	v_bfe_u32 v11, v25, 16, 1
	v_add3_u32 v11, v25, v11, s20
	v_lshrrev_b32_e32 v11, 16, v11
	v_and_or_b32 v11, v12, s21, v11
	v_add_u32_e32 v12, 8, v7
	v_mad_i64_i32 v[12:13], s[8:9], v12, s22, v[4:5]
	global_store_dwordx4 v[12:13], v[8:11], off
	ds_read2_b32 v[12:13], v2 offset0:49 offset1:57
	ds_read2_b32 v[14:15], v2 offset0:16 offset1:24
	ds_read2_b32 v[16:17], v2 offset0:82 offset1:90
	ds_read2_b32 v[18:19], v2 offset0:115 offset1:123
	ds_read2_b32 v[20:21], v2 offset0:148 offset1:156
	ds_read2_b32 v[22:23], v2 offset0:181 offset1:189
	ds_read2_b32 v[24:25], v2 offset0:214 offset1:222
	ds_read2_b32 v[26:27], v2 offset0:247 offset1:255
	s_waitcnt lgkmcnt(7)
	v_bfe_u32 v9, v12, 16, 1
	s_waitcnt lgkmcnt(6)
	v_bfe_u32 v8, v14, 16, 1
	v_add3_u32 v8, v14, v8, s20
	v_lshrrev_b32_e32 v8, 16, v8
	v_add3_u32 v9, v12, v9, s20
	v_and_or_b32 v8, v9, s21, v8
	s_waitcnt lgkmcnt(5)
	v_bfe_u32 v9, v16, 16, 1
	v_add3_u32 v9, v16, v9, s20
	s_waitcnt lgkmcnt(4)
	v_bfe_u32 v10, v18, 16, 1
	v_lshrrev_b32_e32 v9, 16, v9
	v_add3_u32 v10, v18, v10, s20
	v_and_or_b32 v9, v10, s21, v9
	s_waitcnt lgkmcnt(3)
	v_bfe_u32 v10, v20, 16, 1
	v_add3_u32 v10, v20, v10, s20
	s_waitcnt lgkmcnt(2)
	v_bfe_u32 v11, v22, 16, 1
	v_lshrrev_b32_e32 v10, 16, v10
	v_add3_u32 v11, v22, v11, s20
	s_waitcnt lgkmcnt(1)
	v_bfe_u32 v2, v24, 16, 1
	v_and_or_b32 v10, v11, s21, v10
	v_add3_u32 v2, v24, v2, s20
	s_waitcnt lgkmcnt(0)
	v_bfe_u32 v11, v26, 16, 1
	v_lshrrev_b32_e32 v2, 16, v2
	v_add3_u32 v11, v26, v11, s20
	v_and_or_b32 v11, v11, s21, v2
	v_add_u32_e32 v2, 16, v7
	v_mad_i64_i32 v[28:29], s[8:9], v2, s22, v[4:5]
	v_bfe_u32 v2, v15, 16, 1
	global_store_dwordx4 v[28:29], v[8:11], off
	v_add3_u32 v2, v15, v2, s20
	v_lshrrev_b32_e32 v2, 16, v2
	v_bfe_u32 v8, v13, 16, 1
	v_add3_u32 v8, v13, v8, s20
	v_and_or_b32 v8, v8, s21, v2
	v_bfe_u32 v2, v17, 16, 1
	v_add3_u32 v2, v17, v2, s20
	v_bfe_u32 v9, v19, 16, 1
	v_lshrrev_b32_e32 v2, 16, v2
	v_add3_u32 v9, v19, v9, s20
	v_and_or_b32 v9, v9, s21, v2
	v_bfe_u32 v2, v21, 16, 1
	v_add3_u32 v2, v21, v2, s20
	v_bfe_u32 v10, v23, 16, 1
	v_lshrrev_b32_e32 v2, 16, v2
	v_add3_u32 v10, v23, v10, s20
	v_and_or_b32 v10, v10, s21, v2
	v_bfe_u32 v2, v25, 16, 1
	v_add3_u32 v2, v25, v2, s20
	v_bfe_u32 v11, v27, 16, 1
	v_lshrrev_b32_e32 v2, 16, v2
	v_add3_u32 v11, v27, v11, s20
	v_and_or_b32 v11, v11, s21, v2
	v_add_u32_e32 v2, 24, v7
	v_mad_i64_i32 v[4:5], s[8:9], v2, s22, v[4:5]
	global_store_dwordx4 v[4:5], v[8:11], off
	s_waitcnt lgkmcnt(0)
	s_mov_b64 s[8:9], 0

;     ...
;     const int kb = item / nblk, nb = item % nblk, k0 = 64 * kb, n0 = 32 * nb;
;     { float wv[32];
;       const float* wp = W + (size_t)(k0 + (lane >> 5)) * ldw + n0 + (lane & 31);
; #pragma unroll
;       for (int i = 0; i < 32; ++i) wv[i] = wp[(size_t)(2 * i) * ldw];
; #pragma unroll
;       for (int i = 0; i < 32; ++i) scr[(2 * i + (lane >> 5)) * 33 + (lane & 31)] = wv[i]; }
; __device__ __forceinline__ void transpose_early(const Args& a, Frame& F, LAS float* scr, int r) {
;     ...
;     if (r < IT_FG) { p0_transpose_item(a.in[I_W1G], FF, D, W1, 1, FF / 32, scr, r, F.lane); return; } r -= IT_FG;
;     if (r < IT_FG) { p0_transpose_item(a.in[I_W1U], FF, D, W1, 2, FF / 32, scr, r, F.lane); return; } r -= IT_FG;
.LBB0_105:
	s_mul_hi_i32 s6, s10, 0x2e8ba2e9
	s_lshr_b32 s8, s6, 31
	s_ashr_i32 s6, s6, 5
	s_add_i32 s8, s6, s8
	v_mov_b32_e32 v7, v6
	s_mul_i32 s6, s8, 0xb0
	s_sub_i32 s6, s10, s6
	s_lshl_b32 s8, s8, 6
	v_ashrrev_i32_e32 v10, 5, v7
	s_lshl_b32 s10, s6, 5
	v_add_u32_e32 v2, s8, v10
	v_mov_b64_e32 v[4:5], s[58:59]
	v_mad_i64_i32 v[4:5], s[72:73], v2, s23, v[4:5]
	s_ashr_i32 s11, s10, 31
	v_lshlrev_b32_e32 v2, 2, v7
	v_lshl_add_u64 v[4:5], s[10:11], 2, v[4:5]
	v_and_b32_e32 v2, 0x7c, v2
	v_lshl_add_u64 v[4:5], v[4:5], 0, v[2:3]
	v_add_co_u32_e32 v8, vcc, s24, v4
	global_load_dword v11, v[4:5], off nt
	s_nop 0
	v_addc_co_u32_e32 v9, vcc, 0, v5, vcc
	global_load_dword v12, v[8:9], off nt
	v_add_co_u32_e32 v8, vcc, s25, v4
	s_lshl_b32 s6, s6, 6
	s_nop 0
	v_addc_co_u32_e32 v9, vcc, 0, v5, vcc
	global_load_dword v13, v[8:9], off nt
	v_add_co_u32_e32 v8, vcc, s26, v4
	s_and_b32 s6, s6, 0xffffff00
	s_nop 0
	v_addc_co_u32_e32 v9, vcc, 0, v5, vcc
	global_load_dword v14, v[8:9], off nt
	v_add_co_u32_e32 v8, vcc, s17, v4
	s_and_b32 s9, s10, 0x60
	s_nop 0
	v_addc_co_u32_e32 v9, vcc, 0, v5, vcc
	global_load_dword v15, v[8:9], off nt
	v_add_co_u32_e32 v8, vcc, s27, v4
	s_or_b32 s6, s9, s6
	s_nop 0
	v_addc_co_u32_e32 v9, vcc, 0, v5, vcc
	global_load_dword v16, v[8:9], off nt
	v_add_co_u32_e32 v8, vcc, s28, v4
	s_ashr_i32 s9, s8, 31
	s_nop 0
	v_addc_co_u32_e32 v9, vcc, 0, v5, vcc
	global_load_dword v17, v[8:9], off nt
	v_add_co_u32_e32 v8, vcc, s29, v4
	s_lshl_b64 s[8:9], s[8:9], 1
	s_nop 0
	v_addc_co_u32_e32 v9, vcc, 0, v5, vcc
	global_load_dword v18, v[8:9], off nt
	v_add_co_u32_e32 v8, vcc, s18, v4
	s_add_u32 s8, s3, s8
	s_nop 0
	v_addc_co_u32_e32 v9, vcc, 0, v5, vcc
	global_load_dword v19, v[8:9], off nt
	v_add_co_u32_e32 v8, vcc, s30, v4
	s_addc_u32 s9, s33, s9
	s_nop 0
	v_addc_co_u32_e32 v9, vcc, 0, v5, vcc
	global_load_dword v20, v[8:9], off nt
	v_add_co_u32_e32 v8, vcc, s31, v4
	s_nop 1
	v_addc_co_u32_e32 v9, vcc, 0, v5, vcc
	global_load_dword v21, v[8:9], off nt
	v_add_co_u32_e32 v8, vcc, s36, v4
	s_nop 1
	v_addc_co_u32_e32 v9, vcc, 0, v5, vcc
	global_load_dword v22, v[8:9], off nt
	v_add_co_u32_e32 v8, vcc, s37, v4
	s_nop 1
	v_addc_co_u32_e32 v9, vcc, 0, v5, vcc
	global_load_dword v23, v[8:9], off nt
	v_add_co_u32_e32 v8, vcc, s38, v4
	s_nop 1
	v_addc_co_u32_e32 v9, vcc, 0, v5, vcc
	global_load_dword v24, v[8:9], off nt
	v_add_co_u32_e32 v8, vcc, s39, v4
	s_nop 1
	v_addc_co_u32_e32 v9, vcc, 0, v5, vcc
	global_load_dword v25, v[8:9], off nt
	v_add_co_u32_e32 v8, vcc, s40, v4
	s_nop 1
	v_addc_co_u32_e32 v9, vcc, 0, v5, vcc
	global_load_dword v26, v[8:9], off nt
	v_add_co_u32_e32 v8, vcc, s41, v4
	s_nop 1
	v_addc_co_u32_e32 v9, vcc, 0, v5, vcc
	global_load_dword v27, v[8:9], off nt
	v_add_co_u32_e32 v8, vcc, s42, v4
	s_nop 1
	v_addc_co_u32_e32 v9, vcc, 0, v5, vcc
	global_load_dword v28, v[8:9], off nt
	v_add_co_u32_e32 v8, vcc, s43, v4
	s_nop 1
	v_addc_co_u32_e32 v9, vcc, 0, v5, vcc
	global_load_dword v29, v[8:9], off nt
	v_add_co_u32_e32 v8, vcc, s44, v4
	s_nop 1
	v_addc_co_u32_e32 v9, vcc, 0, v5, vcc
	global_load_dword v30, v[8:9], off nt
	v_add_co_u32_e32 v8, vcc, s45, v4
	s_nop 1
	v_addc_co_u32_e32 v9, vcc, 0, v5, vcc
	global_load_dword v31, v[8:9], off nt
	v_add_co_u32_e32 v8, vcc, s46, v4
	s_nop 1
	v_addc_co_u32_e32 v9, vcc, 0, v5, vcc
	global_load_dword v32, v[8:9], off nt
	v_add_co_u32_e32 v8, vcc, s47, v4
	s_nop 1
	v_addc_co_u32_e32 v9, vcc, 0, v5, vcc
	global_load_dword v33, v[8:9], off nt
	v_add_co_u32_e32 v8, vcc, s48, v4
	s_nop 1
	v_addc_co_u32_e32 v9, vcc, 0, v5, vcc
	global_load_dword v34, v[8:9], off nt
	v_add_co_u32_e32 v8, vcc, s49, v4
	s_nop 1
	v_addc_co_u32_e32 v9, vcc, 0, v5, vcc
	global_load_dword v35, v[8:9], off nt
	v_add_co_u32_e32 v8, vcc, s50, v4
	s_nop 1
	v_addc_co_u32_e32 v9, vcc, 0, v5, vcc
	global_load_dword v36, v[8:9], off nt
	v_add_co_u32_e32 v8, vcc, s51, v4
	s_nop 1
	v_addc_co_u32_e32 v9, vcc, 0, v5, vcc
	global_load_dword v37, v[8:9], off nt
	v_add_co_u32_e32 v8, vcc, s52, v4
	s_nop 1
	v_addc_co_u32_e32 v9, vcc, 0, v5, vcc
	global_load_dword v38, v[8:9], off nt
	v_add_co_u32_e32 v8, vcc, s53, v4
	s_nop 1
	v_addc_co_u32_e32 v9, vcc, 0, v5, vcc
	global_load_dword v39, v[8:9], off nt
	v_add_co_u32_e32 v8, vcc, s54, v4
	s_nop 1
	v_addc_co_u32_e32 v9, vcc, 0, v5, vcc
	global_load_dword v40, v[8:9], off nt
	v_add_co_u32_e32 v8, vcc, s55, v4
	s_nop 1
	v_addc_co_u32_e32 v9, vcc, 0, v5, vcc
	v_add_co_u32_e32 v4, vcc, s56, v4
	global_load_dword v8, v[8:9], off nt
	s_nop 0
	v_addc_co_u32_e32 v5, vcc, 0, v5, vcc
	global_load_dword v4, v[4:5], off nt
	v_mul_lo_u32 v5, v10, s19
	v_add3_u32 v2, s12, v2, v5
	v_add_u32_e32 v5, 0x400, v2
	s_waitcnt vmcnt(0)
	ds_write2_b32 v2, v11, v12 offset1:66
	ds_write2_b32 v2, v13, v14 offset0:132 offset1:198
	ds_write2_b32 v5, v15, v16 offset0:8 offset1:74
	ds_write2_b32 v5, v17, v18 offset0:140 offset1:206
	v_add_u32_e32 v5, 0x800, v2
	ds_write2_b32 v5, v19, v20 offset0:16 offset1:82
	ds_write2_b32 v5, v21, v22 offset0:148 offset1:214
	v_add_u32_e32 v5, 0xc00, v2
	ds_write2_b32 v5, v23, v24 offset0:24 offset1:90
	ds_write2_b32 v5, v25, v26 offset0:156 offset1:222
	v_add_u32_e32 v5, 0x1000, v2
	ds_write2_b32 v5, v27, v28 offset0:32 offset1:98
	ds_write2_b32 v5, v29, v30 offset0:164 offset1:230
	v_add_u32_e32 v5, 0x1400, v2
	ds_write2_b32 v5, v31, v32 offset0:40 offset1:106
	ds_write2_b32 v5, v33, v34 offset0:172 offset1:238
	v_add_u32_e32 v5, 0x1800, v2
	v_add_u32_e32 v2, 0x1c00, v2
	ds_write2_b32 v5, v35, v36 offset0:48 offset1:114
	ds_write2_b32 v5, v37, v38 offset0:180 offset1:246
	ds_write2_b32 v2, v39, v40 offset0:56 offset1:122
	ds_write2_b32 v2, v8, v4 offset0:188 offset1:254
	v_lshlrev_b32_e32 v2, 3, v7
	v_and_b32_e32 v2, 56, v2
	v_ashrrev_i32_e32 v28, 3, v7
	v_mul_u32_u24_e32 v7, 0x84, v2
	v_lshlrev_b32_e32 v2, 1, v2
	s_waitcnt lgkmcnt(0)
; #define GAS __attribute__((address_space(1)))
; #define LAS __attribute__((address_space(3)))
; #define LDS_WAIT() asm volatile("s_waitcnt lgkmcnt(0)" ::: "memory")
; __device__ __forceinline__ unsigned pk2(float lo, float hi) { return f2bf(lo) | (f2bf(hi) << 16); }
;     ...
;     LDS_WAIT(); asm volatile("" ::: "memory");
;     const int c = lane & 7;
;     const int r0 = (mode == 0) ? n0 : (256 * (n0 >> 7) + (n0 & 127) + (mode == 2 ? 128 : 0));
; #pragma unroll
;     for (int j = 0; j < 4; ++j) { const int n = (lane >> 3) + 8 * j; const LAS float* s = scr + (8 * c) * 33 + n;
;         v4u o; o.x = pk2(s[0 * 33], s[1 * 33]); o.y = pk2(s[2 * 33], s[3 * 33]); o.z = pk2(s[4 * 33], s[5 * 33]); o.w = pk2(s[6 * 33], s[7 * 33]);
;         *(GAS v4u*)(WT + (size_t)(r0 + n) * ldt + k0 + 8 * c) = o; }
;     LDS_WAIT(); asm volatile("" ::: "memory");
	v_lshl_add_u64 v[4:5], s[8:9], 0, v[2:3]
	v_lshlrev_b32_e32 v2, 2, v28
	v_add3_u32 v2, s12, v7, v2
	ds_read2_b32 v[12:13], v2 offset0:33 offset1:41
	ds_read2_b32 v[14:15], v2 offset1:8
	ds_read2_b32 v[16:17], v2 offset0:66 offset1:74
	ds_read2_b32 v[18:19], v2 offset0:99 offset1:107
	ds_read2_b32 v[20:21], v2 offset0:132 offset1:140
	ds_read2_b32 v[22:23], v2 offset0:165 offset1:173
	ds_read2_b32 v[24:25], v2 offset0:198 offset1:206
	ds_read2_b32 v[26:27], v2 offset0:231 offset1:239
	s_waitcnt lgkmcnt(7)
	v_bfe_u32 v8, v12, 16, 1
	s_waitcnt lgkmcnt(6)
	v_bfe_u32 v7, v14, 16, 1
	v_add3_u32 v7, v14, v7, s20
	v_lshrrev_b32_e32 v7, 16, v7
	v_add3_u32 v8, v12, v8, s20
	v_and_or_b32 v8, v8, s21, v7
	s_waitcnt lgkmcnt(5)
	v_bfe_u32 v7, v16, 16, 1
	v_add3_u32 v7, v16, v7, s20
	s_waitcnt lgkmcnt(4)
	v_bfe_u32 v9, v18, 16, 1
	v_lshrrev_b32_e32 v7, 16, v7
	v_add3_u32 v9, v18, v9, s20
	v_and_or_b32 v9, v9, s21, v7
	s_waitcnt lgkmcnt(3)
	v_bfe_u32 v7, v20, 16, 1
	v_add3_u32 v7, v20, v7, s20
	s_waitcnt lgkmcnt(2)
	v_bfe_u32 v10, v22, 16, 1
	v_lshrrev_b32_e32 v7, 16, v7
	v_add3_u32 v10, v22, v10, s20
	v_and_or_b32 v10, v10, s21, v7
	s_waitcnt lgkmcnt(1)
	v_bfe_u32 v7, v24, 16, 1
	v_add_u32_e32 v28, s6, v28
	v_add3_u32 v7, v24, v7, s20
	s_waitcnt lgkmcnt(0)
	v_bfe_u32 v11, v26, 16, 1
	v_ashrrev_i32_e32 v29, 31, v28
	v_lshrrev_b32_e32 v7, 16, v7
	v_add3_u32 v11, v26, v11, s20
	v_lshlrev_b64 v[30:31], 12, v[28:29]
	v_and_or_b32 v11, v11, s21, v7
	v_lshl_add_u64 v[30:31], v[4:5], 0, v[30:31]
	v_bfe_u32 v7, v15, 16, 1
	global_store_dwordx4 v[30:31], v[8:11], off
	v_add3_u32 v7, v15, v7, s20
	v_lshrrev_b32_e32 v7, 16, v7
	v_bfe_u32 v8, v13, 16, 1
	v_add3_u32 v8, v13, v8, s20
	v_and_or_b32 v8, v8, s21, v7
	v_bfe_u32 v7, v17, 16, 1
	v_add3_u32 v7, v17, v7, s20
	v_bfe_u32 v9, v19, 16, 1
	v_lshrrev_b32_e32 v7, 16, v7
	v_add3_u32 v9, v19, v9, s20
	v_and_or_b32 v9, v9, s21, v7
	v_bfe_u32 v7, v21, 16, 1
	v_add3_u32 v7, v21, v7, s20
	v_bfe_u32 v10, v23, 16, 1
	v_lshrrev_b32_e32 v7, 16, v7
	v_add3_u32 v10, v23, v10, s20
	v_and_or_b32 v10, v10, s21, v7
	v_bfe_u32 v7, v25, 16, 1
	v_add_u32_e32 v12, 8, v28
	v_add3_u32 v7, v25, v7, s20
	v_bfe_u32 v11, v27, 16, 1
	v_ashrrev_i32_e32 v13, 31, v12
	v_lshrrev_b32_e32 v7, 16, v7
	v_add3_u32 v11, v27, v11, s20
	v_lshlrev_b64 v[12:13], 12, v[12:13]
	v_and_or_b32 v11, v11, s21, v7
	v_lshl_add_u64 v[12:13], v[4:5], 0, v[12:13]
	global_store_dwordx4 v[12:13], v[8:11], off
	ds_read2_b32 v[12:13], v2 offset0:49 offset1:57
	ds_read2_b32 v[14:15], v2 offset0:16 offset1:24
	ds_read2_b32 v[16:17], v2 offset0:82 offset1:90
	ds_read2_b32 v[18:19], v2 offset0:115 offset1:123
	ds_read2_b32 v[20:21], v2 offset0:148 offset1:156
	ds_read2_b32 v[22:23], v2 offset0:181 offset1:189
	ds_read2_b32 v[24:25], v2 offset0:214 offset1:222
	ds_read2_b32 v[26:27], v2 offset0:247 offset1:255
	s_waitcnt lgkmcnt(7)
	v_bfe_u32 v8, v12, 16, 1
	s_waitcnt lgkmcnt(6)
	v_bfe_u32 v7, v14, 16, 1
	v_add3_u32 v7, v14, v7, s20
	v_lshrrev_b32_e32 v7, 16, v7
	v_add3_u32 v8, v12, v8, s20
	v_and_or_b32 v8, v8, s21, v7
	s_waitcnt lgkmcnt(5)
	v_bfe_u32 v7, v16, 16, 1
	v_add3_u32 v7, v16, v7, s20
	s_waitcnt lgkmcnt(4)
	v_bfe_u32 v9, v18, 16, 1
	v_lshrrev_b32_e32 v7, 16, v7
	v_add3_u32 v9, v18, v9, s20
	v_and_or_b32 v9, v9, s21, v7
	s_waitcnt lgkmcnt(3)
	v_bfe_u32 v7, v20, 16, 1
	v_add3_u32 v7, v20, v7, s20
	s_waitcnt lgkmcnt(2)
	v_bfe_u32 v10, v22, 16, 1
	v_lshrrev_b32_e32 v7, 16, v7
	v_add3_u32 v10, v22, v10, s20
	s_waitcnt lgkmcnt(1)
	v_bfe_u32 v2, v24, 16, 1
	v_and_or_b32 v10, v10, s21, v7
	v_add3_u32 v2, v24, v2, s20
	s_waitcnt lgkmcnt(0)
	v_bfe_u32 v7, v26, 16, 1
	v_lshrrev_b32_e32 v2, 16, v2
	v_add3_u32 v7, v26, v7, s20
	v_add_u32_e32 v30, 16, v28
	v_and_or_b32 v11, v7, s21, v2
	v_ashrrev_i32_e32 v31, 31, v30
	v_bfe_u32 v2, v15, 16, 1
	v_lshlrev_b64 v[30:31], 12, v[30:31]
	v_add3_u32 v2, v15, v2, s20
	v_bfe_u32 v7, v13, 16, 1
	v_lshl_add_u64 v[30:31], v[4:5], 0, v[30:31]
	v_lshrrev_b32_e32 v2, 16, v2
	v_add3_u32 v7, v13, v7, s20
	global_store_dwordx4 v[30:31], v[8:11], off
	v_add_u32_e32 v12, 24, v28
	v_ashrrev_i32_e32 v13, 31, v12
	v_and_or_b32 v8, v7, s21, v2
	v_bfe_u32 v2, v17, 16, 1
	v_add3_u32 v2, v17, v2, s20
	v_bfe_u32 v7, v19, 16, 1
	v_lshrrev_b32_e32 v2, 16, v2
	v_add3_u32 v7, v19, v7, s20
	v_and_or_b32 v9, v7, s21, v2
	v_bfe_u32 v2, v21, 16, 1
	v_add3_u32 v2, v21, v2, s20
	v_bfe_u32 v7, v23, 16, 1
	v_lshrrev_b32_e32 v2, 16, v2
	v_add3_u32 v7, v23, v7, s20
	v_and_or_b32 v10, v7, s21, v2
	v_bfe_u32 v2, v25, 16, 1
	v_add3_u32 v2, v25, v2, s20
	v_bfe_u32 v7, v27, 16, 1
	v_lshrrev_b32_e32 v2, 16, v2
	v_add3_u32 v7, v27, v7, s20
	v_lshlrev_b64 v[12:13], 12, v[12:13]
	v_and_or_b32 v11, v7, s21, v2
	v_lshl_add_u64 v[4:5], v[4:5], 0, v[12:13]
	global_store_dwordx4 v[4:5], v[8:11], off
	s_waitcnt lgkmcnt(0)
	s_branch .LBB0_97

; #define LAS __attribute__((address_space(3)))
;     ...
;     const int kb = item / nblk, nb = item % nblk, k0 = 64 * kb, n0 = 32 * nb;
;     { float wv[32];
;       const float* wp = W + (size_t)(k0 + (lane >> 5)) * ldw + n0 + (lane & 31);
; #pragma unroll
;       for (int i = 0; i < 32; ++i) wv[i] = wp[(size_t)(2 * i) * ldw];
; __device__ __forceinline__ void transpose_early(const Args& a, Frame& F, LAS float* scr, int r) {
;     bf16 *W1 = WSP(bf16, WS_W1), *W1D = WSP(bf16, WS_W1D), *WIN = WSP(bf16, WS_WIN);
;     if (r < IT_FG) { p0_transpose_item(a.in[I_W1G], FF, D, W1, 1, FF / 32, scr, r, F.lane); return; } r -= IT_FG;
;     if (r < IT_FG) { p0_transpose_item(a.in[I_W1U], FF, D, W1, 2, FF / 32, scr, r, F.lane); return; } r -= IT_FG;
;     if (r < IT_FD) { p0_transpose_item(a.in[I_W1D], D, FF, W1D, 0, D / 32, scr, r, F.lane); return; } r -= IT_FD;
;     if (r < IT_INA) { p0_transpose_item(a.in[I_WIN], 14344, D, WIN, 0, 6144 / 32, scr, r, F.lane); return; } r -= IT_INA;
;     p0_transpose_item(a.in[I_WIN] + 6152, 14344, D, WIN + (size_t)6144 * D, 0, 8192 / 32, scr, r, F.lane);
.LBB0_205:
	s_cmpk_gt_u32 s12, 0x2bff
	s_cbranch_scc0 .LBB0_215
	s_cmp_lt_u32 s83, 0xffffbe00
	s_cbranch_scc0 .LBB0_212
	s_cmpk_gt_u32 s12, 0x59ff
	s_cbranch_scc0 .LBB0_209
	v_mov_b32_e32 v7, v6
	s_bfe_u32 s11, s37, 0x80008
	v_ashrrev_i32_e32 v10, 5, v7
	s_and_b32 s10, s38, 0x1fe0
	v_lshl_add_u32 v2, s11, 6, v10
	v_mov_b64_e32 v[4:5], s[6:7]
	v_mad_i64_i32 v[4:5], s[16:17], v2, s18, v[4:5]
	s_lshl_b32 s8, s10, 2
	v_lshlrev_b32_e32 v2, 2, v7
	v_lshl_add_u64 v[4:5], v[4:5], 0, s[8:9]
	v_and_b32_e32 v2, 0x7c, v2
	v_lshl_add_u64 v[4:5], v[4:5], 0, v[2:3]
	v_add_co_u32_e32 v8, vcc, s40, v4
	global_load_dword v11, v[4:5], off nt
	s_nop 0
	v_addc_co_u32_e32 v9, vcc, 0, v5, vcc
	global_load_dword v12, v[8:9], off offset:64 nt
	v_add_co_u32_e32 v8, vcc, s41, v4
	s_mov_b32 s8, 0x1dc000
	s_nop 0
	v_addc_co_u32_e32 v9, vcc, 0, v5, vcc
	global_load_dword v13, v[8:9], off offset:128 nt
	v_add_co_u32_e32 v8, vcc, s42, v4
	s_nop 1
	v_addc_co_u32_e32 v9, vcc, 0, v5, vcc
	global_load_dword v14, v[8:9], off offset:192 nt
	v_add_co_u32_e32 v8, vcc, s43, v4
	s_nop 1
	v_addc_co_u32_e32 v9, vcc, 0, v5, vcc
	global_load_dword v15, v[8:9], off offset:256 nt
	v_add_co_u32_e32 v8, vcc, s19, v4
	s_nop 1
	v_addc_co_u32_e32 v9, vcc, 0, v5, vcc
	global_load_dword v16, v[8:9], off offset:320 nt
	v_add_co_u32_e32 v8, vcc, s24, v4
	s_nop 1
	v_addc_co_u32_e32 v9, vcc, 0, v5, vcc
	global_load_dword v17, v[8:9], off offset:384 nt
	v_add_co_u32_e32 v8, vcc, s25, v4
	s_nop 1
	v_addc_co_u32_e32 v9, vcc, 0, v5, vcc
	global_load_dword v18, v[8:9], off offset:448 nt
	v_add_co_u32_e32 v8, vcc, s26, v4
	s_nop 1
	v_addc_co_u32_e32 v9, vcc, 0, v5, vcc
	global_load_dword v19, v[8:9], off offset:512 nt
	v_add_co_u32_e32 v8, vcc, s27, v4
	s_nop 1
	v_addc_co_u32_e32 v9, vcc, 0, v5, vcc
	global_load_dword v20, v[8:9], off offset:576 nt
	v_add_co_u32_e32 v8, vcc, s28, v4
	s_nop 1
	v_addc_co_u32_e32 v9, vcc, 0, v5, vcc
	global_load_dword v21, v[8:9], off offset:640 nt
	v_add_co_u32_e32 v8, vcc, s50, v4
	s_nop 1
	v_addc_co_u32_e32 v9, vcc, 0, v5, vcc
	global_load_dword v22, v[8:9], off offset:704 nt
	v_add_co_u32_e32 v8, vcc, s29, v4
	s_nop 1
	v_addc_co_u32_e32 v9, vcc, 0, v5, vcc
	global_load_dword v23, v[8:9], off offset:768 nt
	v_add_co_u32_e32 v8, vcc, s30, v4
	s_nop 1
	v_addc_co_u32_e32 v9, vcc, 0, v5, vcc
	global_load_dword v24, v[8:9], off offset:832 nt
	v_add_co_u32_e32 v8, vcc, s31, v4
	s_nop 1
	v_addc_co_u32_e32 v9, vcc, 0, v5, vcc
	global_load_dword v25, v[8:9], off offset:896 nt
	v_add_co_u32_e32 v8, vcc, s84, v4
	s_nop 1
	v_addc_co_u32_e32 v9, vcc, 0, v5, vcc
	global_load_dword v26, v[8:9], off offset:960 nt
	v_add_co_u32_e32 v8, vcc, s97, v4
	s_nop 1
	v_addc_co_u32_e32 v9, vcc, 0, v5, vcc
	global_load_dword v27, v[8:9], off offset:1024 nt
	v_add_co_u32_e32 v8, vcc, s8, v4
	s_mov_b32 s8, 0x1f8000
	s_nop 0
	v_addc_co_u32_e32 v9, vcc, 0, v5, vcc
	global_load_dword v28, v[8:9], off offset:1088 nt
	v_add_co_u32_e32 v8, vcc, s8, v4
	s_mov_b32 s8, 0x214000
	s_nop 0
	v_addc_co_u32_e32 v9, vcc, 0, v5, vcc
	global_load_dword v29, v[8:9], off offset:1152 nt
	v_add_co_u32_e32 v8, vcc, s8, v4
	s_mov_b32 s8, 0x230000
	s_nop 0
	v_addc_co_u32_e32 v9, vcc, 0, v5, vcc
	global_load_dword v30, v[8:9], off offset:1216 nt
	v_add_co_u32_e32 v8, vcc, s8, v4
	s_mov_b32 s8, 0x24c000
	s_nop 0
	v_addc_co_u32_e32 v9, vcc, 0, v5, vcc
	global_load_dword v31, v[8:9], off offset:1280 nt
	v_add_co_u32_e32 v8, vcc, s8, v4
	s_mov_b32 s8, 0x268000
	s_nop 0
	v_addc_co_u32_e32 v9, vcc, 0, v5, vcc
	global_load_dword v32, v[8:9], off offset:1344 nt
	v_add_co_u32_e32 v8, vcc, s8, v4
	s_mov_b32 s8, 0x284000
	s_nop 0
	v_addc_co_u32_e32 v9, vcc, 0, v5, vcc
	global_load_dword v33, v[8:9], off offset:1408 nt
	v_add_co_u32_e32 v8, vcc, s8, v4
	s_mov_b32 s8, 0x2a0000
	s_nop 0
	v_addc_co_u32_e32 v9, vcc, 0, v5, vcc
	global_load_dword v34, v[8:9], off offset:1472 nt
	v_add_co_u32_e32 v8, vcc, s8, v4
	s_mov_b32 s8, 0x2bc000
	s_nop 0
	v_addc_co_u32_e32 v9, vcc, 0, v5, vcc
	global_load_dword v35, v[8:9], off offset:1536 nt
	v_add_co_u32_e32 v8, vcc, s8, v4
	s_mov_b32 s8, 0x2d8000
	s_nop 0
	v_addc_co_u32_e32 v9, vcc, 0, v5, vcc
	global_load_dword v36, v[8:9], off offset:1600 nt
	v_add_co_u32_e32 v8, vcc, s8, v4
	s_mov_b32 s8, 0x2f4000
	s_nop 0
	v_addc_co_u32_e32 v9, vcc, 0, v5, vcc
	global_load_dword v37, v[8:9], off offset:1664 nt
	v_add_co_u32_e32 v8, vcc, s8, v4
	s_mov_b32 s8, 0x310000
	s_nop 0
	v_addc_co_u32_e32 v9, vcc, 0, v5, vcc
	global_load_dword v38, v[8:9], off offset:1728 nt
	v_add_co_u32_e32 v8, vcc, s8, v4
	s_mov_b32 s8, 0x32c000
	s_nop 0
	v_addc_co_u32_e32 v9, vcc, 0, v5, vcc
	global_load_dword v39, v[8:9], off offset:1792 nt
	v_add_co_u32_e32 v8, vcc, s8, v4
	s_mov_b32 s8, 0x348000
	s_nop 0
	v_addc_co_u32_e32 v9, vcc, 0, v5, vcc
	global_load_dword v40, v[8:9], off offset:1856 nt
	v_add_co_u32_e32 v8, vcc, s8, v4
	s_lshl_b32 s8, s11, 7
	s_nop 0
	v_addc_co_u32_e32 v9, vcc, 0, v5, vcc
	v_add_co_u32_e32 v4, vcc, s85, v4
	global_load_dword v8, v[8:9], off offset:1920 nt
	s_nop 0
	v_addc_co_u32_e32 v5, vcc, 0, v5, vcc
	global_load_dword v4, v[4:5], off offset:1984 nt
	v_mul_lo_u32 v5, v10, s86
	v_add3_u32 v2, s14, v2, v5
	v_add_u32_e32 v5, 0x400, v2
	s_waitcnt vmcnt(0)
; #define GAS __attribute__((address_space(1)))
; #define LAS __attribute__((address_space(3)))
; #define LDS_WAIT() asm volatile("s_waitcnt lgkmcnt(0)" ::: "memory")
; __device__ __forceinline__ unsigned pk2(float lo, float hi) { return f2bf(lo) | (f2bf(hi) << 16); }
;     ...
;       for (int i = 0; i < 32; ++i) scr[(2 * i + (lane >> 5)) * 33 + (lane & 31)] = wv[i]; }
;     LDS_WAIT(); asm volatile("" ::: "memory");
;     const int c = lane & 7;
;     const int r0 = (mode == 0) ? n0 : (256 * (n0 >> 7) + (n0 & 127) + (mode == 2 ? 128 : 0));
; #pragma unroll
;     for (int j = 0; j < 4; ++j) { const int n = (lane >> 3) + 8 * j; const LAS float* s = scr + (8 * c) * 33 + n;
;         v4u o; o.x = pk2(s[0 * 33], s[1 * 33]); o.y = pk2(s[2 * 33], s[3 * 33]); o.z = pk2(s[4 * 33], s[5 * 33]); o.w = pk2(s[6 * 33], s[7 * 33]);
;         *(GAS v4u*)(WT + (size_t)(r0 + n) * ldt + k0 + 8 * c) = o; }
;     LDS_WAIT(); asm volatile("" ::: "memory");
; __device__ __forceinline__ void transpose_early(const Args& a, Frame& F, LAS float* scr, int r) {
;     ...
;     p0_transpose_item(a.in[I_WIN] + 6152, 14344, D, WIN + (size_t)6144 * D, 0, 8192 / 32, scr, r, F.lane);
	ds_write2_b32 v2, v11, v12 offset1:66
	ds_write2_b32 v2, v13, v14 offset0:132 offset1:198
	ds_write2_b32 v5, v15, v16 offset0:8 offset1:74
	ds_write2_b32 v5, v17, v18 offset0:140 offset1:206
	v_add_u32_e32 v5, 0x800, v2
	ds_write2_b32 v5, v19, v20 offset0:16 offset1:82
	ds_write2_b32 v5, v21, v22 offset0:148 offset1:214
	v_add_u32_e32 v5, 0xc00, v2
	ds_write2_b32 v5, v23, v24 offset0:24 offset1:90
	ds_write2_b32 v5, v25, v26 offset0:156 offset1:222
	v_add_u32_e32 v5, 0x1000, v2
	ds_write2_b32 v5, v27, v28 offset0:32 offset1:98
	ds_write2_b32 v5, v29, v30 offset0:164 offset1:230
	v_add_u32_e32 v5, 0x1400, v2
	ds_write2_b32 v5, v31, v32 offset0:40 offset1:106
	ds_write2_b32 v5, v33, v34 offset0:172 offset1:238
	v_add_u32_e32 v5, 0x1800, v2
	v_add_u32_e32 v2, 0x1c00, v2
	ds_write2_b32 v5, v35, v36 offset0:48 offset1:114
	ds_write2_b32 v5, v37, v38 offset0:180 offset1:246
	ds_write2_b32 v2, v39, v40 offset0:56 offset1:122
	ds_write2_b32 v2, v8, v4 offset0:188 offset1:254
	v_lshlrev_b32_e32 v2, 3, v7
	v_and_b32_e32 v2, 56, v2
	s_add_u32 s16, s23, s8
	v_ashrrev_i32_e32 v28, 3, v7
	v_mul_u32_u24_e32 v7, 0x84, v2
	s_addc_u32 s17, s36, 0
	v_lshlrev_b32_e32 v2, 1, v2
	s_waitcnt lgkmcnt(0)
	v_lshl_add_u64 v[4:5], s[16:17], 0, v[2:3]
	v_lshlrev_b32_e32 v2, 2, v28
	v_add3_u32 v2, s14, v7, v2
	ds_read2_b32 v[12:13], v2 offset0:33 offset1:41
	ds_read2_b32 v[14:15], v2 offset1:8
	ds_read2_b32 v[16:17], v2 offset0:66 offset1:74
	ds_read2_b32 v[18:19], v2 offset0:99 offset1:107
	ds_read2_b32 v[20:21], v2 offset0:132 offset1:140
	ds_read2_b32 v[22:23], v2 offset0:165 offset1:173
	ds_read2_b32 v[24:25], v2 offset0:198 offset1:206
	ds_read2_b32 v[26:27], v2 offset0:231 offset1:239
	s_waitcnt lgkmcnt(7)
	v_bfe_u32 v8, v12, 16, 1
	s_waitcnt lgkmcnt(6)
	v_bfe_u32 v7, v14, 16, 1
	v_add3_u32 v7, v14, v7, s87
	v_lshrrev_b32_e32 v7, 16, v7
	v_add3_u32 v8, v12, v8, s87
	v_and_or_b32 v8, v8, s88, v7
	s_waitcnt lgkmcnt(5)
	v_bfe_u32 v7, v16, 16, 1
	v_add3_u32 v7, v16, v7, s87
	s_waitcnt lgkmcnt(4)
	v_bfe_u32 v9, v18, 16, 1
	v_lshrrev_b32_e32 v7, 16, v7
	v_add3_u32 v9, v18, v9, s87
	v_and_or_b32 v9, v9, s88, v7
	s_waitcnt lgkmcnt(3)
	v_bfe_u32 v7, v20, 16, 1
	v_add3_u32 v7, v20, v7, s87
	s_waitcnt lgkmcnt(2)
	v_bfe_u32 v10, v22, 16, 1
	v_lshrrev_b32_e32 v7, 16, v7
	v_add3_u32 v10, v22, v10, s87
	v_and_or_b32 v10, v10, s88, v7
	s_waitcnt lgkmcnt(1)
	v_bfe_u32 v7, v24, 16, 1
	v_add_u32_e32 v28, s10, v28
	v_add3_u32 v7, v24, v7, s87
	s_waitcnt lgkmcnt(0)
	v_bfe_u32 v11, v26, 16, 1
	v_ashrrev_i32_e32 v29, 31, v28
	v_lshrrev_b32_e32 v7, 16, v7
	v_add3_u32 v11, v26, v11, s87
	v_lshlrev_b64 v[30:31], 12, v[28:29]
	v_and_or_b32 v11, v11, s88, v7
	v_lshl_add_u64 v[30:31], v[4:5], 0, v[30:31]
	v_bfe_u32 v7, v15, 16, 1
	global_store_dwordx4 v[30:31], v[8:11], off
	v_add3_u32 v7, v15, v7, s87
	v_lshrrev_b32_e32 v7, 16, v7
	v_bfe_u32 v8, v13, 16, 1
	v_add3_u32 v8, v13, v8, s87
	v_and_or_b32 v8, v8, s88, v7
	v_bfe_u32 v7, v17, 16, 1
	v_add3_u32 v7, v17, v7, s87
	v_bfe_u32 v9, v19, 16, 1
	v_lshrrev_b32_e32 v7, 16, v7
	v_add3_u32 v9, v19, v9, s87
	v_and_or_b32 v9, v9, s88, v7
	v_bfe_u32 v7, v21, 16, 1
	v_add3_u32 v7, v21, v7, s87
	v_bfe_u32 v10, v23, 16, 1
	v_lshrrev_b32_e32 v7, 16, v7
	v_add3_u32 v10, v23, v10, s87
	v_and_or_b32 v10, v10, s88, v7
	v_bfe_u32 v7, v25, 16, 1
	v_add_u32_e32 v12, 8, v28
	v_add3_u32 v7, v25, v7, s87
	v_bfe_u32 v11, v27, 16, 1
	v_ashrrev_i32_e32 v13, 31, v12
	v_lshrrev_b32_e32 v7, 16, v7
	v_add3_u32 v11, v27, v11, s87
	v_lshlrev_b64 v[12:13], 12, v[12:13]
	v_and_or_b32 v11, v11, s88, v7
	v_lshl_add_u64 v[12:13], v[4:5], 0, v[12:13]
	global_store_dwordx4 v[12:13], v[8:11], off
	ds_read2_b32 v[12:13], v2 offset0:49 offset1:57
	ds_read2_b32 v[14:15], v2 offset0:16 offset1:24
	ds_read2_b32 v[16:17], v2 offset0:82 offset1:90
	ds_read2_b32 v[18:19], v2 offset0:115 offset1:123
	ds_read2_b32 v[20:21], v2 offset0:148 offset1:156
	ds_read2_b32 v[22:23], v2 offset0:181 offset1:189
	ds_read2_b32 v[24:25], v2 offset0:214 offset1:222
	ds_read2_b32 v[26:27], v2 offset0:247 offset1:255
	s_waitcnt lgkmcnt(7)
	v_bfe_u32 v8, v12, 16, 1
	s_waitcnt lgkmcnt(6)
	v_bfe_u32 v7, v14, 16, 1
	v_add3_u32 v7, v14, v7, s87
	v_lshrrev_b32_e32 v7, 16, v7
	v_add3_u32 v8, v12, v8, s87
	v_and_or_b32 v8, v8, s88, v7
	s_waitcnt lgkmcnt(5)
	v_bfe_u32 v7, v16, 16, 1
	v_add3_u32 v7, v16, v7, s87
	s_waitcnt lgkmcnt(4)
	v_bfe_u32 v9, v18, 16, 1
	v_lshrrev_b32_e32 v7, 16, v7
	v_add3_u32 v9, v18, v9, s87
	v_and_or_b32 v9, v9, s88, v7
	s_waitcnt lgkmcnt(3)
	v_bfe_u32 v7, v20, 16, 1
	v_add3_u32 v7, v20, v7, s87
	s_waitcnt lgkmcnt(2)
	v_bfe_u32 v10, v22, 16, 1
	v_lshrrev_b32_e32 v7, 16, v7
	v_add3_u32 v10, v22, v10, s87
	s_waitcnt lgkmcnt(1)
	v_bfe_u32 v2, v24, 16, 1
	v_and_or_b32 v10, v10, s88, v7
	v_add3_u32 v2, v24, v2, s87
	s_waitcnt lgkmcnt(0)
	v_bfe_u32 v7, v26, 16, 1
	v_lshrrev_b32_e32 v2, 16, v2
	v_add3_u32 v7, v26, v7, s87
	v_add_u32_e32 v30, 16, v28
	v_and_or_b32 v11, v7, s88, v2
	v_ashrrev_i32_e32 v31, 31, v30
	v_bfe_u32 v2, v15, 16, 1
	v_lshlrev_b64 v[30:31], 12, v[30:31]
	v_add3_u32 v2, v15, v2, s87
	v_bfe_u32 v7, v13, 16, 1
	v_lshl_add_u64 v[30:31], v[4:5], 0, v[30:31]
	v_lshrrev_b32_e32 v2, 16, v2
	v_add3_u32 v7, v13, v7, s87
	global_store_dwordx4 v[30:31], v[8:11], off
	v_add_u32_e32 v12, 24, v28
	v_ashrrev_i32_e32 v13, 31, v12
	v_and_or_b32 v8, v7, s88, v2
	v_bfe_u32 v2, v17, 16, 1
	v_add3_u32 v2, v17, v2, s87
	v_bfe_u32 v7, v19, 16, 1
	v_lshrrev_b32_e32 v2, 16, v2
	v_add3_u32 v7, v19, v7, s87
	v_and_or_b32 v9, v7, s88, v2
	v_bfe_u32 v2, v21, 16, 1
	v_add3_u32 v2, v21, v2, s87
	v_bfe_u32 v7, v23, 16, 1
	v_lshrrev_b32_e32 v2, 16, v2
	v_add3_u32 v7, v23, v7, s87
	v_and_or_b32 v10, v7, s88, v2
	v_bfe_u32 v2, v25, 16, 1
	v_add3_u32 v2, v25, v2, s87
	v_bfe_u32 v7, v27, 16, 1
	v_lshrrev_b32_e32 v2, 16, v2
	v_add3_u32 v7, v27, v7, s87
	v_lshlrev_b64 v[12:13], 12, v[12:13]
	v_and_or_b32 v11, v7, s88, v2
	v_lshl_add_u64 v[4:5], v[4:5], 0, v[12:13]
	global_store_dwordx4 v[4:5], v[8:11], off
	s_waitcnt lgkmcnt(0)
	s_mov_b64 s[10:11], 0
;     if (ldt == 0) ldt = K;
;     asm volatile("" : "+v"(lane));
;     const int kb = item / nblk, nb = item % nblk, k0 = 64 * kb, n0 = 32 * nb;
;     { float wv[32];
;       const float* wp = W + (size_t)(k0 + (lane >> 5)) * ldw + n0 + (lane & 31);
; #pragma unroll
;       for (int i = 0; i < 32; ++i) wv[i] = wp[(size_t)(2 * i) * ldw];
; #pragma unroll
;       for (int i = 0; i < 32; ++i) scr[(2 * i + (lane >> 5)) * 33 + (lane & 31)] = wv[i]; }
; __device__ __forceinline__ void transpose_early(const Args& a, Frame& F, LAS float* scr, int r) {
;     ...
;     if (r < IT_INA) { p0_transpose_item(a.in[I_WIN], 14344, D, WIN, 0, 6144 / 32, scr, r, F.lane); return; } r -= IT_INA;
.LBB0_209:
	s_andn2_b64 vcc, exec, s[10:11]
	s_cbranch_vccnz .LBB0_211
	s_add_i32 s8, s12, 0xbe00
	s_and_b32 s10, s8, 0xffff
	s_mul_i32 s10, s10, 0xaaab
	s_lshr_b32 s11, s10, 23
	s_mul_i32 s10, s11, 0xc0
	v_mov_b32_e32 v7, v6
	s_sub_i32 s8, s8, s10
	s_lshl_b32 s8, s8, 5
	v_ashrrev_i32_e32 v10, 5, v7
	s_and_b32 s10, s8, 0xffe0
	v_lshl_add_u32 v2, s11, 6, v10
	v_mov_b64_e32 v[4:5], s[68:69]
	v_mad_i64_i32 v[4:5], s[16:17], v2, s18, v[4:5]
	s_lshl_b32 s8, s10, 2
	v_lshlrev_b32_e32 v2, 2, v7
	v_lshl_add_u64 v[4:5], v[4:5], 0, s[8:9]
	v_and_b32_e32 v2, 0x7c, v2
	v_lshl_add_u64 v[4:5], v[4:5], 0, v[2:3]
	v_add_co_u32_e32 v8, vcc, s40, v4
	global_load_dword v11, v[4:5], off nt
	s_nop 0
	v_addc_co_u32_e32 v9, vcc, 0, v5, vcc
	global_load_dword v12, v[8:9], off offset:64 nt
	v_add_co_u32_e32 v8, vcc, s41, v4
	s_mov_b32 s8, 0x1dc000
	s_nop 0
	v_addc_co_u32_e32 v9, vcc, 0, v5, vcc
	global_load_dword v13, v[8:9], off offset:128 nt
	v_add_co_u32_e32 v8, vcc, s42, v4
	s_nop 1
	v_addc_co_u32_e32 v9, vcc, 0, v5, vcc
	global_load_dword v14, v[8:9], off offset:192 nt
	v_add_co_u32_e32 v8, vcc, s43, v4
	s_nop 1
	v_addc_co_u32_e32 v9, vcc, 0, v5, vcc
	global_load_dword v15, v[8:9], off offset:256 nt
	v_add_co_u32_e32 v8, vcc, s19, v4
	s_nop 1
	v_addc_co_u32_e32 v9, vcc, 0, v5, vcc
	global_load_dword v16, v[8:9], off offset:320 nt
	v_add_co_u32_e32 v8, vcc, s24, v4
	s_nop 1
	v_addc_co_u32_e32 v9, vcc, 0, v5, vcc
	global_load_dword v17, v[8:9], off offset:384 nt
	v_add_co_u32_e32 v8, vcc, s25, v4
	s_nop 1
	v_addc_co_u32_e32 v9, vcc, 0, v5, vcc
	global_load_dword v18, v[8:9], off offset:448 nt
	v_add_co_u32_e32 v8, vcc, s26, v4
	s_nop 1
	v_addc_co_u32_e32 v9, vcc, 0, v5, vcc
	global_load_dword v19, v[8:9], off offset:512 nt
	v_add_co_u32_e32 v8, vcc, s27, v4
	s_nop 1
	v_addc_co_u32_e32 v9, vcc, 0, v5, vcc
	global_load_dword v20, v[8:9], off offset:576 nt
	v_add_co_u32_e32 v8, vcc, s28, v4
	s_nop 1
	v_addc_co_u32_e32 v9, vcc, 0, v5, vcc
	global_load_dword v21, v[8:9], off offset:640 nt
	v_add_co_u32_e32 v8, vcc, s50, v4
	s_nop 1
	v_addc_co_u32_e32 v9, vcc, 0, v5, vcc
	global_load_dword v22, v[8:9], off offset:704 nt
	v_add_co_u32_e32 v8, vcc, s29, v4
	s_nop 1
	v_addc_co_u32_e32 v9, vcc, 0, v5, vcc
	global_load_dword v23, v[8:9], off offset:768 nt
	v_add_co_u32_e32 v8, vcc, s30, v4
	s_nop 1
	v_addc_co_u32_e32 v9, vcc, 0, v5, vcc
	global_load_dword v24, v[8:9], off offset:832 nt
	v_add_co_u32_e32 v8, vcc, s31, v4
	s_nop 1
	v_addc_co_u32_e32 v9, vcc, 0, v5, vcc
	global_load_dword v25, v[8:9], off offset:896 nt
	v_add_co_u32_e32 v8, vcc, s84, v4
	s_nop 1
	v_addc_co_u32_e32 v9, vcc, 0, v5, vcc
	global_load_dword v26, v[8:9], off offset:960 nt
	v_add_co_u32_e32 v8, vcc, s97, v4
	s_nop 1
	v_addc_co_u32_e32 v9, vcc, 0, v5, vcc
	global_load_dword v27, v[8:9], off offset:1024 nt
	v_add_co_u32_e32 v8, vcc, s8, v4
	s_mov_b32 s8, 0x1f8000
	s_nop 0
	v_addc_co_u32_e32 v9, vcc, 0, v5, vcc
	global_load_dword v28, v[8:9], off offset:1088 nt
	v_add_co_u32_e32 v8, vcc, s8, v4
	s_mov_b32 s8, 0x214000
	s_nop 0
	v_addc_co_u32_e32 v9, vcc, 0, v5, vcc
	global_load_dword v29, v[8:9], off offset:1152 nt
	v_add_co_u32_e32 v8, vcc, s8, v4
	s_mov_b32 s8, 0x230000
	s_nop 0
	v_addc_co_u32_e32 v9, vcc, 0, v5, vcc
	global_load_dword v30, v[8:9], off offset:1216 nt
	v_add_co_u32_e32 v8, vcc, s8, v4
	s_mov_b32 s8, 0x24c000
	s_nop 0
	v_addc_co_u32_e32 v9, vcc, 0, v5, vcc
	global_load_dword v31, v[8:9], off offset:1280 nt
	v_add_co_u32_e32 v8, vcc, s8, v4
	s_mov_b32 s8, 0x268000
	s_nop 0
	v_addc_co_u32_e32 v9, vcc, 0, v5, vcc
	global_load_dword v32, v[8:9], off offset:1344 nt
	v_add_co_u32_e32 v8, vcc, s8, v4
	s_mov_b32 s8, 0x284000
	s_nop 0
	v_addc_co_u32_e32 v9, vcc, 0, v5, vcc
	global_load_dword v33, v[8:9], off offset:1408 nt
	v_add_co_u32_e32 v8, vcc, s8, v4
	s_mov_b32 s8, 0x2a0000
	s_nop 0
	v_addc_co_u32_e32 v9, vcc, 0, v5, vcc
	global_load_dword v34, v[8:9], off offset:1472 nt
	v_add_co_u32_e32 v8, vcc, s8, v4
	s_mov_b32 s8, 0x2bc000
	s_nop 0
	v_addc_co_u32_e32 v9, vcc, 0, v5, vcc
	global_load_dword v35, v[8:9], off offset:1536 nt
	v_add_co_u32_e32 v8, vcc, s8, v4
	s_mov_b32 s8, 0x2d8000
	s_nop 0
	v_addc_co_u32_e32 v9, vcc, 0, v5, vcc
	global_load_dword v36, v[8:9], off offset:1600 nt
	v_add_co_u32_e32 v8, vcc, s8, v4
	s_mov_b32 s8, 0x2f4000
	s_nop 0
	v_addc_co_u32_e32 v9, vcc, 0, v5, vcc
	global_load_dword v37, v[8:9], off offset:1664 nt
	v_add_co_u32_e32 v8, vcc, s8, v4
	s_mov_b32 s8, 0x310000
	s_nop 0
	v_addc_co_u32_e32 v9, vcc, 0, v5, vcc
	global_load_dword v38, v[8:9], off offset:1728 nt
	v_add_co_u32_e32 v8, vcc, s8, v4
	s_mov_b32 s8, 0x32c000
	s_nop 0
	v_addc_co_u32_e32 v9, vcc, 0, v5, vcc
	global_load_dword v39, v[8:9], off offset:1792 nt
	v_add_co_u32_e32 v8, vcc, s8, v4
	s_mov_b32 s8, 0x348000
	s_nop 0
	v_addc_co_u32_e32 v9, vcc, 0, v5, vcc
	global_load_dword v40, v[8:9], off offset:1856 nt
	v_add_co_u32_e32 v8, vcc, s8, v4
	s_lshl_b32 s8, s11, 7
	s_nop 0
	v_addc_co_u32_e32 v9, vcc, 0, v5, vcc
	v_add_co_u32_e32 v4, vcc, s85, v4
	global_load_dword v8, v[8:9], off offset:1920 nt
	s_nop 0
	v_addc_co_u32_e32 v5, vcc, 0, v5, vcc
	global_load_dword v4, v[4:5], off offset:1984 nt
	v_mul_lo_u32 v5, v10, s86
	v_add3_u32 v2, s14, v2, v5
	v_add_u32_e32 v5, 0x400, v2
	s_waitcnt vmcnt(0)
; #define GAS __attribute__((address_space(1)))
; #define LAS __attribute__((address_space(3)))
; #define LDS_WAIT() asm volatile("s_waitcnt lgkmcnt(0)" ::: "memory")
; __device__ __forceinline__ unsigned pk2(float lo, float hi) { return f2bf(lo) | (f2bf(hi) << 16); }
;     ...
;       for (int i = 0; i < 32; ++i) scr[(2 * i + (lane >> 5)) * 33 + (lane & 31)] = wv[i]; }
;     LDS_WAIT(); asm volatile("" ::: "memory");
;     const int c = lane & 7;
;     const int r0 = (mode == 0) ? n0 : (256 * (n0 >> 7) + (n0 & 127) + (mode == 2 ? 128 : 0));
; #pragma unroll
;     for (int j = 0; j < 4; ++j) { const int n = (lane >> 3) + 8 * j; const LAS float* s = scr + (8 * c) * 33 + n;
;         v4u o; o.x = pk2(s[0 * 33], s[1 * 33]); o.y = pk2(s[2 * 33], s[3 * 33]); o.z = pk2(s[4 * 33], s[5 * 33]); o.w = pk2(s[6 * 33], s[7 * 33]);
;         *(GAS v4u*)(WT + (size_t)(r0 + n) * ldt + k0 + 8 * c) = o; }
;     LDS_WAIT(); asm volatile("" ::: "memory");
	ds_write2_b32 v2, v11, v12 offset1:66
	ds_write2_b32 v2, v13, v14 offset0:132 offset1:198
	ds_write2_b32 v5, v15, v16 offset0:8 offset1:74
	ds_write2_b32 v5, v17, v18 offset0:140 offset1:206
	v_add_u32_e32 v5, 0x800, v2
	ds_write2_b32 v5, v19, v20 offset0:16 offset1:82
	ds_write2_b32 v5, v21, v22 offset0:148 offset1:214
	v_add_u32_e32 v5, 0xc00, v2
	ds_write2_b32 v5, v23, v24 offset0:24 offset1:90
	ds_write2_b32 v5, v25, v26 offset0:156 offset1:222
	v_add_u32_e32 v5, 0x1000, v2
	ds_write2_b32 v5, v27, v28 offset0:32 offset1:98
	ds_write2_b32 v5, v29, v30 offset0:164 offset1:230
	v_add_u32_e32 v5, 0x1400, v2
	ds_write2_b32 v5, v31, v32 offset0:40 offset1:106
	ds_write2_b32 v5, v33, v34 offset0:172 offset1:238
	v_add_u32_e32 v5, 0x1800, v2
	v_add_u32_e32 v2, 0x1c00, v2
	ds_write2_b32 v5, v35, v36 offset0:48 offset1:114
	ds_write2_b32 v5, v37, v38 offset0:180 offset1:246
	ds_write2_b32 v2, v39, v40 offset0:56 offset1:122
	ds_write2_b32 v2, v8, v4 offset0:188 offset1:254
	v_lshlrev_b32_e32 v2, 3, v7
	v_and_b32_e32 v2, 56, v2
	s_add_u32 s16, s21, s8
	v_ashrrev_i32_e32 v28, 3, v7
	v_mul_u32_u24_e32 v7, 0x84, v2
	s_addc_u32 s17, s22, 0
	v_lshlrev_b32_e32 v2, 1, v2
	s_waitcnt lgkmcnt(0)
	v_lshl_add_u64 v[4:5], s[16:17], 0, v[2:3]
	v_lshlrev_b32_e32 v2, 2, v28
	v_add3_u32 v2, s14, v7, v2
	ds_read2_b32 v[12:13], v2 offset0:33 offset1:41
	ds_read2_b32 v[14:15], v2 offset1:8
	ds_read2_b32 v[16:17], v2 offset0:66 offset1:74
	ds_read2_b32 v[18:19], v2 offset0:99 offset1:107
	ds_read2_b32 v[20:21], v2 offset0:132 offset1:140
	ds_read2_b32 v[22:23], v2 offset0:165 offset1:173
	ds_read2_b32 v[24:25], v2 offset0:198 offset1:206
	ds_read2_b32 v[26:27], v2 offset0:231 offset1:239
	s_waitcnt lgkmcnt(7)
	v_bfe_u32 v8, v12, 16, 1
	s_waitcnt lgkmcnt(6)
	v_bfe_u32 v7, v14, 16, 1
	v_add3_u32 v7, v14, v7, s87
	v_lshrrev_b32_e32 v7, 16, v7
	v_add3_u32 v8, v12, v8, s87
	v_and_or_b32 v8, v8, s88, v7
	s_waitcnt lgkmcnt(5)
	v_bfe_u32 v7, v16, 16, 1
	v_add3_u32 v7, v16, v7, s87
	s_waitcnt lgkmcnt(4)
	v_bfe_u32 v9, v18, 16, 1
	v_lshrrev_b32_e32 v7, 16, v7
	v_add3_u32 v9, v18, v9, s87
	v_and_or_b32 v9, v9, s88, v7
	s_waitcnt lgkmcnt(3)
	v_bfe_u32 v7, v20, 16, 1
	v_add3_u32 v7, v20, v7, s87
	s_waitcnt lgkmcnt(2)
	v_bfe_u32 v10, v22, 16, 1
	v_lshrrev_b32_e32 v7, 16, v7
	v_add3_u32 v10, v22, v10, s87
	v_and_or_b32 v10, v10, s88, v7
	s_waitcnt lgkmcnt(1)
	v_bfe_u32 v7, v24, 16, 1
	v_add_u32_e32 v28, s10, v28
	v_add3_u32 v7, v24, v7, s87
	s_waitcnt lgkmcnt(0)
	v_bfe_u32 v11, v26, 16, 1
	v_ashrrev_i32_e32 v29, 31, v28
	v_lshrrev_b32_e32 v7, 16, v7
	v_add3_u32 v11, v26, v11, s87
	v_lshlrev_b64 v[30:31], 12, v[28:29]
	v_and_or_b32 v11, v11, s88, v7
	v_lshl_add_u64 v[30:31], v[4:5], 0, v[30:31]
	v_bfe_u32 v7, v15, 16, 1
	global_store_dwordx4 v[30:31], v[8:11], off
	v_add3_u32 v7, v15, v7, s87
	v_lshrrev_b32_e32 v7, 16, v7
	v_bfe_u32 v8, v13, 16, 1
	v_add3_u32 v8, v13, v8, s87
	v_and_or_b32 v8, v8, s88, v7
	v_bfe_u32 v7, v17, 16, 1
	v_add3_u32 v7, v17, v7, s87
	v_bfe_u32 v9, v19, 16, 1
	v_lshrrev_b32_e32 v7, 16, v7
	v_add3_u32 v9, v19, v9, s87
	v_and_or_b32 v9, v9, s88, v7
	v_bfe_u32 v7, v21, 16, 1
	v_add3_u32 v7, v21, v7, s87
	v_bfe_u32 v10, v23, 16, 1
	v_lshrrev_b32_e32 v7, 16, v7
	v_add3_u32 v10, v23, v10, s87
	v_and_or_b32 v10, v10, s88, v7
	v_bfe_u32 v7, v25, 16, 1
	v_add_u32_e32 v12, 8, v28
	v_add3_u32 v7, v25, v7, s87
	v_bfe_u32 v11, v27, 16, 1
	v_ashrrev_i32_e32 v13, 31, v12
	v_lshrrev_b32_e32 v7, 16, v7
	v_add3_u32 v11, v27, v11, s87
	v_lshlrev_b64 v[12:13], 12, v[12:13]
	v_and_or_b32 v11, v11, s88, v7
	v_lshl_add_u64 v[12:13], v[4:5], 0, v[12:13]
	global_store_dwordx4 v[12:13], v[8:11], off
	ds_read2_b32 v[12:13], v2 offset0:49 offset1:57
	ds_read2_b32 v[14:15], v2 offset0:16 offset1:24
	ds_read2_b32 v[16:17], v2 offset0:82 offset1:90
	ds_read2_b32 v[18:19], v2 offset0:115 offset1:123
	ds_read2_b32 v[20:21], v2 offset0:148 offset1:156
	ds_read2_b32 v[22:23], v2 offset0:181 offset1:189
	ds_read2_b32 v[24:25], v2 offset0:214 offset1:222
	ds_read2_b32 v[26:27], v2 offset0:247 offset1:255
	s_waitcnt lgkmcnt(7)
	v_bfe_u32 v8, v12, 16, 1
	s_waitcnt lgkmcnt(6)
	v_bfe_u32 v7, v14, 16, 1
	v_add3_u32 v7, v14, v7, s87
	v_lshrrev_b32_e32 v7, 16, v7
	v_add3_u32 v8, v12, v8, s87
	v_and_or_b32 v8, v8, s88, v7
	s_waitcnt lgkmcnt(5)
	v_bfe_u32 v7, v16, 16, 1
	v_add3_u32 v7, v16, v7, s87
	s_waitcnt lgkmcnt(4)
	v_bfe_u32 v9, v18, 16, 1
	v_lshrrev_b32_e32 v7, 16, v7
	v_add3_u32 v9, v18, v9, s87
	v_and_or_b32 v9, v9, s88, v7
	s_waitcnt lgkmcnt(3)
	v_bfe_u32 v7, v20, 16, 1
	v_add3_u32 v7, v20, v7, s87
	s_waitcnt lgkmcnt(2)
	v_bfe_u32 v10, v22, 16, 1
	v_lshrrev_b32_e32 v7, 16, v7
	v_add3_u32 v10, v22, v10, s87
	s_waitcnt lgkmcnt(1)
	v_bfe_u32 v2, v24, 16, 1
	v_and_or_b32 v10, v10, s88, v7
	v_add3_u32 v2, v24, v2, s87
	s_waitcnt lgkmcnt(0)
	v_bfe_u32 v7, v26, 16, 1
	v_lshrrev_b32_e32 v2, 16, v2
	v_add3_u32 v7, v26, v7, s87
	v_add_u32_e32 v30, 16, v28
	v_and_or_b32 v11, v7, s88, v2
	v_ashrrev_i32_e32 v31, 31, v30
	v_bfe_u32 v2, v15, 16, 1
	v_lshlrev_b64 v[30:31], 12, v[30:31]
	v_add3_u32 v2, v15, v2, s87
	v_bfe_u32 v7, v13, 16, 1
	v_lshl_add_u64 v[30:31], v[4:5], 0, v[30:31]
	v_lshrrev_b32_e32 v2, 16, v2
	v_add3_u32 v7, v13, v7, s87
	global_store_dwordx4 v[30:31], v[8:11], off
	v_add_u32_e32 v12, 24, v28
	v_ashrrev_i32_e32 v13, 31, v12
	v_and_or_b32 v8, v7, s88, v2
	v_bfe_u32 v2, v17, 16, 1
	v_add3_u32 v2, v17, v2, s87
	v_bfe_u32 v7, v19, 16, 1
	v_lshrrev_b32_e32 v2, 16, v2
	v_add3_u32 v7, v19, v7, s87
	v_and_or_b32 v9, v7, s88, v2
	v_bfe_u32 v2, v21, 16, 1
	v_add3_u32 v2, v21, v2, s87
	v_bfe_u32 v7, v23, 16, 1
	v_lshrrev_b32_e32 v2, 16, v2
	v_add3_u32 v7, v23, v7, s87
	v_and_or_b32 v10, v7, s88, v2
	v_bfe_u32 v2, v25, 16, 1
	v_add3_u32 v2, v25, v2, s87
	v_bfe_u32 v7, v27, 16, 1
	v_lshrrev_b32_e32 v2, 16, v2
	v_add3_u32 v7, v27, v7, s87
	v_lshlrev_b64 v[12:13], 12, v[12:13]
	v_and_or_b32 v11, v7, s88, v2
	v_lshl_add_u64 v[4:5], v[4:5], 0, v[12:13]
	global_store_dwordx4 v[4:5], v[8:11], off
	s_waitcnt lgkmcnt(0)

;     ...
;     const int kb = item / nblk, nb = item % nblk, k0 = 64 * kb, n0 = 32 * nb;
;     { float wv[32];
;       const float* wp = W + (size_t)(k0 + (lane >> 5)) * ldw + n0 + (lane & 31);
; #pragma unroll
;       for (int i = 0; i < 32; ++i) wv[i] = wp[(size_t)(2 * i) * ldw];
; #pragma unroll
;       for (int i = 0; i < 32; ++i) scr[(2 * i + (lane >> 5)) * 33 + (lane & 31)] = wv[i]; }
; __device__ __forceinline__ void transpose_early(const Args& a, Frame& F, LAS float* scr, int r) {
;     ...
;     if (r < IT_FD) { p0_transpose_item(a.in[I_W1D], D, FF, W1D, 0, D / 32, scr, r, F.lane); return; } r -= IT_FD;
.LBB0_212:
	s_andn2_b64 vcc, exec, s[10:11]
	s_cbranch_vccnz .LBB0_214
	s_add_i32 s8, s37, 0xffff2e00
	v_mov_b32_e32 v7, v6
	s_and_b32 s11, s8, 0xffc0
	v_ashrrev_i32_e32 v10, 5, v7
	v_add_u32_e32 v4, s11, v10
	v_ashrrev_i32_e32 v5, 31, v4
	s_and_b32 s10, s38, 0x7e0
	v_lshlrev_b64 v[4:5], 13, v[4:5]
	v_lshl_add_u64 v[4:5], s[62:63], 0, v[4:5]
	s_lshl_b32 s8, s10, 2
	v_lshlrev_b32_e32 v2, 2, v7
	v_lshl_add_u64 v[4:5], v[4:5], 0, s[8:9]
	v_and_b32_e32 v2, 0x7c, v2
	v_lshl_add_u64 v[4:5], v[4:5], 0, v[2:3]
	s_movk_i32 s8, 0x4000
	v_add_co_u32_e32 v8, vcc, s8, v4
	s_mov_b32 s8, 0x8000
	s_nop 0
	v_addc_co_u32_e32 v9, vcc, 0, v5, vcc
	global_load_dword v11, v[4:5], off nt
	global_load_dword v12, v[8:9], off nt
	v_add_co_u32_e32 v8, vcc, s8, v4
	s_mov_b32 s8, 0xc000
	s_nop 0
	v_addc_co_u32_e32 v9, vcc, 0, v5, vcc
	global_load_dword v13, v[8:9], off nt
	v_add_co_u32_e32 v8, vcc, s8, v4
	s_mov_b32 s8, 0x10000
	s_nop 0
	v_addc_co_u32_e32 v9, vcc, 0, v5, vcc
	global_load_dword v14, v[8:9], off nt
	v_add_co_u32_e32 v8, vcc, s8, v4
	s_mov_b32 s8, 0x14000
	s_nop 0
	v_addc_co_u32_e32 v9, vcc, 0, v5, vcc
	global_load_dword v15, v[8:9], off nt
	v_add_co_u32_e32 v8, vcc, s8, v4
	s_mov_b32 s8, 0x18000
	s_nop 0
	v_addc_co_u32_e32 v9, vcc, 0, v5, vcc
	global_load_dword v16, v[8:9], off nt
	v_add_co_u32_e32 v8, vcc, s8, v4
	s_mov_b32 s8, 0x20000
	s_nop 0
	v_addc_co_u32_e32 v9, vcc, 0, v5, vcc
	global_load_dword v17, v[8:9], off nt
	v_add_co_u32_e32 v8, vcc, s40, v4
	s_nop 1
	v_addc_co_u32_e32 v9, vcc, 0, v5, vcc
	global_load_dword v18, v[8:9], off nt
	v_add_co_u32_e32 v8, vcc, s8, v4
	s_mov_b32 s8, 0x24000
	s_nop 0
	v_addc_co_u32_e32 v9, vcc, 0, v5, vcc
	global_load_dword v19, v[8:9], off nt
	v_add_co_u32_e32 v8, vcc, s8, v4
	s_mov_b32 s8, 0x28000
	s_nop 0
	v_addc_co_u32_e32 v9, vcc, 0, v5, vcc
	global_load_dword v20, v[8:9], off nt
	v_add_co_u32_e32 v8, vcc, s8, v4
	s_mov_b32 s8, 0x30000
	s_nop 0
	v_addc_co_u32_e32 v9, vcc, 0, v5, vcc
	global_load_dword v21, v[8:9], off nt
	v_add_co_u32_e32 v8, vcc, s89, v4
	s_nop 1
	v_addc_co_u32_e32 v9, vcc, 0, v5, vcc
	global_load_dword v22, v[8:9], off nt
	v_add_co_u32_e32 v8, vcc, s8, v4
	s_mov_b32 s8, 0x34000
	s_nop 0
	v_addc_co_u32_e32 v9, vcc, 0, v5, vcc
	global_load_dword v23, v[8:9], off nt
	v_add_co_u32_e32 v8, vcc, s8, v4
	s_mov_b32 s8, 0x3c000
	s_nop 0
	v_addc_co_u32_e32 v9, vcc, 0, v5, vcc
	global_load_dword v24, v[8:9], off nt
	v_add_co_u32_e32 v8, vcc, s41, v4
	s_nop 1
	v_addc_co_u32_e32 v9, vcc, 0, v5, vcc
	global_load_dword v25, v[8:9], off nt
	v_add_co_u32_e32 v8, vcc, s8, v4
	s_mov_b32 s8, 0x40000
	s_nop 0
	v_addc_co_u32_e32 v9, vcc, 0, v5, vcc
	global_load_dword v26, v[8:9], off nt
	v_add_co_u32_e32 v8, vcc, s8, v4
	s_mov_b32 s8, 0x44000
	s_nop 0
	v_addc_co_u32_e32 v9, vcc, 0, v5, vcc
	global_load_dword v27, v[8:9], off nt
	v_add_co_u32_e32 v8, vcc, s8, v4
	s_mov_b32 s8, 0x48000
	s_nop 0
	v_addc_co_u32_e32 v9, vcc, 0, v5, vcc
	global_load_dword v28, v[8:9], off nt
	v_add_co_u32_e32 v8, vcc, s8, v4
	s_mov_b32 s8, 0x4c000
	s_nop 0
	v_addc_co_u32_e32 v9, vcc, 0, v5, vcc
	global_load_dword v29, v[8:9], off nt
	v_add_co_u32_e32 v8, vcc, s8, v4
	s_mov_b32 s8, 0x50000
	s_nop 0
	v_addc_co_u32_e32 v9, vcc, 0, v5, vcc
	global_load_dword v30, v[8:9], off nt
	v_add_co_u32_e32 v8, vcc, s8, v4
	s_mov_b32 s8, 0x5c000
	s_nop 0
	v_addc_co_u32_e32 v9, vcc, 0, v5, vcc
	global_load_dword v31, v[8:9], off nt
	v_add_co_u32_e32 v8, vcc, s42, v4
	s_nop 1
	v_addc_co_u32_e32 v9, vcc, 0, v5, vcc
	global_load_dword v32, v[8:9], off nt
	v_add_co_u32_e32 v8, vcc, s90, v4
	s_nop 1
	v_addc_co_u32_e32 v9, vcc, 0, v5, vcc
	global_load_dword v33, v[8:9], off nt
	v_add_co_u32_e32 v8, vcc, s8, v4
	s_mov_b32 s8, 0x60000
	s_nop 0
	v_addc_co_u32_e32 v9, vcc, 0, v5, vcc
	global_load_dword v34, v[8:9], off nt
	v_add_co_u32_e32 v8, vcc, s8, v4
	s_mov_b32 s8, 0x64000
	s_nop 0
	v_addc_co_u32_e32 v9, vcc, 0, v5, vcc
	global_load_dword v35, v[8:9], off nt
	v_add_co_u32_e32 v8, vcc, s8, v4
	s_mov_b32 s8, 0x68000
	s_nop 0
	v_addc_co_u32_e32 v9, vcc, 0, v5, vcc
	global_load_dword v36, v[8:9], off nt
	v_add_co_u32_e32 v8, vcc, s8, v4
	s_mov_b32 s8, 0x6c000
	s_nop 0
	v_addc_co_u32_e32 v9, vcc, 0, v5, vcc
	global_load_dword v37, v[8:9], off nt
	v_add_co_u32_e32 v8, vcc, s8, v4
	s_mov_b32 s8, 0x74000
	s_nop 0
	v_addc_co_u32_e32 v9, vcc, 0, v5, vcc
	global_load_dword v38, v[8:9], off nt
	v_add_co_u32_e32 v8, vcc, s43, v4
	s_nop 1
	v_addc_co_u32_e32 v9, vcc, 0, v5, vcc
	global_load_dword v39, v[8:9], off nt
	v_add_co_u32_e32 v8, vcc, s8, v4
	s_mov_b32 s8, 0x78000
	s_nop 0
	v_addc_co_u32_e32 v9, vcc, 0, v5, vcc
	global_load_dword v40, v[8:9], off nt
	v_add_co_u32_e32 v8, vcc, s8, v4
	s_mov_b32 s8, 0x7c000
	s_nop 0
	v_addc_co_u32_e32 v9, vcc, 0, v5, vcc
	v_add_co_u32_e32 v4, vcc, s8, v4
	global_load_dword v8, v[8:9], off nt
	s_nop 0
	v_addc_co_u32_e32 v5, vcc, 0, v5, vcc
	global_load_dword v4, v[4:5], off nt
	v_mul_lo_u32 v5, v10, s86
	v_add3_u32 v2, s14, v2, v5
	v_add_u32_e32 v5, 0x400, v2
	s_waitcnt vmcnt(0)
; #define GAS __attribute__((address_space(1)))
; #define LAS __attribute__((address_space(3)))
; #define LDS_WAIT() asm volatile("s_waitcnt lgkmcnt(0)" ::: "memory")
; __device__ __forceinline__ unsigned pk2(float lo, float hi) { return f2bf(lo) | (f2bf(hi) << 16); }
;     ...
;       for (int i = 0; i < 32; ++i) scr[(2 * i + (lane >> 5)) * 33 + (lane & 31)] = wv[i]; }
;     LDS_WAIT(); asm volatile("" ::: "memory");
;     const int c = lane & 7;
;     const int r0 = (mode == 0) ? n0 : (256 * (n0 >> 7) + (n0 & 127) + (mode == 2 ? 128 : 0));
; #pragma unroll
;     for (int j = 0; j < 4; ++j) { const int n = (lane >> 3) + 8 * j; const LAS float* s = scr + (8 * c) * 33 + n;
;         v4u o; o.x = pk2(s[0 * 33], s[1 * 33]); o.y = pk2(s[2 * 33], s[3 * 33]); o.z = pk2(s[4 * 33], s[5 * 33]); o.w = pk2(s[6 * 33], s[7 * 33]);
;         *(GAS v4u*)(WT + (size_t)(r0 + n) * ldt + k0 + 8 * c) = o; }
;     LDS_WAIT(); asm volatile("" ::: "memory");
	ds_write2_b32 v2, v11, v12 offset1:66
	ds_write2_b32 v2, v13, v14 offset0:132 offset1:198
	ds_write2_b32 v5, v15, v16 offset0:8 offset1:74
	ds_write2_b32 v5, v17, v18 offset0:140 offset1:206
	v_add_u32_e32 v5, 0x800, v2
	ds_write2_b32 v5, v19, v20 offset0:16 offset1:82
	ds_write2_b32 v5, v21, v22 offset0:148 offset1:214
	v_add_u32_e32 v5, 0xc00, v2
	ds_write2_b32 v5, v23, v24 offset0:24 offset1:90
	ds_write2_b32 v5, v25, v26 offset0:156 offset1:222
	v_add_u32_e32 v5, 0x1000, v2
	ds_write2_b32 v5, v27, v28 offset0:32 offset1:98
	ds_write2_b32 v5, v29, v30 offset0:164 offset1:230
	v_add_u32_e32 v5, 0x1400, v2
	ds_write2_b32 v5, v31, v32 offset0:40 offset1:106
	ds_write2_b32 v5, v33, v34 offset0:172 offset1:238
	v_add_u32_e32 v5, 0x1800, v2
	v_add_u32_e32 v2, 0x1c00, v2
	ds_write2_b32 v5, v35, v36 offset0:48 offset1:114
	ds_write2_b32 v5, v37, v38 offset0:180 offset1:246
	ds_write2_b32 v2, v39, v40 offset0:56 offset1:122
	ds_write2_b32 v2, v8, v4 offset0:188 offset1:254
	v_lshlrev_b32_e32 v2, 3, v7
	s_lshl_b32 s8, s11, 1
	v_and_b32_e32 v2, 56, v2
	s_add_u32 s16, s3, s8
	v_ashrrev_i32_e32 v28, 3, v7
	v_mul_u32_u24_e32 v7, 0x84, v2
	s_addc_u32 s17, s33, 0
	v_lshlrev_b32_e32 v2, 1, v2
	s_waitcnt lgkmcnt(0)
	v_lshl_add_u64 v[4:5], s[16:17], 0, v[2:3]
	v_lshlrev_b32_e32 v2, 2, v28
	v_add3_u32 v2, s14, v7, v2
	ds_read2_b32 v[12:13], v2 offset0:33 offset1:41
	ds_read2_b32 v[14:15], v2 offset1:8
	ds_read2_b32 v[16:17], v2 offset0:66 offset1:74
	ds_read2_b32 v[18:19], v2 offset0:99 offset1:107
	ds_read2_b32 v[20:21], v2 offset0:132 offset1:140
	ds_read2_b32 v[22:23], v2 offset0:165 offset1:173
	ds_read2_b32 v[24:25], v2 offset0:198 offset1:206
	ds_read2_b32 v[26:27], v2 offset0:231 offset1:239
	s_waitcnt lgkmcnt(7)
	v_bfe_u32 v8, v12, 16, 1
	s_waitcnt lgkmcnt(6)
	v_bfe_u32 v7, v14, 16, 1
	v_add3_u32 v7, v14, v7, s87
	v_lshrrev_b32_e32 v7, 16, v7
	v_add3_u32 v8, v12, v8, s87
	v_and_or_b32 v8, v8, s88, v7
	s_waitcnt lgkmcnt(5)
	v_bfe_u32 v7, v16, 16, 1
	v_add3_u32 v7, v16, v7, s87
	s_waitcnt lgkmcnt(4)
	v_bfe_u32 v9, v18, 16, 1
	v_lshrrev_b32_e32 v7, 16, v7
	v_add3_u32 v9, v18, v9, s87
	v_and_or_b32 v9, v9, s88, v7
	s_waitcnt lgkmcnt(3)
	v_bfe_u32 v7, v20, 16, 1
	v_add3_u32 v7, v20, v7, s87
	s_waitcnt lgkmcnt(2)
	v_bfe_u32 v10, v22, 16, 1
	v_lshrrev_b32_e32 v7, 16, v7
	v_add3_u32 v10, v22, v10, s87
	v_and_or_b32 v10, v10, s88, v7
	s_waitcnt lgkmcnt(1)
	v_bfe_u32 v7, v24, 16, 1
	v_add3_u32 v7, v24, v7, s87
	s_waitcnt lgkmcnt(0)
	v_bfe_u32 v11, v26, 16, 1
	v_lshrrev_b32_e32 v7, 16, v7
	v_add3_u32 v11, v26, v11, s87
	v_and_or_b32 v11, v11, s88, v7
	v_add_u32_e32 v7, s10, v28
	v_mad_i64_i32 v[28:29], s[10:11], v7, s91, v[4:5]
	global_store_dwordx4 v[28:29], v[8:11], off
	v_bfe_u32 v12, v27, 16, 1
	v_add3_u32 v12, v27, v12, s87
	v_bfe_u32 v8, v15, 16, 1
	v_add3_u32 v8, v15, v8, s87
	v_bfe_u32 v9, v13, 16, 1
	v_lshrrev_b32_e32 v8, 16, v8
	v_add3_u32 v9, v13, v9, s87
	v_and_or_b32 v8, v9, s88, v8
	v_bfe_u32 v9, v17, 16, 1
	v_add3_u32 v9, v17, v9, s87
	v_bfe_u32 v10, v19, 16, 1
	v_lshrrev_b32_e32 v9, 16, v9
	v_add3_u32 v10, v19, v10, s87
	v_and_or_b32 v9, v10, s88, v9
	v_bfe_u32 v10, v21, 16, 1
	v_add3_u32 v10, v21, v10, s87
	v_bfe_u32 v11, v23, 16, 1
	v_lshrrev_b32_e32 v10, 16, v10
	v_add3_u32 v11, v23, v11, s87
	v_and_or_b32 v10, v11, s88, v10
	v_bfe_u32 v11, v25, 16, 1
	v_add3_u32 v11, v25, v11, s87
	v_lshrrev_b32_e32 v11, 16, v11
	v_and_or_b32 v11, v12, s88, v11
	v_add_u32_e32 v12, 8, v7
	v_mad_i64_i32 v[12:13], s[10:11], v12, s91, v[4:5]
	global_store_dwordx4 v[12:13], v[8:11], off
	ds_read2_b32 v[12:13], v2 offset0:49 offset1:57
	ds_read2_b32 v[14:15], v2 offset0:16 offset1:24
	ds_read2_b32 v[16:17], v2 offset0:82 offset1:90
	ds_read2_b32 v[18:19], v2 offset0:115 offset1:123
	ds_read2_b32 v[20:21], v2 offset0:148 offset1:156
	ds_read2_b32 v[22:23], v2 offset0:181 offset1:189
	ds_read2_b32 v[24:25], v2 offset0:214 offset1:222
	ds_read2_b32 v[26:27], v2 offset0:247 offset1:255
	s_waitcnt lgkmcnt(7)
	v_bfe_u32 v9, v12, 16, 1
	s_waitcnt lgkmcnt(6)
	v_bfe_u32 v8, v14, 16, 1
	v_add3_u32 v8, v14, v8, s87
	v_lshrrev_b32_e32 v8, 16, v8
	v_add3_u32 v9, v12, v9, s87
	v_and_or_b32 v8, v9, s88, v8
	s_waitcnt lgkmcnt(5)
	v_bfe_u32 v9, v16, 16, 1
	v_add3_u32 v9, v16, v9, s87
	s_waitcnt lgkmcnt(4)
	v_bfe_u32 v10, v18, 16, 1
	v_lshrrev_b32_e32 v9, 16, v9
	v_add3_u32 v10, v18, v10, s87
	v_and_or_b32 v9, v10, s88, v9
	s_waitcnt lgkmcnt(3)
	v_bfe_u32 v10, v20, 16, 1
	v_add3_u32 v10, v20, v10, s87
	s_waitcnt lgkmcnt(2)
	v_bfe_u32 v11, v22, 16, 1
	v_lshrrev_b32_e32 v10, 16, v10
	v_add3_u32 v11, v22, v11, s87
	s_waitcnt lgkmcnt(1)
	v_bfe_u32 v2, v24, 16, 1
	v_and_or_b32 v10, v11, s88, v10
	v_add3_u32 v2, v24, v2, s87
	s_waitcnt lgkmcnt(0)
	v_bfe_u32 v11, v26, 16, 1
	v_lshrrev_b32_e32 v2, 16, v2
	v_add3_u32 v11, v26, v11, s87
	v_and_or_b32 v11, v11, s88, v2
	v_add_u32_e32 v2, 16, v7
	v_mad_i64_i32 v[28:29], s[10:11], v2, s91, v[4:5]
	v_bfe_u32 v2, v15, 16, 1
	global_store_dwordx4 v[28:29], v[8:11], off
	v_add3_u32 v2, v15, v2, s87
	v_lshrrev_b32_e32 v2, 16, v2
	v_bfe_u32 v8, v13, 16, 1
	v_add3_u32 v8, v13, v8, s87
	v_and_or_b32 v8, v8, s88, v2
	v_bfe_u32 v2, v17, 16, 1
	v_add3_u32 v2, v17, v2, s87
	v_bfe_u32 v9, v19, 16, 1
	v_lshrrev_b32_e32 v2, 16, v2
	v_add3_u32 v9, v19, v9, s87
	v_and_or_b32 v9, v9, s88, v2
	v_bfe_u32 v2, v21, 16, 1
	v_add3_u32 v2, v21, v2, s87
	v_bfe_u32 v10, v23, 16, 1
	v_lshrrev_b32_e32 v2, 16, v2
	v_add3_u32 v10, v23, v10, s87
	v_and_or_b32 v10, v10, s88, v2
	v_bfe_u32 v2, v25, 16, 1
	v_add3_u32 v2, v25, v2, s87
	v_bfe_u32 v11, v27, 16, 1
	v_lshrrev_b32_e32 v2, 16, v2
	v_add3_u32 v11, v27, v11, s87
	v_and_or_b32 v11, v11, s88, v2
	v_add_u32_e32 v2, 24, v7
	v_mad_i64_i32 v[4:5], s[10:11], v2, s91, v[4:5]
	global_store_dwordx4 v[4:5], v[8:11], off
	s_waitcnt lgkmcnt(0)

; #define LDS_WAIT() asm volatile("s_waitcnt lgkmcnt(0)" ::: "memory")
;     if (ldt == 0) ldt = K;
;     asm volatile("" : "+v"(lane));
;     const int kb = item / nblk, nb = item % nblk, k0 = 64 * kb, n0 = 32 * nb;
;     { float wv[32];
;       const float* wp = W + (size_t)(k0 + (lane >> 5)) * ldw + n0 + (lane & 31);
; #pragma unroll
;       for (int i = 0; i < 32; ++i) wv[i] = wp[(size_t)(2 * i) * ldw];
; #pragma unroll
;       for (int i = 0; i < 32; ++i) scr[(2 * i + (lane >> 5)) * 33 + (lane & 31)] = wv[i]; }
;     LDS_WAIT(); asm volatile("" ::: "memory");
;     const int c = lane & 7;
;     const int r0 = (mode == 0) ? n0 : (256 * (n0 >> 7) + (n0 & 127) + (mode == 2 ? 128 : 0));
; __device__ __forceinline__ void transpose_early(const Args& a, Frame& F, LAS float* scr, int r) {
;     ...
;     if (r < IT_FG) { p0_transpose_item(a.in[I_W1G], FF, D, W1, 1, FF / 32, scr, r, F.lane); return; } r -= IT_FG;
;     if (r < IT_FG) { p0_transpose_item(a.in[I_W1U], FF, D, W1, 2, FF / 32, scr, r, F.lane); return; } r -= IT_FG;
.LBB0_218:
	s_mul_hi_i32 s8, s12, 0x2e8ba2e9
	s_lshr_b32 s10, s8, 31
	s_ashr_i32 s8, s8, 5
	s_add_i32 s10, s8, s10
	v_mov_b32_e32 v7, v6
	s_mul_i32 s8, s10, 0xb0
	s_sub_i32 s8, s12, s8
	s_lshl_b32 s10, s10, 6
	v_ashrrev_i32_e32 v10, 5, v7
	s_lshl_b32 s12, s8, 5
	v_add_u32_e32 v2, s10, v10
	v_mov_b64_e32 v[4:5], s[58:59]
	v_mad_i64_i32 v[4:5], s[16:17], v2, s92, v[4:5]
	s_ashr_i32 s13, s12, 31
	v_lshlrev_b32_e32 v2, 2, v7
	v_lshl_add_u64 v[4:5], s[12:13], 2, v[4:5]
	v_and_b32_e32 v2, 0x7c, v2
	v_lshl_add_u64 v[4:5], v[4:5], 0, v[2:3]
	v_add_co_u32_e32 v8, vcc, s93, v4
	global_load_dword v11, v[4:5], off nt
	s_nop 0
	v_addc_co_u32_e32 v9, vcc, 0, v5, vcc
	global_load_dword v12, v[8:9], off nt
	v_add_co_u32_e32 v8, vcc, s94, v4
	s_lshl_b32 s8, s8, 6
	s_nop 0
	v_addc_co_u32_e32 v9, vcc, 0, v5, vcc
	global_load_dword v13, v[8:9], off nt
	v_add_co_u32_e32 v8, vcc, s95, v4
	s_and_b32 s8, s8, 0xffffff00
	s_nop 0
	v_addc_co_u32_e32 v9, vcc, 0, v5, vcc
	global_load_dword v14, v[8:9], off nt
	v_add_co_u32_e32 v8, vcc, s89, v4
	s_and_b32 s11, s12, 0x60
	s_nop 0
	v_addc_co_u32_e32 v9, vcc, 0, v5, vcc
	global_load_dword v15, v[8:9], off nt
	v_add_co_u32_e32 v8, vcc, s39, v4
	s_or_b32 s8, s11, s8
	s_nop 0
	v_addc_co_u32_e32 v9, vcc, 0, v5, vcc
	global_load_dword v16, v[8:9], off nt
	v_add_co_u32_e32 v8, vcc, s44, v4
	s_ashr_i32 s11, s10, 31
	s_nop 0
	v_addc_co_u32_e32 v9, vcc, 0, v5, vcc
	global_load_dword v17, v[8:9], off nt
	v_add_co_u32_e32 v8, vcc, s45, v4
	s_lshl_b64 s[10:11], s[10:11], 1
	s_nop 0
	v_addc_co_u32_e32 v9, vcc, 0, v5, vcc
	global_load_dword v18, v[8:9], off nt
	v_add_co_u32_e32 v8, vcc, s90, v4
	s_add_u32 s10, s15, s10
	s_nop 0
	v_addc_co_u32_e32 v9, vcc, 0, v5, vcc
	global_load_dword v19, v[8:9], off nt
	v_add_co_u32_e32 v8, vcc, s46, v4
	s_addc_u32 s11, s20, s11
	s_nop 0
	v_addc_co_u32_e32 v9, vcc, 0, v5, vcc
	global_load_dword v20, v[8:9], off nt
	v_add_co_u32_e32 v8, vcc, s47, v4
	s_nop 1
	v_addc_co_u32_e32 v9, vcc, 0, v5, vcc
	global_load_dword v21, v[8:9], off nt
	v_add_co_u32_e32 v8, vcc, s48, v4
	s_nop 1
	v_addc_co_u32_e32 v9, vcc, 0, v5, vcc
	global_load_dword v22, v[8:9], off nt
	v_add_co_u32_e32 v8, vcc, s49, v4
	s_nop 1
	v_addc_co_u32_e32 v9, vcc, 0, v5, vcc
	global_load_dword v23, v[8:9], off nt
	v_add_co_u32_e32 v8, vcc, s51, v4
	s_nop 1
	v_addc_co_u32_e32 v9, vcc, 0, v5, vcc
	global_load_dword v24, v[8:9], off nt
	v_add_co_u32_e32 v8, vcc, s52, v4
	s_nop 1
	v_addc_co_u32_e32 v9, vcc, 0, v5, vcc
	global_load_dword v25, v[8:9], off nt
	v_add_co_u32_e32 v8, vcc, s53, v4
	s_nop 1
	v_addc_co_u32_e32 v9, vcc, 0, v5, vcc
	global_load_dword v26, v[8:9], off nt
	v_add_co_u32_e32 v8, vcc, s54, v4
	s_nop 1
	v_addc_co_u32_e32 v9, vcc, 0, v5, vcc
	global_load_dword v27, v[8:9], off nt
	v_add_co_u32_e32 v8, vcc, s55, v4
	s_nop 1
	v_addc_co_u32_e32 v9, vcc, 0, v5, vcc
	global_load_dword v28, v[8:9], off nt
	v_add_co_u32_e32 v8, vcc, s56, v4
	s_nop 1
	v_addc_co_u32_e32 v9, vcc, 0, v5, vcc
	global_load_dword v29, v[8:9], off nt
	v_add_co_u32_e32 v8, vcc, s57, v4
	s_nop 1
	v_addc_co_u32_e32 v9, vcc, 0, v5, vcc
	global_load_dword v30, v[8:9], off nt
	v_add_co_u32_e32 v8, vcc, s72, v4
	s_nop 1
	v_addc_co_u32_e32 v9, vcc, 0, v5, vcc
	global_load_dword v31, v[8:9], off nt
	v_add_co_u32_e32 v8, vcc, s73, v4
	s_nop 1
	v_addc_co_u32_e32 v9, vcc, 0, v5, vcc
	global_load_dword v32, v[8:9], off nt
	v_add_co_u32_e32 v8, vcc, s74, v4
	s_nop 1
	v_addc_co_u32_e32 v9, vcc, 0, v5, vcc
	global_load_dword v33, v[8:9], off nt
	v_add_co_u32_e32 v8, vcc, s75, v4
	s_nop 1
	v_addc_co_u32_e32 v9, vcc, 0, v5, vcc
	global_load_dword v34, v[8:9], off nt
	v_add_co_u32_e32 v8, vcc, s76, v4
	s_nop 1
	v_addc_co_u32_e32 v9, vcc, 0, v5, vcc
	global_load_dword v35, v[8:9], off nt
	v_add_co_u32_e32 v8, vcc, s77, v4
	s_nop 1
	v_addc_co_u32_e32 v9, vcc, 0, v5, vcc
	global_load_dword v36, v[8:9], off nt
	v_add_co_u32_e32 v8, vcc, s78, v4
	s_nop 1
	v_addc_co_u32_e32 v9, vcc, 0, v5, vcc
	global_load_dword v37, v[8:9], off nt
	v_add_co_u32_e32 v8, vcc, s79, v4
	s_nop 1
	v_addc_co_u32_e32 v9, vcc, 0, v5, vcc
	global_load_dword v38, v[8:9], off nt
	v_add_co_u32_e32 v8, vcc, s50, v4
	s_nop 1
	v_addc_co_u32_e32 v9, vcc, 0, v5, vcc
	global_load_dword v39, v[8:9], off nt
	v_add_co_u32_e32 v8, vcc, s80, v4
	s_nop 1
	v_addc_co_u32_e32 v9, vcc, 0, v5, vcc
	global_load_dword v40, v[8:9], off nt
	v_add_co_u32_e32 v8, vcc, s81, v4
	s_nop 1
	v_addc_co_u32_e32 v9, vcc, 0, v5, vcc
	v_add_co_u32_e32 v4, vcc, s82, v4
	global_load_dword v8, v[8:9], off nt
	s_nop 0
	v_addc_co_u32_e32 v5, vcc, 0, v5, vcc
	global_load_dword v4, v[4:5], off nt
	v_mul_lo_u32 v5, v10, s86
	v_add3_u32 v2, s14, v2, v5
	v_add_u32_e32 v5, 0x400, v2
	s_waitcnt vmcnt(0)
	ds_write2_b32 v2, v11, v12 offset1:66
	ds_write2_b32 v2, v13, v14 offset0:132 offset1:198
	ds_write2_b32 v5, v15, v16 offset0:8 offset1:74
	ds_write2_b32 v5, v17, v18 offset0:140 offset1:206
	v_add_u32_e32 v5, 0x800, v2
	ds_write2_b32 v5, v19, v20 offset0:16 offset1:82
	ds_write2_b32 v5, v21, v22 offset0:148 offset1:214
	v_add_u32_e32 v5, 0xc00, v2
	ds_write2_b32 v5, v23, v24 offset0:24 offset1:90
	ds_write2_b32 v5, v25, v26 offset0:156 offset1:222
	v_add_u32_e32 v5, 0x1000, v2
	ds_write2_b32 v5, v27, v28 offset0:32 offset1:98
	ds_write2_b32 v5, v29, v30 offset0:164 offset1:230
	v_add_u32_e32 v5, 0x1400, v2
	ds_write2_b32 v5, v31, v32 offset0:40 offset1:106
	ds_write2_b32 v5, v33, v34 offset0:172 offset1:238
	v_add_u32_e32 v5, 0x1800, v2
	v_add_u32_e32 v2, 0x1c00, v2
	ds_write2_b32 v5, v35, v36 offset0:48 offset1:114
	ds_write2_b32 v5, v37, v38 offset0:180 offset1:246
	ds_write2_b32 v2, v39, v40 offset0:56 offset1:122
	ds_write2_b32 v2, v8, v4 offset0:188 offset1:254
	v_lshlrev_b32_e32 v2, 3, v7
	v_and_b32_e32 v2, 56, v2
	v_ashrrev_i32_e32 v28, 3, v7
	v_mul_u32_u24_e32 v7, 0x84, v2
	v_lshlrev_b32_e32 v2, 1, v2
	s_waitcnt lgkmcnt(0)
; #define GAS __attribute__((address_space(1)))
; #define LAS __attribute__((address_space(3)))
; #define LDS_WAIT() asm volatile("s_waitcnt lgkmcnt(0)" ::: "memory")
; __device__ __forceinline__ unsigned pk2(float lo, float hi) { return f2bf(lo) | (f2bf(hi) << 16); }
;     ...
;     const int c = lane & 7;
;     const int r0 = (mode == 0) ? n0 : (256 * (n0 >> 7) + (n0 & 127) + (mode == 2 ? 128 : 0));
; #pragma unroll
;     for (int j = 0; j < 4; ++j) { const int n = (lane >> 3) + 8 * j; const LAS float* s = scr + (8 * c) * 33 + n;
;         v4u o; o.x = pk2(s[0 * 33], s[1 * 33]); o.y = pk2(s[2 * 33], s[3 * 33]); o.z = pk2(s[4 * 33], s[5 * 33]); o.w = pk2(s[6 * 33], s[7 * 33]);
;         *(GAS v4u*)(WT + (size_t)(r0 + n) * ldt + k0 + 8 * c) = o; }
;     LDS_WAIT(); asm volatile("" ::: "memory");
	v_lshl_add_u64 v[4:5], s[10:11], 0, v[2:3]
	v_lshlrev_b32_e32 v2, 2, v28
	v_add3_u32 v2, s14, v7, v2
	ds_read2_b32 v[12:13], v2 offset0:33 offset1:41
	ds_read2_b32 v[14:15], v2 offset1:8
	ds_read2_b32 v[16:17], v2 offset0:66 offset1:74
	ds_read2_b32 v[18:19], v2 offset0:99 offset1:107
	ds_read2_b32 v[20:21], v2 offset0:132 offset1:140
	ds_read2_b32 v[22:23], v2 offset0:165 offset1:173
	ds_read2_b32 v[24:25], v2 offset0:198 offset1:206
	ds_read2_b32 v[26:27], v2 offset0:231 offset1:239
	s_waitcnt lgkmcnt(7)
	v_bfe_u32 v8, v12, 16, 1
	s_waitcnt lgkmcnt(6)
	v_bfe_u32 v7, v14, 16, 1
	v_add3_u32 v7, v14, v7, s87
	v_lshrrev_b32_e32 v7, 16, v7
	v_add3_u32 v8, v12, v8, s87
	v_and_or_b32 v8, v8, s88, v7
	s_waitcnt lgkmcnt(5)
	v_bfe_u32 v7, v16, 16, 1
	v_add3_u32 v7, v16, v7, s87
	s_waitcnt lgkmcnt(4)
	v_bfe_u32 v9, v18, 16, 1
	v_lshrrev_b32_e32 v7, 16, v7
	v_add3_u32 v9, v18, v9, s87
	v_and_or_b32 v9, v9, s88, v7
	s_waitcnt lgkmcnt(3)
	v_bfe_u32 v7, v20, 16, 1
	v_add3_u32 v7, v20, v7, s87
	s_waitcnt lgkmcnt(2)
	v_bfe_u32 v10, v22, 16, 1
	v_lshrrev_b32_e32 v7, 16, v7
	v_add3_u32 v10, v22, v10, s87
	v_and_or_b32 v10, v10, s88, v7
	s_waitcnt lgkmcnt(1)
	v_bfe_u32 v7, v24, 16, 1
	v_add_u32_e32 v28, s8, v28
	v_add3_u32 v7, v24, v7, s87
	s_waitcnt lgkmcnt(0)
	v_bfe_u32 v11, v26, 16, 1
	v_ashrrev_i32_e32 v29, 31, v28
	v_lshrrev_b32_e32 v7, 16, v7
	v_add3_u32 v11, v26, v11, s87
	v_lshlrev_b64 v[30:31], 12, v[28:29]
	v_and_or_b32 v11, v11, s88, v7
	v_lshl_add_u64 v[30:31], v[4:5], 0, v[30:31]
	v_bfe_u32 v7, v15, 16, 1
	global_store_dwordx4 v[30:31], v[8:11], off
	v_add3_u32 v7, v15, v7, s87
	v_lshrrev_b32_e32 v7, 16, v7
	v_bfe_u32 v8, v13, 16, 1
	v_add3_u32 v8, v13, v8, s87
	v_and_or_b32 v8, v8, s88, v7
	v_bfe_u32 v7, v17, 16, 1
	v_add3_u32 v7, v17, v7, s87
	v_bfe_u32 v9, v19, 16, 1
	v_lshrrev_b32_e32 v7, 16, v7
	v_add3_u32 v9, v19, v9, s87
	v_and_or_b32 v9, v9, s88, v7
	v_bfe_u32 v7, v21, 16, 1
	v_add3_u32 v7, v21, v7, s87
	v_bfe_u32 v10, v23, 16, 1
	v_lshrrev_b32_e32 v7, 16, v7
	v_add3_u32 v10, v23, v10, s87
	v_and_or_b32 v10, v10, s88, v7
	v_bfe_u32 v7, v25, 16, 1
	v_add_u32_e32 v12, 8, v28
	v_add3_u32 v7, v25, v7, s87
	v_bfe_u32 v11, v27, 16, 1
	v_ashrrev_i32_e32 v13, 31, v12
	v_lshrrev_b32_e32 v7, 16, v7
	v_add3_u32 v11, v27, v11, s87
	v_lshlrev_b64 v[12:13], 12, v[12:13]
	v_and_or_b32 v11, v11, s88, v7
	v_lshl_add_u64 v[12:13], v[4:5], 0, v[12:13]
	global_store_dwordx4 v[12:13], v[8:11], off
	ds_read2_b32 v[12:13], v2 offset0:49 offset1:57
	ds_read2_b32 v[14:15], v2 offset0:16 offset1:24
	ds_read2_b32 v[16:17], v2 offset0:82 offset1:90
	ds_read2_b32 v[18:19], v2 offset0:115 offset1:123
	ds_read2_b32 v[20:21], v2 offset0:148 offset1:156
	ds_read2_b32 v[22:23], v2 offset0:181 offset1:189
	ds_read2_b32 v[24:25], v2 offset0:214 offset1:222
	ds_read2_b32 v[26:27], v2 offset0:247 offset1:255
	s_waitcnt lgkmcnt(7)
	v_bfe_u32 v8, v12, 16, 1
	s_waitcnt lgkmcnt(6)
	v_bfe_u32 v7, v14, 16, 1
	v_add3_u32 v7, v14, v7, s87
	v_lshrrev_b32_e32 v7, 16, v7
	v_add3_u32 v8, v12, v8, s87
	v_and_or_b32 v8, v8, s88, v7
	s_waitcnt lgkmcnt(5)
	v_bfe_u32 v7, v16, 16, 1
	v_add3_u32 v7, v16, v7, s87
	s_waitcnt lgkmcnt(4)
	v_bfe_u32 v9, v18, 16, 1
	v_lshrrev_b32_e32 v7, 16, v7
	v_add3_u32 v9, v18, v9, s87
	v_and_or_b32 v9, v9, s88, v7
	s_waitcnt lgkmcnt(3)
	v_bfe_u32 v7, v20, 16, 1
	v_add3_u32 v7, v20, v7, s87
	s_waitcnt lgkmcnt(2)
	v_bfe_u32 v10, v22, 16, 1
	v_lshrrev_b32_e32 v7, 16, v7
	v_add3_u32 v10, v22, v10, s87
	s_waitcnt lgkmcnt(1)
	v_bfe_u32 v2, v24, 16, 1
	v_and_or_b32 v10, v10, s88, v7
	v_add3_u32 v2, v24, v2, s87
	s_waitcnt lgkmcnt(0)
	v_bfe_u32 v7, v26, 16, 1
	v_lshrrev_b32_e32 v2, 16, v2
	v_add3_u32 v7, v26, v7, s87
	v_add_u32_e32 v30, 16, v28
	v_and_or_b32 v11, v7, s88, v2
	v_ashrrev_i32_e32 v31, 31, v30
	v_bfe_u32 v2, v15, 16, 1
	v_lshlrev_b64 v[30:31], 12, v[30:31]
	v_add3_u32 v2, v15, v2, s87
	v_bfe_u32 v7, v13, 16, 1
	v_lshl_add_u64 v[30:31], v[4:5], 0, v[30:31]
	v_lshrrev_b32_e32 v2, 16, v2
	v_add3_u32 v7, v13, v7, s87
	global_store_dwordx4 v[30:31], v[8:11], off
	v_add_u32_e32 v12, 24, v28
	v_ashrrev_i32_e32 v13, 31, v12
	v_and_or_b32 v8, v7, s88, v2
	v_bfe_u32 v2, v17, 16, 1
	v_add3_u32 v2, v17, v2, s87
	v_bfe_u32 v7, v19, 16, 1
	v_lshrrev_b32_e32 v2, 16, v2
	v_add3_u32 v7, v19, v7, s87
	v_and_or_b32 v9, v7, s88, v2
	v_bfe_u32 v2, v21, 16, 1
	v_add3_u32 v2, v21, v2, s87
	v_bfe_u32 v7, v23, 16, 1
	v_lshrrev_b32_e32 v2, 16, v2
	v_add3_u32 v7, v23, v7, s87
	v_and_or_b32 v10, v7, s88, v2
	v_bfe_u32 v2, v25, 16, 1
	v_add3_u32 v2, v25, v2, s87
	v_bfe_u32 v7, v27, 16, 1
	v_lshrrev_b32_e32 v2, 16, v2
	v_add3_u32 v7, v27, v7, s87
	v_lshlrev_b64 v[12:13], 12, v[12:13]
	v_and_or_b32 v11, v7, s88, v2
	v_lshl_add_u64 v[4:5], v[4:5], 0, v[12:13]
	global_store_dwordx4 v[4:5], v[8:11], off
	s_waitcnt lgkmcnt(0)
	s_branch .LBB0_202

;     ...
;     const int kb = item / nblk, nb = item % nblk, k0 = 64 * kb, n0 = 32 * nb;
;     { float wv[32];
;       const float* wp = W + (size_t)(k0 + (lane >> 5)) * ldw + n0 + (lane & 31);
; #pragma unroll
;       for (int i = 0; i < 32; ++i) wv[i] = wp[(size_t)(2 * i) * ldw];
; #pragma unroll
;       for (int i = 0; i < 32; ++i) scr[(2 * i + (lane >> 5)) * 33 + (lane & 31)] = wv[i]; }
; __device__ __forceinline__ void transpose_late(const Args& a, Frame& F, LAS float* scr, int r) {
;     ...
;     if (r < IT_SQ) { p0_transpose_item(a.in[I_WBOUT], D, D, WAB + D, 0, D / 32, scr, r, F.lane, 2 * D); return; } r -= IT_SQ;
.LBB0_611:
	s_cmpk_gt_i32 s50, 0x7ff
	s_mov_b64 s[4:5], -1
	s_cbranch_scc0 .LBB0_613
	s_add_i32 s0, s50, 0xf800
	v_mov_b32_e32 v7, v6
	s_and_b32 s5, s0, 0xffc0
	v_ashrrev_i32_e32 v10, 5, v7
	v_add_u32_e32 v4, s5, v10
	s_sub_i32 s0, s12, 24
	v_ashrrev_i32_e32 v5, 31, v4
	v_readlane_b32 s52, v244, 2
	s_and_b32 s4, s0, 0x7e0
	v_lshlrev_b64 v[4:5], 13, v[4:5]
	v_readlane_b32 s54, v244, 4
	v_readlane_b32 s55, v244, 5
	s_lshl_b32 s0, s4, 2
	v_lshlrev_b32_e32 v2, 2, v7
	v_lshl_add_u64 v[4:5], s[54:55], 0, v[4:5]
	v_lshl_add_u64 v[4:5], v[4:5], 0, s[0:1]
	v_and_b32_e32 v2, 0x7c, v2
	v_lshl_add_u64 v[4:5], v[4:5], 0, v[2:3]
	v_add_co_u32_e32 v8, vcc, s13, v4
	global_load_dword v11, v[4:5], off nt
	s_nop 0
	v_addc_co_u32_e32 v9, vcc, 0, v5, vcc
	global_load_dword v12, v[8:9], off nt
	v_add_co_u32_e32 v8, vcc, s14, v4
	s_lshl_b32 s0, s5, 1
	s_nop 0
	v_addc_co_u32_e32 v9, vcc, 0, v5, vcc
	global_load_dword v13, v[8:9], off nt
	v_add_co_u32_e32 v8, vcc, s15, v4
	v_readlane_b32 s53, v244, 3
	s_nop 0
	v_addc_co_u32_e32 v9, vcc, 0, v5, vcc
	global_load_dword v14, v[8:9], off nt
	v_add_co_u32_e32 v8, vcc, s16, v4
	s_add_u32 s52, s8, s0
	s_nop 0
	v_addc_co_u32_e32 v9, vcc, 0, v5, vcc
	global_load_dword v15, v[8:9], off nt
	v_add_co_u32_e32 v8, vcc, s17, v4
	s_addc_u32 s53, s9, 0
	s_nop 0
	v_addc_co_u32_e32 v9, vcc, 0, v5, vcc
	global_load_dword v16, v[8:9], off nt
	v_add_co_u32_e32 v8, vcc, s18, v4
	v_readlane_b32 s56, v244, 6
	s_nop 0
	v_addc_co_u32_e32 v9, vcc, 0, v5, vcc
	global_load_dword v17, v[8:9], off nt
	v_add_co_u32_e32 v8, vcc, s19, v4
	v_readlane_b32 s57, v244, 7
	s_nop 0
	v_addc_co_u32_e32 v9, vcc, 0, v5, vcc
	global_load_dword v18, v[8:9], off nt
	v_add_co_u32_e32 v8, vcc, s20, v4
	v_readlane_b32 s58, v244, 8
	s_nop 0
	v_addc_co_u32_e32 v9, vcc, 0, v5, vcc
	global_load_dword v19, v[8:9], off nt
	v_add_co_u32_e32 v8, vcc, s21, v4
	v_readlane_b32 s59, v244, 9
	s_nop 0
	v_addc_co_u32_e32 v9, vcc, 0, v5, vcc
	global_load_dword v20, v[8:9], off nt
	v_add_co_u32_e32 v8, vcc, s22, v4
	v_readlane_b32 s60, v244, 10
	s_nop 0
	v_addc_co_u32_e32 v9, vcc, 0, v5, vcc
	global_load_dword v21, v[8:9], off nt
	v_add_co_u32_e32 v8, vcc, s23, v4
	v_readlane_b32 s61, v244, 11
	s_nop 0
	v_addc_co_u32_e32 v9, vcc, 0, v5, vcc
	global_load_dword v22, v[8:9], off nt
	v_add_co_u32_e32 v8, vcc, s24, v4
	v_readlane_b32 s62, v244, 12
	s_nop 0
	v_addc_co_u32_e32 v9, vcc, 0, v5, vcc
	global_load_dword v23, v[8:9], off nt
	v_add_co_u32_e32 v8, vcc, s25, v4
	v_readlane_b32 s63, v244, 13
	s_nop 0
	v_addc_co_u32_e32 v9, vcc, 0, v5, vcc
	global_load_dword v24, v[8:9], off nt
	v_add_co_u32_e32 v8, vcc, s26, v4
	v_readlane_b32 s64, v244, 14
	s_nop 0
	v_addc_co_u32_e32 v9, vcc, 0, v5, vcc
	global_load_dword v25, v[8:9], off nt
	v_add_co_u32_e32 v8, vcc, s27, v4
	v_readlane_b32 s65, v244, 15
	s_nop 0
	v_addc_co_u32_e32 v9, vcc, 0, v5, vcc
	global_load_dword v26, v[8:9], off nt
	v_add_co_u32_e32 v8, vcc, s28, v4
	v_readlane_b32 s66, v244, 16
	s_nop 0
	v_addc_co_u32_e32 v9, vcc, 0, v5, vcc
	global_load_dword v27, v[8:9], off nt
	v_add_co_u32_e32 v8, vcc, s29, v4
	v_readlane_b32 s67, v244, 17
	s_nop 0
	v_addc_co_u32_e32 v9, vcc, 0, v5, vcc
	global_load_dword v28, v[8:9], off nt
	v_add_co_u32_e32 v8, vcc, s30, v4
	s_nop 1
	v_addc_co_u32_e32 v9, vcc, 0, v5, vcc
	global_load_dword v29, v[8:9], off nt
	v_add_co_u32_e32 v8, vcc, s31, v4
	s_nop 1
	v_addc_co_u32_e32 v9, vcc, 0, v5, vcc
	global_load_dword v30, v[8:9], off nt
	v_add_co_u32_e32 v8, vcc, s33, v4
	s_nop 1
	v_addc_co_u32_e32 v9, vcc, 0, v5, vcc
	global_load_dword v31, v[8:9], off nt
	v_add_co_u32_e32 v8, vcc, s36, v4
	s_nop 1
	v_addc_co_u32_e32 v9, vcc, 0, v5, vcc
	global_load_dword v32, v[8:9], off nt
	v_add_co_u32_e32 v8, vcc, s37, v4
	s_nop 1
	v_addc_co_u32_e32 v9, vcc, 0, v5, vcc
	global_load_dword v33, v[8:9], off nt
	v_add_co_u32_e32 v8, vcc, s38, v4
	s_nop 1
	v_addc_co_u32_e32 v9, vcc, 0, v5, vcc
	global_load_dword v34, v[8:9], off nt
	v_add_co_u32_e32 v8, vcc, s39, v4
	s_nop 1
	v_addc_co_u32_e32 v9, vcc, 0, v5, vcc
	global_load_dword v35, v[8:9], off nt
	v_add_co_u32_e32 v8, vcc, s40, v4
	s_nop 1
	v_addc_co_u32_e32 v9, vcc, 0, v5, vcc
	global_load_dword v36, v[8:9], off nt
	v_add_co_u32_e32 v8, vcc, s41, v4
	s_nop 1
	v_addc_co_u32_e32 v9, vcc, 0, v5, vcc
	global_load_dword v37, v[8:9], off nt
	v_add_co_u32_e32 v8, vcc, s42, v4
	s_nop 1
	v_addc_co_u32_e32 v9, vcc, 0, v5, vcc
	global_load_dword v38, v[8:9], off nt
	v_add_co_u32_e32 v8, vcc, s43, v4
	s_nop 1
	v_addc_co_u32_e32 v9, vcc, 0, v5, vcc
	global_load_dword v39, v[8:9], off nt
	v_add_co_u32_e32 v8, vcc, s44, v4
	s_nop 1
	v_addc_co_u32_e32 v9, vcc, 0, v5, vcc
	global_load_dword v40, v[8:9], off nt
	v_add_co_u32_e32 v8, vcc, s45, v4
	s_nop 1
	v_addc_co_u32_e32 v9, vcc, 0, v5, vcc
	v_add_co_u32_e32 v4, vcc, s46, v4
	global_load_dword v8, v[8:9], off nt
	s_nop 0
	v_addc_co_u32_e32 v5, vcc, 0, v5, vcc
	global_load_dword v4, v[4:5], off nt
	v_mul_lo_u32 v5, v10, s47
	v_add3_u32 v2, s3, v2, v5
	v_add_u32_e32 v5, 0x400, v2
	s_waitcnt vmcnt(0)
	ds_write2_b32 v2, v11, v12 offset1:66
	ds_write2_b32 v2, v13, v14 offset0:132 offset1:198
	ds_write2_b32 v5, v15, v16 offset0:8 offset1:74
	ds_write2_b32 v5, v17, v18 offset0:140 offset1:206
	v_add_u32_e32 v5, 0x800, v2
	ds_write2_b32 v5, v19, v20 offset0:16 offset1:82
	ds_write2_b32 v5, v21, v22 offset0:148 offset1:214
	v_add_u32_e32 v5, 0xc00, v2
	ds_write2_b32 v5, v23, v24 offset0:24 offset1:90
	ds_write2_b32 v5, v25, v26 offset0:156 offset1:222
	v_add_u32_e32 v5, 0x1000, v2
	ds_write2_b32 v5, v27, v28 offset0:32 offset1:98
	ds_write2_b32 v5, v29, v30 offset0:164 offset1:230
	v_add_u32_e32 v5, 0x1400, v2
	ds_write2_b32 v5, v31, v32 offset0:40 offset1:106
	ds_write2_b32 v5, v33, v34 offset0:172 offset1:238
	v_add_u32_e32 v5, 0x1800, v2
	v_add_u32_e32 v2, 0x1c00, v2
	ds_write2_b32 v5, v35, v36 offset0:48 offset1:114
	ds_write2_b32 v5, v37, v38 offset0:180 offset1:246
	ds_write2_b32 v2, v39, v40 offset0:56 offset1:122
	ds_write2_b32 v2, v8, v4 offset0:188 offset1:254
	v_lshlrev_b32_e32 v2, 3, v7
	v_and_b32_e32 v2, 56, v2
	v_ashrrev_i32_e32 v28, 3, v7
	v_mul_u32_u24_e32 v7, 0x84, v2
	v_lshlrev_b32_e32 v2, 1, v2
	s_waitcnt lgkmcnt(0)
; #define GAS __attribute__((address_space(1)))
; #define LAS __attribute__((address_space(3)))
; #define LDS_WAIT() asm volatile("s_waitcnt lgkmcnt(0)" ::: "memory")
; __device__ __forceinline__ unsigned pk2(float lo, float hi) { return f2bf(lo) | (f2bf(hi) << 16); }
;     ...
;     const int c = lane & 7;
;     const int r0 = (mode == 0) ? n0 : (256 * (n0 >> 7) + (n0 & 127) + (mode == 2 ? 128 : 0));
; #pragma unroll
;     for (int j = 0; j < 4; ++j) { const int n = (lane >> 3) + 8 * j; const LAS float* s = scr + (8 * c) * 33 + n;
;         v4u o; o.x = pk2(s[0 * 33], s[1 * 33]); o.y = pk2(s[2 * 33], s[3 * 33]); o.z = pk2(s[4 * 33], s[5 * 33]); o.w = pk2(s[6 * 33], s[7 * 33]);
;         *(GAS v4u*)(WT + (size_t)(r0 + n) * ldt + k0 + 8 * c) = o; }
;     LDS_WAIT(); asm volatile("" ::: "memory");
	v_lshl_add_u64 v[4:5], s[52:53], 0, v[2:3]
	v_lshlrev_b32_e32 v2, 2, v28
	v_add3_u32 v2, s3, v7, v2
	ds_read2_b32 v[12:13], v2 offset0:33 offset1:41
	ds_read2_b32 v[14:15], v2 offset1:8
	ds_read2_b32 v[16:17], v2 offset0:66 offset1:74
	ds_read2_b32 v[18:19], v2 offset0:99 offset1:107
	ds_read2_b32 v[20:21], v2 offset0:132 offset1:140
	ds_read2_b32 v[22:23], v2 offset0:165 offset1:173
	ds_read2_b32 v[24:25], v2 offset0:198 offset1:206
	ds_read2_b32 v[26:27], v2 offset0:231 offset1:239
	s_waitcnt lgkmcnt(7)
	v_bfe_u32 v8, v12, 16, 1
	s_waitcnt lgkmcnt(6)
	v_bfe_u32 v7, v14, 16, 1
	v_add3_u32 v7, v14, v7, s48
	v_lshrrev_b32_e32 v7, 16, v7
	v_add3_u32 v8, v12, v8, s48
	v_and_or_b32 v8, v8, s49, v7
	s_waitcnt lgkmcnt(5)
	v_bfe_u32 v7, v16, 16, 1
	v_add3_u32 v7, v16, v7, s48
	s_waitcnt lgkmcnt(4)
	v_bfe_u32 v9, v18, 16, 1
	v_lshrrev_b32_e32 v7, 16, v7
	v_add3_u32 v9, v18, v9, s48
	v_and_or_b32 v9, v9, s49, v7
	s_waitcnt lgkmcnt(3)
	v_bfe_u32 v7, v20, 16, 1
	v_add3_u32 v7, v20, v7, s48
	s_waitcnt lgkmcnt(2)
	v_bfe_u32 v10, v22, 16, 1
	v_lshrrev_b32_e32 v7, 16, v7
	v_add3_u32 v10, v22, v10, s48
	v_and_or_b32 v10, v10, s49, v7
	s_waitcnt lgkmcnt(1)
	v_bfe_u32 v7, v24, 16, 1
	v_add_u32_e32 v28, s4, v28
	v_add3_u32 v7, v24, v7, s48
	s_waitcnt lgkmcnt(0)
	v_bfe_u32 v11, v26, 16, 1
	v_ashrrev_i32_e32 v29, 31, v28
	v_lshrrev_b32_e32 v7, 16, v7
	v_add3_u32 v11, v26, v11, s48
	v_lshlrev_b64 v[30:31], 13, v[28:29]
	v_and_or_b32 v11, v11, s49, v7
	v_lshl_add_u64 v[30:31], v[4:5], 0, v[30:31]
	v_bfe_u32 v7, v15, 16, 1
	global_store_dwordx4 v[30:31], v[8:11], off
	v_add3_u32 v7, v15, v7, s48
	v_lshrrev_b32_e32 v7, 16, v7
	v_bfe_u32 v8, v13, 16, 1
	v_add3_u32 v8, v13, v8, s48
	v_and_or_b32 v8, v8, s49, v7
	v_bfe_u32 v7, v17, 16, 1
	v_add3_u32 v7, v17, v7, s48
	v_bfe_u32 v9, v19, 16, 1
	v_lshrrev_b32_e32 v7, 16, v7
	v_add3_u32 v9, v19, v9, s48
	v_and_or_b32 v9, v9, s49, v7
	v_bfe_u32 v7, v21, 16, 1
	v_add3_u32 v7, v21, v7, s48
	v_bfe_u32 v10, v23, 16, 1
	v_lshrrev_b32_e32 v7, 16, v7
	v_add3_u32 v10, v23, v10, s48
	v_and_or_b32 v10, v10, s49, v7
	v_bfe_u32 v7, v25, 16, 1
	v_add_u32_e32 v12, 8, v28
	v_add3_u32 v7, v25, v7, s48
	v_bfe_u32 v11, v27, 16, 1
	v_ashrrev_i32_e32 v13, 31, v12
	v_lshrrev_b32_e32 v7, 16, v7
	v_add3_u32 v11, v27, v11, s48
	v_lshlrev_b64 v[12:13], 13, v[12:13]
	v_and_or_b32 v11, v11, s49, v7
	v_lshl_add_u64 v[12:13], v[4:5], 0, v[12:13]
	global_store_dwordx4 v[12:13], v[8:11], off
	ds_read2_b32 v[12:13], v2 offset0:49 offset1:57
	ds_read2_b32 v[14:15], v2 offset0:16 offset1:24
	ds_read2_b32 v[16:17], v2 offset0:82 offset1:90
	ds_read2_b32 v[18:19], v2 offset0:115 offset1:123
	ds_read2_b32 v[20:21], v2 offset0:148 offset1:156
	ds_read2_b32 v[22:23], v2 offset0:181 offset1:189
	ds_read2_b32 v[24:25], v2 offset0:214 offset1:222
	ds_read2_b32 v[26:27], v2 offset0:247 offset1:255
	s_waitcnt lgkmcnt(7)
	v_bfe_u32 v8, v12, 16, 1
	s_waitcnt lgkmcnt(6)
	v_bfe_u32 v7, v14, 16, 1
	v_add3_u32 v7, v14, v7, s48
	v_lshrrev_b32_e32 v7, 16, v7
	v_add3_u32 v8, v12, v8, s48
	v_and_or_b32 v8, v8, s49, v7
	s_waitcnt lgkmcnt(5)
	v_bfe_u32 v7, v16, 16, 1
	v_add3_u32 v7, v16, v7, s48
	s_waitcnt lgkmcnt(4)
	v_bfe_u32 v9, v18, 16, 1
	v_lshrrev_b32_e32 v7, 16, v7
	v_add3_u32 v9, v18, v9, s48
	v_and_or_b32 v9, v9, s49, v7
	s_waitcnt lgkmcnt(3)
	v_bfe_u32 v7, v20, 16, 1
	v_add3_u32 v7, v20, v7, s48
	s_waitcnt lgkmcnt(2)
	v_bfe_u32 v10, v22, 16, 1
	v_lshrrev_b32_e32 v7, 16, v7
	v_add3_u32 v10, v22, v10, s48
	s_waitcnt lgkmcnt(1)
	v_bfe_u32 v2, v24, 16, 1
	v_and_or_b32 v10, v10, s49, v7
	v_add3_u32 v2, v24, v2, s48
	s_waitcnt lgkmcnt(0)
	v_bfe_u32 v7, v26, 16, 1
	v_lshrrev_b32_e32 v2, 16, v2
	v_add3_u32 v7, v26, v7, s48
	v_add_u32_e32 v30, 16, v28
	v_and_or_b32 v11, v7, s49, v2
	v_ashrrev_i32_e32 v31, 31, v30
	v_bfe_u32 v2, v15, 16, 1
	v_lshlrev_b64 v[30:31], 13, v[30:31]
	v_add3_u32 v2, v15, v2, s48
	v_bfe_u32 v7, v13, 16, 1
	v_lshl_add_u64 v[30:31], v[4:5], 0, v[30:31]
	v_lshrrev_b32_e32 v2, 16, v2
	v_add3_u32 v7, v13, v7, s48
	global_store_dwordx4 v[30:31], v[8:11], off
	v_add_u32_e32 v12, 24, v28
	v_ashrrev_i32_e32 v13, 31, v12
	v_and_or_b32 v8, v7, s49, v2
	v_bfe_u32 v2, v17, 16, 1
	v_add3_u32 v2, v17, v2, s48
	v_bfe_u32 v7, v19, 16, 1
	v_lshrrev_b32_e32 v2, 16, v2
	v_add3_u32 v7, v19, v7, s48
	v_and_or_b32 v9, v7, s49, v2
	v_bfe_u32 v2, v21, 16, 1
	v_add3_u32 v2, v21, v2, s48
	v_bfe_u32 v7, v23, 16, 1
	v_lshrrev_b32_e32 v2, 16, v2
	v_add3_u32 v7, v23, v7, s48
	v_and_or_b32 v10, v7, s49, v2
	v_bfe_u32 v2, v25, 16, 1
	v_add3_u32 v2, v25, v2, s48
	v_bfe_u32 v7, v27, 16, 1
	v_lshrrev_b32_e32 v2, 16, v2
	v_add3_u32 v7, v27, v7, s48
	v_lshlrev_b64 v[12:13], 13, v[12:13]
	v_and_or_b32 v11, v7, s49, v2
	v_lshl_add_u64 v[4:5], v[4:5], 0, v[12:13]
	global_store_dwordx4 v[4:5], v[8:11], off
	s_waitcnt lgkmcnt(0)
	s_mov_b64 s[4:5], 0
;     ...
;     const int kb = item / nblk, nb = item % nblk, k0 = 64 * kb, n0 = 32 * nb;
;     { float wv[32];
;       const float* wp = W + (size_t)(k0 + (lane >> 5)) * ldw + n0 + (lane & 31);
; #pragma unroll
;       for (int i = 0; i < 32; ++i) wv[i] = wp[(size_t)(2 * i) * ldw];
; #pragma unroll
;       for (int i = 0; i < 32; ++i) scr[(2 * i + (lane >> 5)) * 33 + (lane & 31)] = wv[i]; }
; __device__ __forceinline__ void transpose_late(const Args& a, Frame& F, LAS float* scr, int r) {
;     ...
;     if (r < IT_SQ) { p0_transpose_item(a.in[I_WAOUT], D, D, WAB, 0, D / 32, scr, r, F.lane, 2 * D); return; } r -= IT_SQ;
.LBB0_613:
	s_andn2_b64 vcc, exec, s[4:5]
	s_cbranch_vccnz .LBB0_610
	s_ashr_i32 s0, s50, 31
	s_lshr_b32 s0, s0, 26
	v_mov_b32_e32 v7, v6
	s_add_i32 s0, s50, s0
	s_and_b32 s4, s0, 0xffffffc0
	s_lshl_b32 s0, s0, 5
	v_ashrrev_i32_e32 v10, 5, v7
	s_and_b32 s0, s0, 0xfffff800
	v_add_u32_e32 v4, s4, v10
	s_sub_i32 s5, s12, s0
	v_ashrrev_i32_e32 v5, 31, v4
	s_mov_b64 s[54:55], s[82:83]
	v_readlane_b32 s72, v245, 50
	s_sub_i32 s52, s5, 24
	v_lshlrev_b64 v[4:5], 13, v[4:5]
	v_readlane_b32 s80, v245, 58
	v_readlane_b32 s81, v245, 59
	s_ashr_i32 s53, s52, 31
	v_lshlrev_b32_e32 v2, 2, v7
	v_lshl_add_u64 v[4:5], s[80:81], 0, v[4:5]
	v_lshl_add_u64 v[4:5], s[52:53], 2, v[4:5]
	v_and_b32_e32 v2, 0x7c, v2
	v_lshl_add_u64 v[4:5], v[4:5], 0, v[2:3]
	v_add_co_u32_e32 v8, vcc, s13, v4
	global_load_dword v11, v[4:5], off nt
	s_nop 0
	v_addc_co_u32_e32 v9, vcc, 0, v5, vcc
	global_load_dword v12, v[8:9], off nt
	v_add_co_u32_e32 v8, vcc, s14, v4
	s_ashr_i32 s5, s4, 31
	s_nop 0
	v_addc_co_u32_e32 v9, vcc, 0, v5, vcc
	global_load_dword v13, v[8:9], off nt
	v_add_co_u32_e32 v8, vcc, s15, v4
	s_lshl_b64 s[4:5], s[4:5], 1
	s_nop 0
	v_addc_co_u32_e32 v9, vcc, 0, v5, vcc
	global_load_dword v14, v[8:9], off nt
	v_add_co_u32_e32 v8, vcc, s16, v4
	s_add_u32 s4, s10, s4
	s_nop 0
	v_addc_co_u32_e32 v9, vcc, 0, v5, vcc
	global_load_dword v15, v[8:9], off nt
	v_add_co_u32_e32 v8, vcc, s17, v4
	s_addc_u32 s5, s11, s5
	s_nop 0
	v_addc_co_u32_e32 v9, vcc, 0, v5, vcc
	global_load_dword v16, v[8:9], off nt
	v_add_co_u32_e32 v8, vcc, s18, v4
	v_readlane_b32 s86, v244, 0
	s_nop 0
	v_addc_co_u32_e32 v9, vcc, 0, v5, vcc
	global_load_dword v17, v[8:9], off nt
	v_add_co_u32_e32 v8, vcc, s19, v4
	v_readlane_b32 s87, v244, 1
	s_nop 0
	v_addc_co_u32_e32 v9, vcc, 0, v5, vcc
	global_load_dword v18, v[8:9], off nt
	v_add_co_u32_e32 v8, vcc, s20, v4
	v_readlane_b32 s82, v245, 60
	s_nop 0
	v_addc_co_u32_e32 v9, vcc, 0, v5, vcc
	global_load_dword v19, v[8:9], off nt
	v_add_co_u32_e32 v8, vcc, s21, v4
	v_readlane_b32 s83, v245, 61
	s_nop 0
	v_addc_co_u32_e32 v9, vcc, 0, v5, vcc
	global_load_dword v20, v[8:9], off nt
	v_add_co_u32_e32 v8, vcc, s22, v4
	v_readlane_b32 s86, v245, 46
	s_nop 0
	v_addc_co_u32_e32 v9, vcc, 0, v5, vcc
	global_load_dword v21, v[8:9], off nt
	v_add_co_u32_e32 v8, vcc, s23, v4
	s_mov_b64 s[82:83], s[54:55]
	s_nop 0
	v_addc_co_u32_e32 v9, vcc, 0, v5, vcc
	global_load_dword v22, v[8:9], off nt
	v_add_co_u32_e32 v8, vcc, s24, v4
	v_readlane_b32 s87, v245, 47
	s_nop 0
	v_addc_co_u32_e32 v9, vcc, 0, v5, vcc
	global_load_dword v23, v[8:9], off nt
	v_add_co_u32_e32 v8, vcc, s25, v4
	v_readlane_b32 s73, v245, 51
	s_nop 0
	v_addc_co_u32_e32 v9, vcc, 0, v5, vcc
	global_load_dword v24, v[8:9], off nt
	v_add_co_u32_e32 v8, vcc, s26, v4
	v_readlane_b32 s74, v245, 52
	s_nop 0
	v_addc_co_u32_e32 v9, vcc, 0, v5, vcc
	global_load_dword v25, v[8:9], off nt
	v_add_co_u32_e32 v8, vcc, s27, v4
	v_readlane_b32 s75, v245, 53
	s_nop 0
	v_addc_co_u32_e32 v9, vcc, 0, v5, vcc
	global_load_dword v26, v[8:9], off nt
	v_add_co_u32_e32 v8, vcc, s28, v4
	v_readlane_b32 s76, v245, 54
	s_nop 0
	v_addc_co_u32_e32 v9, vcc, 0, v5, vcc
	global_load_dword v27, v[8:9], off nt
	v_add_co_u32_e32 v8, vcc, s29, v4
	v_readlane_b32 s77, v245, 55
	s_nop 0
	v_addc_co_u32_e32 v9, vcc, 0, v5, vcc
	global_load_dword v28, v[8:9], off nt
	v_add_co_u32_e32 v8, vcc, s30, v4
	v_readlane_b32 s78, v245, 56
	s_nop 0
	v_addc_co_u32_e32 v9, vcc, 0, v5, vcc
	global_load_dword v29, v[8:9], off nt
	v_add_co_u32_e32 v8, vcc, s31, v4
	v_readlane_b32 s79, v245, 57
	s_nop 0
	v_addc_co_u32_e32 v9, vcc, 0, v5, vcc
	global_load_dword v30, v[8:9], off nt
	v_add_co_u32_e32 v8, vcc, s33, v4
	v_readlane_b32 s84, v245, 62
	s_nop 0
	v_addc_co_u32_e32 v9, vcc, 0, v5, vcc
	global_load_dword v31, v[8:9], off nt
	v_add_co_u32_e32 v8, vcc, s36, v4
	v_readlane_b32 s85, v245, 63
	s_nop 0
	v_addc_co_u32_e32 v9, vcc, 0, v5, vcc
	global_load_dword v32, v[8:9], off nt
	v_add_co_u32_e32 v8, vcc, s37, v4
	s_nop 1
	v_addc_co_u32_e32 v9, vcc, 0, v5, vcc
	global_load_dword v33, v[8:9], off nt
	v_add_co_u32_e32 v8, vcc, s38, v4
	s_nop 1
	v_addc_co_u32_e32 v9, vcc, 0, v5, vcc
	global_load_dword v34, v[8:9], off nt
	v_add_co_u32_e32 v8, vcc, s39, v4
	s_nop 1
	v_addc_co_u32_e32 v9, vcc, 0, v5, vcc
	global_load_dword v35, v[8:9], off nt
	v_add_co_u32_e32 v8, vcc, s40, v4
	s_nop 1
	v_addc_co_u32_e32 v9, vcc, 0, v5, vcc
	global_load_dword v36, v[8:9], off nt
	v_add_co_u32_e32 v8, vcc, s41, v4
	s_nop 1
	v_addc_co_u32_e32 v9, vcc, 0, v5, vcc
	global_load_dword v37, v[8:9], off nt
	v_add_co_u32_e32 v8, vcc, s42, v4
	s_nop 1
	v_addc_co_u32_e32 v9, vcc, 0, v5, vcc
	global_load_dword v38, v[8:9], off nt
	v_add_co_u32_e32 v8, vcc, s43, v4
	s_nop 1
	v_addc_co_u32_e32 v9, vcc, 0, v5, vcc
	global_load_dword v39, v[8:9], off nt
	v_add_co_u32_e32 v8, vcc, s44, v4
	s_nop 1
	v_addc_co_u32_e32 v9, vcc, 0, v5, vcc
	global_load_dword v40, v[8:9], off nt
	v_add_co_u32_e32 v8, vcc, s45, v4
	s_nop 1
	v_addc_co_u32_e32 v9, vcc, 0, v5, vcc
	v_add_co_u32_e32 v4, vcc, s46, v4
	global_load_dword v8, v[8:9], off nt
	s_nop 0
	v_addc_co_u32_e32 v5, vcc, 0, v5, vcc
	global_load_dword v4, v[4:5], off nt
	v_mul_lo_u32 v5, v10, s47
	v_add3_u32 v2, s3, v2, v5
	v_add_u32_e32 v5, 0x400, v2
	s_waitcnt vmcnt(0)
; #define GAS __attribute__((address_space(1)))
; #define LAS __attribute__((address_space(3)))
; #define LDS_WAIT() asm volatile("s_waitcnt lgkmcnt(0)" ::: "memory")
; __device__ __forceinline__ unsigned pk2(float lo, float hi) { return f2bf(lo) | (f2bf(hi) << 16); }
;     ...
;       for (int i = 0; i < 32; ++i) scr[(2 * i + (lane >> 5)) * 33 + (lane & 31)] = wv[i]; }
;     LDS_WAIT(); asm volatile("" ::: "memory");
;     const int c = lane & 7;
;     const int r0 = (mode == 0) ? n0 : (256 * (n0 >> 7) + (n0 & 127) + (mode == 2 ? 128 : 0));
; #pragma unroll
;     for (int j = 0; j < 4; ++j) { const int n = (lane >> 3) + 8 * j; const LAS float* s = scr + (8 * c) * 33 + n;
;         v4u o; o.x = pk2(s[0 * 33], s[1 * 33]); o.y = pk2(s[2 * 33], s[3 * 33]); o.z = pk2(s[4 * 33], s[5 * 33]); o.w = pk2(s[6 * 33], s[7 * 33]);
;         *(GAS v4u*)(WT + (size_t)(r0 + n) * ldt + k0 + 8 * c) = o; }
;     LDS_WAIT(); asm volatile("" ::: "memory");
	ds_write2_b32 v2, v11, v12 offset1:66
	ds_write2_b32 v2, v13, v14 offset0:132 offset1:198
	ds_write2_b32 v5, v15, v16 offset0:8 offset1:74
	ds_write2_b32 v5, v17, v18 offset0:140 offset1:206
	v_add_u32_e32 v5, 0x800, v2
	ds_write2_b32 v5, v19, v20 offset0:16 offset1:82
	ds_write2_b32 v5, v21, v22 offset0:148 offset1:214
	v_add_u32_e32 v5, 0xc00, v2
	ds_write2_b32 v5, v23, v24 offset0:24 offset1:90
	ds_write2_b32 v5, v25, v26 offset0:156 offset1:222
	v_add_u32_e32 v5, 0x1000, v2
	ds_write2_b32 v5, v27, v28 offset0:32 offset1:98
	ds_write2_b32 v5, v29, v30 offset0:164 offset1:230
	v_add_u32_e32 v5, 0x1400, v2
	ds_write2_b32 v5, v31, v32 offset0:40 offset1:106
	ds_write2_b32 v5, v33, v34 offset0:172 offset1:238
	v_add_u32_e32 v5, 0x1800, v2
	v_add_u32_e32 v2, 0x1c00, v2
	ds_write2_b32 v5, v35, v36 offset0:48 offset1:114
	ds_write2_b32 v5, v37, v38 offset0:180 offset1:246
	ds_write2_b32 v2, v39, v40 offset0:56 offset1:122
	ds_write2_b32 v2, v8, v4 offset0:188 offset1:254
	v_lshlrev_b32_e32 v2, 3, v7
	v_and_b32_e32 v2, 56, v2
	v_ashrrev_i32_e32 v28, 3, v7
	v_mul_u32_u24_e32 v7, 0x84, v2
	v_lshlrev_b32_e32 v2, 1, v2
	s_waitcnt lgkmcnt(0)
	v_lshl_add_u64 v[4:5], s[4:5], 0, v[2:3]
	v_lshlrev_b32_e32 v2, 2, v28
	v_add3_u32 v2, s3, v7, v2
	ds_read2_b32 v[12:13], v2 offset0:33 offset1:41
	ds_read2_b32 v[14:15], v2 offset1:8
	ds_read2_b32 v[16:17], v2 offset0:66 offset1:74
	ds_read2_b32 v[18:19], v2 offset0:99 offset1:107
	ds_read2_b32 v[20:21], v2 offset0:132 offset1:140
	ds_read2_b32 v[22:23], v2 offset0:165 offset1:173
	ds_read2_b32 v[24:25], v2 offset0:198 offset1:206
	ds_read2_b32 v[26:27], v2 offset0:231 offset1:239
	s_waitcnt lgkmcnt(7)
	v_bfe_u32 v8, v12, 16, 1
	s_waitcnt lgkmcnt(6)
	v_bfe_u32 v7, v14, 16, 1
	v_add3_u32 v7, v14, v7, s48
	v_lshrrev_b32_e32 v7, 16, v7
	v_add3_u32 v8, v12, v8, s48
	v_and_or_b32 v8, v8, s49, v7
	s_waitcnt lgkmcnt(5)
	v_bfe_u32 v7, v16, 16, 1
	v_add3_u32 v7, v16, v7, s48
	s_waitcnt lgkmcnt(4)
	v_bfe_u32 v9, v18, 16, 1
	v_lshrrev_b32_e32 v7, 16, v7
	v_add3_u32 v9, v18, v9, s48
	v_and_or_b32 v9, v9, s49, v7
	s_waitcnt lgkmcnt(3)
	v_bfe_u32 v7, v20, 16, 1
	v_add3_u32 v7, v20, v7, s48
	s_waitcnt lgkmcnt(2)
	v_bfe_u32 v10, v22, 16, 1
	v_lshrrev_b32_e32 v7, 16, v7
	v_add3_u32 v10, v22, v10, s48
	v_and_or_b32 v10, v10, s49, v7
	s_waitcnt lgkmcnt(1)
	v_bfe_u32 v7, v24, 16, 1
	v_add3_u32 v7, v24, v7, s48
	s_waitcnt lgkmcnt(0)
	v_bfe_u32 v11, v26, 16, 1
	v_lshrrev_b32_e32 v7, 16, v7
	v_add3_u32 v11, v26, v11, s48
	v_and_or_b32 v11, v11, s49, v7
	v_subrev_u32_e32 v7, s0, v28
	v_add_u32_e32 v12, s12, v7
	v_subrev_u32_e32 v28, 24, v12
	v_ashrrev_i32_e32 v29, 31, v28
	v_lshlrev_b64 v[28:29], 13, v[28:29]
	v_lshl_add_u64 v[28:29], v[4:5], 0, v[28:29]
	v_bfe_u32 v7, v15, 16, 1
	global_store_dwordx4 v[28:29], v[8:11], off
	v_add3_u32 v7, v15, v7, s48
	v_lshrrev_b32_e32 v7, 16, v7
	v_bfe_u32 v8, v13, 16, 1
	v_add3_u32 v8, v13, v8, s48
	v_and_or_b32 v8, v8, s49, v7
	v_bfe_u32 v7, v17, 16, 1
	v_add3_u32 v7, v17, v7, s48
	v_bfe_u32 v9, v19, 16, 1
	v_lshrrev_b32_e32 v7, 16, v7
	v_add3_u32 v9, v19, v9, s48
	v_and_or_b32 v9, v9, s49, v7
	v_bfe_u32 v7, v21, 16, 1
	v_add3_u32 v7, v21, v7, s48
	v_bfe_u32 v10, v23, 16, 1
	v_lshrrev_b32_e32 v7, 16, v7
	v_add3_u32 v10, v23, v10, s48
	v_and_or_b32 v10, v10, s49, v7
	v_bfe_u32 v7, v25, 16, 1
	v_add_u32_e32 v14, -16, v12
	v_add3_u32 v7, v25, v7, s48
	v_bfe_u32 v11, v27, 16, 1
	v_ashrrev_i32_e32 v15, 31, v14
	v_lshrrev_b32_e32 v7, 16, v7
	v_add3_u32 v11, v27, v11, s48
	v_lshlrev_b64 v[14:15], 13, v[14:15]
	v_and_or_b32 v11, v11, s49, v7
	v_lshl_add_u64 v[14:15], v[4:5], 0, v[14:15]
	global_store_dwordx4 v[14:15], v[8:11], off
	ds_read2_b32 v[14:15], v2 offset0:49 offset1:57
	ds_read2_b32 v[16:17], v2 offset0:16 offset1:24
	ds_read2_b32 v[18:19], v2 offset0:82 offset1:90
	ds_read2_b32 v[20:21], v2 offset0:115 offset1:123
	ds_read2_b32 v[22:23], v2 offset0:148 offset1:156
	ds_read2_b32 v[24:25], v2 offset0:181 offset1:189
	ds_read2_b32 v[26:27], v2 offset0:214 offset1:222
	ds_read2_b32 v[28:29], v2 offset0:247 offset1:255
	s_waitcnt lgkmcnt(7)
	v_bfe_u32 v8, v14, 16, 1
	s_waitcnt lgkmcnt(6)
	v_bfe_u32 v7, v16, 16, 1
	v_add3_u32 v7, v16, v7, s48
	v_lshrrev_b32_e32 v7, 16, v7
	v_add3_u32 v8, v14, v8, s48
	v_and_or_b32 v8, v8, s49, v7
	s_waitcnt lgkmcnt(5)
	v_bfe_u32 v7, v18, 16, 1
	v_add3_u32 v7, v18, v7, s48
	s_waitcnt lgkmcnt(4)
	v_bfe_u32 v9, v20, 16, 1
	v_lshrrev_b32_e32 v7, 16, v7
	v_add3_u32 v9, v20, v9, s48
	v_and_or_b32 v9, v9, s49, v7
	s_waitcnt lgkmcnt(3)
	v_bfe_u32 v7, v22, 16, 1
	v_add3_u32 v7, v22, v7, s48
	s_waitcnt lgkmcnt(2)
	v_bfe_u32 v10, v24, 16, 1
	v_lshrrev_b32_e32 v7, 16, v7
	v_add3_u32 v10, v24, v10, s48
	s_waitcnt lgkmcnt(1)
	v_bfe_u32 v2, v26, 16, 1
	v_and_or_b32 v10, v10, s49, v7
	v_add3_u32 v2, v26, v2, s48
	s_waitcnt lgkmcnt(0)
	v_bfe_u32 v7, v28, 16, 1
	v_lshrrev_b32_e32 v2, 16, v2
	v_add3_u32 v7, v28, v7, s48
	v_add_u32_e32 v30, -8, v12
	v_and_or_b32 v11, v7, s49, v2
	v_ashrrev_i32_e32 v31, 31, v30
	v_bfe_u32 v2, v17, 16, 1
	v_lshlrev_b64 v[30:31], 13, v[30:31]
	v_add3_u32 v2, v17, v2, s48
	v_bfe_u32 v7, v15, 16, 1
	v_lshl_add_u64 v[30:31], v[4:5], 0, v[30:31]
	v_lshrrev_b32_e32 v2, 16, v2
	v_add3_u32 v7, v15, v7, s48
	global_store_dwordx4 v[30:31], v[8:11], off
	v_ashrrev_i32_e32 v13, 31, v12
	v_lshlrev_b64 v[12:13], 13, v[12:13]
	v_and_or_b32 v8, v7, s49, v2
	v_bfe_u32 v2, v19, 16, 1
	v_add3_u32 v2, v19, v2, s48
	v_bfe_u32 v7, v21, 16, 1
	v_lshrrev_b32_e32 v2, 16, v2
	v_add3_u32 v7, v21, v7, s48
	v_and_or_b32 v9, v7, s49, v2
	v_bfe_u32 v2, v23, 16, 1
	v_add3_u32 v2, v23, v2, s48
	v_bfe_u32 v7, v25, 16, 1
	v_lshrrev_b32_e32 v2, 16, v2
	v_add3_u32 v7, v25, v7, s48
	v_and_or_b32 v10, v7, s49, v2
	v_bfe_u32 v2, v27, 16, 1
	v_add3_u32 v2, v27, v2, s48
	v_bfe_u32 v7, v29, 16, 1
	v_lshrrev_b32_e32 v2, 16, v2
	v_add3_u32 v7, v29, v7, s48
	v_and_or_b32 v11, v7, s49, v2
	v_lshl_add_u64 v[4:5], v[4:5], 0, v[12:13]
	global_store_dwordx4 v[4:5], v[8:11], off
	s_waitcnt lgkmcnt(0)
	s_branch .LBB0_610

;     ...
;     const int kb = item / nblk, nb = item % nblk, k0 = 64 * kb, n0 = 32 * nb;
;     { float wv[32];
;       const float* wp = W + (size_t)(k0 + (lane >> 5)) * ldw + n0 + (lane & 31);
; #pragma unroll
;       for (int i = 0; i < 32; ++i) wv[i] = wp[(size_t)(2 * i) * ldw];
; #pragma unroll
;       for (int i = 0; i < 32; ++i) scr[(2 * i + (lane >> 5)) * 33 + (lane & 31)] = wv[i]; }
; __device__ __forceinline__ void transpose_late(const Args& a, Frame& F, LAS float* scr, int r) {
;     ...
;     if (r < IT_PU) { p0_transpose_item(a.in[I_WPU], D, DPLE, WPU, 0, D / 32, scr, r, F.lane); return; } r -= IT_PU;
.LBB0_625:
	s_andn2_b64 vcc, exec, s[4:5]
	s_cbranch_vccnz .LBB0_627
	v_mov_b32_e32 v7, v6
	s_and_b32 s5, s81, 0xc0
	v_ashrrev_i32_e32 v10, 5, v7
	v_add_u32_e32 v4, s5, v10
	v_ashrrev_i32_e32 v5, 31, v4
	v_readlane_b32 s24, v245, 0
	s_and_b32 s4, s21, 0x7e0
	v_lshlrev_b64 v[4:5], 13, v[4:5]
	v_readlane_b32 s30, v245, 6
	v_readlane_b32 s31, v245, 7
	s_lshl_b32 s0, s4, 2
	v_lshlrev_b32_e32 v2, 2, v7
	v_lshl_add_u64 v[4:5], s[30:31], 0, v[4:5]
	v_lshl_add_u64 v[4:5], v[4:5], 0, s[0:1]
	v_and_b32_e32 v2, 0x7c, v2
	v_lshl_add_u64 v[4:5], v[4:5], 0, v[2:3]
	v_add_co_u32_e32 v8, vcc, s36, v4
	global_load_dword v11, v[4:5], off nt
	s_nop 0
	v_addc_co_u32_e32 v9, vcc, 0, v5, vcc
	global_load_dword v12, v[8:9], off nt
	v_add_co_u32_e32 v8, vcc, s37, v4
	s_lshl_b32 s0, s5, 1
	s_nop 0
	v_addc_co_u32_e32 v9, vcc, 0, v5, vcc
	global_load_dword v13, v[8:9], off nt
	v_add_co_u32_e32 v8, vcc, s82, v4
	v_readlane_b32 s25, v245, 1
	s_nop 0
	v_addc_co_u32_e32 v9, vcc, 0, v5, vcc
	global_load_dword v14, v[8:9], off nt
	v_add_co_u32_e32 v8, vcc, s83, v4
	s_add_u32 s24, s16, s0
	s_nop 0
	v_addc_co_u32_e32 v9, vcc, 0, v5, vcc
	global_load_dword v15, v[8:9], off nt
	v_add_co_u32_e32 v8, vcc, s84, v4
	s_addc_u32 s25, s17, 0
	s_nop 0
	v_addc_co_u32_e32 v9, vcc, 0, v5, vcc
	global_load_dword v16, v[8:9], off nt
	v_add_co_u32_e32 v8, vcc, s85, v4
	v_readlane_b32 s26, v245, 2
	s_nop 0
	v_addc_co_u32_e32 v9, vcc, 0, v5, vcc
	global_load_dword v17, v[8:9], off nt
	v_add_co_u32_e32 v8, vcc, s56, v4
	v_readlane_b32 s27, v245, 3
	s_nop 0
	v_addc_co_u32_e32 v9, vcc, 0, v5, vcc
	global_load_dword v18, v[8:9], off nt
	v_add_co_u32_e32 v8, vcc, s57, v4
	v_readlane_b32 s28, v245, 4
	s_nop 0
	v_addc_co_u32_e32 v9, vcc, 0, v5, vcc
	global_load_dword v19, v[8:9], off nt
	v_add_co_u32_e32 v8, vcc, s58, v4
	v_readlane_b32 s29, v245, 5
	s_nop 0
	v_addc_co_u32_e32 v9, vcc, 0, v5, vcc
	global_load_dword v20, v[8:9], off nt
	v_add_co_u32_e32 v8, vcc, s59, v4
	s_nop 1
	v_addc_co_u32_e32 v9, vcc, 0, v5, vcc
	global_load_dword v21, v[8:9], off nt
	v_add_co_u32_e32 v8, vcc, s22, v4
	s_nop 1
	v_addc_co_u32_e32 v9, vcc, 0, v5, vcc
	global_load_dword v22, v[8:9], off nt
	v_add_co_u32_e32 v8, vcc, s60, v4
	s_nop 1
	v_addc_co_u32_e32 v9, vcc, 0, v5, vcc
	global_load_dword v23, v[8:9], off nt
	v_add_co_u32_e32 v8, vcc, s61, v4
	s_nop 1
	v_addc_co_u32_e32 v9, vcc, 0, v5, vcc
	global_load_dword v24, v[8:9], off nt
	v_add_co_u32_e32 v8, vcc, s62, v4
	s_nop 1
	v_addc_co_u32_e32 v9, vcc, 0, v5, vcc
	global_load_dword v25, v[8:9], off nt
	v_add_co_u32_e32 v8, vcc, s63, v4
	s_nop 1
	v_addc_co_u32_e32 v9, vcc, 0, v5, vcc
	global_load_dword v26, v[8:9], off nt
	v_add_co_u32_e32 v8, vcc, s64, v4
	s_nop 1
	v_addc_co_u32_e32 v9, vcc, 0, v5, vcc
	global_load_dword v27, v[8:9], off nt
	v_add_co_u32_e32 v8, vcc, s65, v4
	s_nop 1
	v_addc_co_u32_e32 v9, vcc, 0, v5, vcc
	global_load_dword v28, v[8:9], off nt
	v_add_co_u32_e32 v8, vcc, s66, v4
	s_nop 1
	v_addc_co_u32_e32 v9, vcc, 0, v5, vcc
	global_load_dword v29, v[8:9], off nt
	v_add_co_u32_e32 v8, vcc, s67, v4
	s_nop 1
	v_addc_co_u32_e32 v9, vcc, 0, v5, vcc
	global_load_dword v30, v[8:9], off nt
	v_add_co_u32_e32 v8, vcc, s68, v4
	s_nop 1
	v_addc_co_u32_e32 v9, vcc, 0, v5, vcc
	global_load_dword v31, v[8:9], off nt
	v_add_co_u32_e32 v8, vcc, s69, v4
	s_nop 1
	v_addc_co_u32_e32 v9, vcc, 0, v5, vcc
	global_load_dword v32, v[8:9], off nt
	v_add_co_u32_e32 v8, vcc, s23, v4
	s_nop 1
	v_addc_co_u32_e32 v9, vcc, 0, v5, vcc
	global_load_dword v33, v[8:9], off nt
	v_add_co_u32_e32 v8, vcc, s72, v4
	s_nop 1
	v_addc_co_u32_e32 v9, vcc, 0, v5, vcc
	global_load_dword v34, v[8:9], off nt
	v_add_co_u32_e32 v8, vcc, s73, v4
	s_nop 1
	v_addc_co_u32_e32 v9, vcc, 0, v5, vcc
	global_load_dword v35, v[8:9], off nt
	v_add_co_u32_e32 v8, vcc, s74, v4
	s_nop 1
	v_addc_co_u32_e32 v9, vcc, 0, v5, vcc
	global_load_dword v36, v[8:9], off nt
	v_add_co_u32_e32 v8, vcc, s75, v4
	s_nop 1
	v_addc_co_u32_e32 v9, vcc, 0, v5, vcc
	global_load_dword v37, v[8:9], off nt
	v_add_co_u32_e32 v8, vcc, s76, v4
	s_nop 1
	v_addc_co_u32_e32 v9, vcc, 0, v5, vcc
	global_load_dword v38, v[8:9], off nt
	v_add_co_u32_e32 v8, vcc, s77, v4
	s_nop 1
	v_addc_co_u32_e32 v9, vcc, 0, v5, vcc
	global_load_dword v39, v[8:9], off nt
	v_add_co_u32_e32 v8, vcc, s78, v4
	s_nop 1
	v_addc_co_u32_e32 v9, vcc, 0, v5, vcc
	global_load_dword v40, v[8:9], off nt
	v_add_co_u32_e32 v8, vcc, s79, v4
	s_nop 1
	v_addc_co_u32_e32 v9, vcc, 0, v5, vcc
	v_add_co_u32_e32 v4, vcc, s80, v4
	global_load_dword v8, v[8:9], off nt
	s_nop 0
	v_addc_co_u32_e32 v5, vcc, 0, v5, vcc
	global_load_dword v4, v[4:5], off nt
	v_mul_lo_u32 v5, v10, s33
	v_add3_u32 v2, s3, v2, v5
	v_add_u32_e32 v5, 0x400, v2
	s_waitcnt vmcnt(0)
	ds_write2_b32 v2, v11, v12 offset1:66
	ds_write2_b32 v2, v13, v14 offset0:132 offset1:198
	ds_write2_b32 v5, v15, v16 offset0:8 offset1:74
	ds_write2_b32 v5, v17, v18 offset0:140 offset1:206
	v_add_u32_e32 v5, 0x800, v2
	ds_write2_b32 v5, v19, v20 offset0:16 offset1:82
	ds_write2_b32 v5, v21, v22 offset0:148 offset1:214
	v_add_u32_e32 v5, 0xc00, v2
	ds_write2_b32 v5, v23, v24 offset0:24 offset1:90
	ds_write2_b32 v5, v25, v26 offset0:156 offset1:222
	v_add_u32_e32 v5, 0x1000, v2
	ds_write2_b32 v5, v27, v28 offset0:32 offset1:98
	ds_write2_b32 v5, v29, v30 offset0:164 offset1:230
	v_add_u32_e32 v5, 0x1400, v2
	ds_write2_b32 v5, v31, v32 offset0:40 offset1:106
	ds_write2_b32 v5, v33, v34 offset0:172 offset1:238
	v_add_u32_e32 v5, 0x1800, v2
	v_add_u32_e32 v2, 0x1c00, v2
	ds_write2_b32 v5, v35, v36 offset0:48 offset1:114
	ds_write2_b32 v5, v37, v38 offset0:180 offset1:246
	ds_write2_b32 v2, v39, v40 offset0:56 offset1:122
	ds_write2_b32 v2, v8, v4 offset0:188 offset1:254
	v_lshlrev_b32_e32 v2, 3, v7
	v_and_b32_e32 v2, 56, v2
	v_ashrrev_i32_e32 v28, 3, v7
	v_mul_u32_u24_e32 v7, 0x84, v2
	v_lshlrev_b32_e32 v2, 1, v2
	s_waitcnt lgkmcnt(0)
; #define GAS __attribute__((address_space(1)))
; #define LAS __attribute__((address_space(3)))
; #define LDS_WAIT() asm volatile("s_waitcnt lgkmcnt(0)" ::: "memory")
; __device__ __forceinline__ unsigned pk2(float lo, float hi) { return f2bf(lo) | (f2bf(hi) << 16); }
;     ...
;     const int c = lane & 7;
;     const int r0 = (mode == 0) ? n0 : (256 * (n0 >> 7) + (n0 & 127) + (mode == 2 ? 128 : 0));
; #pragma unroll
;     for (int j = 0; j < 4; ++j) { const int n = (lane >> 3) + 8 * j; const LAS float* s = scr + (8 * c) * 33 + n;
;         v4u o; o.x = pk2(s[0 * 33], s[1 * 33]); o.y = pk2(s[2 * 33], s[3 * 33]); o.z = pk2(s[4 * 33], s[5 * 33]); o.w = pk2(s[6 * 33], s[7 * 33]);
;         *(GAS v4u*)(WT + (size_t)(r0 + n) * ldt + k0 + 8 * c) = o; }
;     LDS_WAIT(); asm volatile("" ::: "memory");
	v_lshl_add_u64 v[4:5], s[24:25], 0, v[2:3]
	v_lshlrev_b32_e32 v2, 2, v28
	v_add3_u32 v2, s3, v7, v2
	ds_read2_b32 v[12:13], v2 offset0:33 offset1:41
	ds_read2_b32 v[14:15], v2 offset1:8
	ds_read2_b32 v[16:17], v2 offset0:66 offset1:74
	ds_read2_b32 v[18:19], v2 offset0:99 offset1:107
	ds_read2_b32 v[20:21], v2 offset0:132 offset1:140
	ds_read2_b32 v[22:23], v2 offset0:165 offset1:173
	ds_read2_b32 v[24:25], v2 offset0:198 offset1:206
	ds_read2_b32 v[26:27], v2 offset0:231 offset1:239
	s_waitcnt lgkmcnt(7)
	v_bfe_u32 v8, v12, 16, 1
	s_waitcnt lgkmcnt(6)
	v_bfe_u32 v7, v14, 16, 1
	v_add3_u32 v7, v14, v7, s38
	v_lshrrev_b32_e32 v7, 16, v7
	v_add3_u32 v8, v12, v8, s38
	v_and_or_b32 v8, v8, s39, v7
	s_waitcnt lgkmcnt(5)
	v_bfe_u32 v7, v16, 16, 1
	v_add3_u32 v7, v16, v7, s38
	s_waitcnt lgkmcnt(4)
	v_bfe_u32 v9, v18, 16, 1
	v_lshrrev_b32_e32 v7, 16, v7
	v_add3_u32 v9, v18, v9, s38
	v_and_or_b32 v9, v9, s39, v7
	s_waitcnt lgkmcnt(3)
	v_bfe_u32 v7, v20, 16, 1
	v_add3_u32 v7, v20, v7, s38
	s_waitcnt lgkmcnt(2)
	v_bfe_u32 v10, v22, 16, 1
	v_lshrrev_b32_e32 v7, 16, v7
	v_add3_u32 v10, v22, v10, s38
	v_and_or_b32 v10, v10, s39, v7
	s_waitcnt lgkmcnt(1)
	v_bfe_u32 v7, v24, 16, 1
	v_add_u32_e32 v28, s4, v28
	v_add3_u32 v7, v24, v7, s38
	s_waitcnt lgkmcnt(0)
	v_bfe_u32 v11, v26, 16, 1
	v_ashrrev_i32_e32 v29, 31, v28
	v_lshrrev_b32_e32 v7, 16, v7
	v_add3_u32 v11, v26, v11, s38
	v_lshlrev_b64 v[30:31], 9, v[28:29]
	v_and_or_b32 v11, v11, s39, v7
	v_lshl_add_u64 v[30:31], v[4:5], 0, v[30:31]
	v_bfe_u32 v7, v15, 16, 1
	global_store_dwordx4 v[30:31], v[8:11], off
	v_add3_u32 v7, v15, v7, s38
	v_lshrrev_b32_e32 v7, 16, v7
	v_bfe_u32 v8, v13, 16, 1
	v_add3_u32 v8, v13, v8, s38
	v_and_or_b32 v8, v8, s39, v7
	v_bfe_u32 v7, v17, 16, 1
	v_add3_u32 v7, v17, v7, s38
	v_bfe_u32 v9, v19, 16, 1
	v_lshrrev_b32_e32 v7, 16, v7
	v_add3_u32 v9, v19, v9, s38
	v_and_or_b32 v9, v9, s39, v7
	v_bfe_u32 v7, v21, 16, 1
	v_add3_u32 v7, v21, v7, s38
	v_bfe_u32 v10, v23, 16, 1
	v_lshrrev_b32_e32 v7, 16, v7
	v_add3_u32 v10, v23, v10, s38
	v_and_or_b32 v10, v10, s39, v7
	v_bfe_u32 v7, v25, 16, 1
	v_add_u32_e32 v12, 8, v28
	v_add3_u32 v7, v25, v7, s38
	v_bfe_u32 v11, v27, 16, 1
	v_ashrrev_i32_e32 v13, 31, v12
	v_lshrrev_b32_e32 v7, 16, v7
	v_add3_u32 v11, v27, v11, s38
	v_lshlrev_b64 v[12:13], 9, v[12:13]
	v_and_or_b32 v11, v11, s39, v7
	v_lshl_add_u64 v[12:13], v[4:5], 0, v[12:13]
	global_store_dwordx4 v[12:13], v[8:11], off
	ds_read2_b32 v[12:13], v2 offset0:49 offset1:57
	ds_read2_b32 v[14:15], v2 offset0:16 offset1:24
	ds_read2_b32 v[16:17], v2 offset0:82 offset1:90
	ds_read2_b32 v[18:19], v2 offset0:115 offset1:123
	ds_read2_b32 v[20:21], v2 offset0:148 offset1:156
	ds_read2_b32 v[22:23], v2 offset0:181 offset1:189
	ds_read2_b32 v[24:25], v2 offset0:214 offset1:222
	ds_read2_b32 v[26:27], v2 offset0:247 offset1:255
	s_waitcnt lgkmcnt(7)
	v_bfe_u32 v8, v12, 16, 1
	s_waitcnt lgkmcnt(6)
	v_bfe_u32 v7, v14, 16, 1
	v_add3_u32 v7, v14, v7, s38
	v_lshrrev_b32_e32 v7, 16, v7
	v_add3_u32 v8, v12, v8, s38
	v_and_or_b32 v8, v8, s39, v7
	s_waitcnt lgkmcnt(5)
	v_bfe_u32 v7, v16, 16, 1
	v_add3_u32 v7, v16, v7, s38
	s_waitcnt lgkmcnt(4)
	v_bfe_u32 v9, v18, 16, 1
	v_lshrrev_b32_e32 v7, 16, v7
	v_add3_u32 v9, v18, v9, s38
	v_and_or_b32 v9, v9, s39, v7
	s_waitcnt lgkmcnt(3)
	v_bfe_u32 v7, v20, 16, 1
	v_add3_u32 v7, v20, v7, s38
	s_waitcnt lgkmcnt(2)
	v_bfe_u32 v10, v22, 16, 1
	v_lshrrev_b32_e32 v7, 16, v7
	v_add3_u32 v10, v22, v10, s38
	s_waitcnt lgkmcnt(1)
	v_bfe_u32 v2, v24, 16, 1
	v_and_or_b32 v10, v10, s39, v7
	v_add3_u32 v2, v24, v2, s38
	s_waitcnt lgkmcnt(0)
	v_bfe_u32 v7, v26, 16, 1
	v_lshrrev_b32_e32 v2, 16, v2
	v_add3_u32 v7, v26, v7, s38
	v_add_u32_e32 v30, 16, v28
	v_and_or_b32 v11, v7, s39, v2
	v_ashrrev_i32_e32 v31, 31, v30
	v_bfe_u32 v2, v15, 16, 1
	v_lshlrev_b64 v[30:31], 9, v[30:31]
	v_add3_u32 v2, v15, v2, s38
	v_bfe_u32 v7, v13, 16, 1
	v_lshl_add_u64 v[30:31], v[4:5], 0, v[30:31]
	v_lshrrev_b32_e32 v2, 16, v2
	v_add3_u32 v7, v13, v7, s38
	global_store_dwordx4 v[30:31], v[8:11], off
	v_add_u32_e32 v12, 24, v28
	v_ashrrev_i32_e32 v13, 31, v12
	v_and_or_b32 v8, v7, s39, v2
	v_bfe_u32 v2, v17, 16, 1
	v_add3_u32 v2, v17, v2, s38
	v_bfe_u32 v7, v19, 16, 1
	v_lshrrev_b32_e32 v2, 16, v2
	v_add3_u32 v7, v19, v7, s38
	v_and_or_b32 v9, v7, s39, v2
	v_bfe_u32 v2, v21, 16, 1
	v_add3_u32 v2, v21, v2, s38
	v_bfe_u32 v7, v23, 16, 1
	v_lshrrev_b32_e32 v2, 16, v2
	v_add3_u32 v7, v23, v7, s38
	v_and_or_b32 v10, v7, s39, v2
	v_bfe_u32 v2, v25, 16, 1
	v_add3_u32 v2, v25, v2, s38
	v_bfe_u32 v7, v27, 16, 1
	v_lshrrev_b32_e32 v2, 16, v2
	v_add3_u32 v7, v27, v7, s38
	v_lshlrev_b64 v[12:13], 9, v[12:13]
	v_and_or_b32 v11, v7, s39, v2
	v_lshl_add_u64 v[4:5], v[4:5], 0, v[12:13]
	global_store_dwordx4 v[4:5], v[8:11], off
	s_waitcnt lgkmcnt(0)

;     ...
;     const int kb = item / nblk, nb = item % nblk, k0 = 64 * kb, n0 = 32 * nb;
;     { float wv[32];
;       const float* wp = W + (size_t)(k0 + (lane >> 5)) * ldw + n0 + (lane & 31);
; #pragma unroll
;       for (int i = 0; i < 32; ++i) wv[i] = wp[(size_t)(2 * i) * ldw];
; #pragma unroll
;       for (int i = 0; i < 32; ++i) scr[(2 * i + (lane >> 5)) * 33 + (lane & 31)] = wv[i]; }
; __device__ __forceinline__ void transpose_late(const Args& a, Frame& F, LAS float* scr, int r) {
;     ...
;     if (r < IT_SQ) { p0_transpose_item(a.in[I_WPG], D, D, WPG, 0, D / 32, scr, r, F.lane); return; } r -= IT_SQ;
.LBB0_628:
	s_andn2_b64 vcc, exec, s[4:5]
	s_cbranch_vccnz .LBB0_630
	s_add_i32 s0, s20, 0xfffff800
	v_mov_b32_e32 v7, v6
	s_and_b32 s5, s0, 0xffc0
	v_ashrrev_i32_e32 v10, 5, v7
	v_add_u32_e32 v4, s5, v10
	v_ashrrev_i32_e32 v5, 31, v4
	v_readlane_b32 s24, v245, 0
	s_and_b32 s4, s21, 0x7e0
	v_lshlrev_b64 v[4:5], 13, v[4:5]
	v_readlane_b32 s28, v245, 4
	v_readlane_b32 s29, v245, 5
	s_lshl_b32 s0, s4, 2
	v_lshlrev_b32_e32 v2, 2, v7
	v_lshl_add_u64 v[4:5], s[28:29], 0, v[4:5]
	v_lshl_add_u64 v[4:5], v[4:5], 0, s[0:1]
	v_and_b32_e32 v2, 0x7c, v2
	v_lshl_add_u64 v[4:5], v[4:5], 0, v[2:3]
	v_add_co_u32_e32 v8, vcc, s36, v4
	global_load_dword v11, v[4:5], off nt
	s_nop 0
	v_addc_co_u32_e32 v9, vcc, 0, v5, vcc
	global_load_dword v12, v[8:9], off nt
	v_add_co_u32_e32 v8, vcc, s37, v4
	s_lshl_b32 s0, s5, 1
	s_nop 0
	v_addc_co_u32_e32 v9, vcc, 0, v5, vcc
	global_load_dword v13, v[8:9], off nt
	v_add_co_u32_e32 v8, vcc, s82, v4
	v_readlane_b32 s25, v245, 1
	s_nop 0
	v_addc_co_u32_e32 v9, vcc, 0, v5, vcc
	global_load_dword v14, v[8:9], off nt
	v_add_co_u32_e32 v8, vcc, s83, v4
	s_add_u32 s24, s14, s0
	s_nop 0
	v_addc_co_u32_e32 v9, vcc, 0, v5, vcc
	global_load_dword v15, v[8:9], off nt
	v_add_co_u32_e32 v8, vcc, s84, v4
	s_addc_u32 s25, s15, 0
	s_nop 0
	v_addc_co_u32_e32 v9, vcc, 0, v5, vcc
	global_load_dword v16, v[8:9], off nt
	v_add_co_u32_e32 v8, vcc, s85, v4
	v_readlane_b32 s26, v245, 2
	s_nop 0
	v_addc_co_u32_e32 v9, vcc, 0, v5, vcc
	global_load_dword v17, v[8:9], off nt
	v_add_co_u32_e32 v8, vcc, s56, v4
	v_readlane_b32 s27, v245, 3
	s_nop 0
	v_addc_co_u32_e32 v9, vcc, 0, v5, vcc
	global_load_dword v18, v[8:9], off nt
	v_add_co_u32_e32 v8, vcc, s57, v4
	v_readlane_b32 s30, v245, 6
	s_nop 0
	v_addc_co_u32_e32 v9, vcc, 0, v5, vcc
	global_load_dword v19, v[8:9], off nt
	v_add_co_u32_e32 v8, vcc, s58, v4
	v_readlane_b32 s31, v245, 7
	s_nop 0
	v_addc_co_u32_e32 v9, vcc, 0, v5, vcc
	global_load_dword v20, v[8:9], off nt
	v_add_co_u32_e32 v8, vcc, s59, v4
	s_nop 1
	v_addc_co_u32_e32 v9, vcc, 0, v5, vcc
	global_load_dword v21, v[8:9], off nt
	v_add_co_u32_e32 v8, vcc, s22, v4
	s_nop 1
	v_addc_co_u32_e32 v9, vcc, 0, v5, vcc
	global_load_dword v22, v[8:9], off nt
	v_add_co_u32_e32 v8, vcc, s60, v4
	s_nop 1
	v_addc_co_u32_e32 v9, vcc, 0, v5, vcc
	global_load_dword v23, v[8:9], off nt
	v_add_co_u32_e32 v8, vcc, s61, v4
	s_nop 1
	v_addc_co_u32_e32 v9, vcc, 0, v5, vcc
	global_load_dword v24, v[8:9], off nt
	v_add_co_u32_e32 v8, vcc, s62, v4
	s_nop 1
	v_addc_co_u32_e32 v9, vcc, 0, v5, vcc
	global_load_dword v25, v[8:9], off nt
	v_add_co_u32_e32 v8, vcc, s63, v4
	s_nop 1
	v_addc_co_u32_e32 v9, vcc, 0, v5, vcc
	global_load_dword v26, v[8:9], off nt
	v_add_co_u32_e32 v8, vcc, s64, v4
	s_nop 1
	v_addc_co_u32_e32 v9, vcc, 0, v5, vcc
	global_load_dword v27, v[8:9], off nt
	v_add_co_u32_e32 v8, vcc, s65, v4
	s_nop 1
	v_addc_co_u32_e32 v9, vcc, 0, v5, vcc
	global_load_dword v28, v[8:9], off nt
	v_add_co_u32_e32 v8, vcc, s66, v4
	s_nop 1
	v_addc_co_u32_e32 v9, vcc, 0, v5, vcc
	global_load_dword v29, v[8:9], off nt
	v_add_co_u32_e32 v8, vcc, s67, v4
	s_nop 1
	v_addc_co_u32_e32 v9, vcc, 0, v5, vcc
	global_load_dword v30, v[8:9], off nt
	v_add_co_u32_e32 v8, vcc, s68, v4
	s_nop 1
	v_addc_co_u32_e32 v9, vcc, 0, v5, vcc
	global_load_dword v31, v[8:9], off nt
	v_add_co_u32_e32 v8, vcc, s69, v4
	s_nop 1
	v_addc_co_u32_e32 v9, vcc, 0, v5, vcc
	global_load_dword v32, v[8:9], off nt
	v_add_co_u32_e32 v8, vcc, s23, v4
	s_nop 1
	v_addc_co_u32_e32 v9, vcc, 0, v5, vcc
	global_load_dword v33, v[8:9], off nt
	v_add_co_u32_e32 v8, vcc, s72, v4
	s_nop 1
	v_addc_co_u32_e32 v9, vcc, 0, v5, vcc
	global_load_dword v34, v[8:9], off nt
	v_add_co_u32_e32 v8, vcc, s73, v4
	s_nop 1
	v_addc_co_u32_e32 v9, vcc, 0, v5, vcc
	global_load_dword v35, v[8:9], off nt
	v_add_co_u32_e32 v8, vcc, s74, v4
	s_nop 1
	v_addc_co_u32_e32 v9, vcc, 0, v5, vcc
	global_load_dword v36, v[8:9], off nt
	v_add_co_u32_e32 v8, vcc, s75, v4
	s_nop 1
	v_addc_co_u32_e32 v9, vcc, 0, v5, vcc
	global_load_dword v37, v[8:9], off nt
	v_add_co_u32_e32 v8, vcc, s76, v4
	s_nop 1
	v_addc_co_u32_e32 v9, vcc, 0, v5, vcc
	global_load_dword v38, v[8:9], off nt
	v_add_co_u32_e32 v8, vcc, s77, v4
	s_nop 1
	v_addc_co_u32_e32 v9, vcc, 0, v5, vcc
	global_load_dword v39, v[8:9], off nt
	v_add_co_u32_e32 v8, vcc, s78, v4
	s_nop 1
	v_addc_co_u32_e32 v9, vcc, 0, v5, vcc
	global_load_dword v40, v[8:9], off nt
	v_add_co_u32_e32 v8, vcc, s79, v4
	s_nop 1
	v_addc_co_u32_e32 v9, vcc, 0, v5, vcc
	v_add_co_u32_e32 v4, vcc, s80, v4
	global_load_dword v8, v[8:9], off nt
	s_nop 0
	v_addc_co_u32_e32 v5, vcc, 0, v5, vcc
	global_load_dword v4, v[4:5], off nt
	v_mul_lo_u32 v5, v10, s33
	v_add3_u32 v2, s3, v2, v5
	v_add_u32_e32 v5, 0x400, v2
	s_waitcnt vmcnt(0)
	ds_write2_b32 v2, v11, v12 offset1:66
	ds_write2_b32 v2, v13, v14 offset0:132 offset1:198
	ds_write2_b32 v5, v15, v16 offset0:8 offset1:74
	ds_write2_b32 v5, v17, v18 offset0:140 offset1:206
	v_add_u32_e32 v5, 0x800, v2
	ds_write2_b32 v5, v19, v20 offset0:16 offset1:82
	ds_write2_b32 v5, v21, v22 offset0:148 offset1:214
	v_add_u32_e32 v5, 0xc00, v2
	ds_write2_b32 v5, v23, v24 offset0:24 offset1:90
	ds_write2_b32 v5, v25, v26 offset0:156 offset1:222
	v_add_u32_e32 v5, 0x1000, v2
	ds_write2_b32 v5, v27, v28 offset0:32 offset1:98
	ds_write2_b32 v5, v29, v30 offset0:164 offset1:230
	v_add_u32_e32 v5, 0x1400, v2
	ds_write2_b32 v5, v31, v32 offset0:40 offset1:106
	ds_write2_b32 v5, v33, v34 offset0:172 offset1:238
	v_add_u32_e32 v5, 0x1800, v2
	v_add_u32_e32 v2, 0x1c00, v2
	ds_write2_b32 v5, v35, v36 offset0:48 offset1:114
	ds_write2_b32 v5, v37, v38 offset0:180 offset1:246
	ds_write2_b32 v2, v39, v40 offset0:56 offset1:122
	ds_write2_b32 v2, v8, v4 offset0:188 offset1:254
	v_lshlrev_b32_e32 v2, 3, v7
	v_and_b32_e32 v2, 56, v2
	v_ashrrev_i32_e32 v28, 3, v7
	v_mul_u32_u24_e32 v7, 0x84, v2
	v_lshlrev_b32_e32 v2, 1, v2
	s_waitcnt lgkmcnt(0)
; #define GAS __attribute__((address_space(1)))
; #define LAS __attribute__((address_space(3)))
; #define LDS_WAIT() asm volatile("s_waitcnt lgkmcnt(0)" ::: "memory")
; __device__ __forceinline__ unsigned pk2(float lo, float hi) { return f2bf(lo) | (f2bf(hi) << 16); }
;     ...
;     const int c = lane & 7;
;     const int r0 = (mode == 0) ? n0 : (256 * (n0 >> 7) + (n0 & 127) + (mode == 2 ? 128 : 0));
; #pragma unroll
;     for (int j = 0; j < 4; ++j) { const int n = (lane >> 3) + 8 * j; const LAS float* s = scr + (8 * c) * 33 + n;
;         v4u o; o.x = pk2(s[0 * 33], s[1 * 33]); o.y = pk2(s[2 * 33], s[3 * 33]); o.z = pk2(s[4 * 33], s[5 * 33]); o.w = pk2(s[6 * 33], s[7 * 33]);
;         *(GAS v4u*)(WT + (size_t)(r0 + n) * ldt + k0 + 8 * c) = o; }
;     LDS_WAIT(); asm volatile("" ::: "memory");
	v_lshl_add_u64 v[4:5], s[24:25], 0, v[2:3]
	v_lshlrev_b32_e32 v2, 2, v28
	v_add3_u32 v2, s3, v7, v2
	ds_read2_b32 v[12:13], v2 offset0:33 offset1:41
	ds_read2_b32 v[14:15], v2 offset1:8
	ds_read2_b32 v[16:17], v2 offset0:66 offset1:74
	ds_read2_b32 v[18:19], v2 offset0:99 offset1:107
	ds_read2_b32 v[20:21], v2 offset0:132 offset1:140
	ds_read2_b32 v[22:23], v2 offset0:165 offset1:173
	ds_read2_b32 v[24:25], v2 offset0:198 offset1:206
	ds_read2_b32 v[26:27], v2 offset0:231 offset1:239
	s_waitcnt lgkmcnt(7)
	v_bfe_u32 v8, v12, 16, 1
	s_waitcnt lgkmcnt(6)
	v_bfe_u32 v7, v14, 16, 1
	v_add3_u32 v7, v14, v7, s38
	v_lshrrev_b32_e32 v7, 16, v7
	v_add3_u32 v8, v12, v8, s38
	v_and_or_b32 v8, v8, s39, v7
	s_waitcnt lgkmcnt(5)
	v_bfe_u32 v7, v16, 16, 1
	v_add3_u32 v7, v16, v7, s38
	s_waitcnt lgkmcnt(4)
	v_bfe_u32 v9, v18, 16, 1
	v_lshrrev_b32_e32 v7, 16, v7
	v_add3_u32 v9, v18, v9, s38
	v_and_or_b32 v9, v9, s39, v7
	s_waitcnt lgkmcnt(3)
	v_bfe_u32 v7, v20, 16, 1
	v_add3_u32 v7, v20, v7, s38
	s_waitcnt lgkmcnt(2)
	v_bfe_u32 v10, v22, 16, 1
	v_lshrrev_b32_e32 v7, 16, v7
	v_add3_u32 v10, v22, v10, s38
	v_and_or_b32 v10, v10, s39, v7
	s_waitcnt lgkmcnt(1)
	v_bfe_u32 v7, v24, 16, 1
	v_add_u32_e32 v28, s4, v28
	v_add3_u32 v7, v24, v7, s38
	s_waitcnt lgkmcnt(0)
	v_bfe_u32 v11, v26, 16, 1
	v_ashrrev_i32_e32 v29, 31, v28
	v_lshrrev_b32_e32 v7, 16, v7
	v_add3_u32 v11, v26, v11, s38
	v_lshlrev_b64 v[30:31], 12, v[28:29]
	v_and_or_b32 v11, v11, s39, v7
	v_lshl_add_u64 v[30:31], v[4:5], 0, v[30:31]
	v_bfe_u32 v7, v15, 16, 1
	global_store_dwordx4 v[30:31], v[8:11], off
	v_add3_u32 v7, v15, v7, s38
	v_lshrrev_b32_e32 v7, 16, v7
	v_bfe_u32 v8, v13, 16, 1
	v_add3_u32 v8, v13, v8, s38
	v_and_or_b32 v8, v8, s39, v7
	v_bfe_u32 v7, v17, 16, 1
	v_add3_u32 v7, v17, v7, s38
	v_bfe_u32 v9, v19, 16, 1
	v_lshrrev_b32_e32 v7, 16, v7
	v_add3_u32 v9, v19, v9, s38
	v_and_or_b32 v9, v9, s39, v7
	v_bfe_u32 v7, v21, 16, 1
	v_add3_u32 v7, v21, v7, s38
	v_bfe_u32 v10, v23, 16, 1
	v_lshrrev_b32_e32 v7, 16, v7
	v_add3_u32 v10, v23, v10, s38
	v_and_or_b32 v10, v10, s39, v7
	v_bfe_u32 v7, v25, 16, 1
	v_add_u32_e32 v12, 8, v28
	v_add3_u32 v7, v25, v7, s38
	v_bfe_u32 v11, v27, 16, 1
	v_ashrrev_i32_e32 v13, 31, v12
	v_lshrrev_b32_e32 v7, 16, v7
	v_add3_u32 v11, v27, v11, s38
	v_lshlrev_b64 v[12:13], 12, v[12:13]
	v_and_or_b32 v11, v11, s39, v7
	v_lshl_add_u64 v[12:13], v[4:5], 0, v[12:13]
	global_store_dwordx4 v[12:13], v[8:11], off
	ds_read2_b32 v[12:13], v2 offset0:49 offset1:57
	ds_read2_b32 v[14:15], v2 offset0:16 offset1:24
	ds_read2_b32 v[16:17], v2 offset0:82 offset1:90
	ds_read2_b32 v[18:19], v2 offset0:115 offset1:123
	ds_read2_b32 v[20:21], v2 offset0:148 offset1:156
	ds_read2_b32 v[22:23], v2 offset0:181 offset1:189
	ds_read2_b32 v[24:25], v2 offset0:214 offset1:222
	ds_read2_b32 v[26:27], v2 offset0:247 offset1:255
	s_waitcnt lgkmcnt(7)
	v_bfe_u32 v8, v12, 16, 1
	s_waitcnt lgkmcnt(6)
	v_bfe_u32 v7, v14, 16, 1
	v_add3_u32 v7, v14, v7, s38
	v_lshrrev_b32_e32 v7, 16, v7
	v_add3_u32 v8, v12, v8, s38
	v_and_or_b32 v8, v8, s39, v7
	s_waitcnt lgkmcnt(5)
	v_bfe_u32 v7, v16, 16, 1
	v_add3_u32 v7, v16, v7, s38
	s_waitcnt lgkmcnt(4)
	v_bfe_u32 v9, v18, 16, 1
	v_lshrrev_b32_e32 v7, 16, v7
	v_add3_u32 v9, v18, v9, s38
	v_and_or_b32 v9, v9, s39, v7
	s_waitcnt lgkmcnt(3)
	v_bfe_u32 v7, v20, 16, 1
	v_add3_u32 v7, v20, v7, s38
	s_waitcnt lgkmcnt(2)
	v_bfe_u32 v10, v22, 16, 1
	v_lshrrev_b32_e32 v7, 16, v7
	v_add3_u32 v10, v22, v10, s38
	s_waitcnt lgkmcnt(1)
	v_bfe_u32 v2, v24, 16, 1
	v_and_or_b32 v10, v10, s39, v7
	v_add3_u32 v2, v24, v2, s38
	s_waitcnt lgkmcnt(0)
	v_bfe_u32 v7, v26, 16, 1
	v_lshrrev_b32_e32 v2, 16, v2
	v_add3_u32 v7, v26, v7, s38
	v_add_u32_e32 v30, 16, v28
	v_and_or_b32 v11, v7, s39, v2
	v_ashrrev_i32_e32 v31, 31, v30
	v_bfe_u32 v2, v15, 16, 1
	v_lshlrev_b64 v[30:31], 12, v[30:31]
	v_add3_u32 v2, v15, v2, s38
	v_bfe_u32 v7, v13, 16, 1
	v_lshl_add_u64 v[30:31], v[4:5], 0, v[30:31]
	v_lshrrev_b32_e32 v2, 16, v2
	v_add3_u32 v7, v13, v7, s38
	global_store_dwordx4 v[30:31], v[8:11], off
	v_add_u32_e32 v12, 24, v28
	v_ashrrev_i32_e32 v13, 31, v12
	v_and_or_b32 v8, v7, s39, v2
	v_bfe_u32 v2, v17, 16, 1
	v_add3_u32 v2, v17, v2, s38
	v_bfe_u32 v7, v19, 16, 1
	v_lshrrev_b32_e32 v2, 16, v2
	v_add3_u32 v7, v19, v7, s38
	v_and_or_b32 v9, v7, s39, v2
	v_bfe_u32 v2, v21, 16, 1
	v_add3_u32 v2, v21, v2, s38
	v_bfe_u32 v7, v23, 16, 1
	v_lshrrev_b32_e32 v2, 16, v2
	v_add3_u32 v7, v23, v7, s38
	v_and_or_b32 v10, v7, s39, v2
	v_bfe_u32 v2, v25, 16, 1
	v_add3_u32 v2, v25, v2, s38
	v_bfe_u32 v7, v27, 16, 1
	v_lshrrev_b32_e32 v2, 16, v2
	v_add3_u32 v7, v27, v7, s38
	v_lshlrev_b64 v[12:13], 12, v[12:13]
	v_and_or_b32 v11, v7, s39, v2
	v_lshl_add_u64 v[4:5], v[4:5], 0, v[12:13]
	global_store_dwordx4 v[4:5], v[8:11], off
	s_waitcnt lgkmcnt(0)

;     ...
;     const int kb = item / nblk, nb = item % nblk, k0 = 64 * kb, n0 = 32 * nb;
;     { float wv[32];
;       const float* wp = W + (size_t)(k0 + (lane >> 5)) * ldw + n0 + (lane & 31);
; #pragma unroll
;       for (int i = 0; i < 32; ++i) wv[i] = wp[(size_t)(2 * i) * ldw];
; #pragma unroll
;       for (int i = 0; i < 32; ++i) scr[(2 * i + (lane >> 5)) * 33 + (lane & 31)] = wv[i]; }
; __device__ __forceinline__ void transpose_late(const Args& a, Frame& F, LAS float* scr, int r) {
;     ...
;     if (r < IT_SQ) { p0_transpose_item(a.in[I_WO], D, D, WO, 0, D / 32, scr, r, F.lane); return; } r -= IT_SQ;
.LBB0_631:
	s_andn2_b64 vcc, exec, s[4:5]
	s_cbranch_vccnz .LBB0_633
	v_mov_b32_e32 v7, v6
	s_and_b32 s5, s20, 0xffc0
	v_ashrrev_i32_e32 v10, 5, v7
	v_add_u32_e32 v4, s5, v10
	v_ashrrev_i32_e32 v5, 31, v4
	v_readlane_b32 s40, v244, 2
	s_and_b32 s4, s21, 0x7e0
	v_lshlrev_b64 v[4:5], 13, v[4:5]
	v_readlane_b32 s44, v244, 6
	v_readlane_b32 s45, v244, 7
	s_lshl_b32 s0, s4, 2
	v_lshlrev_b32_e32 v2, 2, v7
	v_lshl_add_u64 v[4:5], s[44:45], 0, v[4:5]
	v_lshl_add_u64 v[4:5], v[4:5], 0, s[0:1]
	v_and_b32_e32 v2, 0x7c, v2
	v_lshl_add_u64 v[4:5], v[4:5], 0, v[2:3]
	v_add_co_u32_e32 v8, vcc, s36, v4
	global_load_dword v11, v[4:5], off nt
	s_nop 0
	v_addc_co_u32_e32 v9, vcc, 0, v5, vcc
	global_load_dword v12, v[8:9], off nt
	v_add_co_u32_e32 v8, vcc, s37, v4
	s_lshl_b32 s0, s5, 1
	s_nop 0
	v_addc_co_u32_e32 v9, vcc, 0, v5, vcc
	global_load_dword v13, v[8:9], off nt
	v_add_co_u32_e32 v8, vcc, s82, v4
	s_add_u32 s24, s12, s0
	s_nop 0
	v_addc_co_u32_e32 v9, vcc, 0, v5, vcc
	global_load_dword v14, v[8:9], off nt
	v_add_co_u32_e32 v8, vcc, s83, v4
	s_addc_u32 s25, s13, 0
	s_nop 0
	v_addc_co_u32_e32 v9, vcc, 0, v5, vcc
	global_load_dword v15, v[8:9], off nt
	v_add_co_u32_e32 v8, vcc, s84, v4
	v_readlane_b32 s41, v244, 3
	s_nop 0
	v_addc_co_u32_e32 v9, vcc, 0, v5, vcc
	global_load_dword v16, v[8:9], off nt
	v_add_co_u32_e32 v8, vcc, s85, v4
	v_readlane_b32 s42, v244, 4
	s_nop 0
	v_addc_co_u32_e32 v9, vcc, 0, v5, vcc
	global_load_dword v17, v[8:9], off nt
	v_add_co_u32_e32 v8, vcc, s56, v4
	v_readlane_b32 s43, v244, 5
	s_nop 0
	v_addc_co_u32_e32 v9, vcc, 0, v5, vcc
	global_load_dword v18, v[8:9], off nt
	v_add_co_u32_e32 v8, vcc, s57, v4
	v_readlane_b32 s46, v244, 8
	s_nop 0
	v_addc_co_u32_e32 v9, vcc, 0, v5, vcc
	global_load_dword v19, v[8:9], off nt
	v_add_co_u32_e32 v8, vcc, s58, v4
	v_readlane_b32 s47, v244, 9
	s_nop 0
	v_addc_co_u32_e32 v9, vcc, 0, v5, vcc
	global_load_dword v20, v[8:9], off nt
	v_add_co_u32_e32 v8, vcc, s59, v4
	v_readlane_b32 s48, v244, 10
	s_nop 0
	v_addc_co_u32_e32 v9, vcc, 0, v5, vcc
	global_load_dword v21, v[8:9], off nt
	v_add_co_u32_e32 v8, vcc, s22, v4
	v_readlane_b32 s49, v244, 11
	s_nop 0
	v_addc_co_u32_e32 v9, vcc, 0, v5, vcc
	global_load_dword v22, v[8:9], off nt
	v_add_co_u32_e32 v8, vcc, s60, v4
	v_readlane_b32 s50, v244, 12
	s_nop 0
	v_addc_co_u32_e32 v9, vcc, 0, v5, vcc
	global_load_dword v23, v[8:9], off nt
	v_add_co_u32_e32 v8, vcc, s61, v4
	v_readlane_b32 s51, v244, 13
	s_nop 0
	v_addc_co_u32_e32 v9, vcc, 0, v5, vcc
	global_load_dword v24, v[8:9], off nt
	v_add_co_u32_e32 v8, vcc, s62, v4
	v_readlane_b32 s52, v244, 14
	s_nop 0
	v_addc_co_u32_e32 v9, vcc, 0, v5, vcc
	global_load_dword v25, v[8:9], off nt
	v_add_co_u32_e32 v8, vcc, s63, v4
	v_readlane_b32 s53, v244, 15
	s_nop 0
	v_addc_co_u32_e32 v9, vcc, 0, v5, vcc
	global_load_dword v26, v[8:9], off nt
	v_add_co_u32_e32 v8, vcc, s64, v4
	v_readlane_b32 s54, v244, 16
	s_nop 0
	v_addc_co_u32_e32 v9, vcc, 0, v5, vcc
	global_load_dword v27, v[8:9], off nt
	v_add_co_u32_e32 v8, vcc, s65, v4
	v_readlane_b32 s55, v244, 17
	s_nop 0
	v_addc_co_u32_e32 v9, vcc, 0, v5, vcc
	global_load_dword v28, v[8:9], off nt
	v_add_co_u32_e32 v8, vcc, s66, v4
	s_nop 1
	v_addc_co_u32_e32 v9, vcc, 0, v5, vcc
	global_load_dword v29, v[8:9], off nt
	v_add_co_u32_e32 v8, vcc, s67, v4
	s_nop 1
	v_addc_co_u32_e32 v9, vcc, 0, v5, vcc
	global_load_dword v30, v[8:9], off nt
	v_add_co_u32_e32 v8, vcc, s68, v4
	s_nop 1
	v_addc_co_u32_e32 v9, vcc, 0, v5, vcc
	global_load_dword v31, v[8:9], off nt
	v_add_co_u32_e32 v8, vcc, s69, v4
	s_nop 1
	v_addc_co_u32_e32 v9, vcc, 0, v5, vcc
	global_load_dword v32, v[8:9], off nt
	v_add_co_u32_e32 v8, vcc, s23, v4
	s_nop 1
	v_addc_co_u32_e32 v9, vcc, 0, v5, vcc
	global_load_dword v33, v[8:9], off nt
	v_add_co_u32_e32 v8, vcc, s72, v4
	s_nop 1
	v_addc_co_u32_e32 v9, vcc, 0, v5, vcc
	global_load_dword v34, v[8:9], off nt
	v_add_co_u32_e32 v8, vcc, s73, v4
	s_nop 1
	v_addc_co_u32_e32 v9, vcc, 0, v5, vcc
	global_load_dword v35, v[8:9], off nt
	v_add_co_u32_e32 v8, vcc, s74, v4
	s_nop 1
	v_addc_co_u32_e32 v9, vcc, 0, v5, vcc
	global_load_dword v36, v[8:9], off nt
	v_add_co_u32_e32 v8, vcc, s75, v4
	s_nop 1
	v_addc_co_u32_e32 v9, vcc, 0, v5, vcc
	global_load_dword v37, v[8:9], off nt
	v_add_co_u32_e32 v8, vcc, s76, v4
	s_nop 1
	v_addc_co_u32_e32 v9, vcc, 0, v5, vcc
	global_load_dword v38, v[8:9], off nt
	v_add_co_u32_e32 v8, vcc, s77, v4
	s_nop 1
	v_addc_co_u32_e32 v9, vcc, 0, v5, vcc
	global_load_dword v39, v[8:9], off nt
	v_add_co_u32_e32 v8, vcc, s78, v4
	s_nop 1
	v_addc_co_u32_e32 v9, vcc, 0, v5, vcc
	global_load_dword v40, v[8:9], off nt
	v_add_co_u32_e32 v8, vcc, s79, v4
	s_nop 1
	v_addc_co_u32_e32 v9, vcc, 0, v5, vcc
	v_add_co_u32_e32 v4, vcc, s80, v4
	global_load_dword v8, v[8:9], off nt
	s_nop 0
	v_addc_co_u32_e32 v5, vcc, 0, v5, vcc
	global_load_dword v4, v[4:5], off nt
	v_mul_lo_u32 v5, v10, s33
	v_add3_u32 v2, s3, v2, v5
	v_add_u32_e32 v5, 0x400, v2
	s_waitcnt vmcnt(0)
; #define GAS __attribute__((address_space(1)))
; #define LAS __attribute__((address_space(3)))
; #define LDS_WAIT() asm volatile("s_waitcnt lgkmcnt(0)" ::: "memory")
; __device__ __forceinline__ unsigned pk2(float lo, float hi) { return f2bf(lo) | (f2bf(hi) << 16); }
;     ...
;       for (int i = 0; i < 32; ++i) scr[(2 * i + (lane >> 5)) * 33 + (lane & 31)] = wv[i]; }
;     LDS_WAIT(); asm volatile("" ::: "memory");
;     const int c = lane & 7;
;     const int r0 = (mode == 0) ? n0 : (256 * (n0 >> 7) + (n0 & 127) + (mode == 2 ? 128 : 0));
; #pragma unroll
;     for (int j = 0; j < 4; ++j) { const int n = (lane >> 3) + 8 * j; const LAS float* s = scr + (8 * c) * 33 + n;
;         v4u o; o.x = pk2(s[0 * 33], s[1 * 33]); o.y = pk2(s[2 * 33], s[3 * 33]); o.z = pk2(s[4 * 33], s[5 * 33]); o.w = pk2(s[6 * 33], s[7 * 33]);
;         *(GAS v4u*)(WT + (size_t)(r0 + n) * ldt + k0 + 8 * c) = o; }
;     LDS_WAIT(); asm volatile("" ::: "memory");
	ds_write2_b32 v2, v11, v12 offset1:66
	ds_write2_b32 v2, v13, v14 offset0:132 offset1:198
	ds_write2_b32 v5, v15, v16 offset0:8 offset1:74
	ds_write2_b32 v5, v17, v18 offset0:140 offset1:206
	v_add_u32_e32 v5, 0x800, v2
	ds_write2_b32 v5, v19, v20 offset0:16 offset1:82
	ds_write2_b32 v5, v21, v22 offset0:148 offset1:214
	v_add_u32_e32 v5, 0xc00, v2
	ds_write2_b32 v5, v23, v24 offset0:24 offset1:90
	ds_write2_b32 v5, v25, v26 offset0:156 offset1:222
	v_add_u32_e32 v5, 0x1000, v2
	ds_write2_b32 v5, v27, v28 offset0:32 offset1:98
	ds_write2_b32 v5, v29, v30 offset0:164 offset1:230
	v_add_u32_e32 v5, 0x1400, v2
	ds_write2_b32 v5, v31, v32 offset0:40 offset1:106
	ds_write2_b32 v5, v33, v34 offset0:172 offset1:238
	v_add_u32_e32 v5, 0x1800, v2
	v_add_u32_e32 v2, 0x1c00, v2
	ds_write2_b32 v5, v35, v36 offset0:48 offset1:114
	ds_write2_b32 v5, v37, v38 offset0:180 offset1:246
	ds_write2_b32 v2, v39, v40 offset0:56 offset1:122
	ds_write2_b32 v2, v8, v4 offset0:188 offset1:254
	v_lshlrev_b32_e32 v2, 3, v7
	v_and_b32_e32 v2, 56, v2
	v_ashrrev_i32_e32 v28, 3, v7
	v_mul_u32_u24_e32 v7, 0x84, v2
	v_lshlrev_b32_e32 v2, 1, v2
	s_waitcnt lgkmcnt(0)
	v_lshl_add_u64 v[4:5], s[24:25], 0, v[2:3]
	v_lshlrev_b32_e32 v2, 2, v28
	v_add3_u32 v2, s3, v7, v2
	ds_read2_b32 v[12:13], v2 offset0:33 offset1:41
	ds_read2_b32 v[14:15], v2 offset1:8
	ds_read2_b32 v[16:17], v2 offset0:66 offset1:74
	ds_read2_b32 v[18:19], v2 offset0:99 offset1:107
	ds_read2_b32 v[20:21], v2 offset0:132 offset1:140
	ds_read2_b32 v[22:23], v2 offset0:165 offset1:173
	ds_read2_b32 v[24:25], v2 offset0:198 offset1:206
	ds_read2_b32 v[26:27], v2 offset0:231 offset1:239
	s_waitcnt lgkmcnt(7)
	v_bfe_u32 v8, v12, 16, 1
	s_waitcnt lgkmcnt(6)
	v_bfe_u32 v7, v14, 16, 1
	v_add3_u32 v7, v14, v7, s38
	v_lshrrev_b32_e32 v7, 16, v7
	v_add3_u32 v8, v12, v8, s38
	v_and_or_b32 v8, v8, s39, v7
	s_waitcnt lgkmcnt(5)
	v_bfe_u32 v7, v16, 16, 1
	v_add3_u32 v7, v16, v7, s38
	s_waitcnt lgkmcnt(4)
	v_bfe_u32 v9, v18, 16, 1
	v_lshrrev_b32_e32 v7, 16, v7
	v_add3_u32 v9, v18, v9, s38
	v_and_or_b32 v9, v9, s39, v7
	s_waitcnt lgkmcnt(3)
	v_bfe_u32 v7, v20, 16, 1
	v_add3_u32 v7, v20, v7, s38
	s_waitcnt lgkmcnt(2)
	v_bfe_u32 v10, v22, 16, 1
	v_lshrrev_b32_e32 v7, 16, v7
	v_add3_u32 v10, v22, v10, s38
	v_and_or_b32 v10, v10, s39, v7
	s_waitcnt lgkmcnt(1)
	v_bfe_u32 v7, v24, 16, 1
	v_add_u32_e32 v28, s4, v28
	v_add3_u32 v7, v24, v7, s38
	s_waitcnt lgkmcnt(0)
	v_bfe_u32 v11, v26, 16, 1
	v_ashrrev_i32_e32 v29, 31, v28
	v_lshrrev_b32_e32 v7, 16, v7
	v_add3_u32 v11, v26, v11, s38
	v_lshlrev_b64 v[30:31], 12, v[28:29]
	v_and_or_b32 v11, v11, s39, v7
	v_lshl_add_u64 v[30:31], v[4:5], 0, v[30:31]
	v_bfe_u32 v7, v15, 16, 1
	global_store_dwordx4 v[30:31], v[8:11], off
	v_add3_u32 v7, v15, v7, s38
	v_lshrrev_b32_e32 v7, 16, v7
	v_bfe_u32 v8, v13, 16, 1
	v_add3_u32 v8, v13, v8, s38
	v_and_or_b32 v8, v8, s39, v7
	v_bfe_u32 v7, v17, 16, 1
	v_add3_u32 v7, v17, v7, s38
	v_bfe_u32 v9, v19, 16, 1
	v_lshrrev_b32_e32 v7, 16, v7
	v_add3_u32 v9, v19, v9, s38
	v_and_or_b32 v9, v9, s39, v7
	v_bfe_u32 v7, v21, 16, 1
	v_add3_u32 v7, v21, v7, s38
	v_bfe_u32 v10, v23, 16, 1
	v_lshrrev_b32_e32 v7, 16, v7
	v_add3_u32 v10, v23, v10, s38
	v_and_or_b32 v10, v10, s39, v7
	v_bfe_u32 v7, v25, 16, 1
	v_add_u32_e32 v12, 8, v28
	v_add3_u32 v7, v25, v7, s38
	v_bfe_u32 v11, v27, 16, 1
	v_ashrrev_i32_e32 v13, 31, v12
	v_lshrrev_b32_e32 v7, 16, v7
	v_add3_u32 v11, v27, v11, s38
	v_lshlrev_b64 v[12:13], 12, v[12:13]
	v_and_or_b32 v11, v11, s39, v7
	v_lshl_add_u64 v[12:13], v[4:5], 0, v[12:13]
	global_store_dwordx4 v[12:13], v[8:11], off
	ds_read2_b32 v[12:13], v2 offset0:49 offset1:57
	ds_read2_b32 v[14:15], v2 offset0:16 offset1:24
	ds_read2_b32 v[16:17], v2 offset0:82 offset1:90
	ds_read2_b32 v[18:19], v2 offset0:115 offset1:123
	ds_read2_b32 v[20:21], v2 offset0:148 offset1:156
	ds_read2_b32 v[22:23], v2 offset0:181 offset1:189
	ds_read2_b32 v[24:25], v2 offset0:214 offset1:222
	ds_read2_b32 v[26:27], v2 offset0:247 offset1:255
	s_waitcnt lgkmcnt(7)
	v_bfe_u32 v8, v12, 16, 1
	s_waitcnt lgkmcnt(6)
	v_bfe_u32 v7, v14, 16, 1
	v_add3_u32 v7, v14, v7, s38
	v_lshrrev_b32_e32 v7, 16, v7
	v_add3_u32 v8, v12, v8, s38
	v_and_or_b32 v8, v8, s39, v7
	s_waitcnt lgkmcnt(5)
	v_bfe_u32 v7, v16, 16, 1
	v_add3_u32 v7, v16, v7, s38
	s_waitcnt lgkmcnt(4)
	v_bfe_u32 v9, v18, 16, 1
	v_lshrrev_b32_e32 v7, 16, v7
	v_add3_u32 v9, v18, v9, s38
	v_and_or_b32 v9, v9, s39, v7
	s_waitcnt lgkmcnt(3)
	v_bfe_u32 v7, v20, 16, 1
	v_add3_u32 v7, v20, v7, s38
	s_waitcnt lgkmcnt(2)
	v_bfe_u32 v10, v22, 16, 1
	v_lshrrev_b32_e32 v7, 16, v7
	v_add3_u32 v10, v22, v10, s38
	s_waitcnt lgkmcnt(1)
	v_bfe_u32 v2, v24, 16, 1
	v_and_or_b32 v10, v10, s39, v7
	v_add3_u32 v2, v24, v2, s38
	s_waitcnt lgkmcnt(0)
	v_bfe_u32 v7, v26, 16, 1
	v_lshrrev_b32_e32 v2, 16, v2
	v_add3_u32 v7, v26, v7, s38
	v_add_u32_e32 v30, 16, v28
	v_and_or_b32 v11, v7, s39, v2
	v_ashrrev_i32_e32 v31, 31, v30
	v_bfe_u32 v2, v15, 16, 1
	v_lshlrev_b64 v[30:31], 12, v[30:31]
	v_add3_u32 v2, v15, v2, s38
	v_bfe_u32 v7, v13, 16, 1
	v_lshl_add_u64 v[30:31], v[4:5], 0, v[30:31]
	v_lshrrev_b32_e32 v2, 16, v2
	v_add3_u32 v7, v13, v7, s38
	global_store_dwordx4 v[30:31], v[8:11], off
	v_add_u32_e32 v12, 24, v28
	v_ashrrev_i32_e32 v13, 31, v12
	v_and_or_b32 v8, v7, s39, v2
	v_bfe_u32 v2, v17, 16, 1
	v_add3_u32 v2, v17, v2, s38
	v_bfe_u32 v7, v19, 16, 1
	v_lshrrev_b32_e32 v2, 16, v2
	v_add3_u32 v7, v19, v7, s38
	v_and_or_b32 v9, v7, s39, v2
	v_bfe_u32 v2, v21, 16, 1
	v_add3_u32 v2, v21, v2, s38
	v_bfe_u32 v7, v23, 16, 1
	v_lshrrev_b32_e32 v2, 16, v2
	v_add3_u32 v7, v23, v7, s38
	v_and_or_b32 v10, v7, s39, v2
	v_bfe_u32 v2, v25, 16, 1
	v_add3_u32 v2, v25, v2, s38
	v_bfe_u32 v7, v27, 16, 1
	v_lshrrev_b32_e32 v2, 16, v2
	v_add3_u32 v7, v27, v7, s38
	v_lshlrev_b64 v[12:13], 12, v[12:13]
	v_and_or_b32 v11, v7, s39, v2
	v_lshl_add_u64 v[4:5], v[4:5], 0, v[12:13]
	global_store_dwordx4 v[4:5], v[8:11], off
	s_waitcnt lgkmcnt(0)

;     ...
;     const int kb = item / nblk, nb = item % nblk, k0 = 64 * kb, n0 = 32 * nb;
;     { float wv[32];
;       const float* wp = W + (size_t)(k0 + (lane >> 5)) * ldw + n0 + (lane & 31);
; #pragma unroll
;       for (int i = 0; i < 32; ++i) wv[i] = wp[(size_t)(2 * i) * ldw];
; #pragma unroll
;       for (int i = 0; i < 32; ++i) scr[(2 * i + (lane >> 5)) * 33 + (lane & 31)] = wv[i]; }
; __device__ __forceinline__ void transpose_late(const Args& a, Frame& F, LAS float* scr, int r) {
;     ...
;     if (r < IT_SQ) { p0_transpose_item(a.in[I_WBOUT], D, D, WAB + D, 0, D / 32, scr, r, F.lane, 2 * D); return; } r -= IT_SQ;
.LBB0_634:
	s_andn2_b64 vcc, exec, s[4:5]
	s_cbranch_vccnz .LBB0_636
	s_add_i32 s0, s20, 0x800
	v_mov_b32_e32 v7, v6
	s_and_b32 s5, s0, 0xffc0
	v_ashrrev_i32_e32 v10, 5, v7
	v_add_u32_e32 v4, s5, v10
	v_ashrrev_i32_e32 v5, 31, v4
	v_readlane_b32 s40, v244, 2
	s_and_b32 s4, s21, 0x7e0
	v_lshlrev_b64 v[4:5], 13, v[4:5]
	v_readlane_b32 s42, v244, 4
	v_readlane_b32 s43, v244, 5
	s_lshl_b32 s0, s4, 2
	v_lshlrev_b32_e32 v2, 2, v7
	v_lshl_add_u64 v[4:5], s[42:43], 0, v[4:5]
	v_lshl_add_u64 v[4:5], v[4:5], 0, s[0:1]
	v_and_b32_e32 v2, 0x7c, v2
	v_lshl_add_u64 v[4:5], v[4:5], 0, v[2:3]
	v_add_co_u32_e32 v8, vcc, s36, v4
	global_load_dword v11, v[4:5], off nt
	s_nop 0
	v_addc_co_u32_e32 v9, vcc, 0, v5, vcc
	global_load_dword v12, v[8:9], off nt
	v_add_co_u32_e32 v8, vcc, s37, v4
	s_lshl_b32 s0, s5, 1
	s_nop 0
	v_addc_co_u32_e32 v9, vcc, 0, v5, vcc
	global_load_dword v13, v[8:9], off nt
	v_add_co_u32_e32 v8, vcc, s82, v4
	s_add_u32 s24, s8, s0
	s_nop 0
	v_addc_co_u32_e32 v9, vcc, 0, v5, vcc
	global_load_dword v14, v[8:9], off nt
	v_add_co_u32_e32 v8, vcc, s83, v4
	s_addc_u32 s25, s9, 0
	s_nop 0
	v_addc_co_u32_e32 v9, vcc, 0, v5, vcc
	global_load_dword v15, v[8:9], off nt
	v_add_co_u32_e32 v8, vcc, s84, v4
	v_readlane_b32 s41, v244, 3
	s_nop 0
	v_addc_co_u32_e32 v9, vcc, 0, v5, vcc
	global_load_dword v16, v[8:9], off nt
	v_add_co_u32_e32 v8, vcc, s85, v4
	v_readlane_b32 s44, v244, 6
	s_nop 0
	v_addc_co_u32_e32 v9, vcc, 0, v5, vcc
	global_load_dword v17, v[8:9], off nt
	v_add_co_u32_e32 v8, vcc, s56, v4
	v_readlane_b32 s45, v244, 7
	s_nop 0
	v_addc_co_u32_e32 v9, vcc, 0, v5, vcc
	global_load_dword v18, v[8:9], off nt
	v_add_co_u32_e32 v8, vcc, s57, v4
	v_readlane_b32 s46, v244, 8
	s_nop 0
	v_addc_co_u32_e32 v9, vcc, 0, v5, vcc
	global_load_dword v19, v[8:9], off nt
	v_add_co_u32_e32 v8, vcc, s58, v4
	v_readlane_b32 s47, v244, 9
	s_nop 0
	v_addc_co_u32_e32 v9, vcc, 0, v5, vcc
	global_load_dword v20, v[8:9], off nt
	v_add_co_u32_e32 v8, vcc, s59, v4
	v_readlane_b32 s48, v244, 10
	s_nop 0
	v_addc_co_u32_e32 v9, vcc, 0, v5, vcc
	global_load_dword v21, v[8:9], off nt
	v_add_co_u32_e32 v8, vcc, s22, v4
	v_readlane_b32 s49, v244, 11
	s_nop 0
	v_addc_co_u32_e32 v9, vcc, 0, v5, vcc
	global_load_dword v22, v[8:9], off nt
	v_add_co_u32_e32 v8, vcc, s60, v4
	v_readlane_b32 s50, v244, 12
	s_nop 0
	v_addc_co_u32_e32 v9, vcc, 0, v5, vcc
	global_load_dword v23, v[8:9], off nt
	v_add_co_u32_e32 v8, vcc, s61, v4
	v_readlane_b32 s51, v244, 13
	s_nop 0
	v_addc_co_u32_e32 v9, vcc, 0, v5, vcc
	global_load_dword v24, v[8:9], off nt
	v_add_co_u32_e32 v8, vcc, s62, v4
	v_readlane_b32 s52, v244, 14
	s_nop 0
	v_addc_co_u32_e32 v9, vcc, 0, v5, vcc
	global_load_dword v25, v[8:9], off nt
	v_add_co_u32_e32 v8, vcc, s63, v4
	v_readlane_b32 s53, v244, 15
	s_nop 0
	v_addc_co_u32_e32 v9, vcc, 0, v5, vcc
	global_load_dword v26, v[8:9], off nt
	v_add_co_u32_e32 v8, vcc, s64, v4
	v_readlane_b32 s54, v244, 16
	s_nop 0
	v_addc_co_u32_e32 v9, vcc, 0, v5, vcc
	global_load_dword v27, v[8:9], off nt
	v_add_co_u32_e32 v8, vcc, s65, v4
	v_readlane_b32 s55, v244, 17
	s_nop 0
	v_addc_co_u32_e32 v9, vcc, 0, v5, vcc
	global_load_dword v28, v[8:9], off nt
	v_add_co_u32_e32 v8, vcc, s66, v4
	s_nop 1
	v_addc_co_u32_e32 v9, vcc, 0, v5, vcc
	global_load_dword v29, v[8:9], off nt
	v_add_co_u32_e32 v8, vcc, s67, v4
	s_nop 1
	v_addc_co_u32_e32 v9, vcc, 0, v5, vcc
	global_load_dword v30, v[8:9], off nt
	v_add_co_u32_e32 v8, vcc, s68, v4
	s_nop 1
	v_addc_co_u32_e32 v9, vcc, 0, v5, vcc
	global_load_dword v31, v[8:9], off nt
	v_add_co_u32_e32 v8, vcc, s69, v4
	s_nop 1
	v_addc_co_u32_e32 v9, vcc, 0, v5, vcc
	global_load_dword v32, v[8:9], off nt
	v_add_co_u32_e32 v8, vcc, s23, v4
	s_nop 1
	v_addc_co_u32_e32 v9, vcc, 0, v5, vcc
	global_load_dword v33, v[8:9], off nt
	v_add_co_u32_e32 v8, vcc, s72, v4
	s_nop 1
	v_addc_co_u32_e32 v9, vcc, 0, v5, vcc
	global_load_dword v34, v[8:9], off nt
	v_add_co_u32_e32 v8, vcc, s73, v4
	s_nop 1
	v_addc_co_u32_e32 v9, vcc, 0, v5, vcc
	global_load_dword v35, v[8:9], off nt
	v_add_co_u32_e32 v8, vcc, s74, v4
	s_nop 1
	v_addc_co_u32_e32 v9, vcc, 0, v5, vcc
	global_load_dword v36, v[8:9], off nt
	v_add_co_u32_e32 v8, vcc, s75, v4
	s_nop 1
	v_addc_co_u32_e32 v9, vcc, 0, v5, vcc
	global_load_dword v37, v[8:9], off nt
	v_add_co_u32_e32 v8, vcc, s76, v4
	s_nop 1
	v_addc_co_u32_e32 v9, vcc, 0, v5, vcc
	global_load_dword v38, v[8:9], off nt
	v_add_co_u32_e32 v8, vcc, s77, v4
	s_nop 1
	v_addc_co_u32_e32 v9, vcc, 0, v5, vcc
	global_load_dword v39, v[8:9], off nt
	v_add_co_u32_e32 v8, vcc, s78, v4
	s_nop 1
	v_addc_co_u32_e32 v9, vcc, 0, v5, vcc
	global_load_dword v40, v[8:9], off nt
	v_add_co_u32_e32 v8, vcc, s79, v4
	s_nop 1
	v_addc_co_u32_e32 v9, vcc, 0, v5, vcc
	v_add_co_u32_e32 v4, vcc, s80, v4
	global_load_dword v8, v[8:9], off nt
	s_nop 0
	v_addc_co_u32_e32 v5, vcc, 0, v5, vcc
	global_load_dword v4, v[4:5], off nt
	v_mul_lo_u32 v5, v10, s33
	v_add3_u32 v2, s3, v2, v5
	v_add_u32_e32 v5, 0x400, v2
	s_waitcnt vmcnt(0)
; #define GAS __attribute__((address_space(1)))
; #define LAS __attribute__((address_space(3)))
; #define LDS_WAIT() asm volatile("s_waitcnt lgkmcnt(0)" ::: "memory")
; __device__ __forceinline__ unsigned pk2(float lo, float hi) { return f2bf(lo) | (f2bf(hi) << 16); }
;     ...
;       for (int i = 0; i < 32; ++i) scr[(2 * i + (lane >> 5)) * 33 + (lane & 31)] = wv[i]; }
;     LDS_WAIT(); asm volatile("" ::: "memory");
;     const int c = lane & 7;
;     const int r0 = (mode == 0) ? n0 : (256 * (n0 >> 7) + (n0 & 127) + (mode == 2 ? 128 : 0));
; #pragma unroll
;     for (int j = 0; j < 4; ++j) { const int n = (lane >> 3) + 8 * j; const LAS float* s = scr + (8 * c) * 33 + n;
;         v4u o; o.x = pk2(s[0 * 33], s[1 * 33]); o.y = pk2(s[2 * 33], s[3 * 33]); o.z = pk2(s[4 * 33], s[5 * 33]); o.w = pk2(s[6 * 33], s[7 * 33]);
;         *(GAS v4u*)(WT + (size_t)(r0 + n) * ldt + k0 + 8 * c) = o; }
;     LDS_WAIT(); asm volatile("" ::: "memory");
	ds_write2_b32 v2, v11, v12 offset1:66
	ds_write2_b32 v2, v13, v14 offset0:132 offset1:198
	ds_write2_b32 v5, v15, v16 offset0:8 offset1:74
	ds_write2_b32 v5, v17, v18 offset0:140 offset1:206
	v_add_u32_e32 v5, 0x800, v2
	ds_write2_b32 v5, v19, v20 offset0:16 offset1:82
	ds_write2_b32 v5, v21, v22 offset0:148 offset1:214
	v_add_u32_e32 v5, 0xc00, v2
	ds_write2_b32 v5, v23, v24 offset0:24 offset1:90
	ds_write2_b32 v5, v25, v26 offset0:156 offset1:222
	v_add_u32_e32 v5, 0x1000, v2
	ds_write2_b32 v5, v27, v28 offset0:32 offset1:98
	ds_write2_b32 v5, v29, v30 offset0:164 offset1:230
	v_add_u32_e32 v5, 0x1400, v2
	ds_write2_b32 v5, v31, v32 offset0:40 offset1:106
	ds_write2_b32 v5, v33, v34 offset0:172 offset1:238
	v_add_u32_e32 v5, 0x1800, v2
	v_add_u32_e32 v2, 0x1c00, v2
	ds_write2_b32 v5, v35, v36 offset0:48 offset1:114
	ds_write2_b32 v5, v37, v38 offset0:180 offset1:246
	ds_write2_b32 v2, v39, v40 offset0:56 offset1:122
	ds_write2_b32 v2, v8, v4 offset0:188 offset1:254
	v_lshlrev_b32_e32 v2, 3, v7
	v_and_b32_e32 v2, 56, v2
	v_ashrrev_i32_e32 v28, 3, v7
	v_mul_u32_u24_e32 v7, 0x84, v2
	v_lshlrev_b32_e32 v2, 1, v2
	s_waitcnt lgkmcnt(0)
	v_lshl_add_u64 v[4:5], s[24:25], 0, v[2:3]
	v_lshlrev_b32_e32 v2, 2, v28
	v_add3_u32 v2, s3, v7, v2
	ds_read2_b32 v[12:13], v2 offset0:33 offset1:41
	ds_read2_b32 v[14:15], v2 offset1:8
	ds_read2_b32 v[16:17], v2 offset0:66 offset1:74
	ds_read2_b32 v[18:19], v2 offset0:99 offset1:107
	ds_read2_b32 v[20:21], v2 offset0:132 offset1:140
	ds_read2_b32 v[22:23], v2 offset0:165 offset1:173
	ds_read2_b32 v[24:25], v2 offset0:198 offset1:206
	ds_read2_b32 v[26:27], v2 offset0:231 offset1:239
	s_waitcnt lgkmcnt(7)
	v_bfe_u32 v8, v12, 16, 1
	s_waitcnt lgkmcnt(6)
	v_bfe_u32 v7, v14, 16, 1
	v_add3_u32 v7, v14, v7, s38
	v_lshrrev_b32_e32 v7, 16, v7
	v_add3_u32 v8, v12, v8, s38
	v_and_or_b32 v8, v8, s39, v7
	s_waitcnt lgkmcnt(5)
	v_bfe_u32 v7, v16, 16, 1
	v_add3_u32 v7, v16, v7, s38
	s_waitcnt lgkmcnt(4)
	v_bfe_u32 v9, v18, 16, 1
	v_lshrrev_b32_e32 v7, 16, v7
	v_add3_u32 v9, v18, v9, s38
	v_and_or_b32 v9, v9, s39, v7
	s_waitcnt lgkmcnt(3)
	v_bfe_u32 v7, v20, 16, 1
	v_add3_u32 v7, v20, v7, s38
	s_waitcnt lgkmcnt(2)
	v_bfe_u32 v10, v22, 16, 1
	v_lshrrev_b32_e32 v7, 16, v7
	v_add3_u32 v10, v22, v10, s38
	v_and_or_b32 v10, v10, s39, v7
	s_waitcnt lgkmcnt(1)
	v_bfe_u32 v7, v24, 16, 1
	v_add_u32_e32 v28, s4, v28
	v_add3_u32 v7, v24, v7, s38
	s_waitcnt lgkmcnt(0)
	v_bfe_u32 v11, v26, 16, 1
	v_ashrrev_i32_e32 v29, 31, v28
	v_lshrrev_b32_e32 v7, 16, v7
	v_add3_u32 v11, v26, v11, s38
	v_lshlrev_b64 v[30:31], 13, v[28:29]
	v_and_or_b32 v11, v11, s39, v7
	v_lshl_add_u64 v[30:31], v[4:5], 0, v[30:31]
	v_bfe_u32 v7, v15, 16, 1
	global_store_dwordx4 v[30:31], v[8:11], off
	v_add3_u32 v7, v15, v7, s38
	v_lshrrev_b32_e32 v7, 16, v7
	v_bfe_u32 v8, v13, 16, 1
	v_add3_u32 v8, v13, v8, s38
	v_and_or_b32 v8, v8, s39, v7
	v_bfe_u32 v7, v17, 16, 1
	v_add3_u32 v7, v17, v7, s38
	v_bfe_u32 v9, v19, 16, 1
	v_lshrrev_b32_e32 v7, 16, v7
	v_add3_u32 v9, v19, v9, s38
	v_and_or_b32 v9, v9, s39, v7
	v_bfe_u32 v7, v21, 16, 1
	v_add3_u32 v7, v21, v7, s38
	v_bfe_u32 v10, v23, 16, 1
	v_lshrrev_b32_e32 v7, 16, v7
	v_add3_u32 v10, v23, v10, s38
	v_and_or_b32 v10, v10, s39, v7
	v_bfe_u32 v7, v25, 16, 1
	v_add_u32_e32 v12, 8, v28
	v_add3_u32 v7, v25, v7, s38
	v_bfe_u32 v11, v27, 16, 1
	v_ashrrev_i32_e32 v13, 31, v12
	v_lshrrev_b32_e32 v7, 16, v7
	v_add3_u32 v11, v27, v11, s38
	v_lshlrev_b64 v[12:13], 13, v[12:13]
	v_and_or_b32 v11, v11, s39, v7
	v_lshl_add_u64 v[12:13], v[4:5], 0, v[12:13]
	global_store_dwordx4 v[12:13], v[8:11], off
	ds_read2_b32 v[12:13], v2 offset0:49 offset1:57
	ds_read2_b32 v[14:15], v2 offset0:16 offset1:24
	ds_read2_b32 v[16:17], v2 offset0:82 offset1:90
	ds_read2_b32 v[18:19], v2 offset0:115 offset1:123
	ds_read2_b32 v[20:21], v2 offset0:148 offset1:156
	ds_read2_b32 v[22:23], v2 offset0:181 offset1:189
	ds_read2_b32 v[24:25], v2 offset0:214 offset1:222
	ds_read2_b32 v[26:27], v2 offset0:247 offset1:255
	s_waitcnt lgkmcnt(7)
	v_bfe_u32 v8, v12, 16, 1
	s_waitcnt lgkmcnt(6)
	v_bfe_u32 v7, v14, 16, 1
	v_add3_u32 v7, v14, v7, s38
	v_lshrrev_b32_e32 v7, 16, v7
	v_add3_u32 v8, v12, v8, s38
	v_and_or_b32 v8, v8, s39, v7
	s_waitcnt lgkmcnt(5)
	v_bfe_u32 v7, v16, 16, 1
	v_add3_u32 v7, v16, v7, s38
	s_waitcnt lgkmcnt(4)
	v_bfe_u32 v9, v18, 16, 1
	v_lshrrev_b32_e32 v7, 16, v7
	v_add3_u32 v9, v18, v9, s38
	v_and_or_b32 v9, v9, s39, v7
	s_waitcnt lgkmcnt(3)
	v_bfe_u32 v7, v20, 16, 1
	v_add3_u32 v7, v20, v7, s38
	s_waitcnt lgkmcnt(2)
	v_bfe_u32 v10, v22, 16, 1
	v_lshrrev_b32_e32 v7, 16, v7
	v_add3_u32 v10, v22, v10, s38
	s_waitcnt lgkmcnt(1)
	v_bfe_u32 v2, v24, 16, 1
	v_and_or_b32 v10, v10, s39, v7
	v_add3_u32 v2, v24, v2, s38
	s_waitcnt lgkmcnt(0)
	v_bfe_u32 v7, v26, 16, 1
	v_lshrrev_b32_e32 v2, 16, v2
	v_add3_u32 v7, v26, v7, s38
	v_add_u32_e32 v30, 16, v28
	v_and_or_b32 v11, v7, s39, v2
	v_ashrrev_i32_e32 v31, 31, v30
	v_bfe_u32 v2, v15, 16, 1
	v_lshlrev_b64 v[30:31], 13, v[30:31]
	v_add3_u32 v2, v15, v2, s38
	v_bfe_u32 v7, v13, 16, 1
	v_lshl_add_u64 v[30:31], v[4:5], 0, v[30:31]
	v_lshrrev_b32_e32 v2, 16, v2
	v_add3_u32 v7, v13, v7, s38
	global_store_dwordx4 v[30:31], v[8:11], off
	v_add_u32_e32 v12, 24, v28
	v_ashrrev_i32_e32 v13, 31, v12
	v_and_or_b32 v8, v7, s39, v2
	v_bfe_u32 v2, v17, 16, 1
	v_add3_u32 v2, v17, v2, s38
	v_bfe_u32 v7, v19, 16, 1
	v_lshrrev_b32_e32 v2, 16, v2
	v_add3_u32 v7, v19, v7, s38
	v_and_or_b32 v9, v7, s39, v2
	v_bfe_u32 v2, v21, 16, 1
	v_add3_u32 v2, v21, v2, s38
	v_bfe_u32 v7, v23, 16, 1
	v_lshrrev_b32_e32 v2, 16, v2
	v_add3_u32 v7, v23, v7, s38
	v_and_or_b32 v10, v7, s39, v2
	v_bfe_u32 v2, v25, 16, 1
	v_add3_u32 v2, v25, v2, s38
	v_bfe_u32 v7, v27, 16, 1
	v_lshrrev_b32_e32 v2, 16, v2
	v_add3_u32 v7, v27, v7, s38
	v_lshlrev_b64 v[12:13], 13, v[12:13]
	v_and_or_b32 v11, v7, s39, v2
	v_lshl_add_u64 v[4:5], v[4:5], 0, v[12:13]
	global_store_dwordx4 v[4:5], v[8:11], off
	s_waitcnt lgkmcnt(0)

;     ...
;     const int kb = item / nblk, nb = item % nblk, k0 = 64 * kb, n0 = 32 * nb;
;     { float wv[32];
;       const float* wp = W + (size_t)(k0 + (lane >> 5)) * ldw + n0 + (lane & 31);
; #pragma unroll
;       for (int i = 0; i < 32; ++i) wv[i] = wp[(size_t)(2 * i) * ldw];
; #pragma unroll
;       for (int i = 0; i < 32; ++i) scr[(2 * i + (lane >> 5)) * 33 + (lane & 31)] = wv[i]; }
; __device__ __forceinline__ void transpose_late(const Args& a, Frame& F, LAS float* scr, int r) {
;     ...
;     if (r < IT_SQ) { p0_transpose_item(a.in[I_WAOUT], D, D, WAB, 0, D / 32, scr, r, F.lane, 2 * D); return; } r -= IT_SQ;
.LBB0_637:
	s_ashr_i32 s0, s7, 31
	s_lshr_b32 s0, s0, 26
	v_mov_b32_e32 v7, v6
	s_add_i32 s0, s7, s0
	s_and_b32 s6, s0, 0xffffffc0
	v_ashrrev_i32_e32 v10, 5, v7
	v_add_u32_e32 v4, s6, v10
	s_sub_i32 s0, s7, s6
	v_ashrrev_i32_e32 v5, 31, v4
	v_readlane_b32 s40, v245, 50
	s_lshl_b32 s4, s0, 5
	v_lshlrev_b64 v[4:5], 13, v[4:5]
	v_readlane_b32 s48, v245, 58
	v_readlane_b32 s49, v245, 59
	s_ashr_i32 s5, s4, 31
	v_lshlrev_b32_e32 v2, 2, v7
	v_lshl_add_u64 v[4:5], s[48:49], 0, v[4:5]
	v_lshl_add_u64 v[4:5], s[4:5], 2, v[4:5]
	v_and_b32_e32 v2, 0x7c, v2
	v_lshl_add_u64 v[4:5], v[4:5], 0, v[2:3]
	v_add_co_u32_e32 v8, vcc, s36, v4
	global_load_dword v11, v[4:5], off nt
	s_nop 0
	v_addc_co_u32_e32 v9, vcc, 0, v5, vcc
	global_load_dword v12, v[8:9], off nt
	v_add_co_u32_e32 v8, vcc, s37, v4
	s_ashr_i32 s7, s6, 31
	s_nop 0
	v_addc_co_u32_e32 v9, vcc, 0, v5, vcc
	global_load_dword v13, v[8:9], off nt
	v_add_co_u32_e32 v8, vcc, s82, v4
	s_lshl_b64 s[6:7], s[6:7], 1
	s_nop 0
	v_addc_co_u32_e32 v9, vcc, 0, v5, vcc
	global_load_dword v14, v[8:9], off nt
	v_add_co_u32_e32 v8, vcc, s83, v4
	s_add_u32 s6, s10, s6
	s_nop 0
	v_addc_co_u32_e32 v9, vcc, 0, v5, vcc
	global_load_dword v15, v[8:9], off nt
	v_add_co_u32_e32 v8, vcc, s84, v4
	s_addc_u32 s7, s11, s7
	s_nop 0
	v_addc_co_u32_e32 v9, vcc, 0, v5, vcc
	global_load_dword v16, v[8:9], off nt
	v_add_co_u32_e32 v8, vcc, s85, v4
	v_readlane_b32 s41, v245, 51
	s_nop 0
	v_addc_co_u32_e32 v9, vcc, 0, v5, vcc
	global_load_dword v17, v[8:9], off nt
	v_add_co_u32_e32 v8, vcc, s56, v4
	v_readlane_b32 s42, v245, 52
	s_nop 0
	v_addc_co_u32_e32 v9, vcc, 0, v5, vcc
	global_load_dword v18, v[8:9], off nt
	v_add_co_u32_e32 v8, vcc, s57, v4
	v_readlane_b32 s43, v245, 53
	s_nop 0
	v_addc_co_u32_e32 v9, vcc, 0, v5, vcc
	global_load_dword v19, v[8:9], off nt
	v_add_co_u32_e32 v8, vcc, s58, v4
	v_readlane_b32 s44, v245, 54
	s_nop 0
	v_addc_co_u32_e32 v9, vcc, 0, v5, vcc
	global_load_dword v20, v[8:9], off nt
	v_add_co_u32_e32 v8, vcc, s59, v4
	v_readlane_b32 s45, v245, 55
	s_nop 0
	v_addc_co_u32_e32 v9, vcc, 0, v5, vcc
	global_load_dword v21, v[8:9], off nt
	v_add_co_u32_e32 v8, vcc, s22, v4
	v_readlane_b32 s46, v245, 56
	s_nop 0
	v_addc_co_u32_e32 v9, vcc, 0, v5, vcc
	global_load_dword v22, v[8:9], off nt
	v_add_co_u32_e32 v8, vcc, s60, v4
	v_readlane_b32 s47, v245, 57
	s_nop 0
	v_addc_co_u32_e32 v9, vcc, 0, v5, vcc
	global_load_dword v23, v[8:9], off nt
	v_add_co_u32_e32 v8, vcc, s61, v4
	v_readlane_b32 s50, v245, 60
	s_nop 0
	v_addc_co_u32_e32 v9, vcc, 0, v5, vcc
	global_load_dword v24, v[8:9], off nt
	v_add_co_u32_e32 v8, vcc, s62, v4
	v_readlane_b32 s51, v245, 61
	s_nop 0
	v_addc_co_u32_e32 v9, vcc, 0, v5, vcc
	global_load_dword v25, v[8:9], off nt
	v_add_co_u32_e32 v8, vcc, s63, v4
	v_readlane_b32 s52, v245, 62
	s_nop 0
	v_addc_co_u32_e32 v9, vcc, 0, v5, vcc
	global_load_dword v26, v[8:9], off nt
	v_add_co_u32_e32 v8, vcc, s64, v4
	v_readlane_b32 s53, v245, 63
	s_nop 0
	v_addc_co_u32_e32 v9, vcc, 0, v5, vcc
	global_load_dword v27, v[8:9], off nt
	v_add_co_u32_e32 v8, vcc, s65, v4
	v_readlane_b32 s54, v244, 0
	s_nop 0
	v_addc_co_u32_e32 v9, vcc, 0, v5, vcc
	global_load_dword v28, v[8:9], off nt
	v_add_co_u32_e32 v8, vcc, s66, v4
	v_readlane_b32 s55, v244, 1
	s_nop 0
	v_addc_co_u32_e32 v9, vcc, 0, v5, vcc
	global_load_dword v29, v[8:9], off nt
	v_add_co_u32_e32 v8, vcc, s67, v4
	s_nop 1
	v_addc_co_u32_e32 v9, vcc, 0, v5, vcc
	global_load_dword v30, v[8:9], off nt
	v_add_co_u32_e32 v8, vcc, s68, v4
	s_nop 1
	v_addc_co_u32_e32 v9, vcc, 0, v5, vcc
	global_load_dword v31, v[8:9], off nt
	v_add_co_u32_e32 v8, vcc, s69, v4
	s_nop 1
	v_addc_co_u32_e32 v9, vcc, 0, v5, vcc
	global_load_dword v32, v[8:9], off nt
	v_add_co_u32_e32 v8, vcc, s23, v4
	s_nop 1
	v_addc_co_u32_e32 v9, vcc, 0, v5, vcc
	global_load_dword v33, v[8:9], off nt
	v_add_co_u32_e32 v8, vcc, s72, v4
	s_nop 1
	v_addc_co_u32_e32 v9, vcc, 0, v5, vcc
	global_load_dword v34, v[8:9], off nt
	v_add_co_u32_e32 v8, vcc, s73, v4
	s_nop 1
	v_addc_co_u32_e32 v9, vcc, 0, v5, vcc
	global_load_dword v35, v[8:9], off nt
	v_add_co_u32_e32 v8, vcc, s74, v4
	s_nop 1
	v_addc_co_u32_e32 v9, vcc, 0, v5, vcc
	global_load_dword v36, v[8:9], off nt
	v_add_co_u32_e32 v8, vcc, s75, v4
	s_nop 1
	v_addc_co_u32_e32 v9, vcc, 0, v5, vcc
	global_load_dword v37, v[8:9], off nt
	v_add_co_u32_e32 v8, vcc, s76, v4
	s_nop 1
	v_addc_co_u32_e32 v9, vcc, 0, v5, vcc
	global_load_dword v38, v[8:9], off nt
	v_add_co_u32_e32 v8, vcc, s77, v4
	s_nop 1
	v_addc_co_u32_e32 v9, vcc, 0, v5, vcc
	global_load_dword v39, v[8:9], off nt
	v_add_co_u32_e32 v8, vcc, s78, v4
	s_nop 1
	v_addc_co_u32_e32 v9, vcc, 0, v5, vcc
	global_load_dword v40, v[8:9], off nt
	v_add_co_u32_e32 v8, vcc, s79, v4
	s_nop 1
	v_addc_co_u32_e32 v9, vcc, 0, v5, vcc
	v_add_co_u32_e32 v4, vcc, s80, v4
	global_load_dword v8, v[8:9], off nt
	s_nop 0
	v_addc_co_u32_e32 v5, vcc, 0, v5, vcc
	global_load_dword v4, v[4:5], off nt
	v_mul_lo_u32 v5, v10, s33
	v_add3_u32 v2, s3, v2, v5
	v_add_u32_e32 v5, 0x400, v2
	s_waitcnt vmcnt(0)
; #define GAS __attribute__((address_space(1)))
; #define LAS __attribute__((address_space(3)))
; #define LDS_WAIT() asm volatile("s_waitcnt lgkmcnt(0)" ::: "memory")
; __device__ __forceinline__ unsigned pk2(float lo, float hi) { return f2bf(lo) | (f2bf(hi) << 16); }
;     ...
;       for (int i = 0; i < 32; ++i) scr[(2 * i + (lane >> 5)) * 33 + (lane & 31)] = wv[i]; }
;     LDS_WAIT(); asm volatile("" ::: "memory");
;     const int c = lane & 7;
;     const int r0 = (mode == 0) ? n0 : (256 * (n0 >> 7) + (n0 & 127) + (mode == 2 ? 128 : 0));
; #pragma unroll
;     for (int j = 0; j < 4; ++j) { const int n = (lane >> 3) + 8 * j; const LAS float* s = scr + (8 * c) * 33 + n;
;         v4u o; o.x = pk2(s[0 * 33], s[1 * 33]); o.y = pk2(s[2 * 33], s[3 * 33]); o.z = pk2(s[4 * 33], s[5 * 33]); o.w = pk2(s[6 * 33], s[7 * 33]);
;         *(GAS v4u*)(WT + (size_t)(r0 + n) * ldt + k0 + 8 * c) = o; }
	ds_write2_b32 v2, v11, v12 offset1:66
	ds_write2_b32 v2, v13, v14 offset0:132 offset1:198
	ds_write2_b32 v5, v15, v16 offset0:8 offset1:74
	ds_write2_b32 v5, v17, v18 offset0:140 offset1:206
	v_add_u32_e32 v5, 0x800, v2
	ds_write2_b32 v5, v19, v20 offset0:16 offset1:82
	ds_write2_b32 v5, v21, v22 offset0:148 offset1:214
	v_add_u32_e32 v5, 0xc00, v2
	ds_write2_b32 v5, v23, v24 offset0:24 offset1:90
	ds_write2_b32 v5, v25, v26 offset0:156 offset1:222
	v_add_u32_e32 v5, 0x1000, v2
	ds_write2_b32 v5, v27, v28 offset0:32 offset1:98
	ds_write2_b32 v5, v29, v30 offset0:164 offset1:230
	v_add_u32_e32 v5, 0x1400, v2
	ds_write2_b32 v5, v31, v32 offset0:40 offset1:106
	ds_write2_b32 v5, v33, v34 offset0:172 offset1:238
	v_add_u32_e32 v5, 0x1800, v2
	v_add_u32_e32 v2, 0x1c00, v2
	ds_write2_b32 v5, v35, v36 offset0:48 offset1:114
	ds_write2_b32 v5, v37, v38 offset0:180 offset1:246
	ds_write2_b32 v2, v39, v40 offset0:56 offset1:122
	ds_write2_b32 v2, v8, v4 offset0:188 offset1:254
	v_lshlrev_b32_e32 v2, 3, v7
	v_and_b32_e32 v2, 56, v2
	v_ashrrev_i32_e32 v28, 3, v7
	v_mul_u32_u24_e32 v7, 0x84, v2
	v_lshlrev_b32_e32 v2, 1, v2
	s_waitcnt lgkmcnt(0)
	v_lshl_add_u64 v[4:5], s[6:7], 0, v[2:3]
	v_lshlrev_b32_e32 v2, 2, v28
	v_add3_u32 v2, s3, v7, v2
	ds_read2_b32 v[12:13], v2 offset0:33 offset1:41
	ds_read2_b32 v[14:15], v2 offset1:8
	ds_read2_b32 v[16:17], v2 offset0:66 offset1:74
	ds_read2_b32 v[18:19], v2 offset0:99 offset1:107
	ds_read2_b32 v[20:21], v2 offset0:132 offset1:140
	ds_read2_b32 v[22:23], v2 offset0:165 offset1:173
	ds_read2_b32 v[24:25], v2 offset0:198 offset1:206
	ds_read2_b32 v[26:27], v2 offset0:231 offset1:239
	s_waitcnt lgkmcnt(7)
	v_bfe_u32 v8, v12, 16, 1
	s_waitcnt lgkmcnt(6)
	v_bfe_u32 v7, v14, 16, 1
	v_add3_u32 v7, v14, v7, s38
	v_lshrrev_b32_e32 v7, 16, v7
	v_add3_u32 v8, v12, v8, s38
	v_and_or_b32 v8, v8, s39, v7
	s_waitcnt lgkmcnt(5)
	v_bfe_u32 v7, v16, 16, 1
	v_add3_u32 v7, v16, v7, s38
	s_waitcnt lgkmcnt(4)
	v_bfe_u32 v9, v18, 16, 1
	v_lshrrev_b32_e32 v7, 16, v7
	v_add3_u32 v9, v18, v9, s38
	v_and_or_b32 v9, v9, s39, v7
	s_waitcnt lgkmcnt(3)
	v_bfe_u32 v7, v20, 16, 1
	v_add3_u32 v7, v20, v7, s38
	s_waitcnt lgkmcnt(2)
	v_bfe_u32 v10, v22, 16, 1
	v_lshrrev_b32_e32 v7, 16, v7
	v_add3_u32 v10, v22, v10, s38
	v_and_or_b32 v10, v10, s39, v7
	s_waitcnt lgkmcnt(1)
	v_bfe_u32 v7, v24, 16, 1
	v_add_u32_e32 v28, s4, v28
	v_add3_u32 v7, v24, v7, s38
	s_waitcnt lgkmcnt(0)
	v_bfe_u32 v11, v26, 16, 1
	v_ashrrev_i32_e32 v29, 31, v28
	v_lshrrev_b32_e32 v7, 16, v7
	v_add3_u32 v11, v26, v11, s38
	v_lshlrev_b64 v[30:31], 13, v[28:29]
	v_and_or_b32 v11, v11, s39, v7
	v_lshl_add_u64 v[30:31], v[4:5], 0, v[30:31]
	v_bfe_u32 v7, v15, 16, 1
	global_store_dwordx4 v[30:31], v[8:11], off
	v_add3_u32 v7, v15, v7, s38
	v_lshrrev_b32_e32 v7, 16, v7
	v_bfe_u32 v8, v13, 16, 1
	v_add3_u32 v8, v13, v8, s38
	v_and_or_b32 v8, v8, s39, v7
	v_bfe_u32 v7, v17, 16, 1
	v_add3_u32 v7, v17, v7, s38
	v_bfe_u32 v9, v19, 16, 1
	v_lshrrev_b32_e32 v7, 16, v7
	v_add3_u32 v9, v19, v9, s38
	v_and_or_b32 v9, v9, s39, v7
	v_bfe_u32 v7, v21, 16, 1
	v_add3_u32 v7, v21, v7, s38
	v_bfe_u32 v10, v23, 16, 1
	v_lshrrev_b32_e32 v7, 16, v7
	v_add3_u32 v10, v23, v10, s38
	v_and_or_b32 v10, v10, s39, v7
	v_bfe_u32 v7, v25, 16, 1
	v_add_u32_e32 v12, 8, v28
	v_add3_u32 v7, v25, v7, s38
	v_bfe_u32 v11, v27, 16, 1
	v_ashrrev_i32_e32 v13, 31, v12
	v_lshrrev_b32_e32 v7, 16, v7
	v_add3_u32 v11, v27, v11, s38
	v_lshlrev_b64 v[12:13], 13, v[12:13]
	v_and_or_b32 v11, v11, s39, v7
	v_lshl_add_u64 v[12:13], v[4:5], 0, v[12:13]
	global_store_dwordx4 v[12:13], v[8:11], off
	ds_read2_b32 v[12:13], v2 offset0:49 offset1:57
	ds_read2_b32 v[14:15], v2 offset0:16 offset1:24
	ds_read2_b32 v[16:17], v2 offset0:82 offset1:90
	ds_read2_b32 v[18:19], v2 offset0:115 offset1:123
	ds_read2_b32 v[20:21], v2 offset0:148 offset1:156
	ds_read2_b32 v[22:23], v2 offset0:181 offset1:189
	ds_read2_b32 v[24:25], v2 offset0:214 offset1:222
	ds_read2_b32 v[26:27], v2 offset0:247 offset1:255
	s_waitcnt lgkmcnt(7)
	v_bfe_u32 v8, v12, 16, 1
	s_waitcnt lgkmcnt(6)
	v_bfe_u32 v7, v14, 16, 1
	v_add3_u32 v7, v14, v7, s38
	v_lshrrev_b32_e32 v7, 16, v7
	v_add3_u32 v8, v12, v8, s38
	v_and_or_b32 v8, v8, s39, v7
	s_waitcnt lgkmcnt(5)
	v_bfe_u32 v7, v16, 16, 1
	v_add3_u32 v7, v16, v7, s38
	s_waitcnt lgkmcnt(4)
	v_bfe_u32 v9, v18, 16, 1
	v_lshrrev_b32_e32 v7, 16, v7
	v_add3_u32 v9, v18, v9, s38
	v_and_or_b32 v9, v9, s39, v7
	s_waitcnt lgkmcnt(3)
	v_bfe_u32 v7, v20, 16, 1
	v_add3_u32 v7, v20, v7, s38
	s_waitcnt lgkmcnt(2)
	v_bfe_u32 v10, v22, 16, 1
	v_lshrrev_b32_e32 v7, 16, v7
	v_add3_u32 v10, v22, v10, s38
	s_waitcnt lgkmcnt(1)
	v_bfe_u32 v2, v24, 16, 1
	v_and_or_b32 v10, v10, s39, v7
	v_add3_u32 v2, v24, v2, s38
	s_waitcnt lgkmcnt(0)
	v_bfe_u32 v7, v26, 16, 1
	v_lshrrev_b32_e32 v2, 16, v2
	v_add3_u32 v7, v26, v7, s38
	v_add_u32_e32 v30, 16, v28
	v_and_or_b32 v11, v7, s39, v2
	v_ashrrev_i32_e32 v31, 31, v30
	v_bfe_u32 v2, v15, 16, 1
	v_lshlrev_b64 v[30:31], 13, v[30:31]
	v_add3_u32 v2, v15, v2, s38
	v_bfe_u32 v7, v13, 16, 1
	v_lshl_add_u64 v[30:31], v[4:5], 0, v[30:31]
	v_lshrrev_b32_e32 v2, 16, v2
	v_add3_u32 v7, v13, v7, s38
	global_store_dwordx4 v[30:31], v[8:11], off
	v_add_u32_e32 v12, 24, v28
	v_ashrrev_i32_e32 v13, 31, v12
	v_and_or_b32 v8, v7, s39, v2
	v_bfe_u32 v2, v17, 16, 1
	v_add3_u32 v2, v17, v2, s38
	v_bfe_u32 v7, v19, 16, 1
	v_lshrrev_b32_e32 v2, 16, v2
	v_add3_u32 v7, v19, v7, s38
	v_and_or_b32 v9, v7, s39, v2
	v_bfe_u32 v2, v21, 16, 1
	v_add3_u32 v2, v21, v2, s38
	v_bfe_u32 v7, v23, 16, 1
	v_lshrrev_b32_e32 v2, 16, v2
	v_add3_u32 v7, v23, v7, s38
	v_and_or_b32 v10, v7, s39, v2
	v_bfe_u32 v2, v25, 16, 1
	v_add3_u32 v2, v25, v2, s38
	v_bfe_u32 v7, v27, 16, 1
	v_lshrrev_b32_e32 v2, 16, v2
	v_add3_u32 v7, v27, v7, s38
	v_lshlrev_b64 v[12:13], 13, v[12:13]
	v_and_or_b32 v11, v7, s39, v2
	v_lshl_add_u64 v[4:5], v[4:5], 0, v[12:13]
	global_store_dwordx4 v[4:5], v[8:11], off
	s_waitcnt lgkmcnt(0)
	s_branch .LBB0_617

; #define LAS __attribute__((address_space(3)))
;     if (ldt == 0) ldt = K;
;     asm volatile("" : "+v"(lane));
;     const int kb = item / nblk, nb = item % nblk, k0 = 64 * kb, n0 = 32 * nb;
;     { float wv[32];
;       const float* wp = W + (size_t)(k0 + (lane >> 5)) * ldw + n0 + (lane & 31);
; #pragma unroll
;       for (int i = 0; i < 32; ++i) wv[i] = wp[(size_t)(2 * i) * ldw];
; __device__ __forceinline__ void transpose_late(const Args& a, Frame& F, LAS float* scr, int r) {
;     bf16 *WAB = WSP(bf16, WS_WAB), *WO = WSP(bf16, WS_WO), *WPG = WSP(bf16, WS_WPG), *WPU = WSP(bf16, WS_WPU), *W2 = WSP(bf16, WS_W2), *W2D = WSP(bf16, WS_W2D);
;     if (r < IT_SQ) { p0_transpose_item(a.in[I_WAOUT], D, D, WAB, 0, D / 32, scr, r, F.lane, 2 * D); return; } r -= IT_SQ;
;     if (r < IT_SQ) { p0_transpose_item(a.in[I_WBOUT], D, D, WAB + D, 0, D / 32, scr, r, F.lane, 2 * D); return; } r -= IT_SQ;
;     if (r < IT_SQ) { p0_transpose_item(a.in[I_WO], D, D, WO, 0, D / 32, scr, r, F.lane); return; } r -= IT_SQ;
;     if (r < IT_SQ) { p0_transpose_item(a.in[I_WPG], D, D, WPG, 0, D / 32, scr, r, F.lane); return; } r -= IT_SQ;
;     if (r < IT_PU) { p0_transpose_item(a.in[I_WPU], D, DPLE, WPU, 0, D / 32, scr, r, F.lane); return; } r -= IT_PU;
;     if (r < IT_FG) { p0_transpose_item(a.in[I_W2G], FF, D, W2, 1, FF / 32, scr, r, F.lane); return; } r -= IT_FG;
;     if (r < IT_FG) { p0_transpose_item(a.in[I_W2U], FF, D, W2, 2, FF / 32, scr, r, F.lane); return; } r -= IT_FG;
;     p0_transpose_item(a.in[I_W2D], D, FF, W2D, 0, D / 32, scr, r, F.lane);
; }
.LBB0_998:
	s_add_i32 s61, s5, s62
	s_cmp_ge_i32 s61, s67
	s_cbranch_scc1 .LBB0_997
	s_cmpk_gt_i32 s61, 0x7ff
	s_mov_b64 s[58:59], -1
	s_cbranch_scc0 .LBB0_1025
	s_cmpk_gt_u32 s61, 0xfff
	s_cbranch_scc0 .LBB0_1022
	s_cmpk_gt_u32 s61, 0x17ff
	s_cbranch_scc0 .LBB0_1019
	s_cmpk_gt_u32 s61, 0x1fff
	s_cbranch_scc0 .LBB0_1016
	s_cmpk_gt_u32 s61, 0x20ff
	s_cbranch_scc0 .LBB0_1013
	s_cmpk_gt_u32 s61, 0x36ff
	s_cbranch_scc0 .LBB0_1010
	s_cmpk_gt_u32 s61, 0x4cff
	s_cbranch_scc0 .LBB0_1007
	v_mov_b32_e32 v10, v145
	v_readlane_b32 s16, v244, 63
	v_ashrrev_i32_e32 v11, 5, v10
	v_readlane_b32 s44, v244, 2
	v_add_u32_e32 v6, s16, v11
	v_ashrrev_i32_e32 v7, 31, v6
	s_and_b32 s26, s95, 0x7e0
	v_lshlrev_b64 v[6:7], 13, v[6:7]
	v_readlane_b32 s58, v244, 16
	v_readlane_b32 s59, v244, 17
	s_lshl_b32 s86, s26, 2
	v_lshlrev_b32_e32 v8, 2, v10
	v_lshl_add_u64 v[6:7], s[58:59], 0, v[6:7]
	v_lshl_add_u64 v[6:7], v[6:7], 0, s[86:87]
	v_and_b32_e32 v66, 0x7c, v8
	v_lshl_add_u64 v[6:7], v[6:7], 0, v[66:67]
	v_add_co_u32_e32 v8, vcc, s83, v6
	global_load_dword v12, v[6:7], off nt
	s_nop 0
	v_addc_co_u32_e32 v9, vcc, 0, v7, vcc
	global_load_dword v13, v[8:9], off nt
	v_add_co_u32_e32 v8, vcc, s85, v6
	s_mov_b32 s16, 0x30000
	s_nop 0
	v_addc_co_u32_e32 v9, vcc, 0, v7, vcc
	global_load_dword v14, v[8:9], off nt
	v_add_co_u32_e32 v8, vcc, s72, v6
	v_readlane_b32 s45, v244, 3
	s_nop 0
	v_addc_co_u32_e32 v9, vcc, 0, v7, vcc
	global_load_dword v15, v[8:9], off nt
	v_add_co_u32_e32 v8, vcc, s73, v6
	v_readlane_b32 s46, v244, 4
	s_nop 0
	v_addc_co_u32_e32 v9, vcc, 0, v7, vcc
	global_load_dword v16, v[8:9], off nt
	v_add_co_u32_e32 v8, vcc, s74, v6
	v_readlane_b32 s47, v244, 5
	s_nop 0
	v_addc_co_u32_e32 v9, vcc, 0, v7, vcc
	global_load_dword v17, v[8:9], off nt
	v_add_co_u32_e32 v8, vcc, s75, v6
	v_readlane_b32 s48, v244, 6
	s_nop 0
	v_addc_co_u32_e32 v9, vcc, 0, v7, vcc
	global_load_dword v18, v[8:9], off nt
	v_add_co_u32_e32 v8, vcc, s88, v6
	v_readlane_b32 s49, v244, 7
	s_nop 0
	v_addc_co_u32_e32 v9, vcc, 0, v7, vcc
	global_load_dword v19, v[8:9], off nt
	v_add_co_u32_e32 v8, vcc, s15, v6
	v_readlane_b32 s50, v244, 8
	s_nop 0
	v_addc_co_u32_e32 v9, vcc, 0, v7, vcc
	global_load_dword v20, v[8:9], off nt
	v_add_co_u32_e32 v8, vcc, s78, v6
	v_readlane_b32 s51, v244, 9
	s_nop 0
	v_addc_co_u32_e32 v9, vcc, 0, v7, vcc
	global_load_dword v21, v[8:9], off nt
	v_add_co_u32_e32 v8, vcc, s79, v6
	v_readlane_b32 s52, v244, 10
	s_nop 0
	v_addc_co_u32_e32 v9, vcc, 0, v7, vcc
	global_load_dword v22, v[8:9], off nt
	v_add_co_u32_e32 v8, vcc, s14, v6
	v_readlane_b32 s53, v244, 11
	s_nop 0
	v_addc_co_u32_e32 v9, vcc, 0, v7, vcc
	global_load_dword v23, v[8:9], off nt
	v_add_co_u32_e32 v8, vcc, s16, v6
	s_mov_b32 s16, 0x34000
	s_nop 0
	v_addc_co_u32_e32 v9, vcc, 0, v7, vcc
	global_load_dword v24, v[8:9], off nt
	v_add_co_u32_e32 v8, vcc, s16, v6
	s_mov_b32 s16, 0x38000
	s_nop 0
	v_addc_co_u32_e32 v9, vcc, 0, v7, vcc
	global_load_dword v25, v[8:9], off nt
	v_add_co_u32_e32 v8, vcc, s16, v6
	s_mov_b32 s16, 0x3c000
	s_nop 0
	v_addc_co_u32_e32 v9, vcc, 0, v7, vcc
	global_load_dword v26, v[8:9], off nt
	v_add_co_u32_e32 v8, vcc, s16, v6
	s_mov_b32 s16, 0x40000
	s_nop 0
	v_addc_co_u32_e32 v9, vcc, 0, v7, vcc
	global_load_dword v27, v[8:9], off nt
	v_add_co_u32_e32 v8, vcc, s16, v6
	s_mov_b32 s16, 0x44000
	s_nop 0
	v_addc_co_u32_e32 v9, vcc, 0, v7, vcc
	global_load_dword v28, v[8:9], off nt
	v_add_co_u32_e32 v8, vcc, s16, v6
	s_mov_b32 s16, 0x48000
	s_nop 0
	v_addc_co_u32_e32 v9, vcc, 0, v7, vcc
	global_load_dword v29, v[8:9], off nt
	v_add_co_u32_e32 v8, vcc, s16, v6
	s_mov_b32 s16, 0x4c000
	s_nop 0
	v_addc_co_u32_e32 v9, vcc, 0, v7, vcc
	global_load_dword v30, v[8:9], off nt
	v_add_co_u32_e32 v8, vcc, s16, v6
	s_mov_b32 s16, 0x50000
	s_nop 0
	v_addc_co_u32_e32 v9, vcc, 0, v7, vcc
	global_load_dword v31, v[8:9], off nt
	v_add_co_u32_e32 v8, vcc, s16, v6
	s_mov_b32 s16, 0x54000
	s_nop 0
	v_addc_co_u32_e32 v9, vcc, 0, v7, vcc
	global_load_dword v32, v[8:9], off nt
	v_add_co_u32_e32 v8, vcc, s16, v6
	s_mov_b32 s16, 0x5c000
	s_nop 0
	v_addc_co_u32_e32 v9, vcc, 0, v7, vcc
	global_load_dword v33, v[8:9], off nt
	v_add_co_u32_e32 v8, vcc, s64, v6
	v_readlane_b32 s54, v244, 12
	s_nop 0
	v_addc_co_u32_e32 v9, vcc, 0, v7, vcc
	global_load_dword v34, v[8:9], off nt
	v_add_co_u32_e32 v8, vcc, s16, v6
	s_mov_b32 s16, 0x60000
	s_nop 0
	v_addc_co_u32_e32 v9, vcc, 0, v7, vcc
	global_load_dword v35, v[8:9], off nt
	v_add_co_u32_e32 v8, vcc, s16, v6
	s_mov_b32 s16, 0x64000
	s_nop 0
	v_addc_co_u32_e32 v9, vcc, 0, v7, vcc
	global_load_dword v36, v[8:9], off nt
	v_add_co_u32_e32 v8, vcc, s16, v6
	s_mov_b32 s16, 0x68000
	s_nop 0
	v_addc_co_u32_e32 v9, vcc, 0, v7, vcc
	global_load_dword v37, v[8:9], off nt
	v_add_co_u32_e32 v8, vcc, s16, v6
	s_mov_b32 s16, 0x6c000
	s_nop 0
	v_addc_co_u32_e32 v9, vcc, 0, v7, vcc
	global_load_dword v38, v[8:9], off nt
	v_add_co_u32_e32 v8, vcc, s16, v6
	s_mov_b32 s16, 0x70000
	s_nop 0
	v_addc_co_u32_e32 v9, vcc, 0, v7, vcc
	global_load_dword v39, v[8:9], off nt
	v_add_co_u32_e32 v8, vcc, s16, v6
	s_mov_b32 s16, 0x74000
	s_nop 0
	v_addc_co_u32_e32 v9, vcc, 0, v7, vcc
	global_load_dword v40, v[8:9], off nt
	v_add_co_u32_e32 v8, vcc, s16, v6
	s_mov_b32 s16, 0x78000
	s_nop 0
	v_addc_co_u32_e32 v9, vcc, 0, v7, vcc
	global_load_dword v41, v[8:9], off nt
	v_add_co_u32_e32 v8, vcc, s16, v6
	s_mov_b32 s16, 0x7c000
	s_nop 0
	v_addc_co_u32_e32 v9, vcc, 0, v7, vcc
	v_add_co_u32_e32 v6, vcc, s16, v6
	global_load_dword v8, v[8:9], off nt
	s_nop 0
	v_addc_co_u32_e32 v7, vcc, 0, v7, vcc
	global_load_dword v6, v[6:7], off nt
	s_movk_i32 s16, 0x84
	v_mul_lo_u32 v7, v11, s16
	v_add3_u32 v7, s41, v66, v7
	v_add_u32_e32 v9, 0x400, v7
	s_waitcnt vmcnt(30)
; #define GAS __attribute__((address_space(1)))
; #define LAS __attribute__((address_space(3)))
; #define LDS_WAIT() asm volatile("s_waitcnt lgkmcnt(0)" ::: "memory")
; __device__ __forceinline__ unsigned pk2(float lo, float hi) { return f2bf(lo) | (f2bf(hi) << 16); }
;     ...
;       for (int i = 0; i < 32; ++i) scr[(2 * i + (lane >> 5)) * 33 + (lane & 31)] = wv[i]; }
;     LDS_WAIT(); asm volatile("" ::: "memory");
;     const int c = lane & 7;
;     const int r0 = (mode == 0) ? n0 : (256 * (n0 >> 7) + (n0 & 127) + (mode == 2 ? 128 : 0));
; #pragma unroll
;     for (int j = 0; j < 4; ++j) { const int n = (lane >> 3) + 8 * j; const LAS float* s = scr + (8 * c) * 33 + n;
;         v4u o; o.x = pk2(s[0 * 33], s[1 * 33]); o.y = pk2(s[2 * 33], s[3 * 33]); o.z = pk2(s[4 * 33], s[5 * 33]); o.w = pk2(s[6 * 33], s[7 * 33]);
;         *(GAS v4u*)(WT + (size_t)(r0 + n) * ldt + k0 + 8 * c) = o; }
;     LDS_WAIT(); asm volatile("" ::: "memory");
	ds_write2_b32 v7, v12, v13 offset1:66
	s_waitcnt vmcnt(28)
	ds_write2_b32 v7, v14, v15 offset0:132 offset1:198
	s_waitcnt vmcnt(26)
	ds_write2_b32 v9, v16, v17 offset0:8 offset1:74
	s_waitcnt vmcnt(24)
	ds_write2_b32 v9, v18, v19 offset0:140 offset1:206
	v_add_u32_e32 v9, 0x800, v7
	s_waitcnt vmcnt(22)
	ds_write2_b32 v9, v20, v21 offset0:16 offset1:82
	s_waitcnt vmcnt(20)
	ds_write2_b32 v9, v22, v23 offset0:148 offset1:214
	v_add_u32_e32 v9, 0xc00, v7
	s_waitcnt vmcnt(18)
	ds_write2_b32 v9, v24, v25 offset0:24 offset1:90
	s_waitcnt vmcnt(16)
	ds_write2_b32 v9, v26, v27 offset0:156 offset1:222
	v_add_u32_e32 v9, 0x1000, v7
	s_waitcnt vmcnt(14)
	ds_write2_b32 v9, v28, v29 offset0:32 offset1:98
	s_waitcnt vmcnt(12)
	ds_write2_b32 v9, v30, v31 offset0:164 offset1:230
	v_add_u32_e32 v9, 0x1400, v7
	s_waitcnt vmcnt(10)
	ds_write2_b32 v9, v32, v33 offset0:40 offset1:106
	s_waitcnt vmcnt(8)
	ds_write2_b32 v9, v34, v35 offset0:172 offset1:238
	v_add_u32_e32 v9, 0x1800, v7
	v_add_u32_e32 v7, 0x1c00, v7
	s_waitcnt vmcnt(6)
	ds_write2_b32 v9, v36, v37 offset0:48 offset1:114
	s_waitcnt vmcnt(4)
	ds_write2_b32 v9, v38, v39 offset0:180 offset1:246
	s_waitcnt vmcnt(2)
	ds_write2_b32 v7, v40, v41 offset0:56 offset1:122
	s_waitcnt vmcnt(0)
	ds_write2_b32 v7, v8, v6 offset0:188 offset1:254
	v_lshlrev_b32_e32 v6, 3, v10
	v_ashrrev_i32_e32 v28, 3, v10
	v_and_b32_e32 v6, 56, v6
	s_waitcnt lgkmcnt(0)
	v_mul_u32_u24_e32 v8, 0x84, v6
	v_lshlrev_b32_e32 v9, 2, v28
	v_add3_u32 v30, s41, v8, v9
	ds_read2_b32 v[12:13], v30 offset0:33 offset1:41
	ds_read2_b32 v[14:15], v30 offset1:8
	ds_read2_b32 v[16:17], v30 offset0:66 offset1:74
	ds_read2_b32 v[18:19], v30 offset0:99 offset1:107
	ds_read2_b32 v[20:21], v30 offset0:132 offset1:140
	ds_read2_b32 v[22:23], v30 offset0:165 offset1:173
	ds_read2_b32 v[24:25], v30 offset0:198 offset1:206
	ds_read2_b32 v[26:27], v30 offset0:231 offset1:239
	s_waitcnt lgkmcnt(7)
	v_bfe_u32 v9, v12, 16, 1
	s_waitcnt lgkmcnt(6)
	v_bfe_u32 v8, v14, 16, 1
	v_add3_u32 v8, v14, v8, s3
	v_lshrrev_b32_e32 v8, 16, v8
	v_add3_u32 v9, v12, v9, s3
	v_and_or_b32 v8, v9, s66, v8
	s_waitcnt lgkmcnt(5)
	v_bfe_u32 v9, v16, 16, 1
	v_add3_u32 v9, v16, v9, s3
	s_waitcnt lgkmcnt(4)
	v_bfe_u32 v10, v18, 16, 1
	v_lshrrev_b32_e32 v9, 16, v9
	v_add3_u32 v10, v18, v10, s3
	v_and_or_b32 v9, v10, s66, v9
	s_waitcnt lgkmcnt(3)
	v_bfe_u32 v10, v20, 16, 1
	v_add3_u32 v10, v20, v10, s3
	s_waitcnt lgkmcnt(2)
	v_bfe_u32 v11, v22, 16, 1
	v_lshrrev_b32_e32 v10, 16, v10
	v_add3_u32 v11, v22, v11, s3
	v_and_or_b32 v10, v11, s66, v10
	s_waitcnt lgkmcnt(1)
	v_bfe_u32 v11, v24, 16, 1
	v_lshlrev_b32_e32 v66, 1, v6
	v_add3_u32 v11, v24, v11, s3
	s_waitcnt lgkmcnt(0)
	v_bfe_u32 v12, v26, 16, 1
	v_lshl_add_u64 v[6:7], s[0:1], 0, v[66:67]
	v_lshrrev_b32_e32 v11, 16, v11
	v_add3_u32 v12, v26, v12, s3
	v_add_u32_e32 v31, s26, v28
	s_movk_i32 s16, 0x2c00
	v_and_or_b32 v11, v12, s66, v11
	v_mad_i64_i32 v[28:29], s[26:27], v31, s16, v[6:7]
	global_store_dwordx4 v[28:29], v[8:11], off
	v_bfe_u32 v12, v27, 16, 1
	v_add3_u32 v12, v27, v12, s3
	v_bfe_u32 v8, v15, 16, 1
	v_add3_u32 v8, v15, v8, s3
	v_bfe_u32 v9, v13, 16, 1
	v_lshrrev_b32_e32 v8, 16, v8
	v_add3_u32 v9, v13, v9, s3
	v_and_or_b32 v8, v9, s66, v8
	v_bfe_u32 v9, v17, 16, 1
	v_add3_u32 v9, v17, v9, s3
	v_bfe_u32 v10, v19, 16, 1
	v_lshrrev_b32_e32 v9, 16, v9
	v_add3_u32 v10, v19, v10, s3
	v_and_or_b32 v9, v10, s66, v9
	v_bfe_u32 v10, v21, 16, 1
	v_add3_u32 v10, v21, v10, s3
	v_bfe_u32 v11, v23, 16, 1
	v_lshrrev_b32_e32 v10, 16, v10
	v_add3_u32 v11, v23, v11, s3
	v_and_or_b32 v10, v11, s66, v10
	v_bfe_u32 v11, v25, 16, 1
	v_add3_u32 v11, v25, v11, s3
	v_lshrrev_b32_e32 v11, 16, v11
	v_and_or_b32 v11, v12, s66, v11
	v_add_u32_e32 v12, 8, v31
	v_mad_i64_i32 v[12:13], s[26:27], v12, s16, v[6:7]
	global_store_dwordx4 v[12:13], v[8:11], off
	ds_read2_b32 v[12:13], v30 offset0:49 offset1:57
	ds_read2_b32 v[14:15], v30 offset0:16 offset1:24
	ds_read2_b32 v[16:17], v30 offset0:82 offset1:90
	ds_read2_b32 v[18:19], v30 offset0:115 offset1:123
	ds_read2_b32 v[20:21], v30 offset0:148 offset1:156
	ds_read2_b32 v[22:23], v30 offset0:181 offset1:189
	ds_read2_b32 v[24:25], v30 offset0:214 offset1:222
	ds_read2_b32 v[26:27], v30 offset0:247 offset1:255
	s_waitcnt lgkmcnt(7)
	v_bfe_u32 v9, v12, 16, 1
	s_waitcnt lgkmcnt(6)
	v_bfe_u32 v8, v14, 16, 1
	v_add3_u32 v8, v14, v8, s3
	v_lshrrev_b32_e32 v8, 16, v8
	v_add3_u32 v9, v12, v9, s3
	v_and_or_b32 v8, v9, s66, v8
	s_waitcnt lgkmcnt(5)
	v_bfe_u32 v9, v16, 16, 1
	v_add3_u32 v9, v16, v9, s3
	s_waitcnt lgkmcnt(4)
	v_bfe_u32 v10, v18, 16, 1
	v_lshrrev_b32_e32 v9, 16, v9
	v_add3_u32 v10, v18, v10, s3
	v_and_or_b32 v9, v10, s66, v9
	s_waitcnt lgkmcnt(3)
	v_bfe_u32 v10, v20, 16, 1
	v_add3_u32 v10, v20, v10, s3
	s_waitcnt lgkmcnt(2)
	v_bfe_u32 v11, v22, 16, 1
	v_lshrrev_b32_e32 v10, 16, v10
	v_add3_u32 v11, v22, v11, s3
	v_and_or_b32 v10, v11, s66, v10
	s_waitcnt lgkmcnt(1)
	v_bfe_u32 v11, v24, 16, 1
	v_add3_u32 v11, v24, v11, s3
	s_waitcnt lgkmcnt(0)
	v_bfe_u32 v12, v26, 16, 1
	v_lshrrev_b32_e32 v11, 16, v11
	v_add3_u32 v12, v26, v12, s3
	v_and_or_b32 v11, v12, s66, v11
	v_add_u32_e32 v12, 16, v31
	v_mad_i64_i32 v[28:29], s[26:27], v12, s16, v[6:7]
	global_store_dwordx4 v[28:29], v[8:11], off
	v_bfe_u32 v12, v27, 16, 1
	v_add3_u32 v12, v27, v12, s3
	v_bfe_u32 v8, v15, 16, 1
	v_add3_u32 v8, v15, v8, s3
	v_bfe_u32 v9, v13, 16, 1
	v_lshrrev_b32_e32 v8, 16, v8
	v_add3_u32 v9, v13, v9, s3
	v_and_or_b32 v8, v9, s66, v8
	v_bfe_u32 v9, v17, 16, 1
	v_add3_u32 v9, v17, v9, s3
	v_bfe_u32 v10, v19, 16, 1
	v_lshrrev_b32_e32 v9, 16, v9
	v_add3_u32 v10, v19, v10, s3
	v_and_or_b32 v9, v10, s66, v9
	v_bfe_u32 v10, v21, 16, 1
	v_add3_u32 v10, v21, v10, s3
	v_bfe_u32 v11, v23, 16, 1
	v_lshrrev_b32_e32 v10, 16, v10
	v_add3_u32 v11, v23, v11, s3
	v_and_or_b32 v10, v11, s66, v10
	v_bfe_u32 v11, v25, 16, 1
	v_add3_u32 v11, v25, v11, s3
	v_lshrrev_b32_e32 v11, 16, v11
	v_and_or_b32 v11, v12, s66, v11
	v_add_u32_e32 v12, 24, v31
	v_mad_i64_i32 v[6:7], s[26:27], v12, s16, v[6:7]
	global_store_dwordx4 v[6:7], v[8:11], off
	s_waitcnt lgkmcnt(0)
	v_readlane_b32 s55, v244, 13
	v_readlane_b32 s56, v244, 14
	v_readlane_b32 s57, v244, 15
	s_mov_b64 s[58:59], 0

;     if (ldt == 0) ldt = K;
;     asm volatile("" : "+v"(lane));
;     const int kb = item / nblk, nb = item % nblk, k0 = 64 * kb, n0 = 32 * nb;
;     { float wv[32];
;       const float* wp = W + (size_t)(k0 + (lane >> 5)) * ldw + n0 + (lane & 31);
; #pragma unroll
;       for (int i = 0; i < 32; ++i) wv[i] = wp[(size_t)(2 * i) * ldw];
; #pragma unroll
;       for (int i = 0; i < 32; ++i) scr[(2 * i + (lane >> 5)) * 33 + (lane & 31)] = wv[i]; }
; __device__ __forceinline__ void transpose_late(const Args& a, Frame& F, LAS float* scr, int r) {
;     ...
;     if (r < IT_PU) { p0_transpose_item(a.in[I_WPU], D, DPLE, WPU, 0, D / 32, scr, r, F.lane); return; } r -= IT_PU;
.LBB0_1013:
	s_andn2_b64 vcc, exec, s[58:59]
	s_cbranch_vccnz .LBB0_1015
	v_mov_b32_e32 v10, v145
	v_readlane_b32 s44, v245, 0
	v_ashrrev_i32_e32 v11, 5, v10
	v_add_u32_e32 v6, s63, v11
	v_ashrrev_i32_e32 v7, 31, v6
	s_and_b32 s26, s95, 0x7e0
	v_lshlrev_b64 v[6:7], 13, v[6:7]
	v_readlane_b32 s50, v245, 6
	v_readlane_b32 s51, v245, 7
	s_lshl_b32 s86, s26, 2
	v_lshlrev_b32_e32 v8, 2, v10
	v_lshl_add_u64 v[6:7], s[50:51], 0, v[6:7]
	v_lshl_add_u64 v[6:7], v[6:7], 0, s[86:87]
	v_and_b32_e32 v66, 0x7c, v8
	v_lshl_add_u64 v[6:7], v[6:7], 0, v[66:67]
	v_add_co_u32_e32 v8, vcc, s83, v6
	global_load_dword v12, v[6:7], off nt
	s_nop 0
	v_addc_co_u32_e32 v9, vcc, 0, v7, vcc
	global_load_dword v13, v[8:9], off nt
	v_add_co_u32_e32 v8, vcc, s85, v6
	s_mov_b32 s16, 0x30000
	s_nop 0
	v_addc_co_u32_e32 v9, vcc, 0, v7, vcc
	global_load_dword v14, v[8:9], off nt
	v_add_co_u32_e32 v8, vcc, s72, v6
	v_readlane_b32 s45, v245, 1
	s_nop 0
	v_addc_co_u32_e32 v9, vcc, 0, v7, vcc
	global_load_dword v15, v[8:9], off nt
	v_add_co_u32_e32 v8, vcc, s73, v6
	v_readlane_b32 s46, v245, 2
	s_nop 0
	v_addc_co_u32_e32 v9, vcc, 0, v7, vcc
	global_load_dword v16, v[8:9], off nt
	v_add_co_u32_e32 v8, vcc, s74, v6
	v_readlane_b32 s47, v245, 3
	s_nop 0
	v_addc_co_u32_e32 v9, vcc, 0, v7, vcc
	global_load_dword v17, v[8:9], off nt
	v_add_co_u32_e32 v8, vcc, s75, v6
	v_readlane_b32 s48, v245, 4
	s_nop 0
	v_addc_co_u32_e32 v9, vcc, 0, v7, vcc
	global_load_dword v18, v[8:9], off nt
	v_add_co_u32_e32 v8, vcc, s88, v6
	v_readlane_b32 s49, v245, 5
	s_nop 0
	v_addc_co_u32_e32 v9, vcc, 0, v7, vcc
	global_load_dword v19, v[8:9], off nt
	v_add_co_u32_e32 v8, vcc, s15, v6
	s_nop 1
	v_addc_co_u32_e32 v9, vcc, 0, v7, vcc
	global_load_dword v20, v[8:9], off nt
	v_add_co_u32_e32 v8, vcc, s78, v6
	s_nop 1
	v_addc_co_u32_e32 v9, vcc, 0, v7, vcc
	global_load_dword v21, v[8:9], off nt
	v_add_co_u32_e32 v8, vcc, s79, v6
	s_nop 1
	v_addc_co_u32_e32 v9, vcc, 0, v7, vcc
	global_load_dword v22, v[8:9], off nt
	v_add_co_u32_e32 v8, vcc, s14, v6
	s_nop 1
	v_addc_co_u32_e32 v9, vcc, 0, v7, vcc
	global_load_dword v23, v[8:9], off nt
	v_add_co_u32_e32 v8, vcc, s16, v6
	s_mov_b32 s16, 0x34000
	s_nop 0
	v_addc_co_u32_e32 v9, vcc, 0, v7, vcc
	global_load_dword v24, v[8:9], off nt
	v_add_co_u32_e32 v8, vcc, s16, v6
	s_mov_b32 s16, 0x38000
	s_nop 0
	v_addc_co_u32_e32 v9, vcc, 0, v7, vcc
	global_load_dword v25, v[8:9], off nt
	v_add_co_u32_e32 v8, vcc, s16, v6
	s_mov_b32 s16, 0x3c000
	s_nop 0
	v_addc_co_u32_e32 v9, vcc, 0, v7, vcc
	global_load_dword v26, v[8:9], off nt
	v_add_co_u32_e32 v8, vcc, s16, v6
	s_mov_b32 s16, 0x40000
	s_nop 0
	v_addc_co_u32_e32 v9, vcc, 0, v7, vcc
	global_load_dword v27, v[8:9], off nt
	v_add_co_u32_e32 v8, vcc, s16, v6
	s_mov_b32 s16, 0x44000
	s_nop 0
	v_addc_co_u32_e32 v9, vcc, 0, v7, vcc
	global_load_dword v28, v[8:9], off nt
	v_add_co_u32_e32 v8, vcc, s16, v6
	s_mov_b32 s16, 0x48000
	s_nop 0
	v_addc_co_u32_e32 v9, vcc, 0, v7, vcc
	global_load_dword v29, v[8:9], off nt
	v_add_co_u32_e32 v8, vcc, s16, v6
	s_mov_b32 s16, 0x4c000
	s_nop 0
	v_addc_co_u32_e32 v9, vcc, 0, v7, vcc
	global_load_dword v30, v[8:9], off nt
	v_add_co_u32_e32 v8, vcc, s16, v6
	s_mov_b32 s16, 0x50000
	s_nop 0
	v_addc_co_u32_e32 v9, vcc, 0, v7, vcc
	global_load_dword v31, v[8:9], off nt
	v_add_co_u32_e32 v8, vcc, s16, v6
	s_mov_b32 s16, 0x54000
	s_nop 0
	v_addc_co_u32_e32 v9, vcc, 0, v7, vcc
	global_load_dword v32, v[8:9], off nt
	v_add_co_u32_e32 v8, vcc, s16, v6
	s_mov_b32 s16, 0x5c000
	s_nop 0
	v_addc_co_u32_e32 v9, vcc, 0, v7, vcc
	global_load_dword v33, v[8:9], off nt
	v_add_co_u32_e32 v8, vcc, s64, v6
	s_nop 1
	v_addc_co_u32_e32 v9, vcc, 0, v7, vcc
	global_load_dword v34, v[8:9], off nt
	v_add_co_u32_e32 v8, vcc, s16, v6
	s_mov_b32 s16, 0x60000
	s_nop 0
	v_addc_co_u32_e32 v9, vcc, 0, v7, vcc
	global_load_dword v35, v[8:9], off nt
	v_add_co_u32_e32 v8, vcc, s16, v6
	s_mov_b32 s16, 0x64000
	s_nop 0
	v_addc_co_u32_e32 v9, vcc, 0, v7, vcc
	global_load_dword v36, v[8:9], off nt
	v_add_co_u32_e32 v8, vcc, s16, v6
	s_mov_b32 s16, 0x68000
	s_nop 0
	v_addc_co_u32_e32 v9, vcc, 0, v7, vcc
	global_load_dword v37, v[8:9], off nt
	v_add_co_u32_e32 v8, vcc, s16, v6
	s_mov_b32 s16, 0x6c000
	s_nop 0
	v_addc_co_u32_e32 v9, vcc, 0, v7, vcc
	global_load_dword v38, v[8:9], off nt
	v_add_co_u32_e32 v8, vcc, s16, v6
	s_mov_b32 s16, 0x70000
	s_nop 0
	v_addc_co_u32_e32 v9, vcc, 0, v7, vcc
	global_load_dword v39, v[8:9], off nt
	v_add_co_u32_e32 v8, vcc, s16, v6
	s_mov_b32 s16, 0x74000
	s_nop 0
	v_addc_co_u32_e32 v9, vcc, 0, v7, vcc
	global_load_dword v40, v[8:9], off nt
	v_add_co_u32_e32 v8, vcc, s16, v6
	s_mov_b32 s16, 0x78000
	s_nop 0
	v_addc_co_u32_e32 v9, vcc, 0, v7, vcc
	global_load_dword v41, v[8:9], off nt
	v_add_co_u32_e32 v8, vcc, s16, v6
	s_mov_b32 s16, 0x7c000
	s_nop 0
	v_addc_co_u32_e32 v9, vcc, 0, v7, vcc
	v_add_co_u32_e32 v6, vcc, s16, v6
	global_load_dword v8, v[8:9], off nt
	s_nop 0
	v_addc_co_u32_e32 v7, vcc, 0, v7, vcc
	global_load_dword v6, v[6:7], off nt
	s_movk_i32 s16, 0x84
	v_mul_lo_u32 v7, v11, s16
	v_add3_u32 v7, s41, v66, v7
	v_add_u32_e32 v9, 0x400, v7
	s_waitcnt vmcnt(30)
	ds_write2_b32 v7, v12, v13 offset1:66
	s_waitcnt vmcnt(28)
	ds_write2_b32 v7, v14, v15 offset0:132 offset1:198
	s_waitcnt vmcnt(26)
	ds_write2_b32 v9, v16, v17 offset0:8 offset1:74
	s_waitcnt vmcnt(24)
	ds_write2_b32 v9, v18, v19 offset0:140 offset1:206
	v_add_u32_e32 v9, 0x800, v7
	s_waitcnt vmcnt(22)
	ds_write2_b32 v9, v20, v21 offset0:16 offset1:82
	s_waitcnt vmcnt(20)
	ds_write2_b32 v9, v22, v23 offset0:148 offset1:214
	v_add_u32_e32 v9, 0xc00, v7
	s_waitcnt vmcnt(18)
	ds_write2_b32 v9, v24, v25 offset0:24 offset1:90
	s_waitcnt vmcnt(16)
; #define GAS __attribute__((address_space(1)))
; #define LAS __attribute__((address_space(3)))
; #define LDS_WAIT() asm volatile("s_waitcnt lgkmcnt(0)" ::: "memory")
; __device__ __forceinline__ unsigned pk2(float lo, float hi) { return f2bf(lo) | (f2bf(hi) << 16); }
;     ...
;       for (int i = 0; i < 32; ++i) scr[(2 * i + (lane >> 5)) * 33 + (lane & 31)] = wv[i]; }
;     LDS_WAIT(); asm volatile("" ::: "memory");
;     const int c = lane & 7;
;     const int r0 = (mode == 0) ? n0 : (256 * (n0 >> 7) + (n0 & 127) + (mode == 2 ? 128 : 0));
; #pragma unroll
;     for (int j = 0; j < 4; ++j) { const int n = (lane >> 3) + 8 * j; const LAS float* s = scr + (8 * c) * 33 + n;
;         v4u o; o.x = pk2(s[0 * 33], s[1 * 33]); o.y = pk2(s[2 * 33], s[3 * 33]); o.z = pk2(s[4 * 33], s[5 * 33]); o.w = pk2(s[6 * 33], s[7 * 33]);
;         *(GAS v4u*)(WT + (size_t)(r0 + n) * ldt + k0 + 8 * c) = o; }
;     LDS_WAIT(); asm volatile("" ::: "memory");
	ds_write2_b32 v9, v26, v27 offset0:156 offset1:222
	v_add_u32_e32 v9, 0x1000, v7
	s_waitcnt vmcnt(14)
	ds_write2_b32 v9, v28, v29 offset0:32 offset1:98
	s_waitcnt vmcnt(12)
	ds_write2_b32 v9, v30, v31 offset0:164 offset1:230
	v_add_u32_e32 v9, 0x1400, v7
	s_waitcnt vmcnt(10)
	ds_write2_b32 v9, v32, v33 offset0:40 offset1:106
	s_waitcnt vmcnt(8)
	ds_write2_b32 v9, v34, v35 offset0:172 offset1:238
	v_add_u32_e32 v9, 0x1800, v7
	v_add_u32_e32 v7, 0x1c00, v7
	s_waitcnt vmcnt(6)
	ds_write2_b32 v9, v36, v37 offset0:48 offset1:114
	s_waitcnt vmcnt(4)
	ds_write2_b32 v9, v38, v39 offset0:180 offset1:246
	s_waitcnt vmcnt(2)
	ds_write2_b32 v7, v40, v41 offset0:56 offset1:122
	s_waitcnt vmcnt(0)
	ds_write2_b32 v7, v8, v6 offset0:188 offset1:254
	v_lshlrev_b32_e32 v6, 3, v10
	v_ashrrev_i32_e32 v28, 3, v10
	v_and_b32_e32 v6, 56, v6
	s_waitcnt lgkmcnt(0)
	v_mul_u32_u24_e32 v8, 0x84, v6
	v_lshlrev_b32_e32 v9, 2, v28
	v_add3_u32 v32, s41, v8, v9
	ds_read2_b32 v[12:13], v32 offset0:33 offset1:41
	ds_read2_b32 v[14:15], v32 offset1:8
	ds_read2_b32 v[16:17], v32 offset0:66 offset1:74
	ds_read2_b32 v[18:19], v32 offset0:99 offset1:107
	ds_read2_b32 v[20:21], v32 offset0:132 offset1:140
	ds_read2_b32 v[22:23], v32 offset0:165 offset1:173
	ds_read2_b32 v[24:25], v32 offset0:198 offset1:206
	ds_read2_b32 v[26:27], v32 offset0:231 offset1:239
	s_waitcnt lgkmcnt(7)
	v_bfe_u32 v9, v12, 16, 1
	s_waitcnt lgkmcnt(6)
	v_bfe_u32 v8, v14, 16, 1
	v_add3_u32 v8, v14, v8, s3
	v_lshrrev_b32_e32 v8, 16, v8
	v_add3_u32 v9, v12, v9, s3
	v_and_or_b32 v8, v9, s66, v8
	s_waitcnt lgkmcnt(5)
	v_bfe_u32 v9, v16, 16, 1
	v_add3_u32 v9, v16, v9, s3
	s_waitcnt lgkmcnt(4)
	v_bfe_u32 v10, v18, 16, 1
	v_lshrrev_b32_e32 v9, 16, v9
	v_add3_u32 v10, v18, v10, s3
	v_and_or_b32 v9, v10, s66, v9
	s_waitcnt lgkmcnt(3)
	v_bfe_u32 v10, v20, 16, 1
	v_add3_u32 v10, v20, v10, s3
	s_waitcnt lgkmcnt(2)
	v_bfe_u32 v11, v22, 16, 1
	v_lshrrev_b32_e32 v10, 16, v10
	v_add3_u32 v11, v22, v11, s3
	v_and_or_b32 v10, v11, s66, v10
	s_waitcnt lgkmcnt(1)
	v_bfe_u32 v11, v24, 16, 1
	v_add_u32_e32 v28, s26, v28
	v_lshlrev_b32_e32 v66, 1, v6
	v_add3_u32 v11, v24, v11, s3
	s_waitcnt lgkmcnt(0)
	v_bfe_u32 v12, v26, 16, 1
	v_ashrrev_i32_e32 v29, 31, v28
	v_lshl_add_u64 v[6:7], s[6:7], 0, v[66:67]
	v_lshrrev_b32_e32 v11, 16, v11
	v_add3_u32 v12, v26, v12, s3
	v_lshlrev_b64 v[30:31], 9, v[28:29]
	v_and_or_b32 v11, v12, s66, v11
	v_lshl_add_u64 v[30:31], v[6:7], 0, v[30:31]
	global_store_dwordx4 v[30:31], v[8:11], off
	v_bfe_u32 v12, v27, 16, 1
	v_add3_u32 v12, v27, v12, s3
	v_bfe_u32 v8, v15, 16, 1
	v_add3_u32 v8, v15, v8, s3
	v_bfe_u32 v9, v13, 16, 1
	v_lshrrev_b32_e32 v8, 16, v8
	v_add3_u32 v9, v13, v9, s3
	v_and_or_b32 v8, v9, s66, v8
	v_bfe_u32 v9, v17, 16, 1
	v_add3_u32 v9, v17, v9, s3
	v_bfe_u32 v10, v19, 16, 1
	v_lshrrev_b32_e32 v9, 16, v9
	v_add3_u32 v10, v19, v10, s3
	v_and_or_b32 v9, v10, s66, v9
	v_bfe_u32 v10, v21, 16, 1
	v_add3_u32 v10, v21, v10, s3
	v_bfe_u32 v11, v23, 16, 1
	v_lshrrev_b32_e32 v10, 16, v10
	v_add3_u32 v11, v23, v11, s3
	v_and_or_b32 v10, v11, s66, v10
	v_bfe_u32 v11, v25, 16, 1
	v_add3_u32 v11, v25, v11, s3
	v_lshrrev_b32_e32 v11, 16, v11
	v_and_or_b32 v11, v12, s66, v11
	v_add_u32_e32 v12, 8, v28
	v_ashrrev_i32_e32 v13, 31, v12
	v_lshlrev_b64 v[12:13], 9, v[12:13]
	v_lshl_add_u64 v[12:13], v[6:7], 0, v[12:13]
	global_store_dwordx4 v[12:13], v[8:11], off
	ds_read2_b32 v[12:13], v32 offset0:49 offset1:57
	ds_read2_b32 v[14:15], v32 offset0:16 offset1:24
	ds_read2_b32 v[16:17], v32 offset0:82 offset1:90
	ds_read2_b32 v[18:19], v32 offset0:115 offset1:123
	ds_read2_b32 v[20:21], v32 offset0:148 offset1:156
	ds_read2_b32 v[22:23], v32 offset0:181 offset1:189
	ds_read2_b32 v[24:25], v32 offset0:214 offset1:222
	ds_read2_b32 v[26:27], v32 offset0:247 offset1:255
	s_waitcnt lgkmcnt(7)
	v_bfe_u32 v9, v12, 16, 1
	s_waitcnt lgkmcnt(6)
	v_bfe_u32 v8, v14, 16, 1
	v_add3_u32 v8, v14, v8, s3
	v_lshrrev_b32_e32 v8, 16, v8
	v_add3_u32 v9, v12, v9, s3
	v_and_or_b32 v8, v9, s66, v8
	s_waitcnt lgkmcnt(5)
	v_bfe_u32 v9, v16, 16, 1
	v_add3_u32 v9, v16, v9, s3
	s_waitcnt lgkmcnt(4)
	v_bfe_u32 v10, v18, 16, 1
	v_lshrrev_b32_e32 v9, 16, v9
	v_add3_u32 v10, v18, v10, s3
	v_and_or_b32 v9, v10, s66, v9
	s_waitcnt lgkmcnt(3)
	v_bfe_u32 v10, v20, 16, 1
	v_add3_u32 v10, v20, v10, s3
	s_waitcnt lgkmcnt(2)
	v_bfe_u32 v11, v22, 16, 1
	v_lshrrev_b32_e32 v10, 16, v10
	v_add3_u32 v11, v22, v11, s3
	v_and_or_b32 v10, v11, s66, v10
	s_waitcnt lgkmcnt(1)
	v_bfe_u32 v11, v24, 16, 1
	v_add_u32_e32 v30, 16, v28
	v_add3_u32 v11, v24, v11, s3
	s_waitcnt lgkmcnt(0)
	v_bfe_u32 v12, v26, 16, 1
	v_ashrrev_i32_e32 v31, 31, v30
	v_lshrrev_b32_e32 v11, 16, v11
	v_add3_u32 v12, v26, v12, s3
	v_lshlrev_b64 v[30:31], 9, v[30:31]
	v_and_or_b32 v11, v12, s66, v11
	v_lshl_add_u64 v[30:31], v[6:7], 0, v[30:31]
	global_store_dwordx4 v[30:31], v[8:11], off
	v_bfe_u32 v12, v27, 16, 1
	v_add3_u32 v12, v27, v12, s3
	v_bfe_u32 v8, v15, 16, 1
	v_add3_u32 v8, v15, v8, s3
	v_bfe_u32 v9, v13, 16, 1
	v_lshrrev_b32_e32 v8, 16, v8
	v_add3_u32 v9, v13, v9, s3
	v_and_or_b32 v8, v9, s66, v8
	v_bfe_u32 v9, v17, 16, 1
	v_add3_u32 v9, v17, v9, s3
	v_bfe_u32 v10, v19, 16, 1
	v_lshrrev_b32_e32 v9, 16, v9
	v_add3_u32 v10, v19, v10, s3
	v_and_or_b32 v9, v10, s66, v9
	v_bfe_u32 v10, v21, 16, 1
	v_add3_u32 v10, v21, v10, s3
	v_bfe_u32 v11, v23, 16, 1
	v_lshrrev_b32_e32 v10, 16, v10
	v_add3_u32 v11, v23, v11, s3
	v_and_or_b32 v10, v11, s66, v10
	v_bfe_u32 v11, v25, 16, 1
	v_add3_u32 v11, v25, v11, s3
	v_lshrrev_b32_e32 v11, 16, v11
	v_and_or_b32 v11, v12, s66, v11
	v_add_u32_e32 v12, 24, v28
	v_ashrrev_i32_e32 v13, 31, v12
	v_lshlrev_b64 v[12:13], 9, v[12:13]
	v_lshl_add_u64 v[6:7], v[6:7], 0, v[12:13]
	global_store_dwordx4 v[6:7], v[8:11], off
	s_waitcnt lgkmcnt(0)

;     if (ldt == 0) ldt = K;
;     asm volatile("" : "+v"(lane));
;     const int kb = item / nblk, nb = item % nblk, k0 = 64 * kb, n0 = 32 * nb;
;     { float wv[32];
;       const float* wp = W + (size_t)(k0 + (lane >> 5)) * ldw + n0 + (lane & 31);
; #pragma unroll
;       for (int i = 0; i < 32; ++i) wv[i] = wp[(size_t)(2 * i) * ldw];
; #pragma unroll
;       for (int i = 0; i < 32; ++i) scr[(2 * i + (lane >> 5)) * 33 + (lane & 31)] = wv[i]; }
; __device__ __forceinline__ void transpose_late(const Args& a, Frame& F, LAS float* scr, int r) {
;     ...
;     if (r < IT_SQ) { p0_transpose_item(a.in[I_WPG], D, D, WPG, 0, D / 32, scr, r, F.lane); return; } r -= IT_SQ;
.LBB0_1016:
	s_andn2_b64 vcc, exec, s[58:59]
	s_cbranch_vccnz .LBB0_1018
	v_mov_b32_e32 v10, v145
	v_readlane_b32 s44, v245, 0
	v_ashrrev_i32_e32 v11, 5, v10
	v_add_u32_e32 v6, s92, v11
	v_ashrrev_i32_e32 v7, 31, v6
	s_and_b32 s26, s95, 0x7e0
	v_lshlrev_b64 v[6:7], 13, v[6:7]
	v_readlane_b32 s48, v245, 4
	v_readlane_b32 s49, v245, 5
	s_lshl_b32 s86, s26, 2
	v_lshlrev_b32_e32 v8, 2, v10
	v_lshl_add_u64 v[6:7], s[48:49], 0, v[6:7]
	v_lshl_add_u64 v[6:7], v[6:7], 0, s[86:87]
	v_and_b32_e32 v66, 0x7c, v8
	v_lshl_add_u64 v[6:7], v[6:7], 0, v[66:67]
	v_add_co_u32_e32 v8, vcc, s83, v6
	global_load_dword v12, v[6:7], off nt
	s_nop 0
	v_addc_co_u32_e32 v9, vcc, 0, v7, vcc
	global_load_dword v13, v[8:9], off nt
	v_add_co_u32_e32 v8, vcc, s85, v6
	s_mov_b32 s16, 0x30000
	s_nop 0
	v_addc_co_u32_e32 v9, vcc, 0, v7, vcc
	global_load_dword v14, v[8:9], off nt
	v_add_co_u32_e32 v8, vcc, s72, v6
	v_readlane_b32 s45, v245, 1
	s_nop 0
	v_addc_co_u32_e32 v9, vcc, 0, v7, vcc
	global_load_dword v15, v[8:9], off nt
	v_add_co_u32_e32 v8, vcc, s73, v6
	v_readlane_b32 s46, v245, 2
	s_nop 0
	v_addc_co_u32_e32 v9, vcc, 0, v7, vcc
	global_load_dword v16, v[8:9], off nt
	v_add_co_u32_e32 v8, vcc, s74, v6
	v_readlane_b32 s47, v245, 3
	s_nop 0
	v_addc_co_u32_e32 v9, vcc, 0, v7, vcc
	global_load_dword v17, v[8:9], off nt
	v_add_co_u32_e32 v8, vcc, s75, v6
	v_readlane_b32 s50, v245, 6
	s_nop 0
	v_addc_co_u32_e32 v9, vcc, 0, v7, vcc
	global_load_dword v18, v[8:9], off nt
	v_add_co_u32_e32 v8, vcc, s88, v6
	v_readlane_b32 s51, v245, 7
	s_nop 0
	v_addc_co_u32_e32 v9, vcc, 0, v7, vcc
	global_load_dword v19, v[8:9], off nt
	v_add_co_u32_e32 v8, vcc, s15, v6
	s_nop 1
	v_addc_co_u32_e32 v9, vcc, 0, v7, vcc
	global_load_dword v20, v[8:9], off nt
	v_add_co_u32_e32 v8, vcc, s78, v6
	s_nop 1
	v_addc_co_u32_e32 v9, vcc, 0, v7, vcc
	global_load_dword v21, v[8:9], off nt
	v_add_co_u32_e32 v8, vcc, s79, v6
	s_nop 1
	v_addc_co_u32_e32 v9, vcc, 0, v7, vcc
	global_load_dword v22, v[8:9], off nt
	v_add_co_u32_e32 v8, vcc, s14, v6
	s_nop 1
	v_addc_co_u32_e32 v9, vcc, 0, v7, vcc
	global_load_dword v23, v[8:9], off nt
	v_add_co_u32_e32 v8, vcc, s16, v6
	s_mov_b32 s16, 0x34000
	s_nop 0
	v_addc_co_u32_e32 v9, vcc, 0, v7, vcc
	global_load_dword v24, v[8:9], off nt
	v_add_co_u32_e32 v8, vcc, s16, v6
	s_mov_b32 s16, 0x38000
	s_nop 0
	v_addc_co_u32_e32 v9, vcc, 0, v7, vcc
	global_load_dword v25, v[8:9], off nt
	v_add_co_u32_e32 v8, vcc, s16, v6
	s_mov_b32 s16, 0x3c000
	s_nop 0
	v_addc_co_u32_e32 v9, vcc, 0, v7, vcc
	global_load_dword v26, v[8:9], off nt
	v_add_co_u32_e32 v8, vcc, s16, v6
	s_mov_b32 s16, 0x40000
	s_nop 0
	v_addc_co_u32_e32 v9, vcc, 0, v7, vcc
	global_load_dword v27, v[8:9], off nt
	v_add_co_u32_e32 v8, vcc, s16, v6
	s_mov_b32 s16, 0x44000
	s_nop 0
	v_addc_co_u32_e32 v9, vcc, 0, v7, vcc
	global_load_dword v28, v[8:9], off nt
	v_add_co_u32_e32 v8, vcc, s16, v6
	s_mov_b32 s16, 0x48000
	s_nop 0
	v_addc_co_u32_e32 v9, vcc, 0, v7, vcc
	global_load_dword v29, v[8:9], off nt
	v_add_co_u32_e32 v8, vcc, s16, v6
	s_mov_b32 s16, 0x4c000
	s_nop 0
	v_addc_co_u32_e32 v9, vcc, 0, v7, vcc
	global_load_dword v30, v[8:9], off nt
	v_add_co_u32_e32 v8, vcc, s16, v6
	s_mov_b32 s16, 0x50000
	s_nop 0
	v_addc_co_u32_e32 v9, vcc, 0, v7, vcc
	global_load_dword v31, v[8:9], off nt
	v_add_co_u32_e32 v8, vcc, s16, v6
	s_mov_b32 s16, 0x54000
	s_nop 0
	v_addc_co_u32_e32 v9, vcc, 0, v7, vcc
	global_load_dword v32, v[8:9], off nt
	v_add_co_u32_e32 v8, vcc, s16, v6
	s_mov_b32 s16, 0x5c000
	s_nop 0
	v_addc_co_u32_e32 v9, vcc, 0, v7, vcc
	global_load_dword v33, v[8:9], off nt
	v_add_co_u32_e32 v8, vcc, s64, v6
	s_nop 1
	v_addc_co_u32_e32 v9, vcc, 0, v7, vcc
	global_load_dword v34, v[8:9], off nt
	v_add_co_u32_e32 v8, vcc, s16, v6
	s_mov_b32 s16, 0x60000
	s_nop 0
	v_addc_co_u32_e32 v9, vcc, 0, v7, vcc
	global_load_dword v35, v[8:9], off nt
	v_add_co_u32_e32 v8, vcc, s16, v6
	s_mov_b32 s16, 0x64000
	s_nop 0
	v_addc_co_u32_e32 v9, vcc, 0, v7, vcc
	global_load_dword v36, v[8:9], off nt
	v_add_co_u32_e32 v8, vcc, s16, v6
	s_mov_b32 s16, 0x68000
	s_nop 0
	v_addc_co_u32_e32 v9, vcc, 0, v7, vcc
	global_load_dword v37, v[8:9], off nt
	v_add_co_u32_e32 v8, vcc, s16, v6
	s_mov_b32 s16, 0x6c000
	s_nop 0
	v_addc_co_u32_e32 v9, vcc, 0, v7, vcc
	global_load_dword v38, v[8:9], off nt
	v_add_co_u32_e32 v8, vcc, s16, v6
	s_mov_b32 s16, 0x70000
	s_nop 0
	v_addc_co_u32_e32 v9, vcc, 0, v7, vcc
	global_load_dword v39, v[8:9], off nt
	v_add_co_u32_e32 v8, vcc, s16, v6
	s_mov_b32 s16, 0x74000
	s_nop 0
	v_addc_co_u32_e32 v9, vcc, 0, v7, vcc
	global_load_dword v40, v[8:9], off nt
	v_add_co_u32_e32 v8, vcc, s16, v6
	s_mov_b32 s16, 0x78000
	s_nop 0
	v_addc_co_u32_e32 v9, vcc, 0, v7, vcc
	global_load_dword v41, v[8:9], off nt
	v_add_co_u32_e32 v8, vcc, s16, v6
	s_mov_b32 s16, 0x7c000
	s_nop 0
	v_addc_co_u32_e32 v9, vcc, 0, v7, vcc
	v_add_co_u32_e32 v6, vcc, s16, v6
	global_load_dword v8, v[8:9], off nt
	s_nop 0
	v_addc_co_u32_e32 v7, vcc, 0, v7, vcc
	global_load_dword v6, v[6:7], off nt
	s_movk_i32 s16, 0x84
	v_mul_lo_u32 v7, v11, s16
	v_add3_u32 v7, s41, v66, v7
	v_add_u32_e32 v9, 0x400, v7
	s_waitcnt vmcnt(30)
	ds_write2_b32 v7, v12, v13 offset1:66
	s_waitcnt vmcnt(28)
	ds_write2_b32 v7, v14, v15 offset0:132 offset1:198
	s_waitcnt vmcnt(26)
	ds_write2_b32 v9, v16, v17 offset0:8 offset1:74
	s_waitcnt vmcnt(24)
	ds_write2_b32 v9, v18, v19 offset0:140 offset1:206
	v_add_u32_e32 v9, 0x800, v7
	s_waitcnt vmcnt(22)
	ds_write2_b32 v9, v20, v21 offset0:16 offset1:82
	s_waitcnt vmcnt(20)
	ds_write2_b32 v9, v22, v23 offset0:148 offset1:214
	v_add_u32_e32 v9, 0xc00, v7
	s_waitcnt vmcnt(18)
	ds_write2_b32 v9, v24, v25 offset0:24 offset1:90
	s_waitcnt vmcnt(16)
; #define GAS __attribute__((address_space(1)))
; #define LAS __attribute__((address_space(3)))
; #define LDS_WAIT() asm volatile("s_waitcnt lgkmcnt(0)" ::: "memory")
; __device__ __forceinline__ unsigned pk2(float lo, float hi) { return f2bf(lo) | (f2bf(hi) << 16); }
;     ...
;       for (int i = 0; i < 32; ++i) scr[(2 * i + (lane >> 5)) * 33 + (lane & 31)] = wv[i]; }
;     LDS_WAIT(); asm volatile("" ::: "memory");
;     const int c = lane & 7;
;     const int r0 = (mode == 0) ? n0 : (256 * (n0 >> 7) + (n0 & 127) + (mode == 2 ? 128 : 0));
; #pragma unroll
;     for (int j = 0; j < 4; ++j) { const int n = (lane >> 3) + 8 * j; const LAS float* s = scr + (8 * c) * 33 + n;
;         v4u o; o.x = pk2(s[0 * 33], s[1 * 33]); o.y = pk2(s[2 * 33], s[3 * 33]); o.z = pk2(s[4 * 33], s[5 * 33]); o.w = pk2(s[6 * 33], s[7 * 33]);
;         *(GAS v4u*)(WT + (size_t)(r0 + n) * ldt + k0 + 8 * c) = o; }
;     LDS_WAIT(); asm volatile("" ::: "memory");
	ds_write2_b32 v9, v26, v27 offset0:156 offset1:222
	v_add_u32_e32 v9, 0x1000, v7
	s_waitcnt vmcnt(14)
	ds_write2_b32 v9, v28, v29 offset0:32 offset1:98
	s_waitcnt vmcnt(12)
	ds_write2_b32 v9, v30, v31 offset0:164 offset1:230
	v_add_u32_e32 v9, 0x1400, v7
	s_waitcnt vmcnt(10)
	ds_write2_b32 v9, v32, v33 offset0:40 offset1:106
	s_waitcnt vmcnt(8)
	ds_write2_b32 v9, v34, v35 offset0:172 offset1:238
	v_add_u32_e32 v9, 0x1800, v7
	v_add_u32_e32 v7, 0x1c00, v7
	s_waitcnt vmcnt(6)
	ds_write2_b32 v9, v36, v37 offset0:48 offset1:114
	s_waitcnt vmcnt(4)
	ds_write2_b32 v9, v38, v39 offset0:180 offset1:246
	s_waitcnt vmcnt(2)
	ds_write2_b32 v7, v40, v41 offset0:56 offset1:122
	s_waitcnt vmcnt(0)
	ds_write2_b32 v7, v8, v6 offset0:188 offset1:254
	v_lshlrev_b32_e32 v6, 3, v10
	v_ashrrev_i32_e32 v28, 3, v10
	v_and_b32_e32 v6, 56, v6
	s_waitcnt lgkmcnt(0)
	v_mul_u32_u24_e32 v8, 0x84, v6
	v_lshlrev_b32_e32 v9, 2, v28
	v_add3_u32 v32, s41, v8, v9
	ds_read2_b32 v[12:13], v32 offset0:33 offset1:41
	ds_read2_b32 v[14:15], v32 offset1:8
	ds_read2_b32 v[16:17], v32 offset0:66 offset1:74
	ds_read2_b32 v[18:19], v32 offset0:99 offset1:107
	ds_read2_b32 v[20:21], v32 offset0:132 offset1:140
	ds_read2_b32 v[22:23], v32 offset0:165 offset1:173
	ds_read2_b32 v[24:25], v32 offset0:198 offset1:206
	ds_read2_b32 v[26:27], v32 offset0:231 offset1:239
	s_waitcnt lgkmcnt(7)
	v_bfe_u32 v9, v12, 16, 1
	s_waitcnt lgkmcnt(6)
	v_bfe_u32 v8, v14, 16, 1
	v_add3_u32 v8, v14, v8, s3
	v_lshrrev_b32_e32 v8, 16, v8
	v_add3_u32 v9, v12, v9, s3
	v_and_or_b32 v8, v9, s66, v8
	s_waitcnt lgkmcnt(5)
	v_bfe_u32 v9, v16, 16, 1
	v_add3_u32 v9, v16, v9, s3
	s_waitcnt lgkmcnt(4)
	v_bfe_u32 v10, v18, 16, 1
	v_lshrrev_b32_e32 v9, 16, v9
	v_add3_u32 v10, v18, v10, s3
	v_and_or_b32 v9, v10, s66, v9
	s_waitcnt lgkmcnt(3)
	v_bfe_u32 v10, v20, 16, 1
	v_add3_u32 v10, v20, v10, s3
	s_waitcnt lgkmcnt(2)
	v_bfe_u32 v11, v22, 16, 1
	v_lshrrev_b32_e32 v10, 16, v10
	v_add3_u32 v11, v22, v11, s3
	v_and_or_b32 v10, v11, s66, v10
	s_waitcnt lgkmcnt(1)
	v_bfe_u32 v11, v24, 16, 1
	v_add_u32_e32 v28, s26, v28
	v_lshlrev_b32_e32 v66, 1, v6
	v_add3_u32 v11, v24, v11, s3
	s_waitcnt lgkmcnt(0)
	v_bfe_u32 v12, v26, 16, 1
	v_ashrrev_i32_e32 v29, 31, v28
	v_lshl_add_u64 v[6:7], s[42:43], 0, v[66:67]
	v_lshrrev_b32_e32 v11, 16, v11
	v_add3_u32 v12, v26, v12, s3
	v_lshlrev_b64 v[30:31], 12, v[28:29]
	v_and_or_b32 v11, v12, s66, v11
	v_lshl_add_u64 v[30:31], v[6:7], 0, v[30:31]
	global_store_dwordx4 v[30:31], v[8:11], off
	v_bfe_u32 v12, v27, 16, 1
	v_add3_u32 v12, v27, v12, s3
	v_bfe_u32 v8, v15, 16, 1
	v_add3_u32 v8, v15, v8, s3
	v_bfe_u32 v9, v13, 16, 1
	v_lshrrev_b32_e32 v8, 16, v8
	v_add3_u32 v9, v13, v9, s3
	v_and_or_b32 v8, v9, s66, v8
	v_bfe_u32 v9, v17, 16, 1
	v_add3_u32 v9, v17, v9, s3
	v_bfe_u32 v10, v19, 16, 1
	v_lshrrev_b32_e32 v9, 16, v9
	v_add3_u32 v10, v19, v10, s3
	v_and_or_b32 v9, v10, s66, v9
	v_bfe_u32 v10, v21, 16, 1
	v_add3_u32 v10, v21, v10, s3
	v_bfe_u32 v11, v23, 16, 1
	v_lshrrev_b32_e32 v10, 16, v10
	v_add3_u32 v11, v23, v11, s3
	v_and_or_b32 v10, v11, s66, v10
	v_bfe_u32 v11, v25, 16, 1
	v_add3_u32 v11, v25, v11, s3
	v_lshrrev_b32_e32 v11, 16, v11
	v_and_or_b32 v11, v12, s66, v11
	v_add_u32_e32 v12, 8, v28
	v_ashrrev_i32_e32 v13, 31, v12
	v_lshlrev_b64 v[12:13], 12, v[12:13]
	v_lshl_add_u64 v[12:13], v[6:7], 0, v[12:13]
	global_store_dwordx4 v[12:13], v[8:11], off
	ds_read2_b32 v[12:13], v32 offset0:49 offset1:57
	ds_read2_b32 v[14:15], v32 offset0:16 offset1:24
	ds_read2_b32 v[16:17], v32 offset0:82 offset1:90
	ds_read2_b32 v[18:19], v32 offset0:115 offset1:123
	ds_read2_b32 v[20:21], v32 offset0:148 offset1:156
	ds_read2_b32 v[22:23], v32 offset0:181 offset1:189
	ds_read2_b32 v[24:25], v32 offset0:214 offset1:222
	ds_read2_b32 v[26:27], v32 offset0:247 offset1:255
	s_waitcnt lgkmcnt(7)
	v_bfe_u32 v9, v12, 16, 1
	s_waitcnt lgkmcnt(6)
	v_bfe_u32 v8, v14, 16, 1
	v_add3_u32 v8, v14, v8, s3
	v_lshrrev_b32_e32 v8, 16, v8
	v_add3_u32 v9, v12, v9, s3
	v_and_or_b32 v8, v9, s66, v8
	s_waitcnt lgkmcnt(5)
	v_bfe_u32 v9, v16, 16, 1
	v_add3_u32 v9, v16, v9, s3
	s_waitcnt lgkmcnt(4)
	v_bfe_u32 v10, v18, 16, 1
	v_lshrrev_b32_e32 v9, 16, v9
	v_add3_u32 v10, v18, v10, s3
	v_and_or_b32 v9, v10, s66, v9
	s_waitcnt lgkmcnt(3)
	v_bfe_u32 v10, v20, 16, 1
	v_add3_u32 v10, v20, v10, s3
	s_waitcnt lgkmcnt(2)
	v_bfe_u32 v11, v22, 16, 1
	v_lshrrev_b32_e32 v10, 16, v10
	v_add3_u32 v11, v22, v11, s3
	v_and_or_b32 v10, v11, s66, v10
	s_waitcnt lgkmcnt(1)
	v_bfe_u32 v11, v24, 16, 1
	v_add_u32_e32 v30, 16, v28
	v_add3_u32 v11, v24, v11, s3
	s_waitcnt lgkmcnt(0)
	v_bfe_u32 v12, v26, 16, 1
	v_ashrrev_i32_e32 v31, 31, v30
	v_lshrrev_b32_e32 v11, 16, v11
	v_add3_u32 v12, v26, v12, s3
	v_lshlrev_b64 v[30:31], 12, v[30:31]
	v_and_or_b32 v11, v12, s66, v11
	v_lshl_add_u64 v[30:31], v[6:7], 0, v[30:31]
	global_store_dwordx4 v[30:31], v[8:11], off
	v_bfe_u32 v12, v27, 16, 1
	v_add3_u32 v12, v27, v12, s3
	v_bfe_u32 v8, v15, 16, 1
	v_add3_u32 v8, v15, v8, s3
	v_bfe_u32 v9, v13, 16, 1
	v_lshrrev_b32_e32 v8, 16, v8
	v_add3_u32 v9, v13, v9, s3
	v_and_or_b32 v8, v9, s66, v8
	v_bfe_u32 v9, v17, 16, 1
	v_add3_u32 v9, v17, v9, s3
	v_bfe_u32 v10, v19, 16, 1
	v_lshrrev_b32_e32 v9, 16, v9
	v_add3_u32 v10, v19, v10, s3
	v_and_or_b32 v9, v10, s66, v9
	v_bfe_u32 v10, v21, 16, 1
	v_add3_u32 v10, v21, v10, s3
	v_bfe_u32 v11, v23, 16, 1
	v_lshrrev_b32_e32 v10, 16, v10
	v_add3_u32 v11, v23, v11, s3
	v_and_or_b32 v10, v11, s66, v10
	v_bfe_u32 v11, v25, 16, 1
	v_add3_u32 v11, v25, v11, s3
	v_lshrrev_b32_e32 v11, 16, v11
	v_and_or_b32 v11, v12, s66, v11
	v_add_u32_e32 v12, 24, v28
	v_ashrrev_i32_e32 v13, 31, v12
	v_lshlrev_b64 v[12:13], 12, v[12:13]
	v_lshl_add_u64 v[6:7], v[6:7], 0, v[12:13]
	global_store_dwordx4 v[6:7], v[8:11], off
	s_waitcnt lgkmcnt(0)

;     if (ldt == 0) ldt = K;
;     asm volatile("" : "+v"(lane));
;     const int kb = item / nblk, nb = item % nblk, k0 = 64 * kb, n0 = 32 * nb;
;     { float wv[32];
;       const float* wp = W + (size_t)(k0 + (lane >> 5)) * ldw + n0 + (lane & 31);
; #pragma unroll
;       for (int i = 0; i < 32; ++i) wv[i] = wp[(size_t)(2 * i) * ldw];
; #pragma unroll
;       for (int i = 0; i < 32; ++i) scr[(2 * i + (lane >> 5)) * 33 + (lane & 31)] = wv[i]; }
; __device__ __forceinline__ void transpose_late(const Args& a, Frame& F, LAS float* scr, int r) {
;     ...
;     if (r < IT_SQ) { p0_transpose_item(a.in[I_WO], D, D, WO, 0, D / 32, scr, r, F.lane); return; } r -= IT_SQ;
.LBB0_1019:
	s_andn2_b64 vcc, exec, s[58:59]
	s_cbranch_vccnz .LBB0_1021
	v_mov_b32_e32 v10, v145
	v_readlane_b32 s44, v244, 2
	v_ashrrev_i32_e32 v11, 5, v10
	v_add_u32_e32 v6, s93, v11
	v_ashrrev_i32_e32 v7, 31, v6
	s_and_b32 s26, s95, 0x7e0
	v_lshlrev_b64 v[6:7], 13, v[6:7]
	v_readlane_b32 s48, v244, 6
	v_readlane_b32 s49, v244, 7
	s_lshl_b32 s86, s26, 2
	v_lshlrev_b32_e32 v8, 2, v10
	v_lshl_add_u64 v[6:7], s[48:49], 0, v[6:7]
	v_lshl_add_u64 v[6:7], v[6:7], 0, s[86:87]
	v_and_b32_e32 v66, 0x7c, v8
	v_lshl_add_u64 v[6:7], v[6:7], 0, v[66:67]
	v_add_co_u32_e32 v8, vcc, s83, v6
	global_load_dword v12, v[6:7], off nt
	s_nop 0
	v_addc_co_u32_e32 v9, vcc, 0, v7, vcc
	global_load_dword v13, v[8:9], off nt
	v_add_co_u32_e32 v8, vcc, s85, v6
	s_mov_b32 s16, 0x30000
	s_nop 0
	v_addc_co_u32_e32 v9, vcc, 0, v7, vcc
	global_load_dword v14, v[8:9], off nt
	v_add_co_u32_e32 v8, vcc, s72, v6
	v_readlane_b32 s45, v244, 3
	s_nop 0
	v_addc_co_u32_e32 v9, vcc, 0, v7, vcc
	global_load_dword v15, v[8:9], off nt
	v_add_co_u32_e32 v8, vcc, s73, v6
	v_readlane_b32 s46, v244, 4
	s_nop 0
	v_addc_co_u32_e32 v9, vcc, 0, v7, vcc
	global_load_dword v16, v[8:9], off nt
	v_add_co_u32_e32 v8, vcc, s74, v6
	v_readlane_b32 s47, v244, 5
	s_nop 0
	v_addc_co_u32_e32 v9, vcc, 0, v7, vcc
	global_load_dword v17, v[8:9], off nt
	v_add_co_u32_e32 v8, vcc, s75, v6
	v_readlane_b32 s50, v244, 8
	s_nop 0
	v_addc_co_u32_e32 v9, vcc, 0, v7, vcc
	global_load_dword v18, v[8:9], off nt
	v_add_co_u32_e32 v8, vcc, s88, v6
	v_readlane_b32 s51, v244, 9
	s_nop 0
	v_addc_co_u32_e32 v9, vcc, 0, v7, vcc
	global_load_dword v19, v[8:9], off nt
	v_add_co_u32_e32 v8, vcc, s15, v6
	v_readlane_b32 s52, v244, 10
	s_nop 0
	v_addc_co_u32_e32 v9, vcc, 0, v7, vcc
	global_load_dword v20, v[8:9], off nt
	v_add_co_u32_e32 v8, vcc, s78, v6
	v_readlane_b32 s53, v244, 11
	s_nop 0
	v_addc_co_u32_e32 v9, vcc, 0, v7, vcc
	global_load_dword v21, v[8:9], off nt
	v_add_co_u32_e32 v8, vcc, s79, v6
	v_readlane_b32 s54, v244, 12
	s_nop 0
	v_addc_co_u32_e32 v9, vcc, 0, v7, vcc
	global_load_dword v22, v[8:9], off nt
	v_add_co_u32_e32 v8, vcc, s14, v6
	v_readlane_b32 s55, v244, 13
	s_nop 0
	v_addc_co_u32_e32 v9, vcc, 0, v7, vcc
	global_load_dword v23, v[8:9], off nt
	v_add_co_u32_e32 v8, vcc, s16, v6
	s_mov_b32 s16, 0x34000
	s_nop 0
	v_addc_co_u32_e32 v9, vcc, 0, v7, vcc
	global_load_dword v24, v[8:9], off nt
	v_add_co_u32_e32 v8, vcc, s16, v6
	s_mov_b32 s16, 0x38000
	s_nop 0
	v_addc_co_u32_e32 v9, vcc, 0, v7, vcc
	global_load_dword v25, v[8:9], off nt
	v_add_co_u32_e32 v8, vcc, s16, v6
	s_mov_b32 s16, 0x3c000
	s_nop 0
	v_addc_co_u32_e32 v9, vcc, 0, v7, vcc
	global_load_dword v26, v[8:9], off nt
	v_add_co_u32_e32 v8, vcc, s16, v6
	s_mov_b32 s16, 0x40000
	s_nop 0
	v_addc_co_u32_e32 v9, vcc, 0, v7, vcc
	global_load_dword v27, v[8:9], off nt
	v_add_co_u32_e32 v8, vcc, s16, v6
	s_mov_b32 s16, 0x44000
	s_nop 0
	v_addc_co_u32_e32 v9, vcc, 0, v7, vcc
	global_load_dword v28, v[8:9], off nt
	v_add_co_u32_e32 v8, vcc, s16, v6
	s_mov_b32 s16, 0x48000
	s_nop 0
	v_addc_co_u32_e32 v9, vcc, 0, v7, vcc
	global_load_dword v29, v[8:9], off nt
	v_add_co_u32_e32 v8, vcc, s16, v6
	s_mov_b32 s16, 0x4c000
	s_nop 0
	v_addc_co_u32_e32 v9, vcc, 0, v7, vcc
	global_load_dword v30, v[8:9], off nt
	v_add_co_u32_e32 v8, vcc, s16, v6
	s_mov_b32 s16, 0x50000
	s_nop 0
	v_addc_co_u32_e32 v9, vcc, 0, v7, vcc
	global_load_dword v31, v[8:9], off nt
	v_add_co_u32_e32 v8, vcc, s16, v6
	s_mov_b32 s16, 0x54000
	s_nop 0
	v_addc_co_u32_e32 v9, vcc, 0, v7, vcc
	global_load_dword v32, v[8:9], off nt
	v_add_co_u32_e32 v8, vcc, s16, v6
	s_mov_b32 s16, 0x5c000
	s_nop 0
	v_addc_co_u32_e32 v9, vcc, 0, v7, vcc
	global_load_dword v33, v[8:9], off nt
	v_add_co_u32_e32 v8, vcc, s64, v6
	v_readlane_b32 s56, v244, 14
	s_nop 0
	v_addc_co_u32_e32 v9, vcc, 0, v7, vcc
	global_load_dword v34, v[8:9], off nt
	v_add_co_u32_e32 v8, vcc, s16, v6
	s_mov_b32 s16, 0x60000
	s_nop 0
	v_addc_co_u32_e32 v9, vcc, 0, v7, vcc
	global_load_dword v35, v[8:9], off nt
	v_add_co_u32_e32 v8, vcc, s16, v6
	s_mov_b32 s16, 0x64000
	s_nop 0
	v_addc_co_u32_e32 v9, vcc, 0, v7, vcc
	global_load_dword v36, v[8:9], off nt
	v_add_co_u32_e32 v8, vcc, s16, v6
	s_mov_b32 s16, 0x68000
	s_nop 0
	v_addc_co_u32_e32 v9, vcc, 0, v7, vcc
	global_load_dword v37, v[8:9], off nt
	v_add_co_u32_e32 v8, vcc, s16, v6
	s_mov_b32 s16, 0x6c000
	s_nop 0
	v_addc_co_u32_e32 v9, vcc, 0, v7, vcc
	global_load_dword v38, v[8:9], off nt
	v_add_co_u32_e32 v8, vcc, s16, v6
	s_mov_b32 s16, 0x70000
	s_nop 0
	v_addc_co_u32_e32 v9, vcc, 0, v7, vcc
	global_load_dword v39, v[8:9], off nt
	v_add_co_u32_e32 v8, vcc, s16, v6
	s_mov_b32 s16, 0x74000
	s_nop 0
	v_addc_co_u32_e32 v9, vcc, 0, v7, vcc
	global_load_dword v40, v[8:9], off nt
	v_add_co_u32_e32 v8, vcc, s16, v6
	s_mov_b32 s16, 0x78000
	s_nop 0
	v_addc_co_u32_e32 v9, vcc, 0, v7, vcc
	global_load_dword v41, v[8:9], off nt
	v_add_co_u32_e32 v8, vcc, s16, v6
	s_mov_b32 s16, 0x7c000
	s_nop 0
	v_addc_co_u32_e32 v9, vcc, 0, v7, vcc
	v_add_co_u32_e32 v6, vcc, s16, v6
	global_load_dword v8, v[8:9], off nt
	s_nop 0
	v_addc_co_u32_e32 v7, vcc, 0, v7, vcc
	global_load_dword v6, v[6:7], off nt
	s_movk_i32 s16, 0x84
	v_mul_lo_u32 v7, v11, s16
	v_add3_u32 v7, s41, v66, v7
	v_add_u32_e32 v9, 0x400, v7
	s_waitcnt vmcnt(30)
	ds_write2_b32 v7, v12, v13 offset1:66
	s_waitcnt vmcnt(28)
	ds_write2_b32 v7, v14, v15 offset0:132 offset1:198
	s_waitcnt vmcnt(26)
	ds_write2_b32 v9, v16, v17 offset0:8 offset1:74
	s_waitcnt vmcnt(24)
	ds_write2_b32 v9, v18, v19 offset0:140 offset1:206
	v_add_u32_e32 v9, 0x800, v7
	s_waitcnt vmcnt(22)
	ds_write2_b32 v9, v20, v21 offset0:16 offset1:82
	s_waitcnt vmcnt(20)
; #define GAS __attribute__((address_space(1)))
; #define LAS __attribute__((address_space(3)))
; #define LDS_WAIT() asm volatile("s_waitcnt lgkmcnt(0)" ::: "memory")
; __device__ __forceinline__ unsigned pk2(float lo, float hi) { return f2bf(lo) | (f2bf(hi) << 16); }
;     ...
;       for (int i = 0; i < 32; ++i) scr[(2 * i + (lane >> 5)) * 33 + (lane & 31)] = wv[i]; }
;     LDS_WAIT(); asm volatile("" ::: "memory");
;     const int c = lane & 7;
;     const int r0 = (mode == 0) ? n0 : (256 * (n0 >> 7) + (n0 & 127) + (mode == 2 ? 128 : 0));
; #pragma unroll
;     for (int j = 0; j < 4; ++j) { const int n = (lane >> 3) + 8 * j; const LAS float* s = scr + (8 * c) * 33 + n;
;         v4u o; o.x = pk2(s[0 * 33], s[1 * 33]); o.y = pk2(s[2 * 33], s[3 * 33]); o.z = pk2(s[4 * 33], s[5 * 33]); o.w = pk2(s[6 * 33], s[7 * 33]);
;         *(GAS v4u*)(WT + (size_t)(r0 + n) * ldt + k0 + 8 * c) = o; }
;     LDS_WAIT(); asm volatile("" ::: "memory");
	ds_write2_b32 v9, v22, v23 offset0:148 offset1:214
	v_add_u32_e32 v9, 0xc00, v7
	s_waitcnt vmcnt(18)
	ds_write2_b32 v9, v24, v25 offset0:24 offset1:90
	s_waitcnt vmcnt(16)
	ds_write2_b32 v9, v26, v27 offset0:156 offset1:222
	v_add_u32_e32 v9, 0x1000, v7
	s_waitcnt vmcnt(14)
	ds_write2_b32 v9, v28, v29 offset0:32 offset1:98
	s_waitcnt vmcnt(12)
	ds_write2_b32 v9, v30, v31 offset0:164 offset1:230
	v_add_u32_e32 v9, 0x1400, v7
	s_waitcnt vmcnt(10)
	ds_write2_b32 v9, v32, v33 offset0:40 offset1:106
	s_waitcnt vmcnt(8)
	ds_write2_b32 v9, v34, v35 offset0:172 offset1:238
	v_add_u32_e32 v9, 0x1800, v7
	v_add_u32_e32 v7, 0x1c00, v7
	s_waitcnt vmcnt(6)
	ds_write2_b32 v9, v36, v37 offset0:48 offset1:114
	s_waitcnt vmcnt(4)
	ds_write2_b32 v9, v38, v39 offset0:180 offset1:246
	s_waitcnt vmcnt(2)
	ds_write2_b32 v7, v40, v41 offset0:56 offset1:122
	s_waitcnt vmcnt(0)
	ds_write2_b32 v7, v8, v6 offset0:188 offset1:254
	v_lshlrev_b32_e32 v6, 3, v10
	v_ashrrev_i32_e32 v28, 3, v10
	v_and_b32_e32 v6, 56, v6
	s_waitcnt lgkmcnt(0)
	v_mul_u32_u24_e32 v8, 0x84, v6
	v_lshlrev_b32_e32 v9, 2, v28
	v_add3_u32 v32, s41, v8, v9
	ds_read2_b32 v[12:13], v32 offset0:33 offset1:41
	ds_read2_b32 v[14:15], v32 offset1:8
	ds_read2_b32 v[16:17], v32 offset0:66 offset1:74
	ds_read2_b32 v[18:19], v32 offset0:99 offset1:107
	ds_read2_b32 v[20:21], v32 offset0:132 offset1:140
	ds_read2_b32 v[22:23], v32 offset0:165 offset1:173
	ds_read2_b32 v[24:25], v32 offset0:198 offset1:206
	ds_read2_b32 v[26:27], v32 offset0:231 offset1:239
	s_waitcnt lgkmcnt(7)
	v_bfe_u32 v9, v12, 16, 1
	s_waitcnt lgkmcnt(6)
	v_bfe_u32 v8, v14, 16, 1
	v_add3_u32 v8, v14, v8, s3
	v_lshrrev_b32_e32 v8, 16, v8
	v_add3_u32 v9, v12, v9, s3
	v_and_or_b32 v8, v9, s66, v8
	s_waitcnt lgkmcnt(5)
	v_bfe_u32 v9, v16, 16, 1
	v_add3_u32 v9, v16, v9, s3
	s_waitcnt lgkmcnt(4)
	v_bfe_u32 v10, v18, 16, 1
	v_lshrrev_b32_e32 v9, 16, v9
	v_add3_u32 v10, v18, v10, s3
	v_and_or_b32 v9, v10, s66, v9
	s_waitcnt lgkmcnt(3)
	v_bfe_u32 v10, v20, 16, 1
	v_add3_u32 v10, v20, v10, s3
	s_waitcnt lgkmcnt(2)
	v_bfe_u32 v11, v22, 16, 1
	v_lshrrev_b32_e32 v10, 16, v10
	v_add3_u32 v11, v22, v11, s3
	v_and_or_b32 v10, v11, s66, v10
	s_waitcnt lgkmcnt(1)
	v_bfe_u32 v11, v24, 16, 1
	v_add_u32_e32 v28, s26, v28
	v_lshlrev_b32_e32 v66, 1, v6
	v_add3_u32 v11, v24, v11, s3
	s_waitcnt lgkmcnt(0)
	v_bfe_u32 v12, v26, 16, 1
	v_ashrrev_i32_e32 v29, 31, v28
	v_lshl_add_u64 v[6:7], s[76:77], 0, v[66:67]
	v_lshrrev_b32_e32 v11, 16, v11
	v_add3_u32 v12, v26, v12, s3
	v_lshlrev_b64 v[30:31], 12, v[28:29]
	v_and_or_b32 v11, v12, s66, v11
	v_lshl_add_u64 v[30:31], v[6:7], 0, v[30:31]
	global_store_dwordx4 v[30:31], v[8:11], off
	v_bfe_u32 v12, v27, 16, 1
	v_add3_u32 v12, v27, v12, s3
	v_bfe_u32 v8, v15, 16, 1
	v_add3_u32 v8, v15, v8, s3
	v_bfe_u32 v9, v13, 16, 1
	v_lshrrev_b32_e32 v8, 16, v8
	v_add3_u32 v9, v13, v9, s3
	v_and_or_b32 v8, v9, s66, v8
	v_bfe_u32 v9, v17, 16, 1
	v_add3_u32 v9, v17, v9, s3
	v_bfe_u32 v10, v19, 16, 1
	v_lshrrev_b32_e32 v9, 16, v9
	v_add3_u32 v10, v19, v10, s3
	v_and_or_b32 v9, v10, s66, v9
	v_bfe_u32 v10, v21, 16, 1
	v_add3_u32 v10, v21, v10, s3
	v_bfe_u32 v11, v23, 16, 1
	v_lshrrev_b32_e32 v10, 16, v10
	v_add3_u32 v11, v23, v11, s3
	v_and_or_b32 v10, v11, s66, v10
	v_bfe_u32 v11, v25, 16, 1
	v_add3_u32 v11, v25, v11, s3
	v_lshrrev_b32_e32 v11, 16, v11
	v_and_or_b32 v11, v12, s66, v11
	v_add_u32_e32 v12, 8, v28
	v_ashrrev_i32_e32 v13, 31, v12
	v_lshlrev_b64 v[12:13], 12, v[12:13]
	v_lshl_add_u64 v[12:13], v[6:7], 0, v[12:13]
	global_store_dwordx4 v[12:13], v[8:11], off
	ds_read2_b32 v[12:13], v32 offset0:49 offset1:57
	ds_read2_b32 v[14:15], v32 offset0:16 offset1:24
	ds_read2_b32 v[16:17], v32 offset0:82 offset1:90
	ds_read2_b32 v[18:19], v32 offset0:115 offset1:123
	ds_read2_b32 v[20:21], v32 offset0:148 offset1:156
	ds_read2_b32 v[22:23], v32 offset0:181 offset1:189
	ds_read2_b32 v[24:25], v32 offset0:214 offset1:222
	ds_read2_b32 v[26:27], v32 offset0:247 offset1:255
	s_waitcnt lgkmcnt(7)
	v_bfe_u32 v9, v12, 16, 1
	s_waitcnt lgkmcnt(6)
	v_bfe_u32 v8, v14, 16, 1
	v_add3_u32 v8, v14, v8, s3
	v_lshrrev_b32_e32 v8, 16, v8
	v_add3_u32 v9, v12, v9, s3
	v_and_or_b32 v8, v9, s66, v8
	s_waitcnt lgkmcnt(5)
	v_bfe_u32 v9, v16, 16, 1
	v_add3_u32 v9, v16, v9, s3
	s_waitcnt lgkmcnt(4)
	v_bfe_u32 v10, v18, 16, 1
	v_lshrrev_b32_e32 v9, 16, v9
	v_add3_u32 v10, v18, v10, s3
	v_and_or_b32 v9, v10, s66, v9
	s_waitcnt lgkmcnt(3)
	v_bfe_u32 v10, v20, 16, 1
	v_add3_u32 v10, v20, v10, s3
	s_waitcnt lgkmcnt(2)
	v_bfe_u32 v11, v22, 16, 1
	v_lshrrev_b32_e32 v10, 16, v10
	v_add3_u32 v11, v22, v11, s3
	v_and_or_b32 v10, v11, s66, v10
	s_waitcnt lgkmcnt(1)
	v_bfe_u32 v11, v24, 16, 1
	v_add_u32_e32 v30, 16, v28
	v_add3_u32 v11, v24, v11, s3
	s_waitcnt lgkmcnt(0)
	v_bfe_u32 v12, v26, 16, 1
	v_ashrrev_i32_e32 v31, 31, v30
	v_lshrrev_b32_e32 v11, 16, v11
	v_add3_u32 v12, v26, v12, s3
	v_lshlrev_b64 v[30:31], 12, v[30:31]
	v_and_or_b32 v11, v12, s66, v11
	v_lshl_add_u64 v[30:31], v[6:7], 0, v[30:31]
	global_store_dwordx4 v[30:31], v[8:11], off
	v_bfe_u32 v12, v27, 16, 1
	v_add3_u32 v12, v27, v12, s3
	v_bfe_u32 v8, v15, 16, 1
	v_add3_u32 v8, v15, v8, s3
	v_bfe_u32 v9, v13, 16, 1
	v_lshrrev_b32_e32 v8, 16, v8
	v_add3_u32 v9, v13, v9, s3
	v_and_or_b32 v8, v9, s66, v8
	v_bfe_u32 v9, v17, 16, 1
	v_add3_u32 v9, v17, v9, s3
	v_bfe_u32 v10, v19, 16, 1
	v_lshrrev_b32_e32 v9, 16, v9
	v_add3_u32 v10, v19, v10, s3
	v_and_or_b32 v9, v10, s66, v9
	v_bfe_u32 v10, v21, 16, 1
	v_add3_u32 v10, v21, v10, s3
	v_bfe_u32 v11, v23, 16, 1
	v_lshrrev_b32_e32 v10, 16, v10
	v_add3_u32 v11, v23, v11, s3
	v_and_or_b32 v10, v11, s66, v10
	v_bfe_u32 v11, v25, 16, 1
	v_add3_u32 v11, v25, v11, s3
	v_lshrrev_b32_e32 v11, 16, v11
	v_and_or_b32 v11, v12, s66, v11
	v_add_u32_e32 v12, 24, v28
	v_ashrrev_i32_e32 v13, 31, v12
	v_lshlrev_b64 v[12:13], 12, v[12:13]
	v_lshl_add_u64 v[6:7], v[6:7], 0, v[12:13]
	global_store_dwordx4 v[6:7], v[8:11], off
	s_waitcnt lgkmcnt(0)
	v_readlane_b32 s57, v244, 15
	v_readlane_b32 s58, v244, 16
	v_readlane_b32 s59, v244, 17

;     if (ldt == 0) ldt = K;
;     asm volatile("" : "+v"(lane));
;     const int kb = item / nblk, nb = item % nblk, k0 = 64 * kb, n0 = 32 * nb;
;     { float wv[32];
;       const float* wp = W + (size_t)(k0 + (lane >> 5)) * ldw + n0 + (lane & 31);
; #pragma unroll
;       for (int i = 0; i < 32; ++i) wv[i] = wp[(size_t)(2 * i) * ldw];
; #pragma unroll
;       for (int i = 0; i < 32; ++i) scr[(2 * i + (lane >> 5)) * 33 + (lane & 31)] = wv[i]; }
; __device__ __forceinline__ void transpose_late(const Args& a, Frame& F, LAS float* scr, int r) {
;     ...
;     if (r < IT_SQ) { p0_transpose_item(a.in[I_WBOUT], D, D, WAB + D, 0, D / 32, scr, r, F.lane, 2 * D); return; } r -= IT_SQ;
.LBB0_1022:
	s_andn2_b64 vcc, exec, s[58:59]
	s_cbranch_vccnz .LBB0_1024
	v_mov_b32_e32 v10, v145
	v_readlane_b32 s44, v244, 2
	v_ashrrev_i32_e32 v11, 5, v10
	v_add_u32_e32 v6, s94, v11
	v_ashrrev_i32_e32 v7, 31, v6
	s_and_b32 s26, s95, 0x7e0
	v_lshlrev_b64 v[6:7], 13, v[6:7]
	v_readlane_b32 s46, v244, 4
	v_readlane_b32 s47, v244, 5
	s_lshl_b32 s86, s26, 2
	v_lshlrev_b32_e32 v8, 2, v10
	v_lshl_add_u64 v[6:7], s[46:47], 0, v[6:7]
	v_lshl_add_u64 v[6:7], v[6:7], 0, s[86:87]
	v_and_b32_e32 v66, 0x7c, v8
	v_lshl_add_u64 v[6:7], v[6:7], 0, v[66:67]
	v_add_co_u32_e32 v8, vcc, s83, v6
	global_load_dword v12, v[6:7], off nt
	s_nop 0
	v_addc_co_u32_e32 v9, vcc, 0, v7, vcc
	global_load_dword v13, v[8:9], off nt
	v_add_co_u32_e32 v8, vcc, s85, v6
	s_mov_b32 s16, 0x30000
	s_nop 0
	v_addc_co_u32_e32 v9, vcc, 0, v7, vcc
	global_load_dword v14, v[8:9], off nt
	v_add_co_u32_e32 v8, vcc, s72, v6
	v_readlane_b32 s45, v244, 3
	s_nop 0
	v_addc_co_u32_e32 v9, vcc, 0, v7, vcc
	global_load_dword v15, v[8:9], off nt
	v_add_co_u32_e32 v8, vcc, s73, v6
	v_readlane_b32 s48, v244, 6
	s_nop 0
	v_addc_co_u32_e32 v9, vcc, 0, v7, vcc
	global_load_dword v16, v[8:9], off nt
	v_add_co_u32_e32 v8, vcc, s74, v6
	v_readlane_b32 s49, v244, 7
	s_nop 0
	v_addc_co_u32_e32 v9, vcc, 0, v7, vcc
	global_load_dword v17, v[8:9], off nt
	v_add_co_u32_e32 v8, vcc, s75, v6
	v_readlane_b32 s50, v244, 8
	s_nop 0
	v_addc_co_u32_e32 v9, vcc, 0, v7, vcc
	global_load_dword v18, v[8:9], off nt
	v_add_co_u32_e32 v8, vcc, s88, v6
	v_readlane_b32 s51, v244, 9
	s_nop 0
	v_addc_co_u32_e32 v9, vcc, 0, v7, vcc
	global_load_dword v19, v[8:9], off nt
	v_add_co_u32_e32 v8, vcc, s15, v6
	v_readlane_b32 s52, v244, 10
	s_nop 0
	v_addc_co_u32_e32 v9, vcc, 0, v7, vcc
	global_load_dword v20, v[8:9], off nt
	v_add_co_u32_e32 v8, vcc, s78, v6
	v_readlane_b32 s53, v244, 11
	s_nop 0
	v_addc_co_u32_e32 v9, vcc, 0, v7, vcc
	global_load_dword v21, v[8:9], off nt
	v_add_co_u32_e32 v8, vcc, s79, v6
	v_readlane_b32 s54, v244, 12
	s_nop 0
	v_addc_co_u32_e32 v9, vcc, 0, v7, vcc
	global_load_dword v22, v[8:9], off nt
	v_add_co_u32_e32 v8, vcc, s14, v6
	v_readlane_b32 s55, v244, 13
	s_nop 0
	v_addc_co_u32_e32 v9, vcc, 0, v7, vcc
	global_load_dword v23, v[8:9], off nt
	v_add_co_u32_e32 v8, vcc, s16, v6
	s_mov_b32 s16, 0x34000
	s_nop 0
	v_addc_co_u32_e32 v9, vcc, 0, v7, vcc
	global_load_dword v24, v[8:9], off nt
	v_add_co_u32_e32 v8, vcc, s16, v6
	s_mov_b32 s16, 0x38000
	s_nop 0
	v_addc_co_u32_e32 v9, vcc, 0, v7, vcc
	global_load_dword v25, v[8:9], off nt
	v_add_co_u32_e32 v8, vcc, s16, v6
	s_mov_b32 s16, 0x3c000
	s_nop 0
	v_addc_co_u32_e32 v9, vcc, 0, v7, vcc
	global_load_dword v26, v[8:9], off nt
	v_add_co_u32_e32 v8, vcc, s16, v6
	s_mov_b32 s16, 0x40000
	s_nop 0
	v_addc_co_u32_e32 v9, vcc, 0, v7, vcc
	global_load_dword v27, v[8:9], off nt
	v_add_co_u32_e32 v8, vcc, s16, v6
	s_mov_b32 s16, 0x44000
	s_nop 0
	v_addc_co_u32_e32 v9, vcc, 0, v7, vcc
	global_load_dword v28, v[8:9], off nt
	v_add_co_u32_e32 v8, vcc, s16, v6
	s_mov_b32 s16, 0x48000
	s_nop 0
	v_addc_co_u32_e32 v9, vcc, 0, v7, vcc
	global_load_dword v29, v[8:9], off nt
	v_add_co_u32_e32 v8, vcc, s16, v6
	s_mov_b32 s16, 0x4c000
	s_nop 0
	v_addc_co_u32_e32 v9, vcc, 0, v7, vcc
	global_load_dword v30, v[8:9], off nt
	v_add_co_u32_e32 v8, vcc, s16, v6
	s_mov_b32 s16, 0x50000
	s_nop 0
	v_addc_co_u32_e32 v9, vcc, 0, v7, vcc
	global_load_dword v31, v[8:9], off nt
	v_add_co_u32_e32 v8, vcc, s16, v6
	s_mov_b32 s16, 0x54000
	s_nop 0
	v_addc_co_u32_e32 v9, vcc, 0, v7, vcc
	global_load_dword v32, v[8:9], off nt
	v_add_co_u32_e32 v8, vcc, s16, v6
	s_mov_b32 s16, 0x5c000
	s_nop 0
	v_addc_co_u32_e32 v9, vcc, 0, v7, vcc
	global_load_dword v33, v[8:9], off nt
	v_add_co_u32_e32 v8, vcc, s64, v6
	v_readlane_b32 s56, v244, 14
	s_nop 0
	v_addc_co_u32_e32 v9, vcc, 0, v7, vcc
	global_load_dword v34, v[8:9], off nt
	v_add_co_u32_e32 v8, vcc, s16, v6
	s_mov_b32 s16, 0x60000
	s_nop 0
	v_addc_co_u32_e32 v9, vcc, 0, v7, vcc
	global_load_dword v35, v[8:9], off nt
	v_add_co_u32_e32 v8, vcc, s16, v6
	s_mov_b32 s16, 0x64000
	s_nop 0
	v_addc_co_u32_e32 v9, vcc, 0, v7, vcc
	global_load_dword v36, v[8:9], off nt
	v_add_co_u32_e32 v8, vcc, s16, v6
	s_mov_b32 s16, 0x68000
	s_nop 0
	v_addc_co_u32_e32 v9, vcc, 0, v7, vcc
	global_load_dword v37, v[8:9], off nt
	v_add_co_u32_e32 v8, vcc, s16, v6
	s_mov_b32 s16, 0x6c000
	s_nop 0
	v_addc_co_u32_e32 v9, vcc, 0, v7, vcc
	global_load_dword v38, v[8:9], off nt
	v_add_co_u32_e32 v8, vcc, s16, v6
	s_mov_b32 s16, 0x70000
	s_nop 0
	v_addc_co_u32_e32 v9, vcc, 0, v7, vcc
	global_load_dword v39, v[8:9], off nt
	v_add_co_u32_e32 v8, vcc, s16, v6
	s_mov_b32 s16, 0x74000
	s_nop 0
	v_addc_co_u32_e32 v9, vcc, 0, v7, vcc
	global_load_dword v40, v[8:9], off nt
	v_add_co_u32_e32 v8, vcc, s16, v6
	s_mov_b32 s16, 0x78000
	s_nop 0
	v_addc_co_u32_e32 v9, vcc, 0, v7, vcc
	global_load_dword v41, v[8:9], off nt
	v_add_co_u32_e32 v8, vcc, s16, v6
	s_mov_b32 s16, 0x7c000
	s_nop 0
	v_addc_co_u32_e32 v9, vcc, 0, v7, vcc
	v_add_co_u32_e32 v6, vcc, s16, v6
	global_load_dword v8, v[8:9], off nt
	s_nop 0
	v_addc_co_u32_e32 v7, vcc, 0, v7, vcc
	global_load_dword v6, v[6:7], off nt
	s_movk_i32 s16, 0x84
	v_mul_lo_u32 v7, v11, s16
	v_add3_u32 v7, s41, v66, v7
	v_add_u32_e32 v9, 0x400, v7
	s_waitcnt vmcnt(30)
	ds_write2_b32 v7, v12, v13 offset1:66
	s_waitcnt vmcnt(28)
	ds_write2_b32 v7, v14, v15 offset0:132 offset1:198
	s_waitcnt vmcnt(26)
	ds_write2_b32 v9, v16, v17 offset0:8 offset1:74
	s_waitcnt vmcnt(24)
	ds_write2_b32 v9, v18, v19 offset0:140 offset1:206
	v_add_u32_e32 v9, 0x800, v7
	s_waitcnt vmcnt(22)
	ds_write2_b32 v9, v20, v21 offset0:16 offset1:82
	s_waitcnt vmcnt(20)
; #define GAS __attribute__((address_space(1)))
; #define LAS __attribute__((address_space(3)))
; #define LDS_WAIT() asm volatile("s_waitcnt lgkmcnt(0)" ::: "memory")
; __device__ __forceinline__ unsigned pk2(float lo, float hi) { return f2bf(lo) | (f2bf(hi) << 16); }
;     ...
;       for (int i = 0; i < 32; ++i) scr[(2 * i + (lane >> 5)) * 33 + (lane & 31)] = wv[i]; }
;     LDS_WAIT(); asm volatile("" ::: "memory");
;     const int c = lane & 7;
;     const int r0 = (mode == 0) ? n0 : (256 * (n0 >> 7) + (n0 & 127) + (mode == 2 ? 128 : 0));
; #pragma unroll
;     for (int j = 0; j < 4; ++j) { const int n = (lane >> 3) + 8 * j; const LAS float* s = scr + (8 * c) * 33 + n;
;         v4u o; o.x = pk2(s[0 * 33], s[1 * 33]); o.y = pk2(s[2 * 33], s[3 * 33]); o.z = pk2(s[4 * 33], s[5 * 33]); o.w = pk2(s[6 * 33], s[7 * 33]);
;         *(GAS v4u*)(WT + (size_t)(r0 + n) * ldt + k0 + 8 * c) = o; }
;     LDS_WAIT(); asm volatile("" ::: "memory");
	ds_write2_b32 v9, v22, v23 offset0:148 offset1:214
	v_add_u32_e32 v9, 0xc00, v7
	s_waitcnt vmcnt(18)
	ds_write2_b32 v9, v24, v25 offset0:24 offset1:90
	s_waitcnt vmcnt(16)
	ds_write2_b32 v9, v26, v27 offset0:156 offset1:222
	v_add_u32_e32 v9, 0x1000, v7
	s_waitcnt vmcnt(14)
	ds_write2_b32 v9, v28, v29 offset0:32 offset1:98
	s_waitcnt vmcnt(12)
	ds_write2_b32 v9, v30, v31 offset0:164 offset1:230
	v_add_u32_e32 v9, 0x1400, v7
	s_waitcnt vmcnt(10)
	ds_write2_b32 v9, v32, v33 offset0:40 offset1:106
	s_waitcnt vmcnt(8)
	ds_write2_b32 v9, v34, v35 offset0:172 offset1:238
	v_add_u32_e32 v9, 0x1800, v7
	v_add_u32_e32 v7, 0x1c00, v7
	s_waitcnt vmcnt(6)
	ds_write2_b32 v9, v36, v37 offset0:48 offset1:114
	s_waitcnt vmcnt(4)
	ds_write2_b32 v9, v38, v39 offset0:180 offset1:246
	s_waitcnt vmcnt(2)
	ds_write2_b32 v7, v40, v41 offset0:56 offset1:122
	s_waitcnt vmcnt(0)
	ds_write2_b32 v7, v8, v6 offset0:188 offset1:254
	v_lshlrev_b32_e32 v6, 3, v10
	v_ashrrev_i32_e32 v28, 3, v10
	v_and_b32_e32 v6, 56, v6
	s_waitcnt lgkmcnt(0)
	v_mul_u32_u24_e32 v8, 0x84, v6
	v_lshlrev_b32_e32 v9, 2, v28
	v_add3_u32 v32, s41, v8, v9
	ds_read2_b32 v[12:13], v32 offset0:33 offset1:41
	ds_read2_b32 v[14:15], v32 offset1:8
	ds_read2_b32 v[16:17], v32 offset0:66 offset1:74
	ds_read2_b32 v[18:19], v32 offset0:99 offset1:107
	ds_read2_b32 v[20:21], v32 offset0:132 offset1:140
	ds_read2_b32 v[22:23], v32 offset0:165 offset1:173
	ds_read2_b32 v[24:25], v32 offset0:198 offset1:206
	ds_read2_b32 v[26:27], v32 offset0:231 offset1:239
	s_waitcnt lgkmcnt(7)
	v_bfe_u32 v9, v12, 16, 1
	s_waitcnt lgkmcnt(6)
	v_bfe_u32 v8, v14, 16, 1
	v_add3_u32 v8, v14, v8, s3
	v_lshrrev_b32_e32 v8, 16, v8
	v_add3_u32 v9, v12, v9, s3
	v_and_or_b32 v8, v9, s66, v8
	s_waitcnt lgkmcnt(5)
	v_bfe_u32 v9, v16, 16, 1
	v_add3_u32 v9, v16, v9, s3
	s_waitcnt lgkmcnt(4)
	v_bfe_u32 v10, v18, 16, 1
	v_lshrrev_b32_e32 v9, 16, v9
	v_add3_u32 v10, v18, v10, s3
	v_and_or_b32 v9, v10, s66, v9
	s_waitcnt lgkmcnt(3)
	v_bfe_u32 v10, v20, 16, 1
	v_add3_u32 v10, v20, v10, s3
	s_waitcnt lgkmcnt(2)
	v_bfe_u32 v11, v22, 16, 1
	v_lshrrev_b32_e32 v10, 16, v10
	v_add3_u32 v11, v22, v11, s3
	v_and_or_b32 v10, v11, s66, v10
	s_waitcnt lgkmcnt(1)
	v_bfe_u32 v11, v24, 16, 1
	v_add_u32_e32 v28, s26, v28
	v_lshlrev_b32_e32 v66, 1, v6
	v_add3_u32 v11, v24, v11, s3
	s_waitcnt lgkmcnt(0)
	v_bfe_u32 v12, v26, 16, 1
	v_ashrrev_i32_e32 v29, 31, v28
	v_lshl_add_u64 v[6:7], s[90:91], 0, v[66:67]
	v_lshrrev_b32_e32 v11, 16, v11
	v_add3_u32 v12, v26, v12, s3
	v_lshlrev_b64 v[30:31], 13, v[28:29]
	v_and_or_b32 v11, v12, s66, v11
	v_lshl_add_u64 v[30:31], v[6:7], 0, v[30:31]
	global_store_dwordx4 v[30:31], v[8:11], off
	v_bfe_u32 v12, v27, 16, 1
	v_add3_u32 v12, v27, v12, s3
	v_bfe_u32 v8, v15, 16, 1
	v_add3_u32 v8, v15, v8, s3
	v_bfe_u32 v9, v13, 16, 1
	v_lshrrev_b32_e32 v8, 16, v8
	v_add3_u32 v9, v13, v9, s3
	v_and_or_b32 v8, v9, s66, v8
	v_bfe_u32 v9, v17, 16, 1
	v_add3_u32 v9, v17, v9, s3
	v_bfe_u32 v10, v19, 16, 1
	v_lshrrev_b32_e32 v9, 16, v9
	v_add3_u32 v10, v19, v10, s3
	v_and_or_b32 v9, v10, s66, v9
	v_bfe_u32 v10, v21, 16, 1
	v_add3_u32 v10, v21, v10, s3
	v_bfe_u32 v11, v23, 16, 1
	v_lshrrev_b32_e32 v10, 16, v10
	v_add3_u32 v11, v23, v11, s3
	v_and_or_b32 v10, v11, s66, v10
	v_bfe_u32 v11, v25, 16, 1
	v_add3_u32 v11, v25, v11, s3
	v_lshrrev_b32_e32 v11, 16, v11
	v_and_or_b32 v11, v12, s66, v11
	v_add_u32_e32 v12, 8, v28
	v_ashrrev_i32_e32 v13, 31, v12
	v_lshlrev_b64 v[12:13], 13, v[12:13]
	v_lshl_add_u64 v[12:13], v[6:7], 0, v[12:13]
	global_store_dwordx4 v[12:13], v[8:11], off
	ds_read2_b32 v[12:13], v32 offset0:49 offset1:57
	ds_read2_b32 v[14:15], v32 offset0:16 offset1:24
	ds_read2_b32 v[16:17], v32 offset0:82 offset1:90
	ds_read2_b32 v[18:19], v32 offset0:115 offset1:123
	ds_read2_b32 v[20:21], v32 offset0:148 offset1:156
	ds_read2_b32 v[22:23], v32 offset0:181 offset1:189
	ds_read2_b32 v[24:25], v32 offset0:214 offset1:222
	ds_read2_b32 v[26:27], v32 offset0:247 offset1:255
	s_waitcnt lgkmcnt(7)
	v_bfe_u32 v9, v12, 16, 1
	s_waitcnt lgkmcnt(6)
	v_bfe_u32 v8, v14, 16, 1
	v_add3_u32 v8, v14, v8, s3
	v_lshrrev_b32_e32 v8, 16, v8
	v_add3_u32 v9, v12, v9, s3
	v_and_or_b32 v8, v9, s66, v8
	s_waitcnt lgkmcnt(5)
	v_bfe_u32 v9, v16, 16, 1
	v_add3_u32 v9, v16, v9, s3
	s_waitcnt lgkmcnt(4)
	v_bfe_u32 v10, v18, 16, 1
	v_lshrrev_b32_e32 v9, 16, v9
	v_add3_u32 v10, v18, v10, s3
	v_and_or_b32 v9, v10, s66, v9
	s_waitcnt lgkmcnt(3)
	v_bfe_u32 v10, v20, 16, 1
	v_add3_u32 v10, v20, v10, s3
	s_waitcnt lgkmcnt(2)
	v_bfe_u32 v11, v22, 16, 1
	v_lshrrev_b32_e32 v10, 16, v10
	v_add3_u32 v11, v22, v11, s3
	v_and_or_b32 v10, v11, s66, v10
	s_waitcnt lgkmcnt(1)
	v_bfe_u32 v11, v24, 16, 1
	v_add_u32_e32 v30, 16, v28
	v_add3_u32 v11, v24, v11, s3
	s_waitcnt lgkmcnt(0)
	v_bfe_u32 v12, v26, 16, 1
	v_ashrrev_i32_e32 v31, 31, v30
	v_lshrrev_b32_e32 v11, 16, v11
	v_add3_u32 v12, v26, v12, s3
	v_lshlrev_b64 v[30:31], 13, v[30:31]
	v_and_or_b32 v11, v12, s66, v11
	v_lshl_add_u64 v[30:31], v[6:7], 0, v[30:31]
	global_store_dwordx4 v[30:31], v[8:11], off
	v_bfe_u32 v12, v27, 16, 1
	v_add3_u32 v12, v27, v12, s3
	v_bfe_u32 v8, v15, 16, 1
	v_add3_u32 v8, v15, v8, s3
	v_bfe_u32 v9, v13, 16, 1
	v_lshrrev_b32_e32 v8, 16, v8
	v_add3_u32 v9, v13, v9, s3
	v_and_or_b32 v8, v9, s66, v8
	v_bfe_u32 v9, v17, 16, 1
	v_add3_u32 v9, v17, v9, s3
	v_bfe_u32 v10, v19, 16, 1
	v_lshrrev_b32_e32 v9, 16, v9
	v_add3_u32 v10, v19, v10, s3
	v_and_or_b32 v9, v10, s66, v9
	v_bfe_u32 v10, v21, 16, 1
	v_add3_u32 v10, v21, v10, s3
	v_bfe_u32 v11, v23, 16, 1
	v_lshrrev_b32_e32 v10, 16, v10
	v_add3_u32 v11, v23, v11, s3
	v_and_or_b32 v10, v11, s66, v10
	v_bfe_u32 v11, v25, 16, 1
	v_add3_u32 v11, v25, v11, s3
	v_lshrrev_b32_e32 v11, 16, v11
	v_and_or_b32 v11, v12, s66, v11
	v_add_u32_e32 v12, 24, v28
	v_ashrrev_i32_e32 v13, 31, v12
	v_lshlrev_b64 v[12:13], 13, v[12:13]
	v_lshl_add_u64 v[6:7], v[6:7], 0, v[12:13]
	global_store_dwordx4 v[6:7], v[8:11], off
	s_waitcnt lgkmcnt(0)
	v_readlane_b32 s57, v244, 15
	v_readlane_b32 s58, v244, 16
	v_readlane_b32 s59, v244, 17

;     if (ldt == 0) ldt = K;
;     asm volatile("" : "+v"(lane));
;     const int kb = item / nblk, nb = item % nblk, k0 = 64 * kb, n0 = 32 * nb;
;     { float wv[32];
;       const float* wp = W + (size_t)(k0 + (lane >> 5)) * ldw + n0 + (lane & 31);
; #pragma unroll
;       for (int i = 0; i < 32; ++i) wv[i] = wp[(size_t)(2 * i) * ldw];
; #pragma unroll
;       for (int i = 0; i < 32; ++i) scr[(2 * i + (lane >> 5)) * 33 + (lane & 31)] = wv[i]; }
; __device__ __forceinline__ void transpose_late(const Args& a, Frame& F, LAS float* scr, int r) {
;     ...
;     if (r < IT_SQ) { p0_transpose_item(a.in[I_WAOUT], D, D, WAB, 0, D / 32, scr, r, F.lane, 2 * D); return; } r -= IT_SQ;
.LBB0_1025:
	s_andn2_b64 vcc, exec, s[58:59]
	s_cbranch_vccnz .LBB0_997
	s_ashr_i32 s16, s61, 31
	s_lshr_b32 s16, s16, 26
	v_mov_b32_e32 v10, v145
	s_add_i32 s16, s61, s16
	s_and_b32 s60, s16, 0xffffffc0
	v_ashrrev_i32_e32 v11, 5, v10
	s_sub_i32 s16, s61, s60
	v_add_u32_e32 v6, s60, v11
	s_lshl_b32 s58, s16, 5
	v_ashrrev_i32_e32 v7, 31, v6
	v_readlane_b32 s16, v245, 50
	v_lshlrev_b64 v[6:7], 13, v[6:7]
	v_readlane_b32 s24, v245, 58
	v_readlane_b32 s25, v245, 59
	s_ashr_i32 s59, s58, 31
	v_lshlrev_b32_e32 v8, 2, v10
	v_lshl_add_u64 v[6:7], s[24:25], 0, v[6:7]
	v_lshl_add_u64 v[6:7], s[58:59], 2, v[6:7]
	v_and_b32_e32 v66, 0x7c, v8
	v_lshl_add_u64 v[6:7], v[6:7], 0, v[66:67]
	v_add_co_u32_e32 v8, vcc, s83, v6
	global_load_dword v12, v[6:7], off nt
	s_nop 0
	v_addc_co_u32_e32 v9, vcc, 0, v7, vcc
	global_load_dword v13, v[8:9], off nt
	v_add_co_u32_e32 v8, vcc, s85, v6
	s_mov_b32 s16, 0x30000
	s_nop 0
	v_addc_co_u32_e32 v9, vcc, 0, v7, vcc
	global_load_dword v14, v[8:9], off nt
	v_add_co_u32_e32 v8, vcc, s72, v6
	v_readlane_b32 s26, v245, 60
	s_nop 0
	v_addc_co_u32_e32 v9, vcc, 0, v7, vcc
	global_load_dword v15, v[8:9], off nt
	v_add_co_u32_e32 v8, vcc, s73, v6
	v_readlane_b32 s27, v245, 61
	s_nop 0
	v_addc_co_u32_e32 v9, vcc, 0, v7, vcc
	global_load_dword v16, v[8:9], off nt
	v_add_co_u32_e32 v8, vcc, s74, v6
	s_ashr_i32 s61, s60, 31
	s_nop 0
	v_addc_co_u32_e32 v9, vcc, 0, v7, vcc
	global_load_dword v17, v[8:9], off nt
	v_add_co_u32_e32 v8, vcc, s75, v6
	s_lshl_b64 s[26:27], s[60:61], 1
	s_nop 0
	v_addc_co_u32_e32 v9, vcc, 0, v7, vcc
	global_load_dword v18, v[8:9], off nt
	v_add_co_u32_e32 v8, vcc, s88, v6
	s_add_u32 s26, s97, s26
	s_nop 0
	v_addc_co_u32_e32 v9, vcc, 0, v7, vcc
	global_load_dword v19, v[8:9], off nt
	v_add_co_u32_e32 v8, vcc, s15, v6
	s_addc_u32 s27, s82, s27
	s_nop 0
	v_addc_co_u32_e32 v9, vcc, 0, v7, vcc
	global_load_dword v20, v[8:9], off nt
	v_add_co_u32_e32 v8, vcc, s78, v6
	v_readlane_b32 s17, v245, 51
	s_nop 0
	v_addc_co_u32_e32 v9, vcc, 0, v7, vcc
	global_load_dword v21, v[8:9], off nt
	v_add_co_u32_e32 v8, vcc, s79, v6
	v_readlane_b32 s18, v245, 52
	s_nop 0
	v_addc_co_u32_e32 v9, vcc, 0, v7, vcc
	global_load_dword v22, v[8:9], off nt
	v_add_co_u32_e32 v8, vcc, s14, v6
	v_readlane_b32 s19, v245, 53
	s_nop 0
	v_addc_co_u32_e32 v9, vcc, 0, v7, vcc
	global_load_dword v23, v[8:9], off nt
	v_add_co_u32_e32 v8, vcc, s16, v6
	s_mov_b32 s16, 0x34000
	s_nop 0
	v_addc_co_u32_e32 v9, vcc, 0, v7, vcc
	global_load_dword v24, v[8:9], off nt
	v_add_co_u32_e32 v8, vcc, s16, v6
	s_mov_b32 s16, 0x38000
	s_nop 0
	v_addc_co_u32_e32 v9, vcc, 0, v7, vcc
	global_load_dword v25, v[8:9], off nt
	v_add_co_u32_e32 v8, vcc, s16, v6
	s_mov_b32 s16, 0x3c000
	s_nop 0
	v_addc_co_u32_e32 v9, vcc, 0, v7, vcc
	global_load_dword v26, v[8:9], off nt
	v_add_co_u32_e32 v8, vcc, s16, v6
	s_mov_b32 s16, 0x40000
	s_nop 0
	v_addc_co_u32_e32 v9, vcc, 0, v7, vcc
	global_load_dword v27, v[8:9], off nt
	v_add_co_u32_e32 v8, vcc, s16, v6
	s_mov_b32 s16, 0x44000
	s_nop 0
	v_addc_co_u32_e32 v9, vcc, 0, v7, vcc
	global_load_dword v28, v[8:9], off nt
	v_add_co_u32_e32 v8, vcc, s16, v6
	s_mov_b32 s16, 0x48000
	s_nop 0
	v_addc_co_u32_e32 v9, vcc, 0, v7, vcc
	global_load_dword v29, v[8:9], off nt
	v_add_co_u32_e32 v8, vcc, s16, v6
	s_mov_b32 s16, 0x4c000
	s_nop 0
	v_addc_co_u32_e32 v9, vcc, 0, v7, vcc
	global_load_dword v30, v[8:9], off nt
	v_add_co_u32_e32 v8, vcc, s16, v6
	s_mov_b32 s16, 0x50000
	s_nop 0
	v_addc_co_u32_e32 v9, vcc, 0, v7, vcc
	global_load_dword v31, v[8:9], off nt
	v_add_co_u32_e32 v8, vcc, s16, v6
	s_mov_b32 s16, 0x54000
	s_nop 0
	v_addc_co_u32_e32 v9, vcc, 0, v7, vcc
	global_load_dword v32, v[8:9], off nt
	v_add_co_u32_e32 v8, vcc, s16, v6
	s_mov_b32 s16, 0x5c000
	s_nop 0
	v_addc_co_u32_e32 v9, vcc, 0, v7, vcc
	global_load_dword v33, v[8:9], off nt
	v_add_co_u32_e32 v8, vcc, s64, v6
	v_readlane_b32 s20, v245, 54
	s_nop 0
	v_addc_co_u32_e32 v9, vcc, 0, v7, vcc
	global_load_dword v34, v[8:9], off nt
	v_add_co_u32_e32 v8, vcc, s16, v6
	s_mov_b32 s16, 0x60000
	s_nop 0
	v_addc_co_u32_e32 v9, vcc, 0, v7, vcc
	global_load_dword v35, v[8:9], off nt
	v_add_co_u32_e32 v8, vcc, s16, v6
	s_mov_b32 s16, 0x64000
	s_nop 0
	v_addc_co_u32_e32 v9, vcc, 0, v7, vcc
	global_load_dword v36, v[8:9], off nt
	v_add_co_u32_e32 v8, vcc, s16, v6
	s_mov_b32 s16, 0x68000
	s_nop 0
	v_addc_co_u32_e32 v9, vcc, 0, v7, vcc
	global_load_dword v37, v[8:9], off nt
	v_add_co_u32_e32 v8, vcc, s16, v6
	s_mov_b32 s16, 0x6c000
	s_nop 0
	v_addc_co_u32_e32 v9, vcc, 0, v7, vcc
	global_load_dword v38, v[8:9], off nt
	v_add_co_u32_e32 v8, vcc, s16, v6
	s_mov_b32 s16, 0x70000
	s_nop 0
	v_addc_co_u32_e32 v9, vcc, 0, v7, vcc
	global_load_dword v39, v[8:9], off nt
	v_add_co_u32_e32 v8, vcc, s16, v6
	s_mov_b32 s16, 0x74000
	s_nop 0
	v_addc_co_u32_e32 v9, vcc, 0, v7, vcc
	global_load_dword v40, v[8:9], off nt
	v_add_co_u32_e32 v8, vcc, s16, v6
	s_mov_b32 s16, 0x78000
	s_nop 0
	v_addc_co_u32_e32 v9, vcc, 0, v7, vcc
	global_load_dword v41, v[8:9], off nt
	v_add_co_u32_e32 v8, vcc, s16, v6
	s_mov_b32 s16, 0x7c000
	s_nop 0
	v_addc_co_u32_e32 v9, vcc, 0, v7, vcc
	v_add_co_u32_e32 v6, vcc, s16, v6
	global_load_dword v8, v[8:9], off nt
	s_nop 0
	v_addc_co_u32_e32 v7, vcc, 0, v7, vcc
	global_load_dword v6, v[6:7], off nt
	s_movk_i32 s16, 0x84
	v_mul_lo_u32 v7, v11, s16
	v_add3_u32 v7, s41, v66, v7
	v_add_u32_e32 v9, 0x400, v7
	s_waitcnt vmcnt(30)
	ds_write2_b32 v7, v12, v13 offset1:66
	s_waitcnt vmcnt(28)
	ds_write2_b32 v7, v14, v15 offset0:132 offset1:198
	s_waitcnt vmcnt(26)
	ds_write2_b32 v9, v16, v17 offset0:8 offset1:74
	s_waitcnt vmcnt(24)
	ds_write2_b32 v9, v18, v19 offset0:140 offset1:206
	v_add_u32_e32 v9, 0x800, v7
	s_waitcnt vmcnt(22)
; #define GAS __attribute__((address_space(1)))
; #define LAS __attribute__((address_space(3)))
; #define LDS_WAIT() asm volatile("s_waitcnt lgkmcnt(0)" ::: "memory")
; __device__ __forceinline__ unsigned pk2(float lo, float hi) { return f2bf(lo) | (f2bf(hi) << 16); }
;     ...
;       for (int i = 0; i < 32; ++i) scr[(2 * i + (lane >> 5)) * 33 + (lane & 31)] = wv[i]; }
;     LDS_WAIT(); asm volatile("" ::: "memory");
;     const int c = lane & 7;
;     const int r0 = (mode == 0) ? n0 : (256 * (n0 >> 7) + (n0 & 127) + (mode == 2 ? 128 : 0));
; #pragma unroll
;     for (int j = 0; j < 4; ++j) { const int n = (lane >> 3) + 8 * j; const LAS float* s = scr + (8 * c) * 33 + n;
;         v4u o; o.x = pk2(s[0 * 33], s[1 * 33]); o.y = pk2(s[2 * 33], s[3 * 33]); o.z = pk2(s[4 * 33], s[5 * 33]); o.w = pk2(s[6 * 33], s[7 * 33]);
;         *(GAS v4u*)(WT + (size_t)(r0 + n) * ldt + k0 + 8 * c) = o; }
;     LDS_WAIT(); asm volatile("" ::: "memory");
	ds_write2_b32 v9, v20, v21 offset0:16 offset1:82
	s_waitcnt vmcnt(20)
	ds_write2_b32 v9, v22, v23 offset0:148 offset1:214
	v_add_u32_e32 v9, 0xc00, v7
	s_waitcnt vmcnt(18)
	ds_write2_b32 v9, v24, v25 offset0:24 offset1:90
	s_waitcnt vmcnt(16)
	ds_write2_b32 v9, v26, v27 offset0:156 offset1:222
	v_add_u32_e32 v9, 0x1000, v7
	s_waitcnt vmcnt(14)
	ds_write2_b32 v9, v28, v29 offset0:32 offset1:98
	s_waitcnt vmcnt(12)
	ds_write2_b32 v9, v30, v31 offset0:164 offset1:230
	v_add_u32_e32 v9, 0x1400, v7
	s_waitcnt vmcnt(10)
	ds_write2_b32 v9, v32, v33 offset0:40 offset1:106
	s_waitcnt vmcnt(8)
	ds_write2_b32 v9, v34, v35 offset0:172 offset1:238
	v_add_u32_e32 v9, 0x1800, v7
	v_add_u32_e32 v7, 0x1c00, v7
	s_waitcnt vmcnt(6)
	ds_write2_b32 v9, v36, v37 offset0:48 offset1:114
	s_waitcnt vmcnt(4)
	ds_write2_b32 v9, v38, v39 offset0:180 offset1:246
	s_waitcnt vmcnt(2)
	ds_write2_b32 v7, v40, v41 offset0:56 offset1:122
	s_waitcnt vmcnt(0)
	ds_write2_b32 v7, v8, v6 offset0:188 offset1:254
	v_lshlrev_b32_e32 v6, 3, v10
	v_ashrrev_i32_e32 v28, 3, v10
	v_and_b32_e32 v6, 56, v6
	s_waitcnt lgkmcnt(0)
	v_mul_u32_u24_e32 v8, 0x84, v6
	v_lshlrev_b32_e32 v9, 2, v28
	v_add3_u32 v32, s41, v8, v9
	ds_read2_b32 v[12:13], v32 offset0:33 offset1:41
	ds_read2_b32 v[14:15], v32 offset1:8
	ds_read2_b32 v[16:17], v32 offset0:66 offset1:74
	ds_read2_b32 v[18:19], v32 offset0:99 offset1:107
	ds_read2_b32 v[20:21], v32 offset0:132 offset1:140
	ds_read2_b32 v[22:23], v32 offset0:165 offset1:173
	ds_read2_b32 v[24:25], v32 offset0:198 offset1:206
	ds_read2_b32 v[26:27], v32 offset0:231 offset1:239
	s_waitcnt lgkmcnt(7)
	v_bfe_u32 v9, v12, 16, 1
	s_waitcnt lgkmcnt(6)
	v_bfe_u32 v8, v14, 16, 1
	v_add3_u32 v8, v14, v8, s3
	v_lshrrev_b32_e32 v8, 16, v8
	v_add3_u32 v9, v12, v9, s3
	v_and_or_b32 v8, v9, s66, v8
	s_waitcnt lgkmcnt(5)
	v_bfe_u32 v9, v16, 16, 1
	v_add3_u32 v9, v16, v9, s3
	s_waitcnt lgkmcnt(4)
	v_bfe_u32 v10, v18, 16, 1
	v_lshrrev_b32_e32 v9, 16, v9
	v_add3_u32 v10, v18, v10, s3
	v_and_or_b32 v9, v10, s66, v9
	s_waitcnt lgkmcnt(3)
	v_bfe_u32 v10, v20, 16, 1
	v_add3_u32 v10, v20, v10, s3
	s_waitcnt lgkmcnt(2)
	v_bfe_u32 v11, v22, 16, 1
	v_lshrrev_b32_e32 v10, 16, v10
	v_add3_u32 v11, v22, v11, s3
	v_and_or_b32 v10, v11, s66, v10
	s_waitcnt lgkmcnt(1)
	v_bfe_u32 v11, v24, 16, 1
	v_add_u32_e32 v28, s58, v28
	v_lshlrev_b32_e32 v66, 1, v6
	v_add3_u32 v11, v24, v11, s3
	s_waitcnt lgkmcnt(0)
	v_bfe_u32 v12, v26, 16, 1
	v_ashrrev_i32_e32 v29, 31, v28
	v_lshl_add_u64 v[6:7], s[26:27], 0, v[66:67]
	v_lshrrev_b32_e32 v11, 16, v11
	v_add3_u32 v12, v26, v12, s3
	v_lshlrev_b64 v[30:31], 13, v[28:29]
	v_and_or_b32 v11, v12, s66, v11
	v_lshl_add_u64 v[30:31], v[6:7], 0, v[30:31]
	global_store_dwordx4 v[30:31], v[8:11], off
	v_bfe_u32 v12, v27, 16, 1
	v_add3_u32 v12, v27, v12, s3
	v_bfe_u32 v8, v15, 16, 1
	v_add3_u32 v8, v15, v8, s3
	v_bfe_u32 v9, v13, 16, 1
	v_lshrrev_b32_e32 v8, 16, v8
	v_add3_u32 v9, v13, v9, s3
	v_and_or_b32 v8, v9, s66, v8
	v_bfe_u32 v9, v17, 16, 1
	v_add3_u32 v9, v17, v9, s3
	v_bfe_u32 v10, v19, 16, 1
	v_lshrrev_b32_e32 v9, 16, v9
	v_add3_u32 v10, v19, v10, s3
	v_and_or_b32 v9, v10, s66, v9
	v_bfe_u32 v10, v21, 16, 1
	v_add3_u32 v10, v21, v10, s3
	v_bfe_u32 v11, v23, 16, 1
	v_lshrrev_b32_e32 v10, 16, v10
	v_add3_u32 v11, v23, v11, s3
	v_and_or_b32 v10, v11, s66, v10
	v_bfe_u32 v11, v25, 16, 1
	v_add3_u32 v11, v25, v11, s3
	v_lshrrev_b32_e32 v11, 16, v11
	v_and_or_b32 v11, v12, s66, v11
	v_add_u32_e32 v12, 8, v28
	v_ashrrev_i32_e32 v13, 31, v12
	v_lshlrev_b64 v[12:13], 13, v[12:13]
	v_lshl_add_u64 v[12:13], v[6:7], 0, v[12:13]
	global_store_dwordx4 v[12:13], v[8:11], off
	ds_read2_b32 v[12:13], v32 offset0:49 offset1:57
	ds_read2_b32 v[14:15], v32 offset0:16 offset1:24
	ds_read2_b32 v[16:17], v32 offset0:82 offset1:90
	ds_read2_b32 v[18:19], v32 offset0:115 offset1:123
	ds_read2_b32 v[20:21], v32 offset0:148 offset1:156
	ds_read2_b32 v[22:23], v32 offset0:181 offset1:189
	ds_read2_b32 v[24:25], v32 offset0:214 offset1:222
	ds_read2_b32 v[26:27], v32 offset0:247 offset1:255
	s_waitcnt lgkmcnt(7)
	v_bfe_u32 v9, v12, 16, 1
	s_waitcnt lgkmcnt(6)
	v_bfe_u32 v8, v14, 16, 1
	v_add3_u32 v8, v14, v8, s3
	v_lshrrev_b32_e32 v8, 16, v8
	v_add3_u32 v9, v12, v9, s3
	v_and_or_b32 v8, v9, s66, v8
	s_waitcnt lgkmcnt(5)
	v_bfe_u32 v9, v16, 16, 1
	v_add3_u32 v9, v16, v9, s3
	s_waitcnt lgkmcnt(4)
	v_bfe_u32 v10, v18, 16, 1
	v_lshrrev_b32_e32 v9, 16, v9
	v_add3_u32 v10, v18, v10, s3
	v_and_or_b32 v9, v10, s66, v9
	s_waitcnt lgkmcnt(3)
	v_bfe_u32 v10, v20, 16, 1
	v_add3_u32 v10, v20, v10, s3
	s_waitcnt lgkmcnt(2)
	v_bfe_u32 v11, v22, 16, 1
	v_lshrrev_b32_e32 v10, 16, v10
	v_add3_u32 v11, v22, v11, s3
	v_and_or_b32 v10, v11, s66, v10
	s_waitcnt lgkmcnt(1)
	v_bfe_u32 v11, v24, 16, 1
	v_add_u32_e32 v30, 16, v28
	v_add3_u32 v11, v24, v11, s3
	s_waitcnt lgkmcnt(0)
	v_bfe_u32 v12, v26, 16, 1
	v_ashrrev_i32_e32 v31, 31, v30
	v_lshrrev_b32_e32 v11, 16, v11
	v_add3_u32 v12, v26, v12, s3
	v_lshlrev_b64 v[30:31], 13, v[30:31]
	v_and_or_b32 v11, v12, s66, v11
	v_lshl_add_u64 v[30:31], v[6:7], 0, v[30:31]
	global_store_dwordx4 v[30:31], v[8:11], off
	v_bfe_u32 v12, v27, 16, 1
	v_add3_u32 v12, v27, v12, s3
	v_bfe_u32 v8, v15, 16, 1
	v_add3_u32 v8, v15, v8, s3
	v_bfe_u32 v9, v13, 16, 1
	v_lshrrev_b32_e32 v8, 16, v8
	v_add3_u32 v9, v13, v9, s3
	v_and_or_b32 v8, v9, s66, v8
	v_bfe_u32 v9, v17, 16, 1
	v_add3_u32 v9, v17, v9, s3
	v_bfe_u32 v10, v19, 16, 1
	v_lshrrev_b32_e32 v9, 16, v9
	v_add3_u32 v10, v19, v10, s3
	v_and_or_b32 v9, v10, s66, v9
	v_bfe_u32 v10, v21, 16, 1
	v_add3_u32 v10, v21, v10, s3
	v_bfe_u32 v11, v23, 16, 1
	v_lshrrev_b32_e32 v10, 16, v10
	v_add3_u32 v11, v23, v11, s3
	v_and_or_b32 v10, v11, s66, v10
	v_bfe_u32 v11, v25, 16, 1
	v_add3_u32 v11, v25, v11, s3
	v_lshrrev_b32_e32 v11, 16, v11
	v_and_or_b32 v11, v12, s66, v11
	v_add_u32_e32 v12, 24, v28
	v_ashrrev_i32_e32 v13, 31, v12
	v_lshlrev_b64 v[12:13], 13, v[12:13]
	v_lshl_add_u64 v[6:7], v[6:7], 0, v[12:13]
	global_store_dwordx4 v[6:7], v[8:11], off
	s_waitcnt lgkmcnt(0)
	v_readlane_b32 s21, v245, 55
	v_readlane_b32 s22, v245, 56
	v_readlane_b32 s23, v245, 57
	v_readlane_b32 s28, v245, 62
	v_readlane_b32 s29, v245, 63
	v_readlane_b32 s30, v244, 0
	v_readlane_b32 s31, v244, 1
	s_branch .LBB0_997

; #define GAS __attribute__((address_space(1)))
; #define LAS __attribute__((address_space(3)))
; #define LDS_WAIT() asm volatile("s_waitcnt lgkmcnt(0)" ::: "memory")
; __device__ __forceinline__ unsigned pk2(float lo, float hi) { return f2bf(lo) | (f2bf(hi) << 16); }
;     ...
;     { float wv[32];
;       const float* wp = W + (size_t)(k0 + (lane >> 5)) * ldw + n0 + (lane & 31);
; #pragma unroll
;       for (int i = 0; i < 32; ++i) wv[i] = wp[(size_t)(2 * i) * ldw];
; #pragma unroll
;       for (int i = 0; i < 32; ++i) scr[(2 * i + (lane >> 5)) * 33 + (lane & 31)] = wv[i]; }
;     LDS_WAIT(); asm volatile("" ::: "memory");
;     const int c = lane & 7;
;     const int r0 = (mode == 0) ? n0 : (256 * (n0 >> 7) + (n0 & 127) + (mode == 2 ? 128 : 0));
; #pragma unroll
;     for (int j = 0; j < 4; ++j) { const int n = (lane >> 3) + 8 * j; const LAS float* s = scr + (8 * c) * 33 + n;
;         v4u o; o.x = pk2(s[0 * 33], s[1 * 33]); o.y = pk2(s[2 * 33], s[3 * 33]); o.z = pk2(s[4 * 33], s[5 * 33]); o.w = pk2(s[6 * 33], s[7 * 33]);
;         *(GAS v4u*)(WT + (size_t)(r0 + n) * ldt + k0 + 8 * c) = o; }
; __device__ __forceinline__ void transpose_late(const Args& a, Frame& F, LAS float* scr, int r) {
;     ...
;     if (r < IT_PU) { p0_transpose_item(a.in[I_WPU], D, DPLE, WPU, 0, D / 32, scr, r, F.lane); return; } r -= IT_PU;
.LBB0_1240:
	s_andn2_b64 vcc, exec, s[6:7]
	s_cbranch_vccnz .LBB0_1242
	v_mov_b32_e32 v7, v6
	s_and_b32 s7, s94, 0xc0
	v_ashrrev_i32_e32 v10, 5, v7
	v_add_u32_e32 v4, s7, v10
	v_ashrrev_i32_e32 v5, 31, v4
	v_readlane_b32 s36, v245, 0
	s_and_b32 s6, s22, 0x7e0
	v_lshlrev_b64 v[4:5], 13, v[4:5]
	v_readlane_b32 s42, v245, 6
	v_readlane_b32 s43, v245, 7
	s_lshl_b32 s0, s6, 2
	v_lshlrev_b32_e32 v2, 2, v7
	v_lshl_add_u64 v[4:5], s[42:43], 0, v[4:5]
	v_lshl_add_u64 v[4:5], v[4:5], 0, s[0:1]
	v_and_b32_e32 v2, 0x7c, v2
	v_lshl_add_u64 v[4:5], v[4:5], 0, v[2:3]
	v_add_co_u32_e32 v8, vcc, s64, v4
	global_load_dword v11, v[4:5], off nt
	s_nop 0
	v_addc_co_u32_e32 v9, vcc, 0, v5, vcc
	global_load_dword v12, v[8:9], off nt
	v_add_co_u32_e32 v8, vcc, s65, v4
	s_lshl_b32 s0, s7, 1
	s_nop 0
	v_addc_co_u32_e32 v9, vcc, 0, v5, vcc
	global_load_dword v13, v[8:9], off nt
	v_add_co_u32_e32 v8, vcc, s66, v4
	s_add_u32 s44, s15, s0
	s_nop 0
	v_addc_co_u32_e32 v9, vcc, 0, v5, vcc
	global_load_dword v14, v[8:9], off nt
	v_add_co_u32_e32 v8, vcc, s67, v4
	s_addc_u32 s45, s16, 0
	s_nop 0
	v_addc_co_u32_e32 v9, vcc, 0, v5, vcc
	global_load_dword v15, v[8:9], off nt
	v_add_co_u32_e32 v8, vcc, s68, v4
	v_readlane_b32 s37, v245, 1
	s_nop 0
	v_addc_co_u32_e32 v9, vcc, 0, v5, vcc
	global_load_dword v16, v[8:9], off nt
	v_add_co_u32_e32 v8, vcc, s69, v4
	v_readlane_b32 s38, v245, 2
	s_nop 0
	v_addc_co_u32_e32 v9, vcc, 0, v5, vcc
	global_load_dword v17, v[8:9], off nt
	v_add_co_u32_e32 v8, vcc, s70, v4
	v_readlane_b32 s39, v245, 3
	s_nop 0
	v_addc_co_u32_e32 v9, vcc, 0, v5, vcc
	global_load_dword v18, v[8:9], off nt
	v_add_co_u32_e32 v8, vcc, s71, v4
	v_readlane_b32 s40, v245, 4
	s_nop 0
	v_addc_co_u32_e32 v9, vcc, 0, v5, vcc
	global_load_dword v19, v[8:9], off nt
	v_add_co_u32_e32 v8, vcc, s72, v4
	v_readlane_b32 s41, v245, 5
	s_nop 0
	v_addc_co_u32_e32 v9, vcc, 0, v5, vcc
	global_load_dword v20, v[8:9], off nt
	v_add_co_u32_e32 v8, vcc, s73, v4
	s_nop 1
	v_addc_co_u32_e32 v9, vcc, 0, v5, vcc
	global_load_dword v21, v[8:9], off nt
	v_add_co_u32_e32 v8, vcc, s27, v4
	s_nop 1
	v_addc_co_u32_e32 v9, vcc, 0, v5, vcc
	global_load_dword v22, v[8:9], off nt
	v_add_co_u32_e32 v8, vcc, s74, v4
	s_nop 1
	v_addc_co_u32_e32 v9, vcc, 0, v5, vcc
	global_load_dword v23, v[8:9], off nt
	v_add_co_u32_e32 v8, vcc, s75, v4
	s_nop 1
	v_addc_co_u32_e32 v9, vcc, 0, v5, vcc
	global_load_dword v24, v[8:9], off nt
	v_add_co_u32_e32 v8, vcc, s76, v4
	s_nop 1
	v_addc_co_u32_e32 v9, vcc, 0, v5, vcc
	global_load_dword v25, v[8:9], off nt
	v_add_co_u32_e32 v8, vcc, s77, v4
	s_nop 1
	v_addc_co_u32_e32 v9, vcc, 0, v5, vcc
	global_load_dword v26, v[8:9], off nt
	v_add_co_u32_e32 v8, vcc, s78, v4
	s_nop 1
	v_addc_co_u32_e32 v9, vcc, 0, v5, vcc
	global_load_dword v27, v[8:9], off nt
	v_add_co_u32_e32 v8, vcc, s79, v4
	s_nop 1
	v_addc_co_u32_e32 v9, vcc, 0, v5, vcc
	global_load_dword v28, v[8:9], off nt
	v_add_co_u32_e32 v8, vcc, s80, v4
	s_nop 1
	v_addc_co_u32_e32 v9, vcc, 0, v5, vcc
	global_load_dword v29, v[8:9], off nt
	v_add_co_u32_e32 v8, vcc, s81, v4
	s_nop 1
	v_addc_co_u32_e32 v9, vcc, 0, v5, vcc
	global_load_dword v30, v[8:9], off nt
	v_add_co_u32_e32 v8, vcc, s82, v4
	s_nop 1
	v_addc_co_u32_e32 v9, vcc, 0, v5, vcc
	global_load_dword v31, v[8:9], off nt
	v_add_co_u32_e32 v8, vcc, s83, v4
	s_nop 1
	v_addc_co_u32_e32 v9, vcc, 0, v5, vcc
	global_load_dword v32, v[8:9], off nt
	v_add_co_u32_e32 v8, vcc, s31, v4
	s_nop 1
	v_addc_co_u32_e32 v9, vcc, 0, v5, vcc
	global_load_dword v33, v[8:9], off nt
	v_add_co_u32_e32 v8, vcc, s85, v4
	s_nop 1
	v_addc_co_u32_e32 v9, vcc, 0, v5, vcc
	global_load_dword v34, v[8:9], off nt
	v_add_co_u32_e32 v8, vcc, s86, v4
	s_nop 1
	v_addc_co_u32_e32 v9, vcc, 0, v5, vcc
	global_load_dword v35, v[8:9], off nt
	v_add_co_u32_e32 v8, vcc, s87, v4
	s_nop 1
	v_addc_co_u32_e32 v9, vcc, 0, v5, vcc
	global_load_dword v36, v[8:9], off nt
	v_add_co_u32_e32 v8, vcc, s88, v4
	s_nop 1
	v_addc_co_u32_e32 v9, vcc, 0, v5, vcc
	global_load_dword v37, v[8:9], off nt
	v_add_co_u32_e32 v8, vcc, s89, v4
	s_nop 1
	v_addc_co_u32_e32 v9, vcc, 0, v5, vcc
	global_load_dword v38, v[8:9], off nt
	v_add_co_u32_e32 v8, vcc, s90, v4
	s_nop 1
	v_addc_co_u32_e32 v9, vcc, 0, v5, vcc
	global_load_dword v39, v[8:9], off nt
	v_add_co_u32_e32 v8, vcc, s91, v4
	s_nop 1
	v_addc_co_u32_e32 v9, vcc, 0, v5, vcc
	global_load_dword v40, v[8:9], off nt
	v_add_co_u32_e32 v8, vcc, s92, v4
	s_nop 1
	v_addc_co_u32_e32 v9, vcc, 0, v5, vcc
	v_add_co_u32_e32 v4, vcc, s93, v4
	global_load_dword v8, v[8:9], off nt
	s_nop 0
	v_addc_co_u32_e32 v5, vcc, 0, v5, vcc
	global_load_dword v4, v[4:5], off nt
	v_mul_lo_u32 v5, v10, s61
	v_add3_u32 v2, s10, v2, v5
	v_add_u32_e32 v5, 0x400, v2
	s_waitcnt vmcnt(0)
	ds_write2_b32 v2, v11, v12 offset1:66
	ds_write2_b32 v2, v13, v14 offset0:132 offset1:198
	ds_write2_b32 v5, v15, v16 offset0:8 offset1:74
	ds_write2_b32 v5, v17, v18 offset0:140 offset1:206
	v_add_u32_e32 v5, 0x800, v2
	ds_write2_b32 v5, v19, v20 offset0:16 offset1:82
	ds_write2_b32 v5, v21, v22 offset0:148 offset1:214
	v_add_u32_e32 v5, 0xc00, v2
	ds_write2_b32 v5, v23, v24 offset0:24 offset1:90
	ds_write2_b32 v5, v25, v26 offset0:156 offset1:222
	v_add_u32_e32 v5, 0x1000, v2
	ds_write2_b32 v5, v27, v28 offset0:32 offset1:98
	ds_write2_b32 v5, v29, v30 offset0:164 offset1:230
	v_add_u32_e32 v5, 0x1400, v2
	ds_write2_b32 v5, v31, v32 offset0:40 offset1:106
	ds_write2_b32 v5, v33, v34 offset0:172 offset1:238
	v_add_u32_e32 v5, 0x1800, v2
	v_add_u32_e32 v2, 0x1c00, v2
	ds_write2_b32 v5, v35, v36 offset0:48 offset1:114
	ds_write2_b32 v5, v37, v38 offset0:180 offset1:246
	ds_write2_b32 v2, v39, v40 offset0:56 offset1:122
	ds_write2_b32 v2, v8, v4 offset0:188 offset1:254
	v_lshlrev_b32_e32 v2, 3, v7
	v_and_b32_e32 v2, 56, v2
	v_ashrrev_i32_e32 v28, 3, v7
	v_mul_u32_u24_e32 v7, 0x84, v2
	v_lshlrev_b32_e32 v2, 1, v2
	s_waitcnt lgkmcnt(0)
; #define GAS __attribute__((address_space(1)))
; #define LAS __attribute__((address_space(3)))
; #define LDS_WAIT() asm volatile("s_waitcnt lgkmcnt(0)" ::: "memory")
; __device__ __forceinline__ unsigned pk2(float lo, float hi) { return f2bf(lo) | (f2bf(hi) << 16); }
;     ...
;     const int c = lane & 7;
;     const int r0 = (mode == 0) ? n0 : (256 * (n0 >> 7) + (n0 & 127) + (mode == 2 ? 128 : 0));
; #pragma unroll
;     for (int j = 0; j < 4; ++j) { const int n = (lane >> 3) + 8 * j; const LAS float* s = scr + (8 * c) * 33 + n;
;         v4u o; o.x = pk2(s[0 * 33], s[1 * 33]); o.y = pk2(s[2 * 33], s[3 * 33]); o.z = pk2(s[4 * 33], s[5 * 33]); o.w = pk2(s[6 * 33], s[7 * 33]);
;         *(GAS v4u*)(WT + (size_t)(r0 + n) * ldt + k0 + 8 * c) = o; }
;     LDS_WAIT(); asm volatile("" ::: "memory");
	v_lshl_add_u64 v[4:5], s[44:45], 0, v[2:3]
	v_lshlrev_b32_e32 v2, 2, v28
	v_add3_u32 v2, s10, v7, v2
	ds_read2_b32 v[12:13], v2 offset0:33 offset1:41
	ds_read2_b32 v[14:15], v2 offset1:8
	ds_read2_b32 v[16:17], v2 offset0:66 offset1:74
	ds_read2_b32 v[18:19], v2 offset0:99 offset1:107
	ds_read2_b32 v[20:21], v2 offset0:132 offset1:140
	ds_read2_b32 v[22:23], v2 offset0:165 offset1:173
	ds_read2_b32 v[24:25], v2 offset0:198 offset1:206
	ds_read2_b32 v[26:27], v2 offset0:231 offset1:239
	s_waitcnt lgkmcnt(7)
	v_bfe_u32 v8, v12, 16, 1
	s_waitcnt lgkmcnt(6)
	v_bfe_u32 v7, v14, 16, 1
	v_add3_u32 v7, v14, v7, s62
	v_lshrrev_b32_e32 v7, 16, v7
	v_add3_u32 v8, v12, v8, s62
	v_and_or_b32 v8, v8, s63, v7
	s_waitcnt lgkmcnt(5)
	v_bfe_u32 v7, v16, 16, 1
	v_add3_u32 v7, v16, v7, s62
	s_waitcnt lgkmcnt(4)
	v_bfe_u32 v9, v18, 16, 1
	v_lshrrev_b32_e32 v7, 16, v7
	v_add3_u32 v9, v18, v9, s62
	v_and_or_b32 v9, v9, s63, v7
	s_waitcnt lgkmcnt(3)
	v_bfe_u32 v7, v20, 16, 1
	v_add3_u32 v7, v20, v7, s62
	s_waitcnt lgkmcnt(2)
	v_bfe_u32 v10, v22, 16, 1
	v_lshrrev_b32_e32 v7, 16, v7
	v_add3_u32 v10, v22, v10, s62
	v_and_or_b32 v10, v10, s63, v7
	s_waitcnt lgkmcnt(1)
	v_bfe_u32 v7, v24, 16, 1
	v_add_u32_e32 v28, s6, v28
	v_add3_u32 v7, v24, v7, s62
	s_waitcnt lgkmcnt(0)
	v_bfe_u32 v11, v26, 16, 1
	v_ashrrev_i32_e32 v29, 31, v28
	v_lshrrev_b32_e32 v7, 16, v7
	v_add3_u32 v11, v26, v11, s62
	v_lshlrev_b64 v[30:31], 9, v[28:29]
	v_and_or_b32 v11, v11, s63, v7
	v_lshl_add_u64 v[30:31], v[4:5], 0, v[30:31]
	v_bfe_u32 v7, v15, 16, 1
	global_store_dwordx4 v[30:31], v[8:11], off
	v_add3_u32 v7, v15, v7, s62
	v_lshrrev_b32_e32 v7, 16, v7
	v_bfe_u32 v8, v13, 16, 1
	v_add3_u32 v8, v13, v8, s62
	v_and_or_b32 v8, v8, s63, v7
	v_bfe_u32 v7, v17, 16, 1
	v_add3_u32 v7, v17, v7, s62
	v_bfe_u32 v9, v19, 16, 1
	v_lshrrev_b32_e32 v7, 16, v7
	v_add3_u32 v9, v19, v9, s62
	v_and_or_b32 v9, v9, s63, v7
	v_bfe_u32 v7, v21, 16, 1
	v_add3_u32 v7, v21, v7, s62
	v_bfe_u32 v10, v23, 16, 1
	v_lshrrev_b32_e32 v7, 16, v7
	v_add3_u32 v10, v23, v10, s62
	v_and_or_b32 v10, v10, s63, v7
	v_bfe_u32 v7, v25, 16, 1
	v_add_u32_e32 v12, 8, v28
	v_add3_u32 v7, v25, v7, s62
	v_bfe_u32 v11, v27, 16, 1
	v_ashrrev_i32_e32 v13, 31, v12
	v_lshrrev_b32_e32 v7, 16, v7
	v_add3_u32 v11, v27, v11, s62
	v_lshlrev_b64 v[12:13], 9, v[12:13]
	v_and_or_b32 v11, v11, s63, v7
	v_lshl_add_u64 v[12:13], v[4:5], 0, v[12:13]
	global_store_dwordx4 v[12:13], v[8:11], off
	ds_read2_b32 v[12:13], v2 offset0:49 offset1:57
	ds_read2_b32 v[14:15], v2 offset0:16 offset1:24
	ds_read2_b32 v[16:17], v2 offset0:82 offset1:90
	ds_read2_b32 v[18:19], v2 offset0:115 offset1:123
	ds_read2_b32 v[20:21], v2 offset0:148 offset1:156
	ds_read2_b32 v[22:23], v2 offset0:181 offset1:189
	ds_read2_b32 v[24:25], v2 offset0:214 offset1:222
	ds_read2_b32 v[26:27], v2 offset0:247 offset1:255
	s_waitcnt lgkmcnt(7)
	v_bfe_u32 v8, v12, 16, 1
	s_waitcnt lgkmcnt(6)
	v_bfe_u32 v7, v14, 16, 1
	v_add3_u32 v7, v14, v7, s62
	v_lshrrev_b32_e32 v7, 16, v7
	v_add3_u32 v8, v12, v8, s62
	v_and_or_b32 v8, v8, s63, v7
	s_waitcnt lgkmcnt(5)
	v_bfe_u32 v7, v16, 16, 1
	v_add3_u32 v7, v16, v7, s62
	s_waitcnt lgkmcnt(4)
	v_bfe_u32 v9, v18, 16, 1
	v_lshrrev_b32_e32 v7, 16, v7
	v_add3_u32 v9, v18, v9, s62
	v_and_or_b32 v9, v9, s63, v7
	s_waitcnt lgkmcnt(3)
	v_bfe_u32 v7, v20, 16, 1
	v_add3_u32 v7, v20, v7, s62
	s_waitcnt lgkmcnt(2)
	v_bfe_u32 v10, v22, 16, 1
	v_lshrrev_b32_e32 v7, 16, v7
	v_add3_u32 v10, v22, v10, s62
	s_waitcnt lgkmcnt(1)
	v_bfe_u32 v2, v24, 16, 1
	v_and_or_b32 v10, v10, s63, v7
	v_add3_u32 v2, v24, v2, s62
	s_waitcnt lgkmcnt(0)
	v_bfe_u32 v7, v26, 16, 1
	v_lshrrev_b32_e32 v2, 16, v2
	v_add3_u32 v7, v26, v7, s62
	v_add_u32_e32 v30, 16, v28
	v_and_or_b32 v11, v7, s63, v2
	v_ashrrev_i32_e32 v31, 31, v30
	v_bfe_u32 v2, v15, 16, 1
	v_lshlrev_b64 v[30:31], 9, v[30:31]
	v_add3_u32 v2, v15, v2, s62
	v_bfe_u32 v7, v13, 16, 1
	v_lshl_add_u64 v[30:31], v[4:5], 0, v[30:31]
	v_lshrrev_b32_e32 v2, 16, v2
	v_add3_u32 v7, v13, v7, s62
	global_store_dwordx4 v[30:31], v[8:11], off
	v_add_u32_e32 v12, 24, v28
	v_ashrrev_i32_e32 v13, 31, v12
	v_and_or_b32 v8, v7, s63, v2
	v_bfe_u32 v2, v17, 16, 1
	v_add3_u32 v2, v17, v2, s62
	v_bfe_u32 v7, v19, 16, 1
	v_lshrrev_b32_e32 v2, 16, v2
	v_add3_u32 v7, v19, v7, s62
	v_and_or_b32 v9, v7, s63, v2
	v_bfe_u32 v2, v21, 16, 1
	v_add3_u32 v2, v21, v2, s62
	v_bfe_u32 v7, v23, 16, 1
	v_lshrrev_b32_e32 v2, 16, v2
	v_add3_u32 v7, v23, v7, s62
	v_and_or_b32 v10, v7, s63, v2
	v_bfe_u32 v2, v25, 16, 1
	v_add3_u32 v2, v25, v2, s62
	v_bfe_u32 v7, v27, 16, 1
	v_lshrrev_b32_e32 v2, 16, v2
	v_add3_u32 v7, v27, v7, s62
	v_lshlrev_b64 v[12:13], 9, v[12:13]
	v_and_or_b32 v11, v7, s63, v2
	v_lshl_add_u64 v[4:5], v[4:5], 0, v[12:13]
	global_store_dwordx4 v[4:5], v[8:11], off
	s_waitcnt lgkmcnt(0)

; #define GAS __attribute__((address_space(1)))
; #define LAS __attribute__((address_space(3)))
; #define LDS_WAIT() asm volatile("s_waitcnt lgkmcnt(0)" ::: "memory")
; __device__ __forceinline__ unsigned pk2(float lo, float hi) { return f2bf(lo) | (f2bf(hi) << 16); }
;     ...
;     { float wv[32];
;       const float* wp = W + (size_t)(k0 + (lane >> 5)) * ldw + n0 + (lane & 31);
; #pragma unroll
;       for (int i = 0; i < 32; ++i) wv[i] = wp[(size_t)(2 * i) * ldw];
; #pragma unroll
;       for (int i = 0; i < 32; ++i) scr[(2 * i + (lane >> 5)) * 33 + (lane & 31)] = wv[i]; }
;     LDS_WAIT(); asm volatile("" ::: "memory");
;     const int c = lane & 7;
;     const int r0 = (mode == 0) ? n0 : (256 * (n0 >> 7) + (n0 & 127) + (mode == 2 ? 128 : 0));
; #pragma unroll
;     for (int j = 0; j < 4; ++j) { const int n = (lane >> 3) + 8 * j; const LAS float* s = scr + (8 * c) * 33 + n;
;         v4u o; o.x = pk2(s[0 * 33], s[1 * 33]); o.y = pk2(s[2 * 33], s[3 * 33]); o.z = pk2(s[4 * 33], s[5 * 33]); o.w = pk2(s[6 * 33], s[7 * 33]);
;         *(GAS v4u*)(WT + (size_t)(r0 + n) * ldt + k0 + 8 * c) = o; }
; __device__ __forceinline__ void transpose_late(const Args& a, Frame& F, LAS float* scr, int r) {
;     ...
;     if (r < IT_SQ) { p0_transpose_item(a.in[I_WPG], D, D, WPG, 0, D / 32, scr, r, F.lane); return; } r -= IT_SQ;
.LBB0_1243:
	s_andn2_b64 vcc, exec, s[6:7]
	s_cbranch_vccnz .LBB0_1245
	v_mov_b32_e32 v7, v6
	s_and_b32 s7, s21, 0xffc0
	v_ashrrev_i32_e32 v10, 5, v7
	v_add_u32_e32 v4, s7, v10
	v_ashrrev_i32_e32 v5, 31, v4
	v_readlane_b32 s36, v245, 0
	s_and_b32 s6, s22, 0x7e0
	v_lshlrev_b64 v[4:5], 13, v[4:5]
	v_readlane_b32 s40, v245, 4
	v_readlane_b32 s41, v245, 5
	s_lshl_b32 s0, s6, 2
	v_lshlrev_b32_e32 v2, 2, v7
	v_lshl_add_u64 v[4:5], s[40:41], 0, v[4:5]
	v_lshl_add_u64 v[4:5], v[4:5], 0, s[0:1]
	v_and_b32_e32 v2, 0x7c, v2
	v_lshl_add_u64 v[4:5], v[4:5], 0, v[2:3]
	v_add_co_u32_e32 v8, vcc, s64, v4
	global_load_dword v11, v[4:5], off nt
	s_nop 0
	v_addc_co_u32_e32 v9, vcc, 0, v5, vcc
	global_load_dword v12, v[8:9], off nt
	v_add_co_u32_e32 v8, vcc, s65, v4
	s_lshl_b32 s0, s7, 1
	s_nop 0
	v_addc_co_u32_e32 v9, vcc, 0, v5, vcc
	global_load_dword v13, v[8:9], off nt
	v_add_co_u32_e32 v8, vcc, s66, v4
	s_add_u32 s44, s13, s0
	s_nop 0
	v_addc_co_u32_e32 v9, vcc, 0, v5, vcc
	global_load_dword v14, v[8:9], off nt
	v_add_co_u32_e32 v8, vcc, s67, v4
	s_addc_u32 s45, s14, 0
	s_nop 0
	v_addc_co_u32_e32 v9, vcc, 0, v5, vcc
	global_load_dword v15, v[8:9], off nt
	v_add_co_u32_e32 v8, vcc, s68, v4
	v_readlane_b32 s37, v245, 1
	s_nop 0
	v_addc_co_u32_e32 v9, vcc, 0, v5, vcc
	global_load_dword v16, v[8:9], off nt
	v_add_co_u32_e32 v8, vcc, s69, v4
	v_readlane_b32 s38, v245, 2
	s_nop 0
	v_addc_co_u32_e32 v9, vcc, 0, v5, vcc
	global_load_dword v17, v[8:9], off nt
	v_add_co_u32_e32 v8, vcc, s70, v4
	v_readlane_b32 s39, v245, 3
	s_nop 0
	v_addc_co_u32_e32 v9, vcc, 0, v5, vcc
	global_load_dword v18, v[8:9], off nt
	v_add_co_u32_e32 v8, vcc, s71, v4
	v_readlane_b32 s42, v245, 6
	s_nop 0
	v_addc_co_u32_e32 v9, vcc, 0, v5, vcc
	global_load_dword v19, v[8:9], off nt
	v_add_co_u32_e32 v8, vcc, s72, v4
	v_readlane_b32 s43, v245, 7
	s_nop 0
	v_addc_co_u32_e32 v9, vcc, 0, v5, vcc
	global_load_dword v20, v[8:9], off nt
	v_add_co_u32_e32 v8, vcc, s73, v4
	s_nop 1
	v_addc_co_u32_e32 v9, vcc, 0, v5, vcc
	global_load_dword v21, v[8:9], off nt
	v_add_co_u32_e32 v8, vcc, s27, v4
	s_nop 1
	v_addc_co_u32_e32 v9, vcc, 0, v5, vcc
	global_load_dword v22, v[8:9], off nt
	v_add_co_u32_e32 v8, vcc, s74, v4
	s_nop 1
	v_addc_co_u32_e32 v9, vcc, 0, v5, vcc
	global_load_dword v23, v[8:9], off nt
	v_add_co_u32_e32 v8, vcc, s75, v4
	s_nop 1
	v_addc_co_u32_e32 v9, vcc, 0, v5, vcc
	global_load_dword v24, v[8:9], off nt
	v_add_co_u32_e32 v8, vcc, s76, v4
	s_nop 1
	v_addc_co_u32_e32 v9, vcc, 0, v5, vcc
	global_load_dword v25, v[8:9], off nt
	v_add_co_u32_e32 v8, vcc, s77, v4
	s_nop 1
	v_addc_co_u32_e32 v9, vcc, 0, v5, vcc
	global_load_dword v26, v[8:9], off nt
	v_add_co_u32_e32 v8, vcc, s78, v4
	s_nop 1
	v_addc_co_u32_e32 v9, vcc, 0, v5, vcc
	global_load_dword v27, v[8:9], off nt
	v_add_co_u32_e32 v8, vcc, s79, v4
	s_nop 1
	v_addc_co_u32_e32 v9, vcc, 0, v5, vcc
	global_load_dword v28, v[8:9], off nt
	v_add_co_u32_e32 v8, vcc, s80, v4
	s_nop 1
	v_addc_co_u32_e32 v9, vcc, 0, v5, vcc
	global_load_dword v29, v[8:9], off nt
	v_add_co_u32_e32 v8, vcc, s81, v4
	s_nop 1
	v_addc_co_u32_e32 v9, vcc, 0, v5, vcc
	global_load_dword v30, v[8:9], off nt
	v_add_co_u32_e32 v8, vcc, s82, v4
	s_nop 1
	v_addc_co_u32_e32 v9, vcc, 0, v5, vcc
	global_load_dword v31, v[8:9], off nt
	v_add_co_u32_e32 v8, vcc, s83, v4
	s_nop 1
	v_addc_co_u32_e32 v9, vcc, 0, v5, vcc
	global_load_dword v32, v[8:9], off nt
	v_add_co_u32_e32 v8, vcc, s31, v4
	s_nop 1
	v_addc_co_u32_e32 v9, vcc, 0, v5, vcc
	global_load_dword v33, v[8:9], off nt
	v_add_co_u32_e32 v8, vcc, s85, v4
	s_nop 1
	v_addc_co_u32_e32 v9, vcc, 0, v5, vcc
	global_load_dword v34, v[8:9], off nt
	v_add_co_u32_e32 v8, vcc, s86, v4
	s_nop 1
	v_addc_co_u32_e32 v9, vcc, 0, v5, vcc
	global_load_dword v35, v[8:9], off nt
	v_add_co_u32_e32 v8, vcc, s87, v4
	s_nop 1
	v_addc_co_u32_e32 v9, vcc, 0, v5, vcc
	global_load_dword v36, v[8:9], off nt
	v_add_co_u32_e32 v8, vcc, s88, v4
	s_nop 1
	v_addc_co_u32_e32 v9, vcc, 0, v5, vcc
	global_load_dword v37, v[8:9], off nt
	v_add_co_u32_e32 v8, vcc, s89, v4
	s_nop 1
	v_addc_co_u32_e32 v9, vcc, 0, v5, vcc
	global_load_dword v38, v[8:9], off nt
	v_add_co_u32_e32 v8, vcc, s90, v4
	s_nop 1
	v_addc_co_u32_e32 v9, vcc, 0, v5, vcc
	global_load_dword v39, v[8:9], off nt
	v_add_co_u32_e32 v8, vcc, s91, v4
	s_nop 1
	v_addc_co_u32_e32 v9, vcc, 0, v5, vcc
	global_load_dword v40, v[8:9], off nt
	v_add_co_u32_e32 v8, vcc, s92, v4
	s_nop 1
	v_addc_co_u32_e32 v9, vcc, 0, v5, vcc
	v_add_co_u32_e32 v4, vcc, s93, v4
	global_load_dword v8, v[8:9], off nt
	s_nop 0
	v_addc_co_u32_e32 v5, vcc, 0, v5, vcc
	global_load_dword v4, v[4:5], off nt
	v_mul_lo_u32 v5, v10, s61
	v_add3_u32 v2, s10, v2, v5
	v_add_u32_e32 v5, 0x400, v2
	s_waitcnt vmcnt(0)
	ds_write2_b32 v2, v11, v12 offset1:66
	ds_write2_b32 v2, v13, v14 offset0:132 offset1:198
	ds_write2_b32 v5, v15, v16 offset0:8 offset1:74
	ds_write2_b32 v5, v17, v18 offset0:140 offset1:206
	v_add_u32_e32 v5, 0x800, v2
	ds_write2_b32 v5, v19, v20 offset0:16 offset1:82
	ds_write2_b32 v5, v21, v22 offset0:148 offset1:214
	v_add_u32_e32 v5, 0xc00, v2
	ds_write2_b32 v5, v23, v24 offset0:24 offset1:90
	ds_write2_b32 v5, v25, v26 offset0:156 offset1:222
	v_add_u32_e32 v5, 0x1000, v2
	ds_write2_b32 v5, v27, v28 offset0:32 offset1:98
	ds_write2_b32 v5, v29, v30 offset0:164 offset1:230
	v_add_u32_e32 v5, 0x1400, v2
	ds_write2_b32 v5, v31, v32 offset0:40 offset1:106
	ds_write2_b32 v5, v33, v34 offset0:172 offset1:238
	v_add_u32_e32 v5, 0x1800, v2
	v_add_u32_e32 v2, 0x1c00, v2
	ds_write2_b32 v5, v35, v36 offset0:48 offset1:114
	ds_write2_b32 v5, v37, v38 offset0:180 offset1:246
	ds_write2_b32 v2, v39, v40 offset0:56 offset1:122
	ds_write2_b32 v2, v8, v4 offset0:188 offset1:254
	v_lshlrev_b32_e32 v2, 3, v7
	v_and_b32_e32 v2, 56, v2
	v_ashrrev_i32_e32 v28, 3, v7
	v_mul_u32_u24_e32 v7, 0x84, v2
	v_lshlrev_b32_e32 v2, 1, v2
	s_waitcnt lgkmcnt(0)
; #define GAS __attribute__((address_space(1)))
; #define LAS __attribute__((address_space(3)))
; #define LDS_WAIT() asm volatile("s_waitcnt lgkmcnt(0)" ::: "memory")
; __device__ __forceinline__ unsigned pk2(float lo, float hi) { return f2bf(lo) | (f2bf(hi) << 16); }
;     ...
;     const int c = lane & 7;
;     const int r0 = (mode == 0) ? n0 : (256 * (n0 >> 7) + (n0 & 127) + (mode == 2 ? 128 : 0));
; #pragma unroll
;     for (int j = 0; j < 4; ++j) { const int n = (lane >> 3) + 8 * j; const LAS float* s = scr + (8 * c) * 33 + n;
;         v4u o; o.x = pk2(s[0 * 33], s[1 * 33]); o.y = pk2(s[2 * 33], s[3 * 33]); o.z = pk2(s[4 * 33], s[5 * 33]); o.w = pk2(s[6 * 33], s[7 * 33]);
;         *(GAS v4u*)(WT + (size_t)(r0 + n) * ldt + k0 + 8 * c) = o; }
;     LDS_WAIT(); asm volatile("" ::: "memory");
	v_lshl_add_u64 v[4:5], s[44:45], 0, v[2:3]
	v_lshlrev_b32_e32 v2, 2, v28
	v_add3_u32 v2, s10, v7, v2
	ds_read2_b32 v[12:13], v2 offset0:33 offset1:41
	ds_read2_b32 v[14:15], v2 offset1:8
	ds_read2_b32 v[16:17], v2 offset0:66 offset1:74
	ds_read2_b32 v[18:19], v2 offset0:99 offset1:107
	ds_read2_b32 v[20:21], v2 offset0:132 offset1:140
	ds_read2_b32 v[22:23], v2 offset0:165 offset1:173
	ds_read2_b32 v[24:25], v2 offset0:198 offset1:206
	ds_read2_b32 v[26:27], v2 offset0:231 offset1:239
	s_waitcnt lgkmcnt(7)
	v_bfe_u32 v8, v12, 16, 1
	s_waitcnt lgkmcnt(6)
	v_bfe_u32 v7, v14, 16, 1
	v_add3_u32 v7, v14, v7, s62
	v_lshrrev_b32_e32 v7, 16, v7
	v_add3_u32 v8, v12, v8, s62
	v_and_or_b32 v8, v8, s63, v7
	s_waitcnt lgkmcnt(5)
	v_bfe_u32 v7, v16, 16, 1
	v_add3_u32 v7, v16, v7, s62
	s_waitcnt lgkmcnt(4)
	v_bfe_u32 v9, v18, 16, 1
	v_lshrrev_b32_e32 v7, 16, v7
	v_add3_u32 v9, v18, v9, s62
	v_and_or_b32 v9, v9, s63, v7
	s_waitcnt lgkmcnt(3)
	v_bfe_u32 v7, v20, 16, 1
	v_add3_u32 v7, v20, v7, s62
	s_waitcnt lgkmcnt(2)
	v_bfe_u32 v10, v22, 16, 1
	v_lshrrev_b32_e32 v7, 16, v7
	v_add3_u32 v10, v22, v10, s62
	v_and_or_b32 v10, v10, s63, v7
	s_waitcnt lgkmcnt(1)
	v_bfe_u32 v7, v24, 16, 1
	v_add_u32_e32 v28, s6, v28
	v_add3_u32 v7, v24, v7, s62
	s_waitcnt lgkmcnt(0)
	v_bfe_u32 v11, v26, 16, 1
	v_ashrrev_i32_e32 v29, 31, v28
	v_lshrrev_b32_e32 v7, 16, v7
	v_add3_u32 v11, v26, v11, s62
	v_lshlrev_b64 v[30:31], 12, v[28:29]
	v_and_or_b32 v11, v11, s63, v7
	v_lshl_add_u64 v[30:31], v[4:5], 0, v[30:31]
	v_bfe_u32 v7, v15, 16, 1
	global_store_dwordx4 v[30:31], v[8:11], off
	v_add3_u32 v7, v15, v7, s62
	v_lshrrev_b32_e32 v7, 16, v7
	v_bfe_u32 v8, v13, 16, 1
	v_add3_u32 v8, v13, v8, s62
	v_and_or_b32 v8, v8, s63, v7
	v_bfe_u32 v7, v17, 16, 1
	v_add3_u32 v7, v17, v7, s62
	v_bfe_u32 v9, v19, 16, 1
	v_lshrrev_b32_e32 v7, 16, v7
	v_add3_u32 v9, v19, v9, s62
	v_and_or_b32 v9, v9, s63, v7
	v_bfe_u32 v7, v21, 16, 1
	v_add3_u32 v7, v21, v7, s62
	v_bfe_u32 v10, v23, 16, 1
	v_lshrrev_b32_e32 v7, 16, v7
	v_add3_u32 v10, v23, v10, s62
	v_and_or_b32 v10, v10, s63, v7
	v_bfe_u32 v7, v25, 16, 1
	v_add_u32_e32 v12, 8, v28
	v_add3_u32 v7, v25, v7, s62
	v_bfe_u32 v11, v27, 16, 1
	v_ashrrev_i32_e32 v13, 31, v12
	v_lshrrev_b32_e32 v7, 16, v7
	v_add3_u32 v11, v27, v11, s62
	v_lshlrev_b64 v[12:13], 12, v[12:13]
	v_and_or_b32 v11, v11, s63, v7
	v_lshl_add_u64 v[12:13], v[4:5], 0, v[12:13]
	global_store_dwordx4 v[12:13], v[8:11], off
	ds_read2_b32 v[12:13], v2 offset0:49 offset1:57
	ds_read2_b32 v[14:15], v2 offset0:16 offset1:24
	ds_read2_b32 v[16:17], v2 offset0:82 offset1:90
	ds_read2_b32 v[18:19], v2 offset0:115 offset1:123
	ds_read2_b32 v[20:21], v2 offset0:148 offset1:156
	ds_read2_b32 v[22:23], v2 offset0:181 offset1:189
	ds_read2_b32 v[24:25], v2 offset0:214 offset1:222
	ds_read2_b32 v[26:27], v2 offset0:247 offset1:255
	s_waitcnt lgkmcnt(7)
	v_bfe_u32 v8, v12, 16, 1
	s_waitcnt lgkmcnt(6)
	v_bfe_u32 v7, v14, 16, 1
	v_add3_u32 v7, v14, v7, s62
	v_lshrrev_b32_e32 v7, 16, v7
	v_add3_u32 v8, v12, v8, s62
	v_and_or_b32 v8, v8, s63, v7
	s_waitcnt lgkmcnt(5)
	v_bfe_u32 v7, v16, 16, 1
	v_add3_u32 v7, v16, v7, s62
	s_waitcnt lgkmcnt(4)
	v_bfe_u32 v9, v18, 16, 1
	v_lshrrev_b32_e32 v7, 16, v7
	v_add3_u32 v9, v18, v9, s62
	v_and_or_b32 v9, v9, s63, v7
	s_waitcnt lgkmcnt(3)
	v_bfe_u32 v7, v20, 16, 1
	v_add3_u32 v7, v20, v7, s62
	s_waitcnt lgkmcnt(2)
	v_bfe_u32 v10, v22, 16, 1
	v_lshrrev_b32_e32 v7, 16, v7
	v_add3_u32 v10, v22, v10, s62
	s_waitcnt lgkmcnt(1)
	v_bfe_u32 v2, v24, 16, 1
	v_and_or_b32 v10, v10, s63, v7
	v_add3_u32 v2, v24, v2, s62
	s_waitcnt lgkmcnt(0)
	v_bfe_u32 v7, v26, 16, 1
	v_lshrrev_b32_e32 v2, 16, v2
	v_add3_u32 v7, v26, v7, s62
	v_add_u32_e32 v30, 16, v28
	v_and_or_b32 v11, v7, s63, v2
	v_ashrrev_i32_e32 v31, 31, v30
	v_bfe_u32 v2, v15, 16, 1
	v_lshlrev_b64 v[30:31], 12, v[30:31]
	v_add3_u32 v2, v15, v2, s62
	v_bfe_u32 v7, v13, 16, 1
	v_lshl_add_u64 v[30:31], v[4:5], 0, v[30:31]
	v_lshrrev_b32_e32 v2, 16, v2
	v_add3_u32 v7, v13, v7, s62
	global_store_dwordx4 v[30:31], v[8:11], off
	v_add_u32_e32 v12, 24, v28
	v_ashrrev_i32_e32 v13, 31, v12
	v_and_or_b32 v8, v7, s63, v2
	v_bfe_u32 v2, v17, 16, 1
	v_add3_u32 v2, v17, v2, s62
	v_bfe_u32 v7, v19, 16, 1
	v_lshrrev_b32_e32 v2, 16, v2
	v_add3_u32 v7, v19, v7, s62
	v_and_or_b32 v9, v7, s63, v2
	v_bfe_u32 v2, v21, 16, 1
	v_add3_u32 v2, v21, v2, s62
	v_bfe_u32 v7, v23, 16, 1
	v_lshrrev_b32_e32 v2, 16, v2
	v_add3_u32 v7, v23, v7, s62
	v_and_or_b32 v10, v7, s63, v2
	v_bfe_u32 v2, v25, 16, 1
	v_add3_u32 v2, v25, v2, s62
	v_bfe_u32 v7, v27, 16, 1
	v_lshrrev_b32_e32 v2, 16, v2
	v_add3_u32 v7, v27, v7, s62
	v_lshlrev_b64 v[12:13], 12, v[12:13]
	v_and_or_b32 v11, v7, s63, v2
	v_lshl_add_u64 v[4:5], v[4:5], 0, v[12:13]
	global_store_dwordx4 v[4:5], v[8:11], off
	s_waitcnt lgkmcnt(0)

;     ...
;     { float wv[32];
;       const float* wp = W + (size_t)(k0 + (lane >> 5)) * ldw + n0 + (lane & 31);
; #pragma unroll
;       for (int i = 0; i < 32; ++i) wv[i] = wp[(size_t)(2 * i) * ldw];
; #pragma unroll
;       for (int i = 0; i < 32; ++i) scr[(2 * i + (lane >> 5)) * 33 + (lane & 31)] = wv[i]; }
; __device__ __forceinline__ void transpose_late(const Args& a, Frame& F, LAS float* scr, int r) {
;     ...
;     if (r < IT_SQ) { p0_transpose_item(a.in[I_WO], D, D, WO, 0, D / 32, scr, r, F.lane); return; } r -= IT_SQ;
.LBB0_1246:
	s_andn2_b64 vcc, exec, s[6:7]
	s_cbranch_vccnz .LBB0_1248
	s_add_i32 s0, s21, 0x800
	v_mov_b32_e32 v7, v6
	s_and_b32 s7, s0, 0xffc0
	v_ashrrev_i32_e32 v10, 5, v7
	v_add_u32_e32 v4, s7, v10
	v_ashrrev_i32_e32 v5, 31, v4
	v_readlane_b32 s36, v244, 2
	s_and_b32 s6, s22, 0x7e0
	v_lshlrev_b64 v[4:5], 13, v[4:5]
	v_readlane_b32 s40, v244, 6
	v_readlane_b32 s41, v244, 7
	s_lshl_b32 s0, s6, 2
	v_lshlrev_b32_e32 v2, 2, v7
	v_lshl_add_u64 v[4:5], s[40:41], 0, v[4:5]
	v_lshl_add_u64 v[4:5], v[4:5], 0, s[0:1]
	v_and_b32_e32 v2, 0x7c, v2
	v_lshl_add_u64 v[4:5], v[4:5], 0, v[2:3]
	v_add_co_u32_e32 v8, vcc, s64, v4
	global_load_dword v11, v[4:5], off nt
	s_nop 0
	v_addc_co_u32_e32 v9, vcc, 0, v5, vcc
	global_load_dword v12, v[8:9], off nt
	v_add_co_u32_e32 v8, vcc, s65, v4
	v_readlane_b32 s44, v244, 10
	s_nop 0
	v_addc_co_u32_e32 v9, vcc, 0, v5, vcc
	global_load_dword v13, v[8:9], off nt
	v_add_co_u32_e32 v8, vcc, s66, v4
	s_lshl_b32 s0, s7, 1
	s_nop 0
	v_addc_co_u32_e32 v9, vcc, 0, v5, vcc
	global_load_dword v14, v[8:9], off nt
	v_add_co_u32_e32 v8, vcc, s67, v4
	v_readlane_b32 s45, v244, 11
	s_nop 0
	v_addc_co_u32_e32 v9, vcc, 0, v5, vcc
	global_load_dword v15, v[8:9], off nt
	v_add_co_u32_e32 v8, vcc, s68, v4
	s_add_u32 s44, s11, s0
	s_nop 0
	v_addc_co_u32_e32 v9, vcc, 0, v5, vcc
	global_load_dword v16, v[8:9], off nt
	v_add_co_u32_e32 v8, vcc, s69, v4
	s_addc_u32 s45, s12, 0
	s_nop 0
	v_addc_co_u32_e32 v9, vcc, 0, v5, vcc
	global_load_dword v17, v[8:9], off nt
	v_add_co_u32_e32 v8, vcc, s70, v4
	v_readlane_b32 s37, v244, 3
	s_nop 0
	v_addc_co_u32_e32 v9, vcc, 0, v5, vcc
	global_load_dword v18, v[8:9], off nt
	v_add_co_u32_e32 v8, vcc, s71, v4
	v_readlane_b32 s38, v244, 4
	s_nop 0
	v_addc_co_u32_e32 v9, vcc, 0, v5, vcc
	global_load_dword v19, v[8:9], off nt
	v_add_co_u32_e32 v8, vcc, s72, v4
	v_readlane_b32 s39, v244, 5
	s_nop 0
	v_addc_co_u32_e32 v9, vcc, 0, v5, vcc
	global_load_dword v20, v[8:9], off nt
	v_add_co_u32_e32 v8, vcc, s73, v4
	v_readlane_b32 s42, v244, 8
	s_nop 0
	v_addc_co_u32_e32 v9, vcc, 0, v5, vcc
	global_load_dword v21, v[8:9], off nt
	v_add_co_u32_e32 v8, vcc, s27, v4
	v_readlane_b32 s43, v244, 9
	s_nop 0
	v_addc_co_u32_e32 v9, vcc, 0, v5, vcc
	global_load_dword v22, v[8:9], off nt
	v_add_co_u32_e32 v8, vcc, s74, v4
	v_readlane_b32 s46, v244, 12
	s_nop 0
	v_addc_co_u32_e32 v9, vcc, 0, v5, vcc
	global_load_dword v23, v[8:9], off nt
	v_add_co_u32_e32 v8, vcc, s75, v4
	v_readlane_b32 s47, v244, 13
	s_nop 0
	v_addc_co_u32_e32 v9, vcc, 0, v5, vcc
	global_load_dword v24, v[8:9], off nt
	v_add_co_u32_e32 v8, vcc, s76, v4
	v_readlane_b32 s48, v244, 14
	s_nop 0
	v_addc_co_u32_e32 v9, vcc, 0, v5, vcc
	global_load_dword v25, v[8:9], off nt
	v_add_co_u32_e32 v8, vcc, s77, v4
	v_readlane_b32 s49, v244, 15
	s_nop 0
	v_addc_co_u32_e32 v9, vcc, 0, v5, vcc
	global_load_dword v26, v[8:9], off nt
	v_add_co_u32_e32 v8, vcc, s78, v4
	v_readlane_b32 s50, v244, 16
	s_nop 0
	v_addc_co_u32_e32 v9, vcc, 0, v5, vcc
	global_load_dword v27, v[8:9], off nt
	v_add_co_u32_e32 v8, vcc, s79, v4
	v_readlane_b32 s51, v244, 17
	s_nop 0
	v_addc_co_u32_e32 v9, vcc, 0, v5, vcc
	global_load_dword v28, v[8:9], off nt
	v_add_co_u32_e32 v8, vcc, s80, v4
	s_nop 1
	v_addc_co_u32_e32 v9, vcc, 0, v5, vcc
	global_load_dword v29, v[8:9], off nt
	v_add_co_u32_e32 v8, vcc, s81, v4
	s_nop 1
	v_addc_co_u32_e32 v9, vcc, 0, v5, vcc
	global_load_dword v30, v[8:9], off nt
	v_add_co_u32_e32 v8, vcc, s82, v4
	s_nop 1
	v_addc_co_u32_e32 v9, vcc, 0, v5, vcc
	global_load_dword v31, v[8:9], off nt
	v_add_co_u32_e32 v8, vcc, s83, v4
	s_nop 1
	v_addc_co_u32_e32 v9, vcc, 0, v5, vcc
	global_load_dword v32, v[8:9], off nt
	v_add_co_u32_e32 v8, vcc, s31, v4
	s_nop 1
	v_addc_co_u32_e32 v9, vcc, 0, v5, vcc
	global_load_dword v33, v[8:9], off nt
	v_add_co_u32_e32 v8, vcc, s85, v4
	s_nop 1
	v_addc_co_u32_e32 v9, vcc, 0, v5, vcc
	global_load_dword v34, v[8:9], off nt
	v_add_co_u32_e32 v8, vcc, s86, v4
	s_nop 1
	v_addc_co_u32_e32 v9, vcc, 0, v5, vcc
	global_load_dword v35, v[8:9], off nt
	v_add_co_u32_e32 v8, vcc, s87, v4
	s_nop 1
	v_addc_co_u32_e32 v9, vcc, 0, v5, vcc
	global_load_dword v36, v[8:9], off nt
	v_add_co_u32_e32 v8, vcc, s88, v4
	s_nop 1
	v_addc_co_u32_e32 v9, vcc, 0, v5, vcc
	global_load_dword v37, v[8:9], off nt
	v_add_co_u32_e32 v8, vcc, s89, v4
	s_nop 1
	v_addc_co_u32_e32 v9, vcc, 0, v5, vcc
	global_load_dword v38, v[8:9], off nt
	v_add_co_u32_e32 v8, vcc, s90, v4
	s_nop 1
	v_addc_co_u32_e32 v9, vcc, 0, v5, vcc
	global_load_dword v39, v[8:9], off nt
	v_add_co_u32_e32 v8, vcc, s91, v4
	s_nop 1
	v_addc_co_u32_e32 v9, vcc, 0, v5, vcc
	global_load_dword v40, v[8:9], off nt
	v_add_co_u32_e32 v8, vcc, s92, v4
	s_nop 1
	v_addc_co_u32_e32 v9, vcc, 0, v5, vcc
	v_add_co_u32_e32 v4, vcc, s93, v4
	global_load_dword v8, v[8:9], off nt
	s_nop 0
	v_addc_co_u32_e32 v5, vcc, 0, v5, vcc
	global_load_dword v4, v[4:5], off nt
	v_mul_lo_u32 v5, v10, s61
	v_add3_u32 v2, s10, v2, v5
	v_add_u32_e32 v5, 0x400, v2
	s_waitcnt vmcnt(0)
; #define GAS __attribute__((address_space(1)))
; #define LAS __attribute__((address_space(3)))
; #define LDS_WAIT() asm volatile("s_waitcnt lgkmcnt(0)" ::: "memory")
; __device__ __forceinline__ unsigned pk2(float lo, float hi) { return f2bf(lo) | (f2bf(hi) << 16); }
;     ...
;       for (int i = 0; i < 32; ++i) scr[(2 * i + (lane >> 5)) * 33 + (lane & 31)] = wv[i]; }
;     LDS_WAIT(); asm volatile("" ::: "memory");
;     const int c = lane & 7;
;     const int r0 = (mode == 0) ? n0 : (256 * (n0 >> 7) + (n0 & 127) + (mode == 2 ? 128 : 0));
; #pragma unroll
;     for (int j = 0; j < 4; ++j) { const int n = (lane >> 3) + 8 * j; const LAS float* s = scr + (8 * c) * 33 + n;
;         v4u o; o.x = pk2(s[0 * 33], s[1 * 33]); o.y = pk2(s[2 * 33], s[3 * 33]); o.z = pk2(s[4 * 33], s[5 * 33]); o.w = pk2(s[6 * 33], s[7 * 33]);
;         *(GAS v4u*)(WT + (size_t)(r0 + n) * ldt + k0 + 8 * c) = o; }
;     LDS_WAIT(); asm volatile("" ::: "memory");
	ds_write2_b32 v2, v11, v12 offset1:66
	ds_write2_b32 v2, v13, v14 offset0:132 offset1:198
	ds_write2_b32 v5, v15, v16 offset0:8 offset1:74
	ds_write2_b32 v5, v17, v18 offset0:140 offset1:206
	v_add_u32_e32 v5, 0x800, v2
	ds_write2_b32 v5, v19, v20 offset0:16 offset1:82
	ds_write2_b32 v5, v21, v22 offset0:148 offset1:214
	v_add_u32_e32 v5, 0xc00, v2
	ds_write2_b32 v5, v23, v24 offset0:24 offset1:90
	ds_write2_b32 v5, v25, v26 offset0:156 offset1:222
	v_add_u32_e32 v5, 0x1000, v2
	ds_write2_b32 v5, v27, v28 offset0:32 offset1:98
	ds_write2_b32 v5, v29, v30 offset0:164 offset1:230
	v_add_u32_e32 v5, 0x1400, v2
	ds_write2_b32 v5, v31, v32 offset0:40 offset1:106
	ds_write2_b32 v5, v33, v34 offset0:172 offset1:238
	v_add_u32_e32 v5, 0x1800, v2
	v_add_u32_e32 v2, 0x1c00, v2
	ds_write2_b32 v5, v35, v36 offset0:48 offset1:114
	ds_write2_b32 v5, v37, v38 offset0:180 offset1:246
	ds_write2_b32 v2, v39, v40 offset0:56 offset1:122
	ds_write2_b32 v2, v8, v4 offset0:188 offset1:254
	v_lshlrev_b32_e32 v2, 3, v7
	v_and_b32_e32 v2, 56, v2
	v_ashrrev_i32_e32 v28, 3, v7
	v_mul_u32_u24_e32 v7, 0x84, v2
	v_lshlrev_b32_e32 v2, 1, v2
	s_waitcnt lgkmcnt(0)
	v_lshl_add_u64 v[4:5], s[44:45], 0, v[2:3]
	v_lshlrev_b32_e32 v2, 2, v28
	v_add3_u32 v2, s10, v7, v2
	ds_read2_b32 v[12:13], v2 offset0:33 offset1:41
	ds_read2_b32 v[14:15], v2 offset1:8
	ds_read2_b32 v[16:17], v2 offset0:66 offset1:74
	ds_read2_b32 v[18:19], v2 offset0:99 offset1:107
	ds_read2_b32 v[20:21], v2 offset0:132 offset1:140
	ds_read2_b32 v[22:23], v2 offset0:165 offset1:173
	ds_read2_b32 v[24:25], v2 offset0:198 offset1:206
	ds_read2_b32 v[26:27], v2 offset0:231 offset1:239
	s_waitcnt lgkmcnt(7)
	v_bfe_u32 v8, v12, 16, 1
	s_waitcnt lgkmcnt(6)
	v_bfe_u32 v7, v14, 16, 1
	v_add3_u32 v7, v14, v7, s62
	v_lshrrev_b32_e32 v7, 16, v7
	v_add3_u32 v8, v12, v8, s62
	v_and_or_b32 v8, v8, s63, v7
	s_waitcnt lgkmcnt(5)
	v_bfe_u32 v7, v16, 16, 1
	v_add3_u32 v7, v16, v7, s62
	s_waitcnt lgkmcnt(4)
	v_bfe_u32 v9, v18, 16, 1
	v_lshrrev_b32_e32 v7, 16, v7
	v_add3_u32 v9, v18, v9, s62
	v_and_or_b32 v9, v9, s63, v7
	s_waitcnt lgkmcnt(3)
	v_bfe_u32 v7, v20, 16, 1
	v_add3_u32 v7, v20, v7, s62
	s_waitcnt lgkmcnt(2)
	v_bfe_u32 v10, v22, 16, 1
	v_lshrrev_b32_e32 v7, 16, v7
	v_add3_u32 v10, v22, v10, s62
	v_and_or_b32 v10, v10, s63, v7
	s_waitcnt lgkmcnt(1)
	v_bfe_u32 v7, v24, 16, 1
	v_add_u32_e32 v28, s6, v28
	v_add3_u32 v7, v24, v7, s62
	s_waitcnt lgkmcnt(0)
	v_bfe_u32 v11, v26, 16, 1
	v_ashrrev_i32_e32 v29, 31, v28
	v_lshrrev_b32_e32 v7, 16, v7
	v_add3_u32 v11, v26, v11, s62
	v_lshlrev_b64 v[30:31], 12, v[28:29]
	v_and_or_b32 v11, v11, s63, v7
	v_lshl_add_u64 v[30:31], v[4:5], 0, v[30:31]
	v_bfe_u32 v7, v15, 16, 1
	global_store_dwordx4 v[30:31], v[8:11], off
	v_add3_u32 v7, v15, v7, s62
	v_lshrrev_b32_e32 v7, 16, v7
	v_bfe_u32 v8, v13, 16, 1
	v_add3_u32 v8, v13, v8, s62
	v_and_or_b32 v8, v8, s63, v7
	v_bfe_u32 v7, v17, 16, 1
	v_add3_u32 v7, v17, v7, s62
	v_bfe_u32 v9, v19, 16, 1
	v_lshrrev_b32_e32 v7, 16, v7
	v_add3_u32 v9, v19, v9, s62
	v_and_or_b32 v9, v9, s63, v7
	v_bfe_u32 v7, v21, 16, 1
	v_add3_u32 v7, v21, v7, s62
	v_bfe_u32 v10, v23, 16, 1
	v_lshrrev_b32_e32 v7, 16, v7
	v_add3_u32 v10, v23, v10, s62
	v_and_or_b32 v10, v10, s63, v7
	v_bfe_u32 v7, v25, 16, 1
	v_add_u32_e32 v12, 8, v28
	v_add3_u32 v7, v25, v7, s62
	v_bfe_u32 v11, v27, 16, 1
	v_ashrrev_i32_e32 v13, 31, v12
	v_lshrrev_b32_e32 v7, 16, v7
	v_add3_u32 v11, v27, v11, s62
	v_lshlrev_b64 v[12:13], 12, v[12:13]
	v_and_or_b32 v11, v11, s63, v7
	v_lshl_add_u64 v[12:13], v[4:5], 0, v[12:13]
	global_store_dwordx4 v[12:13], v[8:11], off
	ds_read2_b32 v[12:13], v2 offset0:49 offset1:57
	ds_read2_b32 v[14:15], v2 offset0:16 offset1:24
	ds_read2_b32 v[16:17], v2 offset0:82 offset1:90
	ds_read2_b32 v[18:19], v2 offset0:115 offset1:123
	ds_read2_b32 v[20:21], v2 offset0:148 offset1:156
	ds_read2_b32 v[22:23], v2 offset0:181 offset1:189
	ds_read2_b32 v[24:25], v2 offset0:214 offset1:222
	ds_read2_b32 v[26:27], v2 offset0:247 offset1:255
	s_waitcnt lgkmcnt(7)
	v_bfe_u32 v8, v12, 16, 1
	s_waitcnt lgkmcnt(6)
	v_bfe_u32 v7, v14, 16, 1
	v_add3_u32 v7, v14, v7, s62
	v_lshrrev_b32_e32 v7, 16, v7
	v_add3_u32 v8, v12, v8, s62
	v_and_or_b32 v8, v8, s63, v7
	s_waitcnt lgkmcnt(5)
	v_bfe_u32 v7, v16, 16, 1
	v_add3_u32 v7, v16, v7, s62
	s_waitcnt lgkmcnt(4)
	v_bfe_u32 v9, v18, 16, 1
	v_lshrrev_b32_e32 v7, 16, v7
	v_add3_u32 v9, v18, v9, s62
	v_and_or_b32 v9, v9, s63, v7
	s_waitcnt lgkmcnt(3)
	v_bfe_u32 v7, v20, 16, 1
	v_add3_u32 v7, v20, v7, s62
	s_waitcnt lgkmcnt(2)
	v_bfe_u32 v10, v22, 16, 1
	v_lshrrev_b32_e32 v7, 16, v7
	v_add3_u32 v10, v22, v10, s62
	s_waitcnt lgkmcnt(1)
	v_bfe_u32 v2, v24, 16, 1
	v_and_or_b32 v10, v10, s63, v7
	v_add3_u32 v2, v24, v2, s62
	s_waitcnt lgkmcnt(0)
	v_bfe_u32 v7, v26, 16, 1
	v_lshrrev_b32_e32 v2, 16, v2
	v_add3_u32 v7, v26, v7, s62
	v_add_u32_e32 v30, 16, v28
	v_and_or_b32 v11, v7, s63, v2
	v_ashrrev_i32_e32 v31, 31, v30
	v_bfe_u32 v2, v15, 16, 1
	v_lshlrev_b64 v[30:31], 12, v[30:31]
	v_add3_u32 v2, v15, v2, s62
	v_bfe_u32 v7, v13, 16, 1
	v_lshl_add_u64 v[30:31], v[4:5], 0, v[30:31]
	v_lshrrev_b32_e32 v2, 16, v2
	v_add3_u32 v7, v13, v7, s62
	global_store_dwordx4 v[30:31], v[8:11], off
	v_add_u32_e32 v12, 24, v28
	v_ashrrev_i32_e32 v13, 31, v12
	v_and_or_b32 v8, v7, s63, v2
	v_bfe_u32 v2, v17, 16, 1
	v_add3_u32 v2, v17, v2, s62
	v_bfe_u32 v7, v19, 16, 1
	v_lshrrev_b32_e32 v2, 16, v2
	v_add3_u32 v7, v19, v7, s62
	v_and_or_b32 v9, v7, s63, v2
	v_bfe_u32 v2, v21, 16, 1
	v_add3_u32 v2, v21, v2, s62
	v_bfe_u32 v7, v23, 16, 1
	v_lshrrev_b32_e32 v2, 16, v2
	v_add3_u32 v7, v23, v7, s62
	v_and_or_b32 v10, v7, s63, v2
	v_bfe_u32 v2, v25, 16, 1
	v_add3_u32 v2, v25, v2, s62
	v_bfe_u32 v7, v27, 16, 1
	v_lshrrev_b32_e32 v2, 16, v2
	v_add3_u32 v7, v27, v7, s62
	v_lshlrev_b64 v[12:13], 12, v[12:13]
	v_and_or_b32 v11, v7, s63, v2
	v_lshl_add_u64 v[4:5], v[4:5], 0, v[12:13]
	global_store_dwordx4 v[4:5], v[8:11], off
	s_waitcnt lgkmcnt(0)

;     ...
;     const int kb = item / nblk, nb = item % nblk, k0 = 64 * kb, n0 = 32 * nb;
;     { float wv[32];
;       const float* wp = W + (size_t)(k0 + (lane >> 5)) * ldw + n0 + (lane & 31);
; #pragma unroll
;       for (int i = 0; i < 32; ++i) wv[i] = wp[(size_t)(2 * i) * ldw];
; #pragma unroll
;       for (int i = 0; i < 32; ++i) scr[(2 * i + (lane >> 5)) * 33 + (lane & 31)] = wv[i]; }
; __device__ __forceinline__ void transpose_late(const Args& a, Frame& F, LAS float* scr, int r) {
;     ...
;     if (r < IT_SQ) { p0_transpose_item(a.in[I_WBOUT], D, D, WAB + D, 0, D / 32, scr, r, F.lane, 2 * D); return; } r -= IT_SQ;
.LBB0_1249:
	s_andn2_b64 vcc, exec, s[6:7]
	s_cbranch_vccnz .LBB0_1251
	s_add_i32 s0, s21, 0x1000
	v_mov_b32_e32 v7, v6
	s_and_b32 s7, s0, 0xffc0
	v_ashrrev_i32_e32 v10, 5, v7
	v_add_u32_e32 v4, s7, v10
	v_ashrrev_i32_e32 v5, 31, v4
	v_readlane_b32 s36, v244, 2
	s_and_b32 s6, s22, 0x7e0
	v_lshlrev_b64 v[4:5], 13, v[4:5]
	v_readlane_b32 s38, v244, 4
	v_readlane_b32 s39, v244, 5
	s_lshl_b32 s0, s6, 2
	v_lshlrev_b32_e32 v2, 2, v7
	v_lshl_add_u64 v[4:5], s[38:39], 0, v[4:5]
	v_lshl_add_u64 v[4:5], v[4:5], 0, s[0:1]
	v_and_b32_e32 v2, 0x7c, v2
	v_lshl_add_u64 v[4:5], v[4:5], 0, v[2:3]
	v_add_co_u32_e32 v8, vcc, s64, v4
	global_load_dword v11, v[4:5], off nt
	s_nop 0
	v_addc_co_u32_e32 v9, vcc, 0, v5, vcc
	global_load_dword v12, v[8:9], off nt
	v_add_co_u32_e32 v8, vcc, s65, v4
	v_readlane_b32 s44, v244, 10
	s_nop 0
	v_addc_co_u32_e32 v9, vcc, 0, v5, vcc
	global_load_dword v13, v[8:9], off nt
	v_add_co_u32_e32 v8, vcc, s66, v4
	s_lshl_b32 s0, s7, 1
	s_nop 0
	v_addc_co_u32_e32 v9, vcc, 0, v5, vcc
	global_load_dword v14, v[8:9], off nt
	v_add_co_u32_e32 v8, vcc, s67, v4
	v_readlane_b32 s45, v244, 11
	s_nop 0
	v_addc_co_u32_e32 v9, vcc, 0, v5, vcc
	global_load_dword v15, v[8:9], off nt
	v_add_co_u32_e32 v8, vcc, s68, v4
	s_add_u32 s44, s19, s0
	s_nop 0
	v_addc_co_u32_e32 v9, vcc, 0, v5, vcc
	global_load_dword v16, v[8:9], off nt
	v_add_co_u32_e32 v8, vcc, s69, v4
	s_addc_u32 s45, s20, 0
	s_nop 0
	v_addc_co_u32_e32 v9, vcc, 0, v5, vcc
	global_load_dword v17, v[8:9], off nt
	v_add_co_u32_e32 v8, vcc, s70, v4
	v_readlane_b32 s37, v244, 3
	s_nop 0
	v_addc_co_u32_e32 v9, vcc, 0, v5, vcc
	global_load_dword v18, v[8:9], off nt
	v_add_co_u32_e32 v8, vcc, s71, v4
	v_readlane_b32 s40, v244, 6
	s_nop 0
	v_addc_co_u32_e32 v9, vcc, 0, v5, vcc
	global_load_dword v19, v[8:9], off nt
	v_add_co_u32_e32 v8, vcc, s72, v4
	v_readlane_b32 s41, v244, 7
	s_nop 0
	v_addc_co_u32_e32 v9, vcc, 0, v5, vcc
	global_load_dword v20, v[8:9], off nt
	v_add_co_u32_e32 v8, vcc, s73, v4
	v_readlane_b32 s42, v244, 8
	s_nop 0
	v_addc_co_u32_e32 v9, vcc, 0, v5, vcc
	global_load_dword v21, v[8:9], off nt
	v_add_co_u32_e32 v8, vcc, s27, v4
	v_readlane_b32 s43, v244, 9
	s_nop 0
	v_addc_co_u32_e32 v9, vcc, 0, v5, vcc
	global_load_dword v22, v[8:9], off nt
	v_add_co_u32_e32 v8, vcc, s74, v4
	v_readlane_b32 s46, v244, 12
	s_nop 0
	v_addc_co_u32_e32 v9, vcc, 0, v5, vcc
	global_load_dword v23, v[8:9], off nt
	v_add_co_u32_e32 v8, vcc, s75, v4
	v_readlane_b32 s47, v244, 13
	s_nop 0
	v_addc_co_u32_e32 v9, vcc, 0, v5, vcc
	global_load_dword v24, v[8:9], off nt
	v_add_co_u32_e32 v8, vcc, s76, v4
	v_readlane_b32 s48, v244, 14
	s_nop 0
	v_addc_co_u32_e32 v9, vcc, 0, v5, vcc
	global_load_dword v25, v[8:9], off nt
	v_add_co_u32_e32 v8, vcc, s77, v4
	v_readlane_b32 s49, v244, 15
	s_nop 0
	v_addc_co_u32_e32 v9, vcc, 0, v5, vcc
	global_load_dword v26, v[8:9], off nt
	v_add_co_u32_e32 v8, vcc, s78, v4
	v_readlane_b32 s50, v244, 16
	s_nop 0
	v_addc_co_u32_e32 v9, vcc, 0, v5, vcc
	global_load_dword v27, v[8:9], off nt
	v_add_co_u32_e32 v8, vcc, s79, v4
	v_readlane_b32 s51, v244, 17
	s_nop 0
	v_addc_co_u32_e32 v9, vcc, 0, v5, vcc
	global_load_dword v28, v[8:9], off nt
	v_add_co_u32_e32 v8, vcc, s80, v4
	s_nop 1
	v_addc_co_u32_e32 v9, vcc, 0, v5, vcc
	global_load_dword v29, v[8:9], off nt
	v_add_co_u32_e32 v8, vcc, s81, v4
	s_nop 1
	v_addc_co_u32_e32 v9, vcc, 0, v5, vcc
	global_load_dword v30, v[8:9], off nt
	v_add_co_u32_e32 v8, vcc, s82, v4
	s_nop 1
	v_addc_co_u32_e32 v9, vcc, 0, v5, vcc
	global_load_dword v31, v[8:9], off nt
	v_add_co_u32_e32 v8, vcc, s83, v4
	s_nop 1
	v_addc_co_u32_e32 v9, vcc, 0, v5, vcc
	global_load_dword v32, v[8:9], off nt
	v_add_co_u32_e32 v8, vcc, s31, v4
	s_nop 1
	v_addc_co_u32_e32 v9, vcc, 0, v5, vcc
	global_load_dword v33, v[8:9], off nt
	v_add_co_u32_e32 v8, vcc, s85, v4
	s_nop 1
	v_addc_co_u32_e32 v9, vcc, 0, v5, vcc
	global_load_dword v34, v[8:9], off nt
	v_add_co_u32_e32 v8, vcc, s86, v4
	s_nop 1
	v_addc_co_u32_e32 v9, vcc, 0, v5, vcc
	global_load_dword v35, v[8:9], off nt
	v_add_co_u32_e32 v8, vcc, s87, v4
	s_nop 1
	v_addc_co_u32_e32 v9, vcc, 0, v5, vcc
	global_load_dword v36, v[8:9], off nt
	v_add_co_u32_e32 v8, vcc, s88, v4
	s_nop 1
	v_addc_co_u32_e32 v9, vcc, 0, v5, vcc
	global_load_dword v37, v[8:9], off nt
	v_add_co_u32_e32 v8, vcc, s89, v4
	s_nop 1
	v_addc_co_u32_e32 v9, vcc, 0, v5, vcc
	global_load_dword v38, v[8:9], off nt
	v_add_co_u32_e32 v8, vcc, s90, v4
	s_nop 1
	v_addc_co_u32_e32 v9, vcc, 0, v5, vcc
	global_load_dword v39, v[8:9], off nt
	v_add_co_u32_e32 v8, vcc, s91, v4
	s_nop 1
	v_addc_co_u32_e32 v9, vcc, 0, v5, vcc
	global_load_dword v40, v[8:9], off nt
	v_add_co_u32_e32 v8, vcc, s92, v4
	s_nop 1
	v_addc_co_u32_e32 v9, vcc, 0, v5, vcc
	v_add_co_u32_e32 v4, vcc, s93, v4
	global_load_dword v8, v[8:9], off nt
	s_nop 0
	v_addc_co_u32_e32 v5, vcc, 0, v5, vcc
	global_load_dword v4, v[4:5], off nt
	v_mul_lo_u32 v5, v10, s61
	v_add3_u32 v2, s10, v2, v5
	v_add_u32_e32 v5, 0x400, v2
	s_waitcnt vmcnt(0)
; #define GAS __attribute__((address_space(1)))
; #define LAS __attribute__((address_space(3)))
; #define LDS_WAIT() asm volatile("s_waitcnt lgkmcnt(0)" ::: "memory")
; __device__ __forceinline__ unsigned pk2(float lo, float hi) { return f2bf(lo) | (f2bf(hi) << 16); }
;     ...
;       for (int i = 0; i < 32; ++i) scr[(2 * i + (lane >> 5)) * 33 + (lane & 31)] = wv[i]; }
;     LDS_WAIT(); asm volatile("" ::: "memory");
;     const int c = lane & 7;
;     const int r0 = (mode == 0) ? n0 : (256 * (n0 >> 7) + (n0 & 127) + (mode == 2 ? 128 : 0));
; #pragma unroll
;     for (int j = 0; j < 4; ++j) { const int n = (lane >> 3) + 8 * j; const LAS float* s = scr + (8 * c) * 33 + n;
;         v4u o; o.x = pk2(s[0 * 33], s[1 * 33]); o.y = pk2(s[2 * 33], s[3 * 33]); o.z = pk2(s[4 * 33], s[5 * 33]); o.w = pk2(s[6 * 33], s[7 * 33]);
;         *(GAS v4u*)(WT + (size_t)(r0 + n) * ldt + k0 + 8 * c) = o; }
;     LDS_WAIT(); asm volatile("" ::: "memory");
	ds_write2_b32 v2, v11, v12 offset1:66
	ds_write2_b32 v2, v13, v14 offset0:132 offset1:198
	ds_write2_b32 v5, v15, v16 offset0:8 offset1:74
	ds_write2_b32 v5, v17, v18 offset0:140 offset1:206
	v_add_u32_e32 v5, 0x800, v2
	ds_write2_b32 v5, v19, v20 offset0:16 offset1:82
	ds_write2_b32 v5, v21, v22 offset0:148 offset1:214
	v_add_u32_e32 v5, 0xc00, v2
	ds_write2_b32 v5, v23, v24 offset0:24 offset1:90
	ds_write2_b32 v5, v25, v26 offset0:156 offset1:222
	v_add_u32_e32 v5, 0x1000, v2
	ds_write2_b32 v5, v27, v28 offset0:32 offset1:98
	ds_write2_b32 v5, v29, v30 offset0:164 offset1:230
	v_add_u32_e32 v5, 0x1400, v2
	ds_write2_b32 v5, v31, v32 offset0:40 offset1:106
	ds_write2_b32 v5, v33, v34 offset0:172 offset1:238
	v_add_u32_e32 v5, 0x1800, v2
	v_add_u32_e32 v2, 0x1c00, v2
	ds_write2_b32 v5, v35, v36 offset0:48 offset1:114
	ds_write2_b32 v5, v37, v38 offset0:180 offset1:246
	ds_write2_b32 v2, v39, v40 offset0:56 offset1:122
	ds_write2_b32 v2, v8, v4 offset0:188 offset1:254
	v_lshlrev_b32_e32 v2, 3, v7
	v_and_b32_e32 v2, 56, v2
	v_ashrrev_i32_e32 v28, 3, v7
	v_mul_u32_u24_e32 v7, 0x84, v2
	v_lshlrev_b32_e32 v2, 1, v2
	s_waitcnt lgkmcnt(0)
	v_lshl_add_u64 v[4:5], s[44:45], 0, v[2:3]
	v_lshlrev_b32_e32 v2, 2, v28
	v_add3_u32 v2, s10, v7, v2
	ds_read2_b32 v[12:13], v2 offset0:33 offset1:41
	ds_read2_b32 v[14:15], v2 offset1:8
	ds_read2_b32 v[16:17], v2 offset0:66 offset1:74
	ds_read2_b32 v[18:19], v2 offset0:99 offset1:107
	ds_read2_b32 v[20:21], v2 offset0:132 offset1:140
	ds_read2_b32 v[22:23], v2 offset0:165 offset1:173
	ds_read2_b32 v[24:25], v2 offset0:198 offset1:206
	ds_read2_b32 v[26:27], v2 offset0:231 offset1:239
	s_waitcnt lgkmcnt(7)
	v_bfe_u32 v8, v12, 16, 1
	s_waitcnt lgkmcnt(6)
	v_bfe_u32 v7, v14, 16, 1
	v_add3_u32 v7, v14, v7, s62
	v_lshrrev_b32_e32 v7, 16, v7
	v_add3_u32 v8, v12, v8, s62
	v_and_or_b32 v8, v8, s63, v7
	s_waitcnt lgkmcnt(5)
	v_bfe_u32 v7, v16, 16, 1
	v_add3_u32 v7, v16, v7, s62
	s_waitcnt lgkmcnt(4)
	v_bfe_u32 v9, v18, 16, 1
	v_lshrrev_b32_e32 v7, 16, v7
	v_add3_u32 v9, v18, v9, s62
	v_and_or_b32 v9, v9, s63, v7
	s_waitcnt lgkmcnt(3)
	v_bfe_u32 v7, v20, 16, 1
	v_add3_u32 v7, v20, v7, s62
	s_waitcnt lgkmcnt(2)
	v_bfe_u32 v10, v22, 16, 1
	v_lshrrev_b32_e32 v7, 16, v7
	v_add3_u32 v10, v22, v10, s62
	v_and_or_b32 v10, v10, s63, v7
	s_waitcnt lgkmcnt(1)
	v_bfe_u32 v7, v24, 16, 1
	v_add_u32_e32 v28, s6, v28
	v_add3_u32 v7, v24, v7, s62
	s_waitcnt lgkmcnt(0)
	v_bfe_u32 v11, v26, 16, 1
	v_ashrrev_i32_e32 v29, 31, v28
	v_lshrrev_b32_e32 v7, 16, v7
	v_add3_u32 v11, v26, v11, s62
	v_lshlrev_b64 v[30:31], 13, v[28:29]
	v_and_or_b32 v11, v11, s63, v7
	v_lshl_add_u64 v[30:31], v[4:5], 0, v[30:31]
	v_bfe_u32 v7, v15, 16, 1
	global_store_dwordx4 v[30:31], v[8:11], off
	v_add3_u32 v7, v15, v7, s62
	v_lshrrev_b32_e32 v7, 16, v7
	v_bfe_u32 v8, v13, 16, 1
	v_add3_u32 v8, v13, v8, s62
	v_and_or_b32 v8, v8, s63, v7
	v_bfe_u32 v7, v17, 16, 1
	v_add3_u32 v7, v17, v7, s62
	v_bfe_u32 v9, v19, 16, 1
	v_lshrrev_b32_e32 v7, 16, v7
	v_add3_u32 v9, v19, v9, s62
	v_and_or_b32 v9, v9, s63, v7
	v_bfe_u32 v7, v21, 16, 1
	v_add3_u32 v7, v21, v7, s62
	v_bfe_u32 v10, v23, 16, 1
	v_lshrrev_b32_e32 v7, 16, v7
	v_add3_u32 v10, v23, v10, s62
	v_and_or_b32 v10, v10, s63, v7
	v_bfe_u32 v7, v25, 16, 1
	v_add_u32_e32 v12, 8, v28
	v_add3_u32 v7, v25, v7, s62
	v_bfe_u32 v11, v27, 16, 1
	v_ashrrev_i32_e32 v13, 31, v12
	v_lshrrev_b32_e32 v7, 16, v7
	v_add3_u32 v11, v27, v11, s62
	v_lshlrev_b64 v[12:13], 13, v[12:13]
	v_and_or_b32 v11, v11, s63, v7
	v_lshl_add_u64 v[12:13], v[4:5], 0, v[12:13]
	global_store_dwordx4 v[12:13], v[8:11], off
	ds_read2_b32 v[12:13], v2 offset0:49 offset1:57
	ds_read2_b32 v[14:15], v2 offset0:16 offset1:24
	ds_read2_b32 v[16:17], v2 offset0:82 offset1:90
	ds_read2_b32 v[18:19], v2 offset0:115 offset1:123
	ds_read2_b32 v[20:21], v2 offset0:148 offset1:156
	ds_read2_b32 v[22:23], v2 offset0:181 offset1:189
	ds_read2_b32 v[24:25], v2 offset0:214 offset1:222
	ds_read2_b32 v[26:27], v2 offset0:247 offset1:255
	s_waitcnt lgkmcnt(7)
	v_bfe_u32 v8, v12, 16, 1
	s_waitcnt lgkmcnt(6)
	v_bfe_u32 v7, v14, 16, 1
	v_add3_u32 v7, v14, v7, s62
	v_lshrrev_b32_e32 v7, 16, v7
	v_add3_u32 v8, v12, v8, s62
	v_and_or_b32 v8, v8, s63, v7
	s_waitcnt lgkmcnt(5)
	v_bfe_u32 v7, v16, 16, 1
	v_add3_u32 v7, v16, v7, s62
	s_waitcnt lgkmcnt(4)
	v_bfe_u32 v9, v18, 16, 1
	v_lshrrev_b32_e32 v7, 16, v7
	v_add3_u32 v9, v18, v9, s62
	v_and_or_b32 v9, v9, s63, v7
	s_waitcnt lgkmcnt(3)
	v_bfe_u32 v7, v20, 16, 1
	v_add3_u32 v7, v20, v7, s62
	s_waitcnt lgkmcnt(2)
	v_bfe_u32 v10, v22, 16, 1
	v_lshrrev_b32_e32 v7, 16, v7
	v_add3_u32 v10, v22, v10, s62
	s_waitcnt lgkmcnt(1)
	v_bfe_u32 v2, v24, 16, 1
	v_and_or_b32 v10, v10, s63, v7
	v_add3_u32 v2, v24, v2, s62
	s_waitcnt lgkmcnt(0)
	v_bfe_u32 v7, v26, 16, 1
	v_lshrrev_b32_e32 v2, 16, v2
	v_add3_u32 v7, v26, v7, s62
	v_add_u32_e32 v30, 16, v28
	v_and_or_b32 v11, v7, s63, v2
	v_ashrrev_i32_e32 v31, 31, v30
	v_bfe_u32 v2, v15, 16, 1
	v_lshlrev_b64 v[30:31], 13, v[30:31]
	v_add3_u32 v2, v15, v2, s62
	v_bfe_u32 v7, v13, 16, 1
	v_lshl_add_u64 v[30:31], v[4:5], 0, v[30:31]
	v_lshrrev_b32_e32 v2, 16, v2
	v_add3_u32 v7, v13, v7, s62
	global_store_dwordx4 v[30:31], v[8:11], off
	v_add_u32_e32 v12, 24, v28
	v_ashrrev_i32_e32 v13, 31, v12
	v_and_or_b32 v8, v7, s63, v2
	v_bfe_u32 v2, v17, 16, 1
	v_add3_u32 v2, v17, v2, s62
	v_bfe_u32 v7, v19, 16, 1
	v_lshrrev_b32_e32 v2, 16, v2
	v_add3_u32 v7, v19, v7, s62
	v_and_or_b32 v9, v7, s63, v2
	v_bfe_u32 v2, v21, 16, 1
	v_add3_u32 v2, v21, v2, s62
	v_bfe_u32 v7, v23, 16, 1
	v_lshrrev_b32_e32 v2, 16, v2
	v_add3_u32 v7, v23, v7, s62
	v_and_or_b32 v10, v7, s63, v2
	v_bfe_u32 v2, v25, 16, 1
	v_add3_u32 v2, v25, v2, s62
	v_bfe_u32 v7, v27, 16, 1
	v_lshrrev_b32_e32 v2, 16, v2
	v_add3_u32 v7, v27, v7, s62
	v_lshlrev_b64 v[12:13], 13, v[12:13]
	v_and_or_b32 v11, v7, s63, v2
	v_lshl_add_u64 v[4:5], v[4:5], 0, v[12:13]
	global_store_dwordx4 v[4:5], v[8:11], off
	s_waitcnt lgkmcnt(0)

;     ...
;     const int kb = item / nblk, nb = item % nblk, k0 = 64 * kb, n0 = 32 * nb;
;     { float wv[32];
;       const float* wp = W + (size_t)(k0 + (lane >> 5)) * ldw + n0 + (lane & 31);
; #pragma unroll
;       for (int i = 0; i < 32; ++i) wv[i] = wp[(size_t)(2 * i) * ldw];
; #pragma unroll
;       for (int i = 0; i < 32; ++i) scr[(2 * i + (lane >> 5)) * 33 + (lane & 31)] = wv[i]; }
; __device__ __forceinline__ void transpose_late(const Args& a, Frame& F, LAS float* scr, int r) {
;     ...
;     if (r < IT_SQ) { p0_transpose_item(a.in[I_WAOUT], D, D, WAB, 0, D / 32, scr, r, F.lane, 2 * D); return; } r -= IT_SQ;
.LBB0_1252:
	s_ashr_i32 s0, s9, 31
	s_lshr_b32 s0, s0, 26
	v_mov_b32_e32 v7, v6
	s_add_i32 s0, s9, s0
	s_and_b32 s8, s0, 0xffffffc0
	v_ashrrev_i32_e32 v10, 5, v7
	v_add_u32_e32 v4, s8, v10
	s_sub_i32 s0, s9, s8
	v_ashrrev_i32_e32 v5, 31, v4
	v_readlane_b32 s36, v245, 50
	s_lshl_b32 s6, s0, 5
	v_lshlrev_b64 v[4:5], 13, v[4:5]
	v_readlane_b32 s44, v245, 58
	v_readlane_b32 s45, v245, 59
	s_ashr_i32 s7, s6, 31
	v_lshlrev_b32_e32 v2, 2, v7
	v_lshl_add_u64 v[4:5], s[44:45], 0, v[4:5]
	v_lshl_add_u64 v[4:5], s[6:7], 2, v[4:5]
	v_and_b32_e32 v2, 0x7c, v2
	v_lshl_add_u64 v[4:5], v[4:5], 0, v[2:3]
	v_add_co_u32_e32 v8, vcc, s64, v4
	global_load_dword v11, v[4:5], off nt
	s_nop 0
	v_addc_co_u32_e32 v9, vcc, 0, v5, vcc
	global_load_dword v12, v[8:9], off nt
	v_add_co_u32_e32 v8, vcc, s65, v4
	s_ashr_i32 s9, s8, 31
	s_nop 0
	v_addc_co_u32_e32 v9, vcc, 0, v5, vcc
	global_load_dword v13, v[8:9], off nt
	v_add_co_u32_e32 v8, vcc, s66, v4
	s_lshl_b64 s[8:9], s[8:9], 1
	s_nop 0
	v_addc_co_u32_e32 v9, vcc, 0, v5, vcc
	global_load_dword v14, v[8:9], off nt
	v_add_co_u32_e32 v8, vcc, s67, v4
	s_add_u32 s8, s3, s8
	s_nop 0
	v_addc_co_u32_e32 v9, vcc, 0, v5, vcc
	global_load_dword v15, v[8:9], off nt
	v_add_co_u32_e32 v8, vcc, s68, v4
	s_addc_u32 s9, s33, s9
	s_nop 0
	v_addc_co_u32_e32 v9, vcc, 0, v5, vcc
	global_load_dword v16, v[8:9], off nt
	v_add_co_u32_e32 v8, vcc, s69, v4
	v_readlane_b32 s37, v245, 51
	s_nop 0
	v_addc_co_u32_e32 v9, vcc, 0, v5, vcc
	global_load_dword v17, v[8:9], off nt
	v_add_co_u32_e32 v8, vcc, s70, v4
	v_readlane_b32 s38, v245, 52
	s_nop 0
	v_addc_co_u32_e32 v9, vcc, 0, v5, vcc
	global_load_dword v18, v[8:9], off nt
	v_add_co_u32_e32 v8, vcc, s71, v4
	v_readlane_b32 s39, v245, 53
	s_nop 0
	v_addc_co_u32_e32 v9, vcc, 0, v5, vcc
	global_load_dword v19, v[8:9], off nt
	v_add_co_u32_e32 v8, vcc, s72, v4
	v_readlane_b32 s40, v245, 54
	s_nop 0
	v_addc_co_u32_e32 v9, vcc, 0, v5, vcc
	global_load_dword v20, v[8:9], off nt
	v_add_co_u32_e32 v8, vcc, s73, v4
	v_readlane_b32 s41, v245, 55
	s_nop 0
	v_addc_co_u32_e32 v9, vcc, 0, v5, vcc
	global_load_dword v21, v[8:9], off nt
	v_add_co_u32_e32 v8, vcc, s27, v4
	v_readlane_b32 s42, v245, 56
	s_nop 0
	v_addc_co_u32_e32 v9, vcc, 0, v5, vcc
	global_load_dword v22, v[8:9], off nt
	v_add_co_u32_e32 v8, vcc, s74, v4
	v_readlane_b32 s43, v245, 57
	s_nop 0
	v_addc_co_u32_e32 v9, vcc, 0, v5, vcc
	global_load_dword v23, v[8:9], off nt
	v_add_co_u32_e32 v8, vcc, s75, v4
	v_readlane_b32 s46, v245, 60
	s_nop 0
	v_addc_co_u32_e32 v9, vcc, 0, v5, vcc
	global_load_dword v24, v[8:9], off nt
	v_add_co_u32_e32 v8, vcc, s76, v4
	v_readlane_b32 s47, v245, 61
	s_nop 0
	v_addc_co_u32_e32 v9, vcc, 0, v5, vcc
	global_load_dword v25, v[8:9], off nt
	v_add_co_u32_e32 v8, vcc, s77, v4
	v_readlane_b32 s48, v245, 62
	s_nop 0
	v_addc_co_u32_e32 v9, vcc, 0, v5, vcc
	global_load_dword v26, v[8:9], off nt
	v_add_co_u32_e32 v8, vcc, s78, v4
	v_readlane_b32 s49, v245, 63
	s_nop 0
	v_addc_co_u32_e32 v9, vcc, 0, v5, vcc
	global_load_dword v27, v[8:9], off nt
	v_add_co_u32_e32 v8, vcc, s79, v4
	v_readlane_b32 s50, v244, 0
	s_nop 0
	v_addc_co_u32_e32 v9, vcc, 0, v5, vcc
	global_load_dword v28, v[8:9], off nt
	v_add_co_u32_e32 v8, vcc, s80, v4
	v_readlane_b32 s51, v244, 1
	s_nop 0
	v_addc_co_u32_e32 v9, vcc, 0, v5, vcc
	global_load_dword v29, v[8:9], off nt
	v_add_co_u32_e32 v8, vcc, s81, v4
	s_nop 1
	v_addc_co_u32_e32 v9, vcc, 0, v5, vcc
	global_load_dword v30, v[8:9], off nt
	v_add_co_u32_e32 v8, vcc, s82, v4
	s_nop 1
	v_addc_co_u32_e32 v9, vcc, 0, v5, vcc
	global_load_dword v31, v[8:9], off nt
	v_add_co_u32_e32 v8, vcc, s83, v4
	s_nop 1
	v_addc_co_u32_e32 v9, vcc, 0, v5, vcc
	global_load_dword v32, v[8:9], off nt
	v_add_co_u32_e32 v8, vcc, s31, v4
	s_nop 1
	v_addc_co_u32_e32 v9, vcc, 0, v5, vcc
	global_load_dword v33, v[8:9], off nt
	v_add_co_u32_e32 v8, vcc, s85, v4
	s_nop 1
	v_addc_co_u32_e32 v9, vcc, 0, v5, vcc
	global_load_dword v34, v[8:9], off nt
	v_add_co_u32_e32 v8, vcc, s86, v4
	s_nop 1
	v_addc_co_u32_e32 v9, vcc, 0, v5, vcc
	global_load_dword v35, v[8:9], off nt
	v_add_co_u32_e32 v8, vcc, s87, v4
	s_nop 1
	v_addc_co_u32_e32 v9, vcc, 0, v5, vcc
	global_load_dword v36, v[8:9], off nt
	v_add_co_u32_e32 v8, vcc, s88, v4
	s_nop 1
	v_addc_co_u32_e32 v9, vcc, 0, v5, vcc
	global_load_dword v37, v[8:9], off nt
	v_add_co_u32_e32 v8, vcc, s89, v4
	s_nop 1
	v_addc_co_u32_e32 v9, vcc, 0, v5, vcc
	global_load_dword v38, v[8:9], off nt
	v_add_co_u32_e32 v8, vcc, s90, v4
	s_nop 1
	v_addc_co_u32_e32 v9, vcc, 0, v5, vcc
	global_load_dword v39, v[8:9], off nt
	v_add_co_u32_e32 v8, vcc, s91, v4
	s_nop 1
	v_addc_co_u32_e32 v9, vcc, 0, v5, vcc
	global_load_dword v40, v[8:9], off nt
	v_add_co_u32_e32 v8, vcc, s92, v4
	s_nop 1
	v_addc_co_u32_e32 v9, vcc, 0, v5, vcc
	v_add_co_u32_e32 v4, vcc, s93, v4
	global_load_dword v8, v[8:9], off nt
	s_nop 0
	v_addc_co_u32_e32 v5, vcc, 0, v5, vcc
	global_load_dword v4, v[4:5], off nt
	v_mul_lo_u32 v5, v10, s61
	v_add3_u32 v2, s10, v2, v5
	v_add_u32_e32 v5, 0x400, v2
	s_waitcnt vmcnt(0)
; #define GAS __attribute__((address_space(1)))
; #define LAS __attribute__((address_space(3)))
; #define LDS_WAIT() asm volatile("s_waitcnt lgkmcnt(0)" ::: "memory")
; __device__ __forceinline__ unsigned pk2(float lo, float hi) { return f2bf(lo) | (f2bf(hi) << 16); }
;     ...
;       for (int i = 0; i < 32; ++i) scr[(2 * i + (lane >> 5)) * 33 + (lane & 31)] = wv[i]; }
;     LDS_WAIT(); asm volatile("" ::: "memory");
;     const int c = lane & 7;
;     const int r0 = (mode == 0) ? n0 : (256 * (n0 >> 7) + (n0 & 127) + (mode == 2 ? 128 : 0));
; #pragma unroll
;     for (int j = 0; j < 4; ++j) { const int n = (lane >> 3) + 8 * j; const LAS float* s = scr + (8 * c) * 33 + n;
;         v4u o; o.x = pk2(s[0 * 33], s[1 * 33]); o.y = pk2(s[2 * 33], s[3 * 33]); o.z = pk2(s[4 * 33], s[5 * 33]); o.w = pk2(s[6 * 33], s[7 * 33]);
;         *(GAS v4u*)(WT + (size_t)(r0 + n) * ldt + k0 + 8 * c) = o; }
;     LDS_WAIT(); asm volatile("" ::: "memory");
	ds_write2_b32 v2, v11, v12 offset1:66
	ds_write2_b32 v2, v13, v14 offset0:132 offset1:198
	ds_write2_b32 v5, v15, v16 offset0:8 offset1:74
	ds_write2_b32 v5, v17, v18 offset0:140 offset1:206
	v_add_u32_e32 v5, 0x800, v2
	ds_write2_b32 v5, v19, v20 offset0:16 offset1:82
	ds_write2_b32 v5, v21, v22 offset0:148 offset1:214
	v_add_u32_e32 v5, 0xc00, v2
	ds_write2_b32 v5, v23, v24 offset0:24 offset1:90
	ds_write2_b32 v5, v25, v26 offset0:156 offset1:222
	v_add_u32_e32 v5, 0x1000, v2
	ds_write2_b32 v5, v27, v28 offset0:32 offset1:98
	ds_write2_b32 v5, v29, v30 offset0:164 offset1:230
	v_add_u32_e32 v5, 0x1400, v2
	ds_write2_b32 v5, v31, v32 offset0:40 offset1:106
	ds_write2_b32 v5, v33, v34 offset0:172 offset1:238
	v_add_u32_e32 v5, 0x1800, v2
	v_add_u32_e32 v2, 0x1c00, v2
	ds_write2_b32 v5, v35, v36 offset0:48 offset1:114
	ds_write2_b32 v5, v37, v38 offset0:180 offset1:246
	ds_write2_b32 v2, v39, v40 offset0:56 offset1:122
	ds_write2_b32 v2, v8, v4 offset0:188 offset1:254
	v_lshlrev_b32_e32 v2, 3, v7
	v_and_b32_e32 v2, 56, v2
	v_ashrrev_i32_e32 v28, 3, v7
	v_mul_u32_u24_e32 v7, 0x84, v2
	v_lshlrev_b32_e32 v2, 1, v2
	s_waitcnt lgkmcnt(0)
	v_lshl_add_u64 v[4:5], s[8:9], 0, v[2:3]
	v_lshlrev_b32_e32 v2, 2, v28
	v_add3_u32 v2, s10, v7, v2
	ds_read2_b32 v[12:13], v2 offset0:33 offset1:41
	ds_read2_b32 v[14:15], v2 offset1:8
	ds_read2_b32 v[16:17], v2 offset0:66 offset1:74
	ds_read2_b32 v[18:19], v2 offset0:99 offset1:107
	ds_read2_b32 v[20:21], v2 offset0:132 offset1:140
	ds_read2_b32 v[22:23], v2 offset0:165 offset1:173
	ds_read2_b32 v[24:25], v2 offset0:198 offset1:206
	ds_read2_b32 v[26:27], v2 offset0:231 offset1:239
	s_waitcnt lgkmcnt(7)
	v_bfe_u32 v8, v12, 16, 1
	s_waitcnt lgkmcnt(6)
	v_bfe_u32 v7, v14, 16, 1
	v_add3_u32 v7, v14, v7, s62
	v_lshrrev_b32_e32 v7, 16, v7
	v_add3_u32 v8, v12, v8, s62
	v_and_or_b32 v8, v8, s63, v7
	s_waitcnt lgkmcnt(5)
	v_bfe_u32 v7, v16, 16, 1
	v_add3_u32 v7, v16, v7, s62
	s_waitcnt lgkmcnt(4)
	v_bfe_u32 v9, v18, 16, 1
	v_lshrrev_b32_e32 v7, 16, v7
	v_add3_u32 v9, v18, v9, s62
	v_and_or_b32 v9, v9, s63, v7
	s_waitcnt lgkmcnt(3)
	v_bfe_u32 v7, v20, 16, 1
	v_add3_u32 v7, v20, v7, s62
	s_waitcnt lgkmcnt(2)
	v_bfe_u32 v10, v22, 16, 1
	v_lshrrev_b32_e32 v7, 16, v7
	v_add3_u32 v10, v22, v10, s62
	v_and_or_b32 v10, v10, s63, v7
	s_waitcnt lgkmcnt(1)
	v_bfe_u32 v7, v24, 16, 1
	v_add_u32_e32 v28, s6, v28
	v_add3_u32 v7, v24, v7, s62
	s_waitcnt lgkmcnt(0)
	v_bfe_u32 v11, v26, 16, 1
	v_ashrrev_i32_e32 v29, 31, v28
	v_lshrrev_b32_e32 v7, 16, v7
	v_add3_u32 v11, v26, v11, s62
	v_lshlrev_b64 v[30:31], 13, v[28:29]
	v_and_or_b32 v11, v11, s63, v7
	v_lshl_add_u64 v[30:31], v[4:5], 0, v[30:31]
	v_bfe_u32 v7, v15, 16, 1
	global_store_dwordx4 v[30:31], v[8:11], off
	v_add3_u32 v7, v15, v7, s62
	v_lshrrev_b32_e32 v7, 16, v7
	v_bfe_u32 v8, v13, 16, 1
	v_add3_u32 v8, v13, v8, s62
	v_and_or_b32 v8, v8, s63, v7
	v_bfe_u32 v7, v17, 16, 1
	v_add3_u32 v7, v17, v7, s62
	v_bfe_u32 v9, v19, 16, 1
	v_lshrrev_b32_e32 v7, 16, v7
	v_add3_u32 v9, v19, v9, s62
	v_and_or_b32 v9, v9, s63, v7
	v_bfe_u32 v7, v21, 16, 1
	v_add3_u32 v7, v21, v7, s62
	v_bfe_u32 v10, v23, 16, 1
	v_lshrrev_b32_e32 v7, 16, v7
	v_add3_u32 v10, v23, v10, s62
	v_and_or_b32 v10, v10, s63, v7
	v_bfe_u32 v7, v25, 16, 1
	v_add_u32_e32 v12, 8, v28
	v_add3_u32 v7, v25, v7, s62
	v_bfe_u32 v11, v27, 16, 1
	v_ashrrev_i32_e32 v13, 31, v12
	v_lshrrev_b32_e32 v7, 16, v7
	v_add3_u32 v11, v27, v11, s62
	v_lshlrev_b64 v[12:13], 13, v[12:13]
	v_and_or_b32 v11, v11, s63, v7
	v_lshl_add_u64 v[12:13], v[4:5], 0, v[12:13]
	global_store_dwordx4 v[12:13], v[8:11], off
	ds_read2_b32 v[12:13], v2 offset0:49 offset1:57
	ds_read2_b32 v[14:15], v2 offset0:16 offset1:24
	ds_read2_b32 v[16:17], v2 offset0:82 offset1:90
	ds_read2_b32 v[18:19], v2 offset0:115 offset1:123
	ds_read2_b32 v[20:21], v2 offset0:148 offset1:156
	ds_read2_b32 v[22:23], v2 offset0:181 offset1:189
	ds_read2_b32 v[24:25], v2 offset0:214 offset1:222
	ds_read2_b32 v[26:27], v2 offset0:247 offset1:255
	s_waitcnt lgkmcnt(7)
	v_bfe_u32 v8, v12, 16, 1
	s_waitcnt lgkmcnt(6)
	v_bfe_u32 v7, v14, 16, 1
	v_add3_u32 v7, v14, v7, s62
	v_lshrrev_b32_e32 v7, 16, v7
	v_add3_u32 v8, v12, v8, s62
	v_and_or_b32 v8, v8, s63, v7
	s_waitcnt lgkmcnt(5)
	v_bfe_u32 v7, v16, 16, 1
	v_add3_u32 v7, v16, v7, s62
	s_waitcnt lgkmcnt(4)
	v_bfe_u32 v9, v18, 16, 1
	v_lshrrev_b32_e32 v7, 16, v7
	v_add3_u32 v9, v18, v9, s62
	v_and_or_b32 v9, v9, s63, v7
	s_waitcnt lgkmcnt(3)
	v_bfe_u32 v7, v20, 16, 1
	v_add3_u32 v7, v20, v7, s62
	s_waitcnt lgkmcnt(2)
	v_bfe_u32 v10, v22, 16, 1
	v_lshrrev_b32_e32 v7, 16, v7
	v_add3_u32 v10, v22, v10, s62
	s_waitcnt lgkmcnt(1)
	v_bfe_u32 v2, v24, 16, 1
	v_and_or_b32 v10, v10, s63, v7
	v_add3_u32 v2, v24, v2, s62
	s_waitcnt lgkmcnt(0)
	v_bfe_u32 v7, v26, 16, 1
	v_lshrrev_b32_e32 v2, 16, v2
	v_add3_u32 v7, v26, v7, s62
	v_add_u32_e32 v30, 16, v28
	v_and_or_b32 v11, v7, s63, v2
	v_ashrrev_i32_e32 v31, 31, v30
	v_bfe_u32 v2, v15, 16, 1
	v_lshlrev_b64 v[30:31], 13, v[30:31]
	v_add3_u32 v2, v15, v2, s62
	v_bfe_u32 v7, v13, 16, 1
	v_lshl_add_u64 v[30:31], v[4:5], 0, v[30:31]
	v_lshrrev_b32_e32 v2, 16, v2
	v_add3_u32 v7, v13, v7, s62
	global_store_dwordx4 v[30:31], v[8:11], off
	v_add_u32_e32 v12, 24, v28
	v_ashrrev_i32_e32 v13, 31, v12
	v_and_or_b32 v8, v7, s63, v2
	v_bfe_u32 v2, v17, 16, 1
	v_add3_u32 v2, v17, v2, s62
	v_bfe_u32 v7, v19, 16, 1
	v_lshrrev_b32_e32 v2, 16, v2
	v_add3_u32 v7, v19, v7, s62
	v_and_or_b32 v9, v7, s63, v2
	v_bfe_u32 v2, v21, 16, 1
	v_add3_u32 v2, v21, v2, s62
	v_bfe_u32 v7, v23, 16, 1
	v_lshrrev_b32_e32 v2, 16, v2
	v_add3_u32 v7, v23, v7, s62
	v_and_or_b32 v10, v7, s63, v2
	v_bfe_u32 v2, v25, 16, 1
	v_add3_u32 v2, v25, v2, s62
	v_bfe_u32 v7, v27, 16, 1
	v_lshrrev_b32_e32 v2, 16, v2
	v_add3_u32 v7, v27, v7, s62
	v_lshlrev_b64 v[12:13], 13, v[12:13]
	v_and_or_b32 v11, v7, s63, v2
	v_lshl_add_u64 v[4:5], v[4:5], 0, v[12:13]
	global_store_dwordx4 v[4:5], v[8:11], off
	s_waitcnt lgkmcnt(0)
	s_branch .LBB0_1228

;     ...
;     const int kb = item / nblk, nb = item % nblk, k0 = 64 * kb, n0 = 32 * nb;
;     { float wv[32];
;       const float* wp = W + (size_t)(k0 + (lane >> 5)) * ldw + n0 + (lane & 31);
; #pragma unroll
;       for (int i = 0; i < 32; ++i) wv[i] = wp[(size_t)(2 * i) * ldw];
; #pragma unroll
;       for (int i = 0; i < 32; ++i) scr[(2 * i + (lane >> 5)) * 33 + (lane & 31)] = wv[i]; }
; __device__ __forceinline__ void transpose_late(const Args& a, Frame& F, LAS float* scr, int r) {
;     ...
;     p0_transpose_item(a.in[I_W2D], D, FF, W2D, 0, D / 32, scr, r, F.lane);
.LBB0_1563:
	s_cmpk_gt_u32 s9, 0xfff
	s_cbranch_scc0 .LBB0_1585
	s_cmpk_gt_u32 s9, 0x17ff
	s_cbranch_scc0 .LBB0_1582
	s_cmpk_gt_u32 s9, 0x1fff
	s_cbranch_scc0 .LBB0_1579
	s_cmpk_gt_u32 s9, 0x20ff
	s_cbranch_scc0 .LBB0_1576
	s_cmpk_gt_u32 s9, 0x36ff
	s_cbranch_scc0 .LBB0_1573
	s_cmp_lt_u32 s67, 0xffffb300
	s_cbranch_scc0 .LBB0_1570
	v_mov_b32_e32 v7, v6
	s_and_b32 s5, s67, 0xffc0
	v_ashrrev_i32_e32 v10, 5, v7
	v_add_u32_e32 v4, s5, v10
	v_ashrrev_i32_e32 v5, 31, v4
	s_mov_b64 s[44:45], s[82:83]
	v_readlane_b32 s68, v244, 2
	s_and_b32 s4, s24, 0x7e0
	v_lshlrev_b64 v[4:5], 13, v[4:5]
	v_readlane_b32 s82, v244, 16
	v_readlane_b32 s83, v244, 17
	s_lshl_b32 s0, s4, 2
	v_lshlrev_b32_e32 v2, 2, v7
	v_lshl_add_u64 v[4:5], s[82:83], 0, v[4:5]
	v_lshl_add_u64 v[4:5], v[4:5], 0, s[0:1]
	v_and_b32_e32 v2, 0x7c, v2
	v_lshl_add_u64 v[4:5], v[4:5], 0, v[2:3]
	v_add_co_u32_e32 v8, vcc, s25, v4
	global_load_dword v11, v[4:5], off nt
	s_nop 0
	v_addc_co_u32_e32 v9, vcc, 0, v5, vcc
	global_load_dword v12, v[8:9], off nt
	v_add_co_u32_e32 v8, vcc, s26, v4
	s_lshl_b32 s0, s5, 1
	s_nop 0
	v_addc_co_u32_e32 v9, vcc, 0, v5, vcc
	global_load_dword v13, v[8:9], off nt
	v_add_co_u32_e32 v8, vcc, s27, v4
	s_mov_b64 s[82:83], s[44:45]
	s_nop 0
	v_addc_co_u32_e32 v9, vcc, 0, v5, vcc
	global_load_dword v14, v[8:9], off nt
	v_add_co_u32_e32 v8, vcc, s28, v4
	s_add_u32 s44, s17, s0
	s_nop 0
	v_addc_co_u32_e32 v9, vcc, 0, v5, vcc
	global_load_dword v15, v[8:9], off nt
	v_add_co_u32_e32 v8, vcc, s29, v4
	s_addc_u32 s45, s18, 0
	s_nop 0
	v_addc_co_u32_e32 v9, vcc, 0, v5, vcc
	global_load_dword v16, v[8:9], off nt
	v_add_co_u32_e32 v8, vcc, s31, v4
	v_readlane_b32 s69, v244, 3
	s_nop 0
	v_addc_co_u32_e32 v9, vcc, 0, v5, vcc
	global_load_dword v17, v[8:9], off nt
	v_add_co_u32_e32 v8, vcc, s33, v4
	v_readlane_b32 s70, v244, 4
	s_nop 0
	v_addc_co_u32_e32 v9, vcc, 0, v5, vcc
	global_load_dword v18, v[8:9], off nt
	v_add_co_u32_e32 v8, vcc, s36, v4
	v_readlane_b32 s71, v244, 5
	s_nop 0
	v_addc_co_u32_e32 v9, vcc, 0, v5, vcc
	global_load_dword v19, v[8:9], off nt
	v_add_co_u32_e32 v8, vcc, s37, v4
	v_readlane_b32 s72, v244, 6
	s_nop 0
	v_addc_co_u32_e32 v9, vcc, 0, v5, vcc
	global_load_dword v20, v[8:9], off nt
	v_add_co_u32_e32 v8, vcc, s38, v4
	v_readlane_b32 s73, v244, 7
	s_nop 0
	v_addc_co_u32_e32 v9, vcc, 0, v5, vcc
	global_load_dword v21, v[8:9], off nt
	v_add_co_u32_e32 v8, vcc, s39, v4
	v_readlane_b32 s74, v244, 8
	s_nop 0
	v_addc_co_u32_e32 v9, vcc, 0, v5, vcc
	global_load_dword v22, v[8:9], off nt
	v_add_co_u32_e32 v8, vcc, s40, v4
	v_readlane_b32 s75, v244, 9
	s_nop 0
	v_addc_co_u32_e32 v9, vcc, 0, v5, vcc
	global_load_dword v23, v[8:9], off nt
	v_add_co_u32_e32 v8, vcc, s41, v4
	v_readlane_b32 s76, v244, 10
	s_nop 0
	v_addc_co_u32_e32 v9, vcc, 0, v5, vcc
	global_load_dword v24, v[8:9], off nt
	v_add_co_u32_e32 v8, vcc, s42, v4
	v_readlane_b32 s77, v244, 11
	s_nop 0
	v_addc_co_u32_e32 v9, vcc, 0, v5, vcc
	global_load_dword v25, v[8:9], off nt
	v_add_co_u32_e32 v8, vcc, s43, v4
	v_readlane_b32 s78, v244, 12
	s_nop 0
	v_addc_co_u32_e32 v9, vcc, 0, v5, vcc
	global_load_dword v26, v[8:9], off nt
	v_add_co_u32_e32 v8, vcc, s46, v4
	v_readlane_b32 s79, v244, 13
	s_nop 0
	v_addc_co_u32_e32 v9, vcc, 0, v5, vcc
	global_load_dword v27, v[8:9], off nt
	v_add_co_u32_e32 v8, vcc, s47, v4
	v_readlane_b32 s80, v244, 14
	s_nop 0
	v_addc_co_u32_e32 v9, vcc, 0, v5, vcc
	global_load_dword v28, v[8:9], off nt
	v_add_co_u32_e32 v8, vcc, s48, v4
	v_readlane_b32 s81, v244, 15
	s_nop 0
	v_addc_co_u32_e32 v9, vcc, 0, v5, vcc
	global_load_dword v29, v[8:9], off nt
	v_add_co_u32_e32 v8, vcc, s49, v4
	s_nop 1
	v_addc_co_u32_e32 v9, vcc, 0, v5, vcc
	global_load_dword v30, v[8:9], off nt
	v_add_co_u32_e32 v8, vcc, s50, v4
	s_nop 1
	v_addc_co_u32_e32 v9, vcc, 0, v5, vcc
	global_load_dword v31, v[8:9], off nt
	v_add_co_u32_e32 v8, vcc, s51, v4
	s_nop 1
	v_addc_co_u32_e32 v9, vcc, 0, v5, vcc
	global_load_dword v32, v[8:9], off nt
	v_add_co_u32_e32 v8, vcc, s52, v4
	s_nop 1
	v_addc_co_u32_e32 v9, vcc, 0, v5, vcc
	global_load_dword v33, v[8:9], off nt
	v_add_co_u32_e32 v8, vcc, s53, v4
	s_nop 1
	v_addc_co_u32_e32 v9, vcc, 0, v5, vcc
	global_load_dword v34, v[8:9], off nt
	v_add_co_u32_e32 v8, vcc, s54, v4
	s_nop 1
	v_addc_co_u32_e32 v9, vcc, 0, v5, vcc
	global_load_dword v35, v[8:9], off nt
	v_add_co_u32_e32 v8, vcc, s55, v4
	s_nop 1
	v_addc_co_u32_e32 v9, vcc, 0, v5, vcc
	global_load_dword v36, v[8:9], off nt
	v_add_co_u32_e32 v8, vcc, s56, v4
	s_nop 1
	v_addc_co_u32_e32 v9, vcc, 0, v5, vcc
	global_load_dword v37, v[8:9], off nt
	v_add_co_u32_e32 v8, vcc, s57, v4
	s_nop 1
	v_addc_co_u32_e32 v9, vcc, 0, v5, vcc
	global_load_dword v38, v[8:9], off nt
	v_add_co_u32_e32 v8, vcc, s58, v4
	s_nop 1
	v_addc_co_u32_e32 v9, vcc, 0, v5, vcc
	global_load_dword v39, v[8:9], off nt
	v_add_co_u32_e32 v8, vcc, s59, v4
	s_nop 1
	v_addc_co_u32_e32 v9, vcc, 0, v5, vcc
	global_load_dword v40, v[8:9], off nt
	v_add_co_u32_e32 v8, vcc, s60, v4
	s_nop 1
	v_addc_co_u32_e32 v9, vcc, 0, v5, vcc
	v_add_co_u32_e32 v4, vcc, s61, v4
	global_load_dword v8, v[8:9], off nt
	s_nop 0
	v_addc_co_u32_e32 v5, vcc, 0, v5, vcc
	global_load_dword v4, v[4:5], off nt
	v_mul_lo_u32 v5, v10, s62
	v_add3_u32 v2, s10, v2, v5
	v_add_u32_e32 v5, 0x400, v2
	s_waitcnt vmcnt(0)
; #define GAS __attribute__((address_space(1)))
; #define LAS __attribute__((address_space(3)))
; #define LDS_WAIT() asm volatile("s_waitcnt lgkmcnt(0)" ::: "memory")
; __device__ __forceinline__ unsigned pk2(float lo, float hi) { return f2bf(lo) | (f2bf(hi) << 16); }
;     ...
;       for (int i = 0; i < 32; ++i) scr[(2 * i + (lane >> 5)) * 33 + (lane & 31)] = wv[i]; }
;     LDS_WAIT(); asm volatile("" ::: "memory");
;     const int c = lane & 7;
;     const int r0 = (mode == 0) ? n0 : (256 * (n0 >> 7) + (n0 & 127) + (mode == 2 ? 128 : 0));
; #pragma unroll
;     for (int j = 0; j < 4; ++j) { const int n = (lane >> 3) + 8 * j; const LAS float* s = scr + (8 * c) * 33 + n;
;         v4u o; o.x = pk2(s[0 * 33], s[1 * 33]); o.y = pk2(s[2 * 33], s[3 * 33]); o.z = pk2(s[4 * 33], s[5 * 33]); o.w = pk2(s[6 * 33], s[7 * 33]);
;         *(GAS v4u*)(WT + (size_t)(r0 + n) * ldt + k0 + 8 * c) = o; }
;     LDS_WAIT(); asm volatile("" ::: "memory");
	ds_write2_b32 v2, v11, v12 offset1:66
	ds_write2_b32 v2, v13, v14 offset0:132 offset1:198
	ds_write2_b32 v5, v15, v16 offset0:8 offset1:74
	ds_write2_b32 v5, v17, v18 offset0:140 offset1:206
	v_add_u32_e32 v5, 0x800, v2
	ds_write2_b32 v5, v19, v20 offset0:16 offset1:82
	ds_write2_b32 v5, v21, v22 offset0:148 offset1:214
	v_add_u32_e32 v5, 0xc00, v2
	ds_write2_b32 v5, v23, v24 offset0:24 offset1:90
	ds_write2_b32 v5, v25, v26 offset0:156 offset1:222
	v_add_u32_e32 v5, 0x1000, v2
	ds_write2_b32 v5, v27, v28 offset0:32 offset1:98
	ds_write2_b32 v5, v29, v30 offset0:164 offset1:230
	v_add_u32_e32 v5, 0x1400, v2
	ds_write2_b32 v5, v31, v32 offset0:40 offset1:106
	ds_write2_b32 v5, v33, v34 offset0:172 offset1:238
	v_add_u32_e32 v5, 0x1800, v2
	v_add_u32_e32 v2, 0x1c00, v2
	ds_write2_b32 v5, v35, v36 offset0:48 offset1:114
	ds_write2_b32 v5, v37, v38 offset0:180 offset1:246
	ds_write2_b32 v2, v39, v40 offset0:56 offset1:122
	ds_write2_b32 v2, v8, v4 offset0:188 offset1:254
	v_lshlrev_b32_e32 v2, 3, v7
	v_and_b32_e32 v2, 56, v2
	v_ashrrev_i32_e32 v28, 3, v7
	v_mul_u32_u24_e32 v7, 0x84, v2
	v_lshlrev_b32_e32 v2, 1, v2
	s_waitcnt lgkmcnt(0)
	v_lshl_add_u64 v[4:5], s[44:45], 0, v[2:3]
	v_lshlrev_b32_e32 v2, 2, v28
	v_add3_u32 v2, s10, v7, v2
	ds_read2_b32 v[12:13], v2 offset0:33 offset1:41
	ds_read2_b32 v[14:15], v2 offset1:8
	ds_read2_b32 v[16:17], v2 offset0:66 offset1:74
	ds_read2_b32 v[18:19], v2 offset0:99 offset1:107
	ds_read2_b32 v[20:21], v2 offset0:132 offset1:140
	ds_read2_b32 v[22:23], v2 offset0:165 offset1:173
	ds_read2_b32 v[24:25], v2 offset0:198 offset1:206
	ds_read2_b32 v[26:27], v2 offset0:231 offset1:239
	s_waitcnt lgkmcnt(7)
	v_bfe_u32 v8, v12, 16, 1
	s_waitcnt lgkmcnt(6)
	v_bfe_u32 v7, v14, 16, 1
	v_add3_u32 v7, v14, v7, s63
	v_lshrrev_b32_e32 v7, 16, v7
	v_add3_u32 v8, v12, v8, s63
	v_and_or_b32 v8, v8, s64, v7
	s_waitcnt lgkmcnt(5)
	v_bfe_u32 v7, v16, 16, 1
	v_add3_u32 v7, v16, v7, s63
	s_waitcnt lgkmcnt(4)
	v_bfe_u32 v9, v18, 16, 1
	v_lshrrev_b32_e32 v7, 16, v7
	v_add3_u32 v9, v18, v9, s63
	v_and_or_b32 v9, v9, s64, v7
	s_waitcnt lgkmcnt(3)
	v_bfe_u32 v7, v20, 16, 1
	v_add3_u32 v7, v20, v7, s63
	s_waitcnt lgkmcnt(2)
	v_bfe_u32 v10, v22, 16, 1
	v_lshrrev_b32_e32 v7, 16, v7
	v_add3_u32 v10, v22, v10, s63
	v_and_or_b32 v10, v10, s64, v7
	s_waitcnt lgkmcnt(1)
	v_bfe_u32 v7, v24, 16, 1
	v_add3_u32 v7, v24, v7, s63
	s_waitcnt lgkmcnt(0)
	v_bfe_u32 v11, v26, 16, 1
	v_lshrrev_b32_e32 v7, 16, v7
	v_add3_u32 v11, v26, v11, s63
	v_and_or_b32 v11, v11, s64, v7
	v_add_u32_e32 v7, s4, v28
	v_mad_i64_i32 v[28:29], s[4:5], v7, s65, v[4:5]
	global_store_dwordx4 v[28:29], v[8:11], off
	v_bfe_u32 v12, v27, 16, 1
	v_add3_u32 v12, v27, v12, s63
	v_bfe_u32 v8, v15, 16, 1
	v_add3_u32 v8, v15, v8, s63
	v_bfe_u32 v9, v13, 16, 1
	v_lshrrev_b32_e32 v8, 16, v8
	v_add3_u32 v9, v13, v9, s63
	v_and_or_b32 v8, v9, s64, v8
	v_bfe_u32 v9, v17, 16, 1
	v_add3_u32 v9, v17, v9, s63
	v_bfe_u32 v10, v19, 16, 1
	v_lshrrev_b32_e32 v9, 16, v9
	v_add3_u32 v10, v19, v10, s63
	v_and_or_b32 v9, v10, s64, v9
	v_bfe_u32 v10, v21, 16, 1
	v_add3_u32 v10, v21, v10, s63
	v_bfe_u32 v11, v23, 16, 1
	v_lshrrev_b32_e32 v10, 16, v10
	v_add3_u32 v11, v23, v11, s63
	v_and_or_b32 v10, v11, s64, v10
	v_bfe_u32 v11, v25, 16, 1
	v_add3_u32 v11, v25, v11, s63
	v_lshrrev_b32_e32 v11, 16, v11
	v_and_or_b32 v11, v12, s64, v11
	v_add_u32_e32 v12, 8, v7
	v_mad_i64_i32 v[12:13], s[4:5], v12, s65, v[4:5]
	global_store_dwordx4 v[12:13], v[8:11], off
	ds_read2_b32 v[12:13], v2 offset0:49 offset1:57
	ds_read2_b32 v[14:15], v2 offset0:16 offset1:24
	ds_read2_b32 v[16:17], v2 offset0:82 offset1:90
	ds_read2_b32 v[18:19], v2 offset0:115 offset1:123
	ds_read2_b32 v[20:21], v2 offset0:148 offset1:156
	ds_read2_b32 v[22:23], v2 offset0:181 offset1:189
	ds_read2_b32 v[24:25], v2 offset0:214 offset1:222
	ds_read2_b32 v[26:27], v2 offset0:247 offset1:255
	s_waitcnt lgkmcnt(7)
	v_bfe_u32 v9, v12, 16, 1
	s_waitcnt lgkmcnt(6)
	v_bfe_u32 v8, v14, 16, 1
	v_add3_u32 v8, v14, v8, s63
	v_lshrrev_b32_e32 v8, 16, v8
	v_add3_u32 v9, v12, v9, s63
	v_and_or_b32 v8, v9, s64, v8
	s_waitcnt lgkmcnt(5)
	v_bfe_u32 v9, v16, 16, 1
	v_add3_u32 v9, v16, v9, s63
	s_waitcnt lgkmcnt(4)
	v_bfe_u32 v10, v18, 16, 1
	v_lshrrev_b32_e32 v9, 16, v9
	v_add3_u32 v10, v18, v10, s63
	v_and_or_b32 v9, v10, s64, v9
	s_waitcnt lgkmcnt(3)
	v_bfe_u32 v10, v20, 16, 1
	v_add3_u32 v10, v20, v10, s63
	s_waitcnt lgkmcnt(2)
	v_bfe_u32 v11, v22, 16, 1
	v_lshrrev_b32_e32 v10, 16, v10
	v_add3_u32 v11, v22, v11, s63
	s_waitcnt lgkmcnt(1)
	v_bfe_u32 v2, v24, 16, 1
	v_and_or_b32 v10, v11, s64, v10
	v_add3_u32 v2, v24, v2, s63
	s_waitcnt lgkmcnt(0)
	v_bfe_u32 v11, v26, 16, 1
	v_lshrrev_b32_e32 v2, 16, v2
	v_add3_u32 v11, v26, v11, s63
	v_and_or_b32 v11, v11, s64, v2
	v_add_u32_e32 v2, 16, v7
	v_mad_i64_i32 v[28:29], s[4:5], v2, s65, v[4:5]
	v_bfe_u32 v2, v15, 16, 1
	global_store_dwordx4 v[28:29], v[8:11], off
	v_add3_u32 v2, v15, v2, s63
	v_lshrrev_b32_e32 v2, 16, v2
	v_bfe_u32 v8, v13, 16, 1
	v_add3_u32 v8, v13, v8, s63
	v_and_or_b32 v8, v8, s64, v2
	v_bfe_u32 v2, v17, 16, 1
	v_add3_u32 v2, v17, v2, s63
	v_bfe_u32 v9, v19, 16, 1
	v_lshrrev_b32_e32 v2, 16, v2
	v_add3_u32 v9, v19, v9, s63
	v_and_or_b32 v9, v9, s64, v2
	v_bfe_u32 v2, v21, 16, 1
	v_add3_u32 v2, v21, v2, s63
	v_bfe_u32 v10, v23, 16, 1
	v_lshrrev_b32_e32 v2, 16, v2
	v_add3_u32 v10, v23, v10, s63
	v_and_or_b32 v10, v10, s64, v2
	v_bfe_u32 v2, v25, 16, 1
	v_add3_u32 v2, v25, v2, s63
	v_bfe_u32 v11, v27, 16, 1
	v_lshrrev_b32_e32 v2, 16, v2
	v_add3_u32 v11, v27, v11, s63
	v_and_or_b32 v11, v11, s64, v2
	v_add_u32_e32 v2, 24, v7
	v_mad_i64_i32 v[4:5], s[4:5], v2, s65, v[4:5]
	global_store_dwordx4 v[4:5], v[8:11], off
	s_waitcnt lgkmcnt(0)
	s_mov_b64 s[4:5], 0

; #define GAS __attribute__((address_space(1)))
; #define LAS __attribute__((address_space(3)))
; #define LDS_WAIT() asm volatile("s_waitcnt lgkmcnt(0)" ::: "memory")
; __device__ __forceinline__ unsigned pk2(float lo, float hi) { return f2bf(lo) | (f2bf(hi) << 16); }
;     ...
;     const int kb = item / nblk, nb = item % nblk, k0 = 64 * kb, n0 = 32 * nb;
;     { float wv[32];
;       const float* wp = W + (size_t)(k0 + (lane >> 5)) * ldw + n0 + (lane & 31);
; #pragma unroll
;       for (int i = 0; i < 32; ++i) wv[i] = wp[(size_t)(2 * i) * ldw];
; #pragma unroll
;       for (int i = 0; i < 32; ++i) scr[(2 * i + (lane >> 5)) * 33 + (lane & 31)] = wv[i]; }
;     LDS_WAIT(); asm volatile("" ::: "memory");
;     const int c = lane & 7;
;     const int r0 = (mode == 0) ? n0 : (256 * (n0 >> 7) + (n0 & 127) + (mode == 2 ? 128 : 0));
; #pragma unroll
;     for (int j = 0; j < 4; ++j) { const int n = (lane >> 3) + 8 * j; const LAS float* s = scr + (8 * c) * 33 + n;
;         v4u o; o.x = pk2(s[0 * 33], s[1 * 33]); o.y = pk2(s[2 * 33], s[3 * 33]); o.z = pk2(s[4 * 33], s[5 * 33]); o.w = pk2(s[6 * 33], s[7 * 33]);
;         *(GAS v4u*)(WT + (size_t)(r0 + n) * ldt + k0 + 8 * c) = o; }
;     LDS_WAIT(); asm volatile("" ::: "memory");
; __device__ __forceinline__ void transpose_late(const Args& a, Frame& F, LAS float* scr, int r) {
;     ...
;     if (r < IT_PU) { p0_transpose_item(a.in[I_WPU], D, DPLE, WPU, 0, D / 32, scr, r, F.lane); return; } r -= IT_PU;
.LBB0_1576:
	s_andn2_b64 vcc, exec, s[4:5]
	s_cbranch_vccnz .LBB0_1578
	v_mov_b32_e32 v7, v6
	s_and_b32 s5, s67, 0xc0
	v_ashrrev_i32_e32 v10, 5, v7
	v_add_u32_e32 v4, s5, v10
	v_ashrrev_i32_e32 v5, 31, v4
	v_readlane_b32 s72, v245, 0
	s_and_b32 s4, s24, 0x7e0
	v_lshlrev_b64 v[4:5], 13, v[4:5]
	v_readlane_b32 s78, v245, 6
	v_readlane_b32 s79, v245, 7
	s_lshl_b32 s0, s4, 2
	v_lshlrev_b32_e32 v2, 2, v7
	v_lshl_add_u64 v[4:5], s[78:79], 0, v[4:5]
	v_lshl_add_u64 v[4:5], v[4:5], 0, s[0:1]
	v_and_b32_e32 v2, 0x7c, v2
	v_lshl_add_u64 v[4:5], v[4:5], 0, v[2:3]
	v_add_co_u32_e32 v8, vcc, s25, v4
	global_load_dword v11, v[4:5], off nt
	s_nop 0
	v_addc_co_u32_e32 v9, vcc, 0, v5, vcc
	global_load_dword v12, v[8:9], off nt
	v_add_co_u32_e32 v8, vcc, s26, v4
	s_lshl_b32 s0, s5, 1
	s_nop 0
	v_addc_co_u32_e32 v9, vcc, 0, v5, vcc
	global_load_dword v13, v[8:9], off nt
	v_add_co_u32_e32 v8, vcc, s27, v4
	s_add_u32 s44, s15, s0
	s_nop 0
	v_addc_co_u32_e32 v9, vcc, 0, v5, vcc
	global_load_dword v14, v[8:9], off nt
	v_add_co_u32_e32 v8, vcc, s28, v4
	s_addc_u32 s45, s16, 0
	s_nop 0
	v_addc_co_u32_e32 v9, vcc, 0, v5, vcc
	global_load_dword v15, v[8:9], off nt
	v_add_co_u32_e32 v8, vcc, s29, v4
	v_readlane_b32 s82, v245, 42
	s_nop 0
	v_addc_co_u32_e32 v9, vcc, 0, v5, vcc
	global_load_dword v16, v[8:9], off nt
	v_add_co_u32_e32 v8, vcc, s31, v4
	v_readlane_b32 s83, v245, 43
	s_nop 0
	v_addc_co_u32_e32 v9, vcc, 0, v5, vcc
	global_load_dword v17, v[8:9], off nt
	v_add_co_u32_e32 v8, vcc, s33, v4
	v_readlane_b32 s73, v245, 1
	s_nop 0
	v_addc_co_u32_e32 v9, vcc, 0, v5, vcc
	global_load_dword v18, v[8:9], off nt
	v_add_co_u32_e32 v8, vcc, s36, v4
	v_readlane_b32 s74, v245, 2
	s_nop 0
	v_addc_co_u32_e32 v9, vcc, 0, v5, vcc
	global_load_dword v19, v[8:9], off nt
	v_add_co_u32_e32 v8, vcc, s37, v4
	v_readlane_b32 s75, v245, 3
	s_nop 0
	v_addc_co_u32_e32 v9, vcc, 0, v5, vcc
	global_load_dword v20, v[8:9], off nt
	v_add_co_u32_e32 v8, vcc, s38, v4
	v_readlane_b32 s76, v245, 4
	s_nop 0
	v_addc_co_u32_e32 v9, vcc, 0, v5, vcc
	global_load_dword v21, v[8:9], off nt
	v_add_co_u32_e32 v8, vcc, s39, v4
	v_readlane_b32 s77, v245, 5
	s_nop 0
	v_addc_co_u32_e32 v9, vcc, 0, v5, vcc
	global_load_dword v22, v[8:9], off nt
	v_add_co_u32_e32 v8, vcc, s40, v4
	s_nop 1
	v_addc_co_u32_e32 v9, vcc, 0, v5, vcc
	global_load_dword v23, v[8:9], off nt
	v_add_co_u32_e32 v8, vcc, s41, v4
	s_nop 1
	v_addc_co_u32_e32 v9, vcc, 0, v5, vcc
	global_load_dword v24, v[8:9], off nt
	v_add_co_u32_e32 v8, vcc, s42, v4
	s_nop 1
	v_addc_co_u32_e32 v9, vcc, 0, v5, vcc
	global_load_dword v25, v[8:9], off nt
	v_add_co_u32_e32 v8, vcc, s43, v4
	s_nop 1
	v_addc_co_u32_e32 v9, vcc, 0, v5, vcc
	global_load_dword v26, v[8:9], off nt
	v_add_co_u32_e32 v8, vcc, s46, v4
	s_nop 1
	v_addc_co_u32_e32 v9, vcc, 0, v5, vcc
	global_load_dword v27, v[8:9], off nt
	v_add_co_u32_e32 v8, vcc, s47, v4
	s_nop 1
	v_addc_co_u32_e32 v9, vcc, 0, v5, vcc
	global_load_dword v28, v[8:9], off nt
	v_add_co_u32_e32 v8, vcc, s48, v4
	s_nop 1
	v_addc_co_u32_e32 v9, vcc, 0, v5, vcc
	global_load_dword v29, v[8:9], off nt
	v_add_co_u32_e32 v8, vcc, s49, v4
	s_nop 1
	v_addc_co_u32_e32 v9, vcc, 0, v5, vcc
	global_load_dword v30, v[8:9], off nt
	v_add_co_u32_e32 v8, vcc, s50, v4
	s_nop 1
	v_addc_co_u32_e32 v9, vcc, 0, v5, vcc
	global_load_dword v31, v[8:9], off nt
	v_add_co_u32_e32 v8, vcc, s51, v4
	s_nop 1
	v_addc_co_u32_e32 v9, vcc, 0, v5, vcc
	global_load_dword v32, v[8:9], off nt
	v_add_co_u32_e32 v8, vcc, s52, v4
	s_nop 1
	v_addc_co_u32_e32 v9, vcc, 0, v5, vcc
	global_load_dword v33, v[8:9], off nt
	v_add_co_u32_e32 v8, vcc, s53, v4
	s_nop 1
	v_addc_co_u32_e32 v9, vcc, 0, v5, vcc
	global_load_dword v34, v[8:9], off nt
	v_add_co_u32_e32 v8, vcc, s54, v4
	s_nop 1
	v_addc_co_u32_e32 v9, vcc, 0, v5, vcc
	global_load_dword v35, v[8:9], off nt
	v_add_co_u32_e32 v8, vcc, s55, v4
	s_nop 1
	v_addc_co_u32_e32 v9, vcc, 0, v5, vcc
	global_load_dword v36, v[8:9], off nt
	v_add_co_u32_e32 v8, vcc, s56, v4
	s_nop 1
	v_addc_co_u32_e32 v9, vcc, 0, v5, vcc
	global_load_dword v37, v[8:9], off nt
	v_add_co_u32_e32 v8, vcc, s57, v4
	s_nop 1
	v_addc_co_u32_e32 v9, vcc, 0, v5, vcc
	global_load_dword v38, v[8:9], off nt
	v_add_co_u32_e32 v8, vcc, s58, v4
	s_nop 1
	v_addc_co_u32_e32 v9, vcc, 0, v5, vcc
	global_load_dword v39, v[8:9], off nt
	v_add_co_u32_e32 v8, vcc, s59, v4
	s_nop 1
	v_addc_co_u32_e32 v9, vcc, 0, v5, vcc
	global_load_dword v40, v[8:9], off nt
	v_add_co_u32_e32 v8, vcc, s60, v4
	s_nop 1
	v_addc_co_u32_e32 v9, vcc, 0, v5, vcc
	v_add_co_u32_e32 v4, vcc, s61, v4
	global_load_dword v8, v[8:9], off nt
	s_nop 0
	v_addc_co_u32_e32 v5, vcc, 0, v5, vcc
	global_load_dword v4, v[4:5], off nt
	v_mul_lo_u32 v5, v10, s62
	v_add3_u32 v2, s10, v2, v5
	v_add_u32_e32 v5, 0x400, v2
	s_waitcnt vmcnt(0)
	ds_write2_b32 v2, v11, v12 offset1:66
	ds_write2_b32 v2, v13, v14 offset0:132 offset1:198
	ds_write2_b32 v5, v15, v16 offset0:8 offset1:74
	ds_write2_b32 v5, v17, v18 offset0:140 offset1:206
	v_add_u32_e32 v5, 0x800, v2
	ds_write2_b32 v5, v19, v20 offset0:16 offset1:82
	ds_write2_b32 v5, v21, v22 offset0:148 offset1:214
	v_add_u32_e32 v5, 0xc00, v2
	ds_write2_b32 v5, v23, v24 offset0:24 offset1:90
	ds_write2_b32 v5, v25, v26 offset0:156 offset1:222
	v_add_u32_e32 v5, 0x1000, v2
	ds_write2_b32 v5, v27, v28 offset0:32 offset1:98
	ds_write2_b32 v5, v29, v30 offset0:164 offset1:230
	v_add_u32_e32 v5, 0x1400, v2
	ds_write2_b32 v5, v31, v32 offset0:40 offset1:106
	ds_write2_b32 v5, v33, v34 offset0:172 offset1:238
	v_add_u32_e32 v5, 0x1800, v2
	v_add_u32_e32 v2, 0x1c00, v2
	ds_write2_b32 v5, v35, v36 offset0:48 offset1:114
	ds_write2_b32 v5, v37, v38 offset0:180 offset1:246
	ds_write2_b32 v2, v39, v40 offset0:56 offset1:122
	ds_write2_b32 v2, v8, v4 offset0:188 offset1:254
	v_lshlrev_b32_e32 v2, 3, v7
	v_and_b32_e32 v2, 56, v2
	v_ashrrev_i32_e32 v28, 3, v7
	v_mul_u32_u24_e32 v7, 0x84, v2
	v_lshlrev_b32_e32 v2, 1, v2
	s_waitcnt lgkmcnt(0)
; #define GAS __attribute__((address_space(1)))
; #define LAS __attribute__((address_space(3)))
; #define LDS_WAIT() asm volatile("s_waitcnt lgkmcnt(0)" ::: "memory")
; __device__ __forceinline__ unsigned pk2(float lo, float hi) { return f2bf(lo) | (f2bf(hi) << 16); }
;     ...
;     const int r0 = (mode == 0) ? n0 : (256 * (n0 >> 7) + (n0 & 127) + (mode == 2 ? 128 : 0));
; #pragma unroll
;     for (int j = 0; j < 4; ++j) { const int n = (lane >> 3) + 8 * j; const LAS float* s = scr + (8 * c) * 33 + n;
;         v4u o; o.x = pk2(s[0 * 33], s[1 * 33]); o.y = pk2(s[2 * 33], s[3 * 33]); o.z = pk2(s[4 * 33], s[5 * 33]); o.w = pk2(s[6 * 33], s[7 * 33]);
;         *(GAS v4u*)(WT + (size_t)(r0 + n) * ldt + k0 + 8 * c) = o; }
;     LDS_WAIT(); asm volatile("" ::: "memory");
	v_lshl_add_u64 v[4:5], s[44:45], 0, v[2:3]
	v_lshlrev_b32_e32 v2, 2, v28
	v_add3_u32 v2, s10, v7, v2
	ds_read2_b32 v[12:13], v2 offset0:33 offset1:41
	ds_read2_b32 v[14:15], v2 offset1:8
	ds_read2_b32 v[16:17], v2 offset0:66 offset1:74
	ds_read2_b32 v[18:19], v2 offset0:99 offset1:107
	ds_read2_b32 v[20:21], v2 offset0:132 offset1:140
	ds_read2_b32 v[22:23], v2 offset0:165 offset1:173
	ds_read2_b32 v[24:25], v2 offset0:198 offset1:206
	ds_read2_b32 v[26:27], v2 offset0:231 offset1:239
	s_waitcnt lgkmcnt(7)
	v_bfe_u32 v8, v12, 16, 1
	s_waitcnt lgkmcnt(6)
	v_bfe_u32 v7, v14, 16, 1
	v_add3_u32 v7, v14, v7, s63
	v_lshrrev_b32_e32 v7, 16, v7
	v_add3_u32 v8, v12, v8, s63
	v_and_or_b32 v8, v8, s64, v7
	s_waitcnt lgkmcnt(5)
	v_bfe_u32 v7, v16, 16, 1
	v_add3_u32 v7, v16, v7, s63
	s_waitcnt lgkmcnt(4)
	v_bfe_u32 v9, v18, 16, 1
	v_lshrrev_b32_e32 v7, 16, v7
	v_add3_u32 v9, v18, v9, s63
	v_and_or_b32 v9, v9, s64, v7
	s_waitcnt lgkmcnt(3)
	v_bfe_u32 v7, v20, 16, 1
	v_add3_u32 v7, v20, v7, s63
	s_waitcnt lgkmcnt(2)
	v_bfe_u32 v10, v22, 16, 1
	v_lshrrev_b32_e32 v7, 16, v7
	v_add3_u32 v10, v22, v10, s63
	v_and_or_b32 v10, v10, s64, v7
	s_waitcnt lgkmcnt(1)
	v_bfe_u32 v7, v24, 16, 1
	v_add_u32_e32 v28, s4, v28
	v_add3_u32 v7, v24, v7, s63
	s_waitcnt lgkmcnt(0)
	v_bfe_u32 v11, v26, 16, 1
	v_ashrrev_i32_e32 v29, 31, v28
	v_lshrrev_b32_e32 v7, 16, v7
	v_add3_u32 v11, v26, v11, s63
	v_lshlrev_b64 v[30:31], 9, v[28:29]
	v_and_or_b32 v11, v11, s64, v7
	v_lshl_add_u64 v[30:31], v[4:5], 0, v[30:31]
	v_bfe_u32 v7, v15, 16, 1
	global_store_dwordx4 v[30:31], v[8:11], off
	v_add3_u32 v7, v15, v7, s63
	v_lshrrev_b32_e32 v7, 16, v7
	v_bfe_u32 v8, v13, 16, 1
	v_add3_u32 v8, v13, v8, s63
	v_and_or_b32 v8, v8, s64, v7
	v_bfe_u32 v7, v17, 16, 1
	v_add3_u32 v7, v17, v7, s63
	v_bfe_u32 v9, v19, 16, 1
	v_lshrrev_b32_e32 v7, 16, v7
	v_add3_u32 v9, v19, v9, s63
	v_and_or_b32 v9, v9, s64, v7
	v_bfe_u32 v7, v21, 16, 1
	v_add3_u32 v7, v21, v7, s63
	v_bfe_u32 v10, v23, 16, 1
	v_lshrrev_b32_e32 v7, 16, v7
	v_add3_u32 v10, v23, v10, s63
	v_and_or_b32 v10, v10, s64, v7
	v_bfe_u32 v7, v25, 16, 1
	v_add_u32_e32 v12, 8, v28
	v_add3_u32 v7, v25, v7, s63
	v_bfe_u32 v11, v27, 16, 1
	v_ashrrev_i32_e32 v13, 31, v12
	v_lshrrev_b32_e32 v7, 16, v7
	v_add3_u32 v11, v27, v11, s63
	v_lshlrev_b64 v[12:13], 9, v[12:13]
	v_and_or_b32 v11, v11, s64, v7
	v_lshl_add_u64 v[12:13], v[4:5], 0, v[12:13]
	global_store_dwordx4 v[12:13], v[8:11], off
	ds_read2_b32 v[12:13], v2 offset0:49 offset1:57
	ds_read2_b32 v[14:15], v2 offset0:16 offset1:24
	ds_read2_b32 v[16:17], v2 offset0:82 offset1:90
	ds_read2_b32 v[18:19], v2 offset0:115 offset1:123
	ds_read2_b32 v[20:21], v2 offset0:148 offset1:156
	ds_read2_b32 v[22:23], v2 offset0:181 offset1:189
	ds_read2_b32 v[24:25], v2 offset0:214 offset1:222
	ds_read2_b32 v[26:27], v2 offset0:247 offset1:255
	s_waitcnt lgkmcnt(7)
	v_bfe_u32 v8, v12, 16, 1
	s_waitcnt lgkmcnt(6)
	v_bfe_u32 v7, v14, 16, 1
	v_add3_u32 v7, v14, v7, s63
	v_lshrrev_b32_e32 v7, 16, v7
	v_add3_u32 v8, v12, v8, s63
	v_and_or_b32 v8, v8, s64, v7
	s_waitcnt lgkmcnt(5)
	v_bfe_u32 v7, v16, 16, 1
	v_add3_u32 v7, v16, v7, s63
	s_waitcnt lgkmcnt(4)
	v_bfe_u32 v9, v18, 16, 1
	v_lshrrev_b32_e32 v7, 16, v7
	v_add3_u32 v9, v18, v9, s63
	v_and_or_b32 v9, v9, s64, v7
	s_waitcnt lgkmcnt(3)
	v_bfe_u32 v7, v20, 16, 1
	v_add3_u32 v7, v20, v7, s63
	s_waitcnt lgkmcnt(2)
	v_bfe_u32 v10, v22, 16, 1
	v_lshrrev_b32_e32 v7, 16, v7
	v_add3_u32 v10, v22, v10, s63
	s_waitcnt lgkmcnt(1)
	v_bfe_u32 v2, v24, 16, 1
	v_and_or_b32 v10, v10, s64, v7
	v_add3_u32 v2, v24, v2, s63
	s_waitcnt lgkmcnt(0)
	v_bfe_u32 v7, v26, 16, 1
	v_lshrrev_b32_e32 v2, 16, v2
	v_add3_u32 v7, v26, v7, s63
	v_add_u32_e32 v30, 16, v28
	v_and_or_b32 v11, v7, s64, v2
	v_ashrrev_i32_e32 v31, 31, v30
	v_bfe_u32 v2, v15, 16, 1
	v_lshlrev_b64 v[30:31], 9, v[30:31]
	v_add3_u32 v2, v15, v2, s63
	v_bfe_u32 v7, v13, 16, 1
	v_lshl_add_u64 v[30:31], v[4:5], 0, v[30:31]
	v_lshrrev_b32_e32 v2, 16, v2
	v_add3_u32 v7, v13, v7, s63
	global_store_dwordx4 v[30:31], v[8:11], off
	v_add_u32_e32 v12, 24, v28
	v_ashrrev_i32_e32 v13, 31, v12
	v_and_or_b32 v8, v7, s64, v2
	v_bfe_u32 v2, v17, 16, 1
	v_add3_u32 v2, v17, v2, s63
	v_bfe_u32 v7, v19, 16, 1
	v_lshrrev_b32_e32 v2, 16, v2
	v_add3_u32 v7, v19, v7, s63
	v_and_or_b32 v9, v7, s64, v2
	v_bfe_u32 v2, v21, 16, 1
	v_add3_u32 v2, v21, v2, s63
	v_bfe_u32 v7, v23, 16, 1
	v_lshrrev_b32_e32 v2, 16, v2
	v_add3_u32 v7, v23, v7, s63
	v_and_or_b32 v10, v7, s64, v2
	v_bfe_u32 v2, v25, 16, 1
	v_add3_u32 v2, v25, v2, s63
	v_bfe_u32 v7, v27, 16, 1
	v_lshrrev_b32_e32 v2, 16, v2
	v_add3_u32 v7, v27, v7, s63
	v_lshlrev_b64 v[12:13], 9, v[12:13]
	v_and_or_b32 v11, v7, s64, v2
	v_lshl_add_u64 v[4:5], v[4:5], 0, v[12:13]
	global_store_dwordx4 v[4:5], v[8:11], off
	s_waitcnt lgkmcnt(0)

; #define GAS __attribute__((address_space(1)))
; #define LAS __attribute__((address_space(3)))
; #define LDS_WAIT() asm volatile("s_waitcnt lgkmcnt(0)" ::: "memory")
; __device__ __forceinline__ unsigned pk2(float lo, float hi) { return f2bf(lo) | (f2bf(hi) << 16); }
;     ...
;     const int kb = item / nblk, nb = item % nblk, k0 = 64 * kb, n0 = 32 * nb;
;     { float wv[32];
;       const float* wp = W + (size_t)(k0 + (lane >> 5)) * ldw + n0 + (lane & 31);
; #pragma unroll
;       for (int i = 0; i < 32; ++i) wv[i] = wp[(size_t)(2 * i) * ldw];
; #pragma unroll
;       for (int i = 0; i < 32; ++i) scr[(2 * i + (lane >> 5)) * 33 + (lane & 31)] = wv[i]; }
;     LDS_WAIT(); asm volatile("" ::: "memory");
;     const int c = lane & 7;
;     const int r0 = (mode == 0) ? n0 : (256 * (n0 >> 7) + (n0 & 127) + (mode == 2 ? 128 : 0));
; #pragma unroll
;     for (int j = 0; j < 4; ++j) { const int n = (lane >> 3) + 8 * j; const LAS float* s = scr + (8 * c) * 33 + n;
;         v4u o; o.x = pk2(s[0 * 33], s[1 * 33]); o.y = pk2(s[2 * 33], s[3 * 33]); o.z = pk2(s[4 * 33], s[5 * 33]); o.w = pk2(s[6 * 33], s[7 * 33]);
;         *(GAS v4u*)(WT + (size_t)(r0 + n) * ldt + k0 + 8 * c) = o; }
;     LDS_WAIT(); asm volatile("" ::: "memory");
; __device__ __forceinline__ void transpose_late(const Args& a, Frame& F, LAS float* scr, int r) {
;     ...
;     if (r < IT_SQ) { p0_transpose_item(a.in[I_WPG], D, D, WPG, 0, D / 32, scr, r, F.lane); return; } r -= IT_SQ;
.LBB0_1579:
	s_andn2_b64 vcc, exec, s[4:5]
	s_cbranch_vccnz .LBB0_1581
	v_mov_b32_e32 v7, v6
	s_and_b32 s5, s23, 0xffc0
	v_ashrrev_i32_e32 v10, 5, v7
	v_add_u32_e32 v4, s5, v10
	v_ashrrev_i32_e32 v5, 31, v4
	v_readlane_b32 s72, v245, 0
	s_and_b32 s4, s24, 0x7e0
	v_lshlrev_b64 v[4:5], 13, v[4:5]
	v_readlane_b32 s76, v245, 4
	v_readlane_b32 s77, v245, 5
	s_lshl_b32 s0, s4, 2
	v_lshlrev_b32_e32 v2, 2, v7
	v_lshl_add_u64 v[4:5], s[76:77], 0, v[4:5]
	v_lshl_add_u64 v[4:5], v[4:5], 0, s[0:1]
	v_and_b32_e32 v2, 0x7c, v2
	v_lshl_add_u64 v[4:5], v[4:5], 0, v[2:3]
	v_add_co_u32_e32 v8, vcc, s25, v4
	global_load_dword v11, v[4:5], off nt
	s_nop 0
	v_addc_co_u32_e32 v9, vcc, 0, v5, vcc
	global_load_dword v12, v[8:9], off nt
	v_add_co_u32_e32 v8, vcc, s26, v4
	s_lshl_b32 s0, s5, 1
	s_nop 0
	v_addc_co_u32_e32 v9, vcc, 0, v5, vcc
	global_load_dword v13, v[8:9], off nt
	v_add_co_u32_e32 v8, vcc, s27, v4
	s_add_u32 s44, s13, s0
	s_nop 0
	v_addc_co_u32_e32 v9, vcc, 0, v5, vcc
	global_load_dword v14, v[8:9], off nt
	v_add_co_u32_e32 v8, vcc, s28, v4
	s_addc_u32 s45, s14, 0
	s_nop 0
	v_addc_co_u32_e32 v9, vcc, 0, v5, vcc
	global_load_dword v15, v[8:9], off nt
	v_add_co_u32_e32 v8, vcc, s29, v4
	v_readlane_b32 s82, v245, 42
	s_nop 0
	v_addc_co_u32_e32 v9, vcc, 0, v5, vcc
	global_load_dword v16, v[8:9], off nt
	v_add_co_u32_e32 v8, vcc, s31, v4
	v_readlane_b32 s83, v245, 43
	s_nop 0
	v_addc_co_u32_e32 v9, vcc, 0, v5, vcc
	global_load_dword v17, v[8:9], off nt
	v_add_co_u32_e32 v8, vcc, s33, v4
	v_readlane_b32 s73, v245, 1
	s_nop 0
	v_addc_co_u32_e32 v9, vcc, 0, v5, vcc
	global_load_dword v18, v[8:9], off nt
	v_add_co_u32_e32 v8, vcc, s36, v4
	v_readlane_b32 s74, v245, 2
	s_nop 0
	v_addc_co_u32_e32 v9, vcc, 0, v5, vcc
	global_load_dword v19, v[8:9], off nt
	v_add_co_u32_e32 v8, vcc, s37, v4
	v_readlane_b32 s75, v245, 3
	s_nop 0
	v_addc_co_u32_e32 v9, vcc, 0, v5, vcc
	global_load_dword v20, v[8:9], off nt
	v_add_co_u32_e32 v8, vcc, s38, v4
	v_readlane_b32 s78, v245, 6
	s_nop 0
	v_addc_co_u32_e32 v9, vcc, 0, v5, vcc
	global_load_dword v21, v[8:9], off nt
	v_add_co_u32_e32 v8, vcc, s39, v4
	v_readlane_b32 s79, v245, 7
	s_nop 0
	v_addc_co_u32_e32 v9, vcc, 0, v5, vcc
	global_load_dword v22, v[8:9], off nt
	v_add_co_u32_e32 v8, vcc, s40, v4
	s_nop 1
	v_addc_co_u32_e32 v9, vcc, 0, v5, vcc
	global_load_dword v23, v[8:9], off nt
	v_add_co_u32_e32 v8, vcc, s41, v4
	s_nop 1
	v_addc_co_u32_e32 v9, vcc, 0, v5, vcc
	global_load_dword v24, v[8:9], off nt
	v_add_co_u32_e32 v8, vcc, s42, v4
	s_nop 1
	v_addc_co_u32_e32 v9, vcc, 0, v5, vcc
	global_load_dword v25, v[8:9], off nt
	v_add_co_u32_e32 v8, vcc, s43, v4
	s_nop 1
	v_addc_co_u32_e32 v9, vcc, 0, v5, vcc
	global_load_dword v26, v[8:9], off nt
	v_add_co_u32_e32 v8, vcc, s46, v4
	s_nop 1
	v_addc_co_u32_e32 v9, vcc, 0, v5, vcc
	global_load_dword v27, v[8:9], off nt
	v_add_co_u32_e32 v8, vcc, s47, v4
	s_nop 1
	v_addc_co_u32_e32 v9, vcc, 0, v5, vcc
	global_load_dword v28, v[8:9], off nt
	v_add_co_u32_e32 v8, vcc, s48, v4
	s_nop 1
	v_addc_co_u32_e32 v9, vcc, 0, v5, vcc
	global_load_dword v29, v[8:9], off nt
	v_add_co_u32_e32 v8, vcc, s49, v4
	s_nop 1
	v_addc_co_u32_e32 v9, vcc, 0, v5, vcc
	global_load_dword v30, v[8:9], off nt
	v_add_co_u32_e32 v8, vcc, s50, v4
	s_nop 1
	v_addc_co_u32_e32 v9, vcc, 0, v5, vcc
	global_load_dword v31, v[8:9], off nt
	v_add_co_u32_e32 v8, vcc, s51, v4
	s_nop 1
	v_addc_co_u32_e32 v9, vcc, 0, v5, vcc
	global_load_dword v32, v[8:9], off nt
	v_add_co_u32_e32 v8, vcc, s52, v4
	s_nop 1
	v_addc_co_u32_e32 v9, vcc, 0, v5, vcc
	global_load_dword v33, v[8:9], off nt
	v_add_co_u32_e32 v8, vcc, s53, v4
	s_nop 1
	v_addc_co_u32_e32 v9, vcc, 0, v5, vcc
	global_load_dword v34, v[8:9], off nt
	v_add_co_u32_e32 v8, vcc, s54, v4
	s_nop 1
	v_addc_co_u32_e32 v9, vcc, 0, v5, vcc
	global_load_dword v35, v[8:9], off nt
	v_add_co_u32_e32 v8, vcc, s55, v4
	s_nop 1
	v_addc_co_u32_e32 v9, vcc, 0, v5, vcc
	global_load_dword v36, v[8:9], off nt
	v_add_co_u32_e32 v8, vcc, s56, v4
	s_nop 1
	v_addc_co_u32_e32 v9, vcc, 0, v5, vcc
	global_load_dword v37, v[8:9], off nt
	v_add_co_u32_e32 v8, vcc, s57, v4
	s_nop 1
	v_addc_co_u32_e32 v9, vcc, 0, v5, vcc
	global_load_dword v38, v[8:9], off nt
	v_add_co_u32_e32 v8, vcc, s58, v4
	s_nop 1
	v_addc_co_u32_e32 v9, vcc, 0, v5, vcc
	global_load_dword v39, v[8:9], off nt
	v_add_co_u32_e32 v8, vcc, s59, v4
	s_nop 1
	v_addc_co_u32_e32 v9, vcc, 0, v5, vcc
	global_load_dword v40, v[8:9], off nt
	v_add_co_u32_e32 v8, vcc, s60, v4
	s_nop 1
	v_addc_co_u32_e32 v9, vcc, 0, v5, vcc
	v_add_co_u32_e32 v4, vcc, s61, v4
	global_load_dword v8, v[8:9], off nt
	s_nop 0
	v_addc_co_u32_e32 v5, vcc, 0, v5, vcc
	global_load_dword v4, v[4:5], off nt
	v_mul_lo_u32 v5, v10, s62
	v_add3_u32 v2, s10, v2, v5
	v_add_u32_e32 v5, 0x400, v2
	s_waitcnt vmcnt(0)
	ds_write2_b32 v2, v11, v12 offset1:66
	ds_write2_b32 v2, v13, v14 offset0:132 offset1:198
	ds_write2_b32 v5, v15, v16 offset0:8 offset1:74
	ds_write2_b32 v5, v17, v18 offset0:140 offset1:206
	v_add_u32_e32 v5, 0x800, v2
	ds_write2_b32 v5, v19, v20 offset0:16 offset1:82
	ds_write2_b32 v5, v21, v22 offset0:148 offset1:214
	v_add_u32_e32 v5, 0xc00, v2
	ds_write2_b32 v5, v23, v24 offset0:24 offset1:90
	ds_write2_b32 v5, v25, v26 offset0:156 offset1:222
	v_add_u32_e32 v5, 0x1000, v2
	ds_write2_b32 v5, v27, v28 offset0:32 offset1:98
	ds_write2_b32 v5, v29, v30 offset0:164 offset1:230
	v_add_u32_e32 v5, 0x1400, v2
	ds_write2_b32 v5, v31, v32 offset0:40 offset1:106
	ds_write2_b32 v5, v33, v34 offset0:172 offset1:238
	v_add_u32_e32 v5, 0x1800, v2
	v_add_u32_e32 v2, 0x1c00, v2
	ds_write2_b32 v5, v35, v36 offset0:48 offset1:114
	ds_write2_b32 v5, v37, v38 offset0:180 offset1:246
	ds_write2_b32 v2, v39, v40 offset0:56 offset1:122
	ds_write2_b32 v2, v8, v4 offset0:188 offset1:254
	v_lshlrev_b32_e32 v2, 3, v7
	v_and_b32_e32 v2, 56, v2
	v_ashrrev_i32_e32 v28, 3, v7
	v_mul_u32_u24_e32 v7, 0x84, v2
	v_lshlrev_b32_e32 v2, 1, v2
	s_waitcnt lgkmcnt(0)
; #define GAS __attribute__((address_space(1)))
; #define LAS __attribute__((address_space(3)))
; #define LDS_WAIT() asm volatile("s_waitcnt lgkmcnt(0)" ::: "memory")
; __device__ __forceinline__ unsigned pk2(float lo, float hi) { return f2bf(lo) | (f2bf(hi) << 16); }
;     ...
;     const int r0 = (mode == 0) ? n0 : (256 * (n0 >> 7) + (n0 & 127) + (mode == 2 ? 128 : 0));
; #pragma unroll
;     for (int j = 0; j < 4; ++j) { const int n = (lane >> 3) + 8 * j; const LAS float* s = scr + (8 * c) * 33 + n;
;         v4u o; o.x = pk2(s[0 * 33], s[1 * 33]); o.y = pk2(s[2 * 33], s[3 * 33]); o.z = pk2(s[4 * 33], s[5 * 33]); o.w = pk2(s[6 * 33], s[7 * 33]);
;         *(GAS v4u*)(WT + (size_t)(r0 + n) * ldt + k0 + 8 * c) = o; }
;     LDS_WAIT(); asm volatile("" ::: "memory");
	v_lshl_add_u64 v[4:5], s[44:45], 0, v[2:3]
	v_lshlrev_b32_e32 v2, 2, v28
	v_add3_u32 v2, s10, v7, v2
	ds_read2_b32 v[12:13], v2 offset0:33 offset1:41
	ds_read2_b32 v[14:15], v2 offset1:8
	ds_read2_b32 v[16:17], v2 offset0:66 offset1:74
	ds_read2_b32 v[18:19], v2 offset0:99 offset1:107
	ds_read2_b32 v[20:21], v2 offset0:132 offset1:140
	ds_read2_b32 v[22:23], v2 offset0:165 offset1:173
	ds_read2_b32 v[24:25], v2 offset0:198 offset1:206
	ds_read2_b32 v[26:27], v2 offset0:231 offset1:239
	s_waitcnt lgkmcnt(7)
	v_bfe_u32 v8, v12, 16, 1
	s_waitcnt lgkmcnt(6)
	v_bfe_u32 v7, v14, 16, 1
	v_add3_u32 v7, v14, v7, s63
	v_lshrrev_b32_e32 v7, 16, v7
	v_add3_u32 v8, v12, v8, s63
	v_and_or_b32 v8, v8, s64, v7
	s_waitcnt lgkmcnt(5)
	v_bfe_u32 v7, v16, 16, 1
	v_add3_u32 v7, v16, v7, s63
	s_waitcnt lgkmcnt(4)
	v_bfe_u32 v9, v18, 16, 1
	v_lshrrev_b32_e32 v7, 16, v7
	v_add3_u32 v9, v18, v9, s63
	v_and_or_b32 v9, v9, s64, v7
	s_waitcnt lgkmcnt(3)
	v_bfe_u32 v7, v20, 16, 1
	v_add3_u32 v7, v20, v7, s63
	s_waitcnt lgkmcnt(2)
	v_bfe_u32 v10, v22, 16, 1
	v_lshrrev_b32_e32 v7, 16, v7
	v_add3_u32 v10, v22, v10, s63
	v_and_or_b32 v10, v10, s64, v7
	s_waitcnt lgkmcnt(1)
	v_bfe_u32 v7, v24, 16, 1
	v_add_u32_e32 v28, s4, v28
	v_add3_u32 v7, v24, v7, s63
	s_waitcnt lgkmcnt(0)
	v_bfe_u32 v11, v26, 16, 1
	v_ashrrev_i32_e32 v29, 31, v28
	v_lshrrev_b32_e32 v7, 16, v7
	v_add3_u32 v11, v26, v11, s63
	v_lshlrev_b64 v[30:31], 12, v[28:29]
	v_and_or_b32 v11, v11, s64, v7
	v_lshl_add_u64 v[30:31], v[4:5], 0, v[30:31]
	v_bfe_u32 v7, v15, 16, 1
	global_store_dwordx4 v[30:31], v[8:11], off
	v_add3_u32 v7, v15, v7, s63
	v_lshrrev_b32_e32 v7, 16, v7
	v_bfe_u32 v8, v13, 16, 1
	v_add3_u32 v8, v13, v8, s63
	v_and_or_b32 v8, v8, s64, v7
	v_bfe_u32 v7, v17, 16, 1
	v_add3_u32 v7, v17, v7, s63
	v_bfe_u32 v9, v19, 16, 1
	v_lshrrev_b32_e32 v7, 16, v7
	v_add3_u32 v9, v19, v9, s63
	v_and_or_b32 v9, v9, s64, v7
	v_bfe_u32 v7, v21, 16, 1
	v_add3_u32 v7, v21, v7, s63
	v_bfe_u32 v10, v23, 16, 1
	v_lshrrev_b32_e32 v7, 16, v7
	v_add3_u32 v10, v23, v10, s63
	v_and_or_b32 v10, v10, s64, v7
	v_bfe_u32 v7, v25, 16, 1
	v_add_u32_e32 v12, 8, v28
	v_add3_u32 v7, v25, v7, s63
	v_bfe_u32 v11, v27, 16, 1
	v_ashrrev_i32_e32 v13, 31, v12
	v_lshrrev_b32_e32 v7, 16, v7
	v_add3_u32 v11, v27, v11, s63
	v_lshlrev_b64 v[12:13], 12, v[12:13]
	v_and_or_b32 v11, v11, s64, v7
	v_lshl_add_u64 v[12:13], v[4:5], 0, v[12:13]
	global_store_dwordx4 v[12:13], v[8:11], off
	ds_read2_b32 v[12:13], v2 offset0:49 offset1:57
	ds_read2_b32 v[14:15], v2 offset0:16 offset1:24
	ds_read2_b32 v[16:17], v2 offset0:82 offset1:90
	ds_read2_b32 v[18:19], v2 offset0:115 offset1:123
	ds_read2_b32 v[20:21], v2 offset0:148 offset1:156
	ds_read2_b32 v[22:23], v2 offset0:181 offset1:189
	ds_read2_b32 v[24:25], v2 offset0:214 offset1:222
	ds_read2_b32 v[26:27], v2 offset0:247 offset1:255
	s_waitcnt lgkmcnt(7)
	v_bfe_u32 v8, v12, 16, 1
	s_waitcnt lgkmcnt(6)
	v_bfe_u32 v7, v14, 16, 1
	v_add3_u32 v7, v14, v7, s63
	v_lshrrev_b32_e32 v7, 16, v7
	v_add3_u32 v8, v12, v8, s63
	v_and_or_b32 v8, v8, s64, v7
	s_waitcnt lgkmcnt(5)
	v_bfe_u32 v7, v16, 16, 1
	v_add3_u32 v7, v16, v7, s63
	s_waitcnt lgkmcnt(4)
	v_bfe_u32 v9, v18, 16, 1
	v_lshrrev_b32_e32 v7, 16, v7
	v_add3_u32 v9, v18, v9, s63
	v_and_or_b32 v9, v9, s64, v7
	s_waitcnt lgkmcnt(3)
	v_bfe_u32 v7, v20, 16, 1
	v_add3_u32 v7, v20, v7, s63
	s_waitcnt lgkmcnt(2)
	v_bfe_u32 v10, v22, 16, 1
	v_lshrrev_b32_e32 v7, 16, v7
	v_add3_u32 v10, v22, v10, s63
	s_waitcnt lgkmcnt(1)
	v_bfe_u32 v2, v24, 16, 1
	v_and_or_b32 v10, v10, s64, v7
	v_add3_u32 v2, v24, v2, s63
	s_waitcnt lgkmcnt(0)
	v_bfe_u32 v7, v26, 16, 1
	v_lshrrev_b32_e32 v2, 16, v2
	v_add3_u32 v7, v26, v7, s63
	v_add_u32_e32 v30, 16, v28
	v_and_or_b32 v11, v7, s64, v2
	v_ashrrev_i32_e32 v31, 31, v30
	v_bfe_u32 v2, v15, 16, 1
	v_lshlrev_b64 v[30:31], 12, v[30:31]
	v_add3_u32 v2, v15, v2, s63
	v_bfe_u32 v7, v13, 16, 1
	v_lshl_add_u64 v[30:31], v[4:5], 0, v[30:31]
	v_lshrrev_b32_e32 v2, 16, v2
	v_add3_u32 v7, v13, v7, s63
	global_store_dwordx4 v[30:31], v[8:11], off
	v_add_u32_e32 v12, 24, v28
	v_ashrrev_i32_e32 v13, 31, v12
	v_and_or_b32 v8, v7, s64, v2
	v_bfe_u32 v2, v17, 16, 1
	v_add3_u32 v2, v17, v2, s63
	v_bfe_u32 v7, v19, 16, 1
	v_lshrrev_b32_e32 v2, 16, v2
	v_add3_u32 v7, v19, v7, s63
	v_and_or_b32 v9, v7, s64, v2
	v_bfe_u32 v2, v21, 16, 1
	v_add3_u32 v2, v21, v2, s63
	v_bfe_u32 v7, v23, 16, 1
	v_lshrrev_b32_e32 v2, 16, v2
	v_add3_u32 v7, v23, v7, s63
	v_and_or_b32 v10, v7, s64, v2
	v_bfe_u32 v2, v25, 16, 1
	v_add3_u32 v2, v25, v2, s63
	v_bfe_u32 v7, v27, 16, 1
	v_lshrrev_b32_e32 v2, 16, v2
	v_add3_u32 v7, v27, v7, s63
	v_lshlrev_b64 v[12:13], 12, v[12:13]
	v_and_or_b32 v11, v7, s64, v2
	v_lshl_add_u64 v[4:5], v[4:5], 0, v[12:13]
	global_store_dwordx4 v[4:5], v[8:11], off
	s_waitcnt lgkmcnt(0)

;     ...
;     const int kb = item / nblk, nb = item % nblk, k0 = 64 * kb, n0 = 32 * nb;
;     { float wv[32];
;       const float* wp = W + (size_t)(k0 + (lane >> 5)) * ldw + n0 + (lane & 31);
; #pragma unroll
;       for (int i = 0; i < 32; ++i) wv[i] = wp[(size_t)(2 * i) * ldw];
; #pragma unroll
;       for (int i = 0; i < 32; ++i) scr[(2 * i + (lane >> 5)) * 33 + (lane & 31)] = wv[i]; }
; __device__ __forceinline__ void transpose_late(const Args& a, Frame& F, LAS float* scr, int r) {
;     ...
;     if (r < IT_SQ) { p0_transpose_item(a.in[I_WO], D, D, WO, 0, D / 32, scr, r, F.lane); return; } r -= IT_SQ;
.LBB0_1582:
	s_andn2_b64 vcc, exec, s[4:5]
	s_cbranch_vccnz .LBB0_1584
	s_add_i32 s0, s23, 0x800
	v_mov_b32_e32 v7, v6
	s_and_b32 s5, s0, 0xffc0
	v_ashrrev_i32_e32 v10, 5, v7
	v_add_u32_e32 v4, s5, v10
	v_ashrrev_i32_e32 v5, 31, v4
	s_mov_b64 s[44:45], s[82:83]
	v_readlane_b32 s68, v244, 2
	s_and_b32 s4, s24, 0x7e0
	v_lshlrev_b64 v[4:5], 13, v[4:5]
	v_readlane_b32 s72, v244, 6
	v_readlane_b32 s73, v244, 7
	s_lshl_b32 s0, s4, 2
	v_lshlrev_b32_e32 v2, 2, v7
	v_lshl_add_u64 v[4:5], s[72:73], 0, v[4:5]
	v_lshl_add_u64 v[4:5], v[4:5], 0, s[0:1]
	v_and_b32_e32 v2, 0x7c, v2
	v_lshl_add_u64 v[4:5], v[4:5], 0, v[2:3]
	v_add_co_u32_e32 v8, vcc, s25, v4
	global_load_dword v11, v[4:5], off nt
	s_nop 0
	v_addc_co_u32_e32 v9, vcc, 0, v5, vcc
	global_load_dword v12, v[8:9], off nt
	v_add_co_u32_e32 v8, vcc, s26, v4
	v_readlane_b32 s82, v244, 16
	s_nop 0
	v_addc_co_u32_e32 v9, vcc, 0, v5, vcc
	global_load_dword v13, v[8:9], off nt
	v_add_co_u32_e32 v8, vcc, s27, v4
	v_readlane_b32 s83, v244, 17
	s_nop 0
	v_addc_co_u32_e32 v9, vcc, 0, v5, vcc
	global_load_dword v14, v[8:9], off nt
	v_add_co_u32_e32 v8, vcc, s28, v4
	s_lshl_b32 s0, s5, 1
	s_nop 0
	v_addc_co_u32_e32 v9, vcc, 0, v5, vcc
	global_load_dword v15, v[8:9], off nt
	v_add_co_u32_e32 v8, vcc, s29, v4
	s_mov_b64 s[82:83], s[44:45]
	s_nop 0
	v_addc_co_u32_e32 v9, vcc, 0, v5, vcc
	global_load_dword v16, v[8:9], off nt
	v_add_co_u32_e32 v8, vcc, s31, v4
	s_add_u32 s44, s11, s0
	s_nop 0
	v_addc_co_u32_e32 v9, vcc, 0, v5, vcc
	global_load_dword v17, v[8:9], off nt
	v_add_co_u32_e32 v8, vcc, s33, v4
	s_addc_u32 s45, s12, 0
	s_nop 0
	v_addc_co_u32_e32 v9, vcc, 0, v5, vcc
	global_load_dword v18, v[8:9], off nt
	v_add_co_u32_e32 v8, vcc, s36, v4
	v_readlane_b32 s69, v244, 3
	s_nop 0
	v_addc_co_u32_e32 v9, vcc, 0, v5, vcc
	global_load_dword v19, v[8:9], off nt
	v_add_co_u32_e32 v8, vcc, s37, v4
	v_readlane_b32 s70, v244, 4
	s_nop 0
	v_addc_co_u32_e32 v9, vcc, 0, v5, vcc
	global_load_dword v20, v[8:9], off nt
	v_add_co_u32_e32 v8, vcc, s38, v4
	v_readlane_b32 s71, v244, 5
	s_nop 0
	v_addc_co_u32_e32 v9, vcc, 0, v5, vcc
	global_load_dword v21, v[8:9], off nt
	v_add_co_u32_e32 v8, vcc, s39, v4
	v_readlane_b32 s74, v244, 8
	s_nop 0
	v_addc_co_u32_e32 v9, vcc, 0, v5, vcc
	global_load_dword v22, v[8:9], off nt
	v_add_co_u32_e32 v8, vcc, s40, v4
	v_readlane_b32 s75, v244, 9
	s_nop 0
	v_addc_co_u32_e32 v9, vcc, 0, v5, vcc
	global_load_dword v23, v[8:9], off nt
	v_add_co_u32_e32 v8, vcc, s41, v4
	v_readlane_b32 s76, v244, 10
	s_nop 0
	v_addc_co_u32_e32 v9, vcc, 0, v5, vcc
	global_load_dword v24, v[8:9], off nt
	v_add_co_u32_e32 v8, vcc, s42, v4
	v_readlane_b32 s77, v244, 11
	s_nop 0
	v_addc_co_u32_e32 v9, vcc, 0, v5, vcc
	global_load_dword v25, v[8:9], off nt
	v_add_co_u32_e32 v8, vcc, s43, v4
	v_readlane_b32 s78, v244, 12
	s_nop 0
	v_addc_co_u32_e32 v9, vcc, 0, v5, vcc
	global_load_dword v26, v[8:9], off nt
	v_add_co_u32_e32 v8, vcc, s46, v4
	v_readlane_b32 s79, v244, 13
	s_nop 0
	v_addc_co_u32_e32 v9, vcc, 0, v5, vcc
	global_load_dword v27, v[8:9], off nt
	v_add_co_u32_e32 v8, vcc, s47, v4
	v_readlane_b32 s80, v244, 14
	s_nop 0
	v_addc_co_u32_e32 v9, vcc, 0, v5, vcc
	global_load_dword v28, v[8:9], off nt
	v_add_co_u32_e32 v8, vcc, s48, v4
	v_readlane_b32 s81, v244, 15
	s_nop 0
	v_addc_co_u32_e32 v9, vcc, 0, v5, vcc
	global_load_dword v29, v[8:9], off nt
	v_add_co_u32_e32 v8, vcc, s49, v4
	s_nop 1
	v_addc_co_u32_e32 v9, vcc, 0, v5, vcc
	global_load_dword v30, v[8:9], off nt
	v_add_co_u32_e32 v8, vcc, s50, v4
	s_nop 1
	v_addc_co_u32_e32 v9, vcc, 0, v5, vcc
	global_load_dword v31, v[8:9], off nt
	v_add_co_u32_e32 v8, vcc, s51, v4
	s_nop 1
	v_addc_co_u32_e32 v9, vcc, 0, v5, vcc
	global_load_dword v32, v[8:9], off nt
	v_add_co_u32_e32 v8, vcc, s52, v4
	s_nop 1
	v_addc_co_u32_e32 v9, vcc, 0, v5, vcc
	global_load_dword v33, v[8:9], off nt
	v_add_co_u32_e32 v8, vcc, s53, v4
	s_nop 1
	v_addc_co_u32_e32 v9, vcc, 0, v5, vcc
	global_load_dword v34, v[8:9], off nt
	v_add_co_u32_e32 v8, vcc, s54, v4
	s_nop 1
	v_addc_co_u32_e32 v9, vcc, 0, v5, vcc
	global_load_dword v35, v[8:9], off nt
	v_add_co_u32_e32 v8, vcc, s55, v4
	s_nop 1
	v_addc_co_u32_e32 v9, vcc, 0, v5, vcc
	global_load_dword v36, v[8:9], off nt
	v_add_co_u32_e32 v8, vcc, s56, v4
	s_nop 1
	v_addc_co_u32_e32 v9, vcc, 0, v5, vcc
	global_load_dword v37, v[8:9], off nt
	v_add_co_u32_e32 v8, vcc, s57, v4
	s_nop 1
	v_addc_co_u32_e32 v9, vcc, 0, v5, vcc
	global_load_dword v38, v[8:9], off nt
	v_add_co_u32_e32 v8, vcc, s58, v4
	s_nop 1
	v_addc_co_u32_e32 v9, vcc, 0, v5, vcc
	global_load_dword v39, v[8:9], off nt
	v_add_co_u32_e32 v8, vcc, s59, v4
	s_nop 1
	v_addc_co_u32_e32 v9, vcc, 0, v5, vcc
	global_load_dword v40, v[8:9], off nt
	v_add_co_u32_e32 v8, vcc, s60, v4
	s_nop 1
	v_addc_co_u32_e32 v9, vcc, 0, v5, vcc
	v_add_co_u32_e32 v4, vcc, s61, v4
	global_load_dword v8, v[8:9], off nt
	s_nop 0
	v_addc_co_u32_e32 v5, vcc, 0, v5, vcc
	global_load_dword v4, v[4:5], off nt
	v_mul_lo_u32 v5, v10, s62
	v_add3_u32 v2, s10, v2, v5
	v_add_u32_e32 v5, 0x400, v2
	s_waitcnt vmcnt(0)
; #define GAS __attribute__((address_space(1)))
; #define LAS __attribute__((address_space(3)))
; #define LDS_WAIT() asm volatile("s_waitcnt lgkmcnt(0)" ::: "memory")
; __device__ __forceinline__ unsigned pk2(float lo, float hi) { return f2bf(lo) | (f2bf(hi) << 16); }
;     ...
;       for (int i = 0; i < 32; ++i) scr[(2 * i + (lane >> 5)) * 33 + (lane & 31)] = wv[i]; }
;     LDS_WAIT(); asm volatile("" ::: "memory");
;     const int c = lane & 7;
;     const int r0 = (mode == 0) ? n0 : (256 * (n0 >> 7) + (n0 & 127) + (mode == 2 ? 128 : 0));
; #pragma unroll
;     for (int j = 0; j < 4; ++j) { const int n = (lane >> 3) + 8 * j; const LAS float* s = scr + (8 * c) * 33 + n;
;         v4u o; o.x = pk2(s[0 * 33], s[1 * 33]); o.y = pk2(s[2 * 33], s[3 * 33]); o.z = pk2(s[4 * 33], s[5 * 33]); o.w = pk2(s[6 * 33], s[7 * 33]);
;         *(GAS v4u*)(WT + (size_t)(r0 + n) * ldt + k0 + 8 * c) = o; }
;     LDS_WAIT(); asm volatile("" ::: "memory");
	ds_write2_b32 v2, v11, v12 offset1:66
	ds_write2_b32 v2, v13, v14 offset0:132 offset1:198
	ds_write2_b32 v5, v15, v16 offset0:8 offset1:74
	ds_write2_b32 v5, v17, v18 offset0:140 offset1:206
	v_add_u32_e32 v5, 0x800, v2
	ds_write2_b32 v5, v19, v20 offset0:16 offset1:82
	ds_write2_b32 v5, v21, v22 offset0:148 offset1:214
	v_add_u32_e32 v5, 0xc00, v2
	ds_write2_b32 v5, v23, v24 offset0:24 offset1:90
	ds_write2_b32 v5, v25, v26 offset0:156 offset1:222
	v_add_u32_e32 v5, 0x1000, v2
	ds_write2_b32 v5, v27, v28 offset0:32 offset1:98
	ds_write2_b32 v5, v29, v30 offset0:164 offset1:230
	v_add_u32_e32 v5, 0x1400, v2
	ds_write2_b32 v5, v31, v32 offset0:40 offset1:106
	ds_write2_b32 v5, v33, v34 offset0:172 offset1:238
	v_add_u32_e32 v5, 0x1800, v2
	v_add_u32_e32 v2, 0x1c00, v2
	ds_write2_b32 v5, v35, v36 offset0:48 offset1:114
	ds_write2_b32 v5, v37, v38 offset0:180 offset1:246
	ds_write2_b32 v2, v39, v40 offset0:56 offset1:122
	ds_write2_b32 v2, v8, v4 offset0:188 offset1:254
	v_lshlrev_b32_e32 v2, 3, v7
	v_and_b32_e32 v2, 56, v2
	v_ashrrev_i32_e32 v28, 3, v7
	v_mul_u32_u24_e32 v7, 0x84, v2
	v_lshlrev_b32_e32 v2, 1, v2
	s_waitcnt lgkmcnt(0)
	v_lshl_add_u64 v[4:5], s[44:45], 0, v[2:3]
	v_lshlrev_b32_e32 v2, 2, v28
	v_add3_u32 v2, s10, v7, v2
	ds_read2_b32 v[12:13], v2 offset0:33 offset1:41
	ds_read2_b32 v[14:15], v2 offset1:8
	ds_read2_b32 v[16:17], v2 offset0:66 offset1:74
	ds_read2_b32 v[18:19], v2 offset0:99 offset1:107
	ds_read2_b32 v[20:21], v2 offset0:132 offset1:140
	ds_read2_b32 v[22:23], v2 offset0:165 offset1:173
	ds_read2_b32 v[24:25], v2 offset0:198 offset1:206
	ds_read2_b32 v[26:27], v2 offset0:231 offset1:239
	s_waitcnt lgkmcnt(7)
	v_bfe_u32 v8, v12, 16, 1
	s_waitcnt lgkmcnt(6)
	v_bfe_u32 v7, v14, 16, 1
	v_add3_u32 v7, v14, v7, s63
	v_lshrrev_b32_e32 v7, 16, v7
	v_add3_u32 v8, v12, v8, s63
	v_and_or_b32 v8, v8, s64, v7
	s_waitcnt lgkmcnt(5)
	v_bfe_u32 v7, v16, 16, 1
	v_add3_u32 v7, v16, v7, s63
	s_waitcnt lgkmcnt(4)
	v_bfe_u32 v9, v18, 16, 1
	v_lshrrev_b32_e32 v7, 16, v7
	v_add3_u32 v9, v18, v9, s63
	v_and_or_b32 v9, v9, s64, v7
	s_waitcnt lgkmcnt(3)
	v_bfe_u32 v7, v20, 16, 1
	v_add3_u32 v7, v20, v7, s63
	s_waitcnt lgkmcnt(2)
	v_bfe_u32 v10, v22, 16, 1
	v_lshrrev_b32_e32 v7, 16, v7
	v_add3_u32 v10, v22, v10, s63
	v_and_or_b32 v10, v10, s64, v7
	s_waitcnt lgkmcnt(1)
	v_bfe_u32 v7, v24, 16, 1
	v_add_u32_e32 v28, s4, v28
	v_add3_u32 v7, v24, v7, s63
	s_waitcnt lgkmcnt(0)
	v_bfe_u32 v11, v26, 16, 1
	v_ashrrev_i32_e32 v29, 31, v28
	v_lshrrev_b32_e32 v7, 16, v7
	v_add3_u32 v11, v26, v11, s63
	v_lshlrev_b64 v[30:31], 12, v[28:29]
	v_and_or_b32 v11, v11, s64, v7
	v_lshl_add_u64 v[30:31], v[4:5], 0, v[30:31]
	v_bfe_u32 v7, v15, 16, 1
	global_store_dwordx4 v[30:31], v[8:11], off
	v_add3_u32 v7, v15, v7, s63
	v_lshrrev_b32_e32 v7, 16, v7
	v_bfe_u32 v8, v13, 16, 1
	v_add3_u32 v8, v13, v8, s63
	v_and_or_b32 v8, v8, s64, v7
	v_bfe_u32 v7, v17, 16, 1
	v_add3_u32 v7, v17, v7, s63
	v_bfe_u32 v9, v19, 16, 1
	v_lshrrev_b32_e32 v7, 16, v7
	v_add3_u32 v9, v19, v9, s63
	v_and_or_b32 v9, v9, s64, v7
	v_bfe_u32 v7, v21, 16, 1
	v_add3_u32 v7, v21, v7, s63
	v_bfe_u32 v10, v23, 16, 1
	v_lshrrev_b32_e32 v7, 16, v7
	v_add3_u32 v10, v23, v10, s63
	v_and_or_b32 v10, v10, s64, v7
	v_bfe_u32 v7, v25, 16, 1
	v_add_u32_e32 v12, 8, v28
	v_add3_u32 v7, v25, v7, s63
	v_bfe_u32 v11, v27, 16, 1
	v_ashrrev_i32_e32 v13, 31, v12
	v_lshrrev_b32_e32 v7, 16, v7
	v_add3_u32 v11, v27, v11, s63
	v_lshlrev_b64 v[12:13], 12, v[12:13]
	v_and_or_b32 v11, v11, s64, v7
	v_lshl_add_u64 v[12:13], v[4:5], 0, v[12:13]
	global_store_dwordx4 v[12:13], v[8:11], off
	ds_read2_b32 v[12:13], v2 offset0:49 offset1:57
	ds_read2_b32 v[14:15], v2 offset0:16 offset1:24
	ds_read2_b32 v[16:17], v2 offset0:82 offset1:90
	ds_read2_b32 v[18:19], v2 offset0:115 offset1:123
	ds_read2_b32 v[20:21], v2 offset0:148 offset1:156
	ds_read2_b32 v[22:23], v2 offset0:181 offset1:189
	ds_read2_b32 v[24:25], v2 offset0:214 offset1:222
	ds_read2_b32 v[26:27], v2 offset0:247 offset1:255
	s_waitcnt lgkmcnt(7)
	v_bfe_u32 v8, v12, 16, 1
	s_waitcnt lgkmcnt(6)
	v_bfe_u32 v7, v14, 16, 1
	v_add3_u32 v7, v14, v7, s63
	v_lshrrev_b32_e32 v7, 16, v7
	v_add3_u32 v8, v12, v8, s63
	v_and_or_b32 v8, v8, s64, v7
	s_waitcnt lgkmcnt(5)
	v_bfe_u32 v7, v16, 16, 1
	v_add3_u32 v7, v16, v7, s63
	s_waitcnt lgkmcnt(4)
	v_bfe_u32 v9, v18, 16, 1
	v_lshrrev_b32_e32 v7, 16, v7
	v_add3_u32 v9, v18, v9, s63
	v_and_or_b32 v9, v9, s64, v7
	s_waitcnt lgkmcnt(3)
	v_bfe_u32 v7, v20, 16, 1
	v_add3_u32 v7, v20, v7, s63
	s_waitcnt lgkmcnt(2)
	v_bfe_u32 v10, v22, 16, 1
	v_lshrrev_b32_e32 v7, 16, v7
	v_add3_u32 v10, v22, v10, s63
	s_waitcnt lgkmcnt(1)
	v_bfe_u32 v2, v24, 16, 1
	v_and_or_b32 v10, v10, s64, v7
	v_add3_u32 v2, v24, v2, s63
	s_waitcnt lgkmcnt(0)
	v_bfe_u32 v7, v26, 16, 1
	v_lshrrev_b32_e32 v2, 16, v2
	v_add3_u32 v7, v26, v7, s63
	v_add_u32_e32 v30, 16, v28
	v_and_or_b32 v11, v7, s64, v2
	v_ashrrev_i32_e32 v31, 31, v30
	v_bfe_u32 v2, v15, 16, 1
	v_lshlrev_b64 v[30:31], 12, v[30:31]
	v_add3_u32 v2, v15, v2, s63
	v_bfe_u32 v7, v13, 16, 1
	v_lshl_add_u64 v[30:31], v[4:5], 0, v[30:31]
	v_lshrrev_b32_e32 v2, 16, v2
	v_add3_u32 v7, v13, v7, s63
	global_store_dwordx4 v[30:31], v[8:11], off
	v_add_u32_e32 v12, 24, v28
	v_ashrrev_i32_e32 v13, 31, v12
	v_and_or_b32 v8, v7, s64, v2
	v_bfe_u32 v2, v17, 16, 1
	v_add3_u32 v2, v17, v2, s63
	v_bfe_u32 v7, v19, 16, 1
	v_lshrrev_b32_e32 v2, 16, v2
	v_add3_u32 v7, v19, v7, s63
	v_and_or_b32 v9, v7, s64, v2
	v_bfe_u32 v2, v21, 16, 1
	v_add3_u32 v2, v21, v2, s63
	v_bfe_u32 v7, v23, 16, 1
	v_lshrrev_b32_e32 v2, 16, v2
	v_add3_u32 v7, v23, v7, s63
	v_and_or_b32 v10, v7, s64, v2
	v_bfe_u32 v2, v25, 16, 1
	v_add3_u32 v2, v25, v2, s63
	v_bfe_u32 v7, v27, 16, 1
	v_lshrrev_b32_e32 v2, 16, v2
	v_add3_u32 v7, v27, v7, s63
	v_lshlrev_b64 v[12:13], 12, v[12:13]
	v_and_or_b32 v11, v7, s64, v2
	v_lshl_add_u64 v[4:5], v[4:5], 0, v[12:13]
	global_store_dwordx4 v[4:5], v[8:11], off
	s_waitcnt lgkmcnt(0)

;     ...
;     const int kb = item / nblk, nb = item % nblk, k0 = 64 * kb, n0 = 32 * nb;
;     { float wv[32];
;       const float* wp = W + (size_t)(k0 + (lane >> 5)) * ldw + n0 + (lane & 31);
; #pragma unroll
;       for (int i = 0; i < 32; ++i) wv[i] = wp[(size_t)(2 * i) * ldw];
; #pragma unroll
;       for (int i = 0; i < 32; ++i) scr[(2 * i + (lane >> 5)) * 33 + (lane & 31)] = wv[i]; }
; __device__ __forceinline__ void transpose_late(const Args& a, Frame& F, LAS float* scr, int r) {
;     ...
;     if (r < IT_SQ) { p0_transpose_item(a.in[I_WBOUT], D, D, WAB + D, 0, D / 32, scr, r, F.lane, 2 * D); return; } r -= IT_SQ;
.LBB0_1585:
	s_andn2_b64 vcc, exec, s[4:5]
	s_cbranch_vccnz .LBB0_1587
	s_add_i32 s0, s23, 0x1000
	v_mov_b32_e32 v7, v6
	s_and_b32 s5, s0, 0xffc0
	v_ashrrev_i32_e32 v10, 5, v7
	v_add_u32_e32 v4, s5, v10
	v_ashrrev_i32_e32 v5, 31, v4
	s_mov_b64 s[44:45], s[82:83]
	v_readlane_b32 s68, v244, 2
	s_and_b32 s4, s24, 0x7e0
	v_lshlrev_b64 v[4:5], 13, v[4:5]
	v_readlane_b32 s70, v244, 4
	v_readlane_b32 s71, v244, 5
	s_lshl_b32 s0, s4, 2
	v_lshlrev_b32_e32 v2, 2, v7
	v_lshl_add_u64 v[4:5], s[70:71], 0, v[4:5]
	v_lshl_add_u64 v[4:5], v[4:5], 0, s[0:1]
	v_and_b32_e32 v2, 0x7c, v2
	v_lshl_add_u64 v[4:5], v[4:5], 0, v[2:3]
	v_add_co_u32_e32 v8, vcc, s25, v4
	global_load_dword v11, v[4:5], off nt
	s_nop 0
	v_addc_co_u32_e32 v9, vcc, 0, v5, vcc
	global_load_dword v12, v[8:9], off nt
	v_add_co_u32_e32 v8, vcc, s26, v4
	v_readlane_b32 s82, v244, 16
	s_nop 0
	v_addc_co_u32_e32 v9, vcc, 0, v5, vcc
	global_load_dword v13, v[8:9], off nt
	v_add_co_u32_e32 v8, vcc, s27, v4
	v_readlane_b32 s83, v244, 17
	s_nop 0
	v_addc_co_u32_e32 v9, vcc, 0, v5, vcc
	global_load_dword v14, v[8:9], off nt
	v_add_co_u32_e32 v8, vcc, s28, v4
	s_lshl_b32 s0, s5, 1
	s_nop 0
	v_addc_co_u32_e32 v9, vcc, 0, v5, vcc
	global_load_dword v15, v[8:9], off nt
	v_add_co_u32_e32 v8, vcc, s29, v4
	s_mov_b64 s[82:83], s[44:45]
	s_nop 0
	v_addc_co_u32_e32 v9, vcc, 0, v5, vcc
	global_load_dword v16, v[8:9], off nt
	v_add_co_u32_e32 v8, vcc, s31, v4
	s_add_u32 s44, s19, s0
	s_nop 0
	v_addc_co_u32_e32 v9, vcc, 0, v5, vcc
	global_load_dword v17, v[8:9], off nt
	v_add_co_u32_e32 v8, vcc, s33, v4
	s_addc_u32 s45, s20, 0
	s_nop 0
	v_addc_co_u32_e32 v9, vcc, 0, v5, vcc
	global_load_dword v18, v[8:9], off nt
	v_add_co_u32_e32 v8, vcc, s36, v4
	v_readlane_b32 s69, v244, 3
	s_nop 0
	v_addc_co_u32_e32 v9, vcc, 0, v5, vcc
	global_load_dword v19, v[8:9], off nt
	v_add_co_u32_e32 v8, vcc, s37, v4
	v_readlane_b32 s72, v244, 6
	s_nop 0
	v_addc_co_u32_e32 v9, vcc, 0, v5, vcc
	global_load_dword v20, v[8:9], off nt
	v_add_co_u32_e32 v8, vcc, s38, v4
	v_readlane_b32 s73, v244, 7
	s_nop 0
	v_addc_co_u32_e32 v9, vcc, 0, v5, vcc
	global_load_dword v21, v[8:9], off nt
	v_add_co_u32_e32 v8, vcc, s39, v4
	v_readlane_b32 s74, v244, 8
	s_nop 0
	v_addc_co_u32_e32 v9, vcc, 0, v5, vcc
	global_load_dword v22, v[8:9], off nt
	v_add_co_u32_e32 v8, vcc, s40, v4
	v_readlane_b32 s75, v244, 9
	s_nop 0
	v_addc_co_u32_e32 v9, vcc, 0, v5, vcc
	global_load_dword v23, v[8:9], off nt
	v_add_co_u32_e32 v8, vcc, s41, v4
	v_readlane_b32 s76, v244, 10
	s_nop 0
	v_addc_co_u32_e32 v9, vcc, 0, v5, vcc
	global_load_dword v24, v[8:9], off nt
	v_add_co_u32_e32 v8, vcc, s42, v4
	v_readlane_b32 s77, v244, 11
	s_nop 0
	v_addc_co_u32_e32 v9, vcc, 0, v5, vcc
	global_load_dword v25, v[8:9], off nt
	v_add_co_u32_e32 v8, vcc, s43, v4
	v_readlane_b32 s78, v244, 12
	s_nop 0
	v_addc_co_u32_e32 v9, vcc, 0, v5, vcc
	global_load_dword v26, v[8:9], off nt
	v_add_co_u32_e32 v8, vcc, s46, v4
	v_readlane_b32 s79, v244, 13
	s_nop 0
	v_addc_co_u32_e32 v9, vcc, 0, v5, vcc
	global_load_dword v27, v[8:9], off nt
	v_add_co_u32_e32 v8, vcc, s47, v4
	v_readlane_b32 s80, v244, 14
	s_nop 0
	v_addc_co_u32_e32 v9, vcc, 0, v5, vcc
	global_load_dword v28, v[8:9], off nt
	v_add_co_u32_e32 v8, vcc, s48, v4
	v_readlane_b32 s81, v244, 15
	s_nop 0
	v_addc_co_u32_e32 v9, vcc, 0, v5, vcc
	global_load_dword v29, v[8:9], off nt
	v_add_co_u32_e32 v8, vcc, s49, v4
	s_nop 1
	v_addc_co_u32_e32 v9, vcc, 0, v5, vcc
	global_load_dword v30, v[8:9], off nt
	v_add_co_u32_e32 v8, vcc, s50, v4
	s_nop 1
	v_addc_co_u32_e32 v9, vcc, 0, v5, vcc
	global_load_dword v31, v[8:9], off nt
	v_add_co_u32_e32 v8, vcc, s51, v4
	s_nop 1
	v_addc_co_u32_e32 v9, vcc, 0, v5, vcc
	global_load_dword v32, v[8:9], off nt
	v_add_co_u32_e32 v8, vcc, s52, v4
	s_nop 1
	v_addc_co_u32_e32 v9, vcc, 0, v5, vcc
	global_load_dword v33, v[8:9], off nt
	v_add_co_u32_e32 v8, vcc, s53, v4
	s_nop 1
	v_addc_co_u32_e32 v9, vcc, 0, v5, vcc
	global_load_dword v34, v[8:9], off nt
	v_add_co_u32_e32 v8, vcc, s54, v4
	s_nop 1
	v_addc_co_u32_e32 v9, vcc, 0, v5, vcc
	global_load_dword v35, v[8:9], off nt
	v_add_co_u32_e32 v8, vcc, s55, v4
	s_nop 1
	v_addc_co_u32_e32 v9, vcc, 0, v5, vcc
	global_load_dword v36, v[8:9], off nt
	v_add_co_u32_e32 v8, vcc, s56, v4
	s_nop 1
	v_addc_co_u32_e32 v9, vcc, 0, v5, vcc
	global_load_dword v37, v[8:9], off nt
	v_add_co_u32_e32 v8, vcc, s57, v4
	s_nop 1
	v_addc_co_u32_e32 v9, vcc, 0, v5, vcc
	global_load_dword v38, v[8:9], off nt
	v_add_co_u32_e32 v8, vcc, s58, v4
	s_nop 1
	v_addc_co_u32_e32 v9, vcc, 0, v5, vcc
	global_load_dword v39, v[8:9], off nt
	v_add_co_u32_e32 v8, vcc, s59, v4
	s_nop 1
	v_addc_co_u32_e32 v9, vcc, 0, v5, vcc
	global_load_dword v40, v[8:9], off nt
	v_add_co_u32_e32 v8, vcc, s60, v4
	s_nop 1
	v_addc_co_u32_e32 v9, vcc, 0, v5, vcc
	v_add_co_u32_e32 v4, vcc, s61, v4
	global_load_dword v8, v[8:9], off nt
	s_nop 0
	v_addc_co_u32_e32 v5, vcc, 0, v5, vcc
	global_load_dword v4, v[4:5], off nt
	v_mul_lo_u32 v5, v10, s62
	v_add3_u32 v2, s10, v2, v5
	v_add_u32_e32 v5, 0x400, v2
	s_waitcnt vmcnt(0)
; #define GAS __attribute__((address_space(1)))
; #define LAS __attribute__((address_space(3)))
; #define LDS_WAIT() asm volatile("s_waitcnt lgkmcnt(0)" ::: "memory")
; __device__ __forceinline__ unsigned pk2(float lo, float hi) { return f2bf(lo) | (f2bf(hi) << 16); }
;     ...
;       for (int i = 0; i < 32; ++i) scr[(2 * i + (lane >> 5)) * 33 + (lane & 31)] = wv[i]; }
;     LDS_WAIT(); asm volatile("" ::: "memory");
;     const int c = lane & 7;
;     const int r0 = (mode == 0) ? n0 : (256 * (n0 >> 7) + (n0 & 127) + (mode == 2 ? 128 : 0));
; #pragma unroll
;     for (int j = 0; j < 4; ++j) { const int n = (lane >> 3) + 8 * j; const LAS float* s = scr + (8 * c) * 33 + n;
;         v4u o; o.x = pk2(s[0 * 33], s[1 * 33]); o.y = pk2(s[2 * 33], s[3 * 33]); o.z = pk2(s[4 * 33], s[5 * 33]); o.w = pk2(s[6 * 33], s[7 * 33]);
;         *(GAS v4u*)(WT + (size_t)(r0 + n) * ldt + k0 + 8 * c) = o; }
;     LDS_WAIT(); asm volatile("" ::: "memory");
	ds_write2_b32 v2, v11, v12 offset1:66
	ds_write2_b32 v2, v13, v14 offset0:132 offset1:198
	ds_write2_b32 v5, v15, v16 offset0:8 offset1:74
	ds_write2_b32 v5, v17, v18 offset0:140 offset1:206
	v_add_u32_e32 v5, 0x800, v2
	ds_write2_b32 v5, v19, v20 offset0:16 offset1:82
	ds_write2_b32 v5, v21, v22 offset0:148 offset1:214
	v_add_u32_e32 v5, 0xc00, v2
	ds_write2_b32 v5, v23, v24 offset0:24 offset1:90
	ds_write2_b32 v5, v25, v26 offset0:156 offset1:222
	v_add_u32_e32 v5, 0x1000, v2
	ds_write2_b32 v5, v27, v28 offset0:32 offset1:98
	ds_write2_b32 v5, v29, v30 offset0:164 offset1:230
	v_add_u32_e32 v5, 0x1400, v2
	ds_write2_b32 v5, v31, v32 offset0:40 offset1:106
	ds_write2_b32 v5, v33, v34 offset0:172 offset1:238
	v_add_u32_e32 v5, 0x1800, v2
	v_add_u32_e32 v2, 0x1c00, v2
	ds_write2_b32 v5, v35, v36 offset0:48 offset1:114
	ds_write2_b32 v5, v37, v38 offset0:180 offset1:246
	ds_write2_b32 v2, v39, v40 offset0:56 offset1:122
	ds_write2_b32 v2, v8, v4 offset0:188 offset1:254
	v_lshlrev_b32_e32 v2, 3, v7
	v_and_b32_e32 v2, 56, v2
	v_ashrrev_i32_e32 v28, 3, v7
	v_mul_u32_u24_e32 v7, 0x84, v2
	v_lshlrev_b32_e32 v2, 1, v2
	s_waitcnt lgkmcnt(0)
	v_lshl_add_u64 v[4:5], s[44:45], 0, v[2:3]
	v_lshlrev_b32_e32 v2, 2, v28
	v_add3_u32 v2, s10, v7, v2
	ds_read2_b32 v[12:13], v2 offset0:33 offset1:41
	ds_read2_b32 v[14:15], v2 offset1:8
	ds_read2_b32 v[16:17], v2 offset0:66 offset1:74
	ds_read2_b32 v[18:19], v2 offset0:99 offset1:107
	ds_read2_b32 v[20:21], v2 offset0:132 offset1:140
	ds_read2_b32 v[22:23], v2 offset0:165 offset1:173
	ds_read2_b32 v[24:25], v2 offset0:198 offset1:206
	ds_read2_b32 v[26:27], v2 offset0:231 offset1:239
	s_waitcnt lgkmcnt(7)
	v_bfe_u32 v8, v12, 16, 1
	s_waitcnt lgkmcnt(6)
	v_bfe_u32 v7, v14, 16, 1
	v_add3_u32 v7, v14, v7, s63
	v_lshrrev_b32_e32 v7, 16, v7
	v_add3_u32 v8, v12, v8, s63
	v_and_or_b32 v8, v8, s64, v7
	s_waitcnt lgkmcnt(5)
	v_bfe_u32 v7, v16, 16, 1
	v_add3_u32 v7, v16, v7, s63
	s_waitcnt lgkmcnt(4)
	v_bfe_u32 v9, v18, 16, 1
	v_lshrrev_b32_e32 v7, 16, v7
	v_add3_u32 v9, v18, v9, s63
	v_and_or_b32 v9, v9, s64, v7
	s_waitcnt lgkmcnt(3)
	v_bfe_u32 v7, v20, 16, 1
	v_add3_u32 v7, v20, v7, s63
	s_waitcnt lgkmcnt(2)
	v_bfe_u32 v10, v22, 16, 1
	v_lshrrev_b32_e32 v7, 16, v7
	v_add3_u32 v10, v22, v10, s63
	v_and_or_b32 v10, v10, s64, v7
	s_waitcnt lgkmcnt(1)
	v_bfe_u32 v7, v24, 16, 1
	v_add_u32_e32 v28, s4, v28
	v_add3_u32 v7, v24, v7, s63
	s_waitcnt lgkmcnt(0)
	v_bfe_u32 v11, v26, 16, 1
	v_ashrrev_i32_e32 v29, 31, v28
	v_lshrrev_b32_e32 v7, 16, v7
	v_add3_u32 v11, v26, v11, s63
	v_lshlrev_b64 v[30:31], 13, v[28:29]
	v_and_or_b32 v11, v11, s64, v7
	v_lshl_add_u64 v[30:31], v[4:5], 0, v[30:31]
	v_bfe_u32 v7, v15, 16, 1
	global_store_dwordx4 v[30:31], v[8:11], off
	v_add3_u32 v7, v15, v7, s63
	v_lshrrev_b32_e32 v7, 16, v7
	v_bfe_u32 v8, v13, 16, 1
	v_add3_u32 v8, v13, v8, s63
	v_and_or_b32 v8, v8, s64, v7
	v_bfe_u32 v7, v17, 16, 1
	v_add3_u32 v7, v17, v7, s63
	v_bfe_u32 v9, v19, 16, 1
	v_lshrrev_b32_e32 v7, 16, v7
	v_add3_u32 v9, v19, v9, s63
	v_and_or_b32 v9, v9, s64, v7
	v_bfe_u32 v7, v21, 16, 1
	v_add3_u32 v7, v21, v7, s63
	v_bfe_u32 v10, v23, 16, 1
	v_lshrrev_b32_e32 v7, 16, v7
	v_add3_u32 v10, v23, v10, s63
	v_and_or_b32 v10, v10, s64, v7
	v_bfe_u32 v7, v25, 16, 1
	v_add_u32_e32 v12, 8, v28
	v_add3_u32 v7, v25, v7, s63
	v_bfe_u32 v11, v27, 16, 1
	v_ashrrev_i32_e32 v13, 31, v12
	v_lshrrev_b32_e32 v7, 16, v7
	v_add3_u32 v11, v27, v11, s63
	v_lshlrev_b64 v[12:13], 13, v[12:13]
	v_and_or_b32 v11, v11, s64, v7
	v_lshl_add_u64 v[12:13], v[4:5], 0, v[12:13]
	global_store_dwordx4 v[12:13], v[8:11], off
	ds_read2_b32 v[12:13], v2 offset0:49 offset1:57
	ds_read2_b32 v[14:15], v2 offset0:16 offset1:24
	ds_read2_b32 v[16:17], v2 offset0:82 offset1:90
	ds_read2_b32 v[18:19], v2 offset0:115 offset1:123
	ds_read2_b32 v[20:21], v2 offset0:148 offset1:156
	ds_read2_b32 v[22:23], v2 offset0:181 offset1:189
	ds_read2_b32 v[24:25], v2 offset0:214 offset1:222
	ds_read2_b32 v[26:27], v2 offset0:247 offset1:255
	s_waitcnt lgkmcnt(7)
	v_bfe_u32 v8, v12, 16, 1
	s_waitcnt lgkmcnt(6)
	v_bfe_u32 v7, v14, 16, 1
	v_add3_u32 v7, v14, v7, s63
	v_lshrrev_b32_e32 v7, 16, v7
	v_add3_u32 v8, v12, v8, s63
	v_and_or_b32 v8, v8, s64, v7
	s_waitcnt lgkmcnt(5)
	v_bfe_u32 v7, v16, 16, 1
	v_add3_u32 v7, v16, v7, s63
	s_waitcnt lgkmcnt(4)
	v_bfe_u32 v9, v18, 16, 1
	v_lshrrev_b32_e32 v7, 16, v7
	v_add3_u32 v9, v18, v9, s63
	v_and_or_b32 v9, v9, s64, v7
	s_waitcnt lgkmcnt(3)
	v_bfe_u32 v7, v20, 16, 1
	v_add3_u32 v7, v20, v7, s63
	s_waitcnt lgkmcnt(2)
	v_bfe_u32 v10, v22, 16, 1
	v_lshrrev_b32_e32 v7, 16, v7
	v_add3_u32 v10, v22, v10, s63
	s_waitcnt lgkmcnt(1)
	v_bfe_u32 v2, v24, 16, 1
	v_and_or_b32 v10, v10, s64, v7
	v_add3_u32 v2, v24, v2, s63
	s_waitcnt lgkmcnt(0)
	v_bfe_u32 v7, v26, 16, 1
	v_lshrrev_b32_e32 v2, 16, v2
	v_add3_u32 v7, v26, v7, s63
	v_add_u32_e32 v30, 16, v28
	v_and_or_b32 v11, v7, s64, v2
	v_ashrrev_i32_e32 v31, 31, v30
	v_bfe_u32 v2, v15, 16, 1
	v_lshlrev_b64 v[30:31], 13, v[30:31]
	v_add3_u32 v2, v15, v2, s63
	v_bfe_u32 v7, v13, 16, 1
	v_lshl_add_u64 v[30:31], v[4:5], 0, v[30:31]
	v_lshrrev_b32_e32 v2, 16, v2
	v_add3_u32 v7, v13, v7, s63
	global_store_dwordx4 v[30:31], v[8:11], off
	v_add_u32_e32 v12, 24, v28
	v_ashrrev_i32_e32 v13, 31, v12
	v_and_or_b32 v8, v7, s64, v2
	v_bfe_u32 v2, v17, 16, 1
	v_add3_u32 v2, v17, v2, s63
	v_bfe_u32 v7, v19, 16, 1
	v_lshrrev_b32_e32 v2, 16, v2
	v_add3_u32 v7, v19, v7, s63
	v_and_or_b32 v9, v7, s64, v2
	v_bfe_u32 v2, v21, 16, 1
	v_add3_u32 v2, v21, v2, s63
	v_bfe_u32 v7, v23, 16, 1
	v_lshrrev_b32_e32 v2, 16, v2
	v_add3_u32 v7, v23, v7, s63
	v_and_or_b32 v10, v7, s64, v2
	v_bfe_u32 v2, v25, 16, 1
	v_add3_u32 v2, v25, v2, s63
	v_bfe_u32 v7, v27, 16, 1
	v_lshrrev_b32_e32 v2, 16, v2
	v_add3_u32 v7, v27, v7, s63
	v_lshlrev_b64 v[12:13], 13, v[12:13]
	v_and_or_b32 v11, v7, s64, v2
	v_lshl_add_u64 v[4:5], v[4:5], 0, v[12:13]
	global_store_dwordx4 v[4:5], v[8:11], off
	s_waitcnt lgkmcnt(0)

;     ...
;     const int kb = item / nblk, nb = item % nblk, k0 = 64 * kb, n0 = 32 * nb;
;     { float wv[32];
;       const float* wp = W + (size_t)(k0 + (lane >> 5)) * ldw + n0 + (lane & 31);
; #pragma unroll
;       for (int i = 0; i < 32; ++i) wv[i] = wp[(size_t)(2 * i) * ldw];
; #pragma unroll
;       for (int i = 0; i < 32; ++i) scr[(2 * i + (lane >> 5)) * 33 + (lane & 31)] = wv[i]; }
; __device__ __forceinline__ void transpose_late(const Args& a, Frame& F, LAS float* scr, int r) {
;     ...
;     if (r < IT_SQ) { p0_transpose_item(a.in[I_WAOUT], D, D, WAB, 0, D / 32, scr, r, F.lane, 2 * D); return; } r -= IT_SQ;
.LBB0_1588:
	s_ashr_i32 s0, s9, 31
	s_lshr_b32 s0, s0, 26
	v_mov_b32_e32 v7, v6
	s_add_i32 s0, s9, s0
	s_and_b32 s8, s0, 0xffffffc0
	v_ashrrev_i32_e32 v10, 5, v7
	v_add_u32_e32 v4, s8, v10
	s_sub_i32 s0, s9, s8
	v_ashrrev_i32_e32 v5, 31, v4
	s_mov_b64 s[44:45], s[82:83]
	v_readlane_b32 s68, v245, 50
	s_lshl_b32 s4, s0, 5
	v_lshlrev_b64 v[4:5], 13, v[4:5]
	v_readlane_b32 s76, v245, 58
	v_readlane_b32 s77, v245, 59
	s_ashr_i32 s5, s4, 31
	v_lshlrev_b32_e32 v2, 2, v7
	v_lshl_add_u64 v[4:5], s[76:77], 0, v[4:5]
	v_lshl_add_u64 v[4:5], s[4:5], 2, v[4:5]
	v_and_b32_e32 v2, 0x7c, v2
	v_lshl_add_u64 v[4:5], v[4:5], 0, v[2:3]
	v_add_co_u32_e32 v8, vcc, s25, v4
	global_load_dword v11, v[4:5], off nt
	s_nop 0
	v_addc_co_u32_e32 v9, vcc, 0, v5, vcc
	global_load_dword v12, v[8:9], off nt
	v_add_co_u32_e32 v8, vcc, s26, v4
	s_ashr_i32 s9, s8, 31
	s_nop 0
	v_addc_co_u32_e32 v9, vcc, 0, v5, vcc
	global_load_dword v13, v[8:9], off nt
	v_add_co_u32_e32 v8, vcc, s27, v4
	s_lshl_b64 s[8:9], s[8:9], 1
	s_nop 0
	v_addc_co_u32_e32 v9, vcc, 0, v5, vcc
	global_load_dword v14, v[8:9], off nt
	v_add_co_u32_e32 v8, vcc, s28, v4
	s_add_u32 s8, s21, s8
	s_nop 0
	v_addc_co_u32_e32 v9, vcc, 0, v5, vcc
	global_load_dword v15, v[8:9], off nt
	v_add_co_u32_e32 v8, vcc, s29, v4
	s_addc_u32 s9, s22, s9
	s_nop 0
	v_addc_co_u32_e32 v9, vcc, 0, v5, vcc
	global_load_dword v16, v[8:9], off nt
	v_add_co_u32_e32 v8, vcc, s31, v4
	v_readlane_b32 s82, v244, 0
	s_nop 0
	v_addc_co_u32_e32 v9, vcc, 0, v5, vcc
	global_load_dword v17, v[8:9], off nt
	v_add_co_u32_e32 v8, vcc, s33, v4
	v_readlane_b32 s83, v244, 1
	s_nop 0
	v_addc_co_u32_e32 v9, vcc, 0, v5, vcc
	global_load_dword v18, v[8:9], off nt
	v_add_co_u32_e32 v8, vcc, s36, v4
	s_mov_b64 s[82:83], s[44:45]
	s_nop 0
	v_addc_co_u32_e32 v9, vcc, 0, v5, vcc
	global_load_dword v19, v[8:9], off nt
	v_add_co_u32_e32 v8, vcc, s37, v4
	v_readlane_b32 s69, v245, 51
	s_nop 0
	v_addc_co_u32_e32 v9, vcc, 0, v5, vcc
	global_load_dword v20, v[8:9], off nt
	v_add_co_u32_e32 v8, vcc, s38, v4
	v_readlane_b32 s70, v245, 52
	s_nop 0
	v_addc_co_u32_e32 v9, vcc, 0, v5, vcc
	global_load_dword v21, v[8:9], off nt
	v_add_co_u32_e32 v8, vcc, s39, v4
	v_readlane_b32 s71, v245, 53
	s_nop 0
	v_addc_co_u32_e32 v9, vcc, 0, v5, vcc
	global_load_dword v22, v[8:9], off nt
	v_add_co_u32_e32 v8, vcc, s40, v4
	v_readlane_b32 s72, v245, 54
	s_nop 0
	v_addc_co_u32_e32 v9, vcc, 0, v5, vcc
	global_load_dword v23, v[8:9], off nt
	v_add_co_u32_e32 v8, vcc, s41, v4
	v_readlane_b32 s73, v245, 55
	s_nop 0
	v_addc_co_u32_e32 v9, vcc, 0, v5, vcc
	global_load_dword v24, v[8:9], off nt
	v_add_co_u32_e32 v8, vcc, s42, v4
	v_readlane_b32 s74, v245, 56
	s_nop 0
	v_addc_co_u32_e32 v9, vcc, 0, v5, vcc
	global_load_dword v25, v[8:9], off nt
	v_add_co_u32_e32 v8, vcc, s43, v4
	v_readlane_b32 s75, v245, 57
	s_nop 0
	v_addc_co_u32_e32 v9, vcc, 0, v5, vcc
	global_load_dword v26, v[8:9], off nt
	v_add_co_u32_e32 v8, vcc, s46, v4
	v_readlane_b32 s78, v245, 60
	s_nop 0
	v_addc_co_u32_e32 v9, vcc, 0, v5, vcc
	global_load_dword v27, v[8:9], off nt
	v_add_co_u32_e32 v8, vcc, s47, v4
	v_readlane_b32 s79, v245, 61
	s_nop 0
	v_addc_co_u32_e32 v9, vcc, 0, v5, vcc
	global_load_dword v28, v[8:9], off nt
	v_add_co_u32_e32 v8, vcc, s48, v4
	v_readlane_b32 s80, v245, 62
	s_nop 0
	v_addc_co_u32_e32 v9, vcc, 0, v5, vcc
	global_load_dword v29, v[8:9], off nt
	v_add_co_u32_e32 v8, vcc, s49, v4
	v_readlane_b32 s81, v245, 63
	s_nop 0
	v_addc_co_u32_e32 v9, vcc, 0, v5, vcc
	global_load_dword v30, v[8:9], off nt
	v_add_co_u32_e32 v8, vcc, s50, v4
	s_nop 1
	v_addc_co_u32_e32 v9, vcc, 0, v5, vcc
	global_load_dword v31, v[8:9], off nt
	v_add_co_u32_e32 v8, vcc, s51, v4
	s_nop 1
	v_addc_co_u32_e32 v9, vcc, 0, v5, vcc
	global_load_dword v32, v[8:9], off nt
	v_add_co_u32_e32 v8, vcc, s52, v4
	s_nop 1
	v_addc_co_u32_e32 v9, vcc, 0, v5, vcc
	global_load_dword v33, v[8:9], off nt
	v_add_co_u32_e32 v8, vcc, s53, v4
	s_nop 1
	v_addc_co_u32_e32 v9, vcc, 0, v5, vcc
	global_load_dword v34, v[8:9], off nt
	v_add_co_u32_e32 v8, vcc, s54, v4
	s_nop 1
	v_addc_co_u32_e32 v9, vcc, 0, v5, vcc
	global_load_dword v35, v[8:9], off nt
	v_add_co_u32_e32 v8, vcc, s55, v4
	s_nop 1
	v_addc_co_u32_e32 v9, vcc, 0, v5, vcc
	global_load_dword v36, v[8:9], off nt
	v_add_co_u32_e32 v8, vcc, s56, v4
	s_nop 1
	v_addc_co_u32_e32 v9, vcc, 0, v5, vcc
	global_load_dword v37, v[8:9], off nt
	v_add_co_u32_e32 v8, vcc, s57, v4
	s_nop 1
	v_addc_co_u32_e32 v9, vcc, 0, v5, vcc
	global_load_dword v38, v[8:9], off nt
	v_add_co_u32_e32 v8, vcc, s58, v4
	s_nop 1
	v_addc_co_u32_e32 v9, vcc, 0, v5, vcc
	global_load_dword v39, v[8:9], off nt
	v_add_co_u32_e32 v8, vcc, s59, v4
	s_nop 1
	v_addc_co_u32_e32 v9, vcc, 0, v5, vcc
	global_load_dword v40, v[8:9], off nt
	v_add_co_u32_e32 v8, vcc, s60, v4
	s_nop 1
	v_addc_co_u32_e32 v9, vcc, 0, v5, vcc
	v_add_co_u32_e32 v4, vcc, s61, v4
	global_load_dword v8, v[8:9], off nt
	s_nop 0
	v_addc_co_u32_e32 v5, vcc, 0, v5, vcc
	global_load_dword v4, v[4:5], off nt
	v_mul_lo_u32 v5, v10, s62
	v_add3_u32 v2, s10, v2, v5
	v_add_u32_e32 v5, 0x400, v2
	s_waitcnt vmcnt(0)
; #define GAS __attribute__((address_space(1)))
; #define LAS __attribute__((address_space(3)))
; #define LDS_WAIT() asm volatile("s_waitcnt lgkmcnt(0)" ::: "memory")
; __device__ __forceinline__ unsigned pk2(float lo, float hi) { return f2bf(lo) | (f2bf(hi) << 16); }
;     ...
;       for (int i = 0; i < 32; ++i) scr[(2 * i + (lane >> 5)) * 33 + (lane & 31)] = wv[i]; }
;     LDS_WAIT(); asm volatile("" ::: "memory");
;     const int c = lane & 7;
;     const int r0 = (mode == 0) ? n0 : (256 * (n0 >> 7) + (n0 & 127) + (mode == 2 ? 128 : 0));
; #pragma unroll
;     for (int j = 0; j < 4; ++j) { const int n = (lane >> 3) + 8 * j; const LAS float* s = scr + (8 * c) * 33 + n;
;         v4u o; o.x = pk2(s[0 * 33], s[1 * 33]); o.y = pk2(s[2 * 33], s[3 * 33]); o.z = pk2(s[4 * 33], s[5 * 33]); o.w = pk2(s[6 * 33], s[7 * 33]);
;         *(GAS v4u*)(WT + (size_t)(r0 + n) * ldt + k0 + 8 * c) = o; }
;     LDS_WAIT(); asm volatile("" ::: "memory");
	ds_write2_b32 v2, v11, v12 offset1:66
	ds_write2_b32 v2, v13, v14 offset0:132 offset1:198
	ds_write2_b32 v5, v15, v16 offset0:8 offset1:74
	ds_write2_b32 v5, v17, v18 offset0:140 offset1:206
	v_add_u32_e32 v5, 0x800, v2
	ds_write2_b32 v5, v19, v20 offset0:16 offset1:82
	ds_write2_b32 v5, v21, v22 offset0:148 offset1:214
	v_add_u32_e32 v5, 0xc00, v2
	ds_write2_b32 v5, v23, v24 offset0:24 offset1:90
	ds_write2_b32 v5, v25, v26 offset0:156 offset1:222
	v_add_u32_e32 v5, 0x1000, v2
	ds_write2_b32 v5, v27, v28 offset0:32 offset1:98
	ds_write2_b32 v5, v29, v30 offset0:164 offset1:230
	v_add_u32_e32 v5, 0x1400, v2
	ds_write2_b32 v5, v31, v32 offset0:40 offset1:106
	ds_write2_b32 v5, v33, v34 offset0:172 offset1:238
	v_add_u32_e32 v5, 0x1800, v2
	v_add_u32_e32 v2, 0x1c00, v2
	ds_write2_b32 v5, v35, v36 offset0:48 offset1:114
	ds_write2_b32 v5, v37, v38 offset0:180 offset1:246
	ds_write2_b32 v2, v39, v40 offset0:56 offset1:122
	ds_write2_b32 v2, v8, v4 offset0:188 offset1:254
	v_lshlrev_b32_e32 v2, 3, v7
	v_and_b32_e32 v2, 56, v2
	v_ashrrev_i32_e32 v28, 3, v7
	v_mul_u32_u24_e32 v7, 0x84, v2
	v_lshlrev_b32_e32 v2, 1, v2
	s_waitcnt lgkmcnt(0)
	v_lshl_add_u64 v[4:5], s[8:9], 0, v[2:3]
	v_lshlrev_b32_e32 v2, 2, v28
	v_add3_u32 v2, s10, v7, v2
	ds_read2_b32 v[12:13], v2 offset0:33 offset1:41
	ds_read2_b32 v[14:15], v2 offset1:8
	ds_read2_b32 v[16:17], v2 offset0:66 offset1:74
	ds_read2_b32 v[18:19], v2 offset0:99 offset1:107
	ds_read2_b32 v[20:21], v2 offset0:132 offset1:140
	ds_read2_b32 v[22:23], v2 offset0:165 offset1:173
	ds_read2_b32 v[24:25], v2 offset0:198 offset1:206
	ds_read2_b32 v[26:27], v2 offset0:231 offset1:239
	s_waitcnt lgkmcnt(7)
	v_bfe_u32 v8, v12, 16, 1
	s_waitcnt lgkmcnt(6)
	v_bfe_u32 v7, v14, 16, 1
	v_add3_u32 v7, v14, v7, s63
	v_lshrrev_b32_e32 v7, 16, v7
	v_add3_u32 v8, v12, v8, s63
	v_and_or_b32 v8, v8, s64, v7
	s_waitcnt lgkmcnt(5)
	v_bfe_u32 v7, v16, 16, 1
	v_add3_u32 v7, v16, v7, s63
	s_waitcnt lgkmcnt(4)
	v_bfe_u32 v9, v18, 16, 1
	v_lshrrev_b32_e32 v7, 16, v7
	v_add3_u32 v9, v18, v9, s63
	v_and_or_b32 v9, v9, s64, v7
	s_waitcnt lgkmcnt(3)
	v_bfe_u32 v7, v20, 16, 1
	v_add3_u32 v7, v20, v7, s63
	s_waitcnt lgkmcnt(2)
	v_bfe_u32 v10, v22, 16, 1
	v_lshrrev_b32_e32 v7, 16, v7
	v_add3_u32 v10, v22, v10, s63
	v_and_or_b32 v10, v10, s64, v7
	s_waitcnt lgkmcnt(1)
	v_bfe_u32 v7, v24, 16, 1
	v_add_u32_e32 v28, s4, v28
	v_add3_u32 v7, v24, v7, s63
	s_waitcnt lgkmcnt(0)
	v_bfe_u32 v11, v26, 16, 1
	v_ashrrev_i32_e32 v29, 31, v28
	v_lshrrev_b32_e32 v7, 16, v7
	v_add3_u32 v11, v26, v11, s63
	v_lshlrev_b64 v[30:31], 13, v[28:29]
	v_and_or_b32 v11, v11, s64, v7
	v_lshl_add_u64 v[30:31], v[4:5], 0, v[30:31]
	v_bfe_u32 v7, v15, 16, 1
	global_store_dwordx4 v[30:31], v[8:11], off
	v_add3_u32 v7, v15, v7, s63
	v_lshrrev_b32_e32 v7, 16, v7
	v_bfe_u32 v8, v13, 16, 1
	v_add3_u32 v8, v13, v8, s63
	v_and_or_b32 v8, v8, s64, v7
	v_bfe_u32 v7, v17, 16, 1
	v_add3_u32 v7, v17, v7, s63
	v_bfe_u32 v9, v19, 16, 1
	v_lshrrev_b32_e32 v7, 16, v7
	v_add3_u32 v9, v19, v9, s63
	v_and_or_b32 v9, v9, s64, v7
	v_bfe_u32 v7, v21, 16, 1
	v_add3_u32 v7, v21, v7, s63
	v_bfe_u32 v10, v23, 16, 1
	v_lshrrev_b32_e32 v7, 16, v7
	v_add3_u32 v10, v23, v10, s63
	v_and_or_b32 v10, v10, s64, v7
	v_bfe_u32 v7, v25, 16, 1
	v_add_u32_e32 v12, 8, v28
	v_add3_u32 v7, v25, v7, s63
	v_bfe_u32 v11, v27, 16, 1
	v_ashrrev_i32_e32 v13, 31, v12
	v_lshrrev_b32_e32 v7, 16, v7
	v_add3_u32 v11, v27, v11, s63
	v_lshlrev_b64 v[12:13], 13, v[12:13]
	v_and_or_b32 v11, v11, s64, v7
	v_lshl_add_u64 v[12:13], v[4:5], 0, v[12:13]
	global_store_dwordx4 v[12:13], v[8:11], off
	ds_read2_b32 v[12:13], v2 offset0:49 offset1:57
	ds_read2_b32 v[14:15], v2 offset0:16 offset1:24
	ds_read2_b32 v[16:17], v2 offset0:82 offset1:90
	ds_read2_b32 v[18:19], v2 offset0:115 offset1:123
	ds_read2_b32 v[20:21], v2 offset0:148 offset1:156
	ds_read2_b32 v[22:23], v2 offset0:181 offset1:189
	ds_read2_b32 v[24:25], v2 offset0:214 offset1:222
	ds_read2_b32 v[26:27], v2 offset0:247 offset1:255
	s_waitcnt lgkmcnt(7)
	v_bfe_u32 v8, v12, 16, 1
	s_waitcnt lgkmcnt(6)
	v_bfe_u32 v7, v14, 16, 1
	v_add3_u32 v7, v14, v7, s63
	v_lshrrev_b32_e32 v7, 16, v7
	v_add3_u32 v8, v12, v8, s63
	v_and_or_b32 v8, v8, s64, v7
	s_waitcnt lgkmcnt(5)
	v_bfe_u32 v7, v16, 16, 1
	v_add3_u32 v7, v16, v7, s63
	s_waitcnt lgkmcnt(4)
	v_bfe_u32 v9, v18, 16, 1
	v_lshrrev_b32_e32 v7, 16, v7
	v_add3_u32 v9, v18, v9, s63
	v_and_or_b32 v9, v9, s64, v7
	s_waitcnt lgkmcnt(3)
	v_bfe_u32 v7, v20, 16, 1
	v_add3_u32 v7, v20, v7, s63
	s_waitcnt lgkmcnt(2)
	v_bfe_u32 v10, v22, 16, 1
	v_lshrrev_b32_e32 v7, 16, v7
	v_add3_u32 v10, v22, v10, s63
	s_waitcnt lgkmcnt(1)
	v_bfe_u32 v2, v24, 16, 1
	v_and_or_b32 v10, v10, s64, v7
	v_add3_u32 v2, v24, v2, s63
	s_waitcnt lgkmcnt(0)
	v_bfe_u32 v7, v26, 16, 1
	v_lshrrev_b32_e32 v2, 16, v2
	v_add3_u32 v7, v26, v7, s63
	v_add_u32_e32 v30, 16, v28
	v_and_or_b32 v11, v7, s64, v2
	v_ashrrev_i32_e32 v31, 31, v30
	v_bfe_u32 v2, v15, 16, 1
	v_lshlrev_b64 v[30:31], 13, v[30:31]
	v_add3_u32 v2, v15, v2, s63
	v_bfe_u32 v7, v13, 16, 1
	v_lshl_add_u64 v[30:31], v[4:5], 0, v[30:31]
	v_lshrrev_b32_e32 v2, 16, v2
	v_add3_u32 v7, v13, v7, s63
	global_store_dwordx4 v[30:31], v[8:11], off
	v_add_u32_e32 v12, 24, v28
	v_ashrrev_i32_e32 v13, 31, v12
	v_and_or_b32 v8, v7, s64, v2
	v_bfe_u32 v2, v17, 16, 1
	v_add3_u32 v2, v17, v2, s63
	v_bfe_u32 v7, v19, 16, 1
	v_lshrrev_b32_e32 v2, 16, v2
	v_add3_u32 v7, v19, v7, s63
	v_and_or_b32 v9, v7, s64, v2
	v_bfe_u32 v2, v21, 16, 1
	v_add3_u32 v2, v21, v2, s63
	v_bfe_u32 v7, v23, 16, 1
	v_lshrrev_b32_e32 v2, 16, v2
	v_add3_u32 v7, v23, v7, s63
	v_and_or_b32 v10, v7, s64, v2
	v_bfe_u32 v2, v25, 16, 1
	v_add3_u32 v2, v25, v2, s63
	v_bfe_u32 v7, v27, 16, 1
	v_lshrrev_b32_e32 v2, 16, v2
	v_add3_u32 v7, v27, v7, s63
	v_lshlrev_b64 v[12:13], 13, v[12:13]
	v_and_or_b32 v11, v7, s64, v2
	v_lshl_add_u64 v[4:5], v[4:5], 0, v[12:13]
	global_store_dwordx4 v[4:5], v[8:11], off
	s_waitcnt lgkmcnt(0)
	s_branch .LBB0_1560
